# priority hand-off across the segment barriers: s_setprio 1 issued before the barrier that opens an MFMA segment, s_setprio 0 issued after the barrier that closes it (64 sites each)
# speedup vs baseline: 1.0004x; 1.0004x over previous
; #define PG8_STAGE(bufoff, gbase, voff) do { _Pragma("unroll") for (int _i = 0; _i < 2; ++_i) \
;         __builtin_amdgcn_global_load_lds((const unsigned*)((const char*)(gbase) + (voff)[_i]), (LAS unsigned*)(lds + (bufoff) + ldsw + _i * 8192), 16, 0, 0); } while (0)
; #define PG8_LDA(dst, b, h) do { _Pragma("unroll") for (int m = 0; m < 4; ++m) _Pragma("unroll") for (int k = 0; k < 2; ++k) dst[m][k] = *(const LAS bf16x8*)(lds + PG8_SA(b, h) + aoff + m * 2048 + k * 1024); } while (0)
; #define PG8_LDB(dst, b, h) do { _Pragma("unroll") for (int n = 0; n < 2; ++n) _Pragma("unroll") for (int k = 0; k < 2; ++k) dst[n][k] = *(const LAS bf16x8*)(lds + PG8_SB(b, h) + boff + n * 2048 + k * 1024); } while (0)
; #define PG8_MMA(ai, bj, At, Bt) do { __builtin_amdgcn_s_setprio(1); _Pragma("unroll") for (int k = 0; k < 2; ++k) _Pragma("unroll") for (int m = 0; m < 4; ++m) _Pragma("unroll") for (int n = 0; n < 2; ++n) \
;         acc[ai][bj][m][n] = __builtin_amdgcn_mfma_f32_16x16x32_bf16(Bt[n][k], At[m][k], acc[ai][bj][m][n], 0, 0, 0); __builtin_amdgcn_s_setprio(0); } while (0)
; template <class Epi, bool ALIGN_EPI>
; __device__ __forceinline__ void gemm_phase(LAS unsigned char* lds, const Gemm g, const StaticOrder& S, const Epi& E, const int tid) {
;     ...
;         const bool has_next = S.next(ui + 1, nxt);
;         const char* nA = has_next ? (const char*)g.A + (size_t)nxt.pm * tA + (size_t)nxt.pn * g.apn * 2 : cA; const char* nB = has_next ? (const char*)g.Bt + (size_t)nxt.pn * tB : cB;
;         for (int t = 0; t < nt; t += 2) {
;             const bool last = (t == nt - 2);
;             const char* a1 = cA + (size_t)(t + 1) * kstep;
;             const char* a2 = last ? nA : cA + (size_t)(t + 2) * kstep; const char* b2 = last ? nB : cB + (size_t)(t + 2) * kstep;
;             const char* a3 = a2 + kstep; const char* b3 = b2 + kstep;
;             PG8_LDB(B0, 0, 0); PG8_LDB(B1, 0, 1); PG8_SCHED; PG8_LDA(At, 0, 0); PG8_STAGE(PG8_SA(1, 1), a1 + hA, voffA);
;             PG8_WAIT_V(8); PG8_WAIT_L(0); PG8_BAR; PG8_MMA(0, 0, At, B0); PG8_MMA(0, 1, At, B1); PG8_BAR; PG8_SCHED;
;             PG8_LDA(At, 0, 1); PG8_STAGE(PG8_SB(0, 0), b2, voffB); PG8_STAGE(PG8_SB(0, 1), b2 + hB, voffB); PG8_STAGE(PG8_SA(0, 0), a2, voffA);
;             PG8_WAIT_V(8); PG8_WAIT_L(0); PG8_BAR; PG8_MMA(1, 0, At, B0); PG8_MMA(1, 1, At, B1); PG8_BAR; PG8_SCHED;
.LBB0_234:
	s_andn2_b64 vcc, exec, s[36:37]
	s_waitcnt lgkmcnt(0)
	s_cbranch_vccnz .LBB0_238
	s_add_u32 s12, s46, 0x100
	v_lshl_add_u64 v[128:129], v[128:129], 0, s[92:93]
	s_addc_u32 s13, s47, 0
	s_mov_b32 s46, 0
	s_add_i32 s47, s46, 2
	s_cmp_eq_u32 s60, s46
	s_cselect_b64 vcc, -1, 0
	s_cselect_b32 s71, s15, s13
	s_cselect_b32 s70, s14, s12
	s_add_i32 s46, 0, 0x14000
	v_lshl_add_u64 v[130:131], v[128:129], 0, s[92:93]
	v_add_u32_e32 v142, s33, v218
	v_add_u32_e32 v166, s46, v218
	v_cndmask_b32_e32 v159, v131, v165, vcc
	v_cndmask_b32_e32 v158, v130, v164, vcc
	ds_read_b128 v[130:133], v142
	ds_read_b128 v[134:137], v142 offset:1024
	ds_read_b128 v[138:141], v142 offset:2048
	ds_read_b128 v[142:145], v142 offset:3072
	ds_read_b128 v[146:149], v166
	ds_read_b128 v[150:153], v166 offset:1024
	ds_read_b128 v[154:157], v166 offset:2048
	ds_read_b128 v[186:189], v166 offset:3072
	v_lshl_add_u64 v[166:167], v[128:129], 0, v[160:161]
	s_add_i32 m0, s53, 0xc000
	ds_read_b128 v[190:193], v219
	ds_read_b128 v[194:197], v219 offset:1024
	ds_read_b128 v[198:201], v219 offset:2048
	ds_read_b128 v[202:205], v219 offset:3072
	ds_read_b128 v[206:209], v219 offset:4096
	ds_read_b128 v[210:213], v219 offset:5120
	ds_read_b128 v[240:243], v219 offset:6144
	ds_read_b128 v[244:247], v219 offset:7168
	global_load_lds_dwordx4 v[166:167], off
	v_lshl_add_u64 v[166:167], v[128:129], 0, v[162:163]
	s_add_i32 m0, s53, 0xe000
	s_nop 0
	global_load_lds_dwordx4 v[166:167], off
	s_waitcnt vmcnt(8)
	s_waitcnt lgkmcnt(0)
	s_setprio 1
	s_barrier
	s_waitcnt lgkmcnt(0)
	v_mfma_f32_16x16x32_bf16 v[120:123], v[130:133], v[190:193], 0
	v_mfma_f32_16x16x32_bf16 v[124:127], v[138:141], v[190:193], 0
	v_mfma_f32_16x16x32_bf16 v[108:111], v[130:133], v[198:201], 0
	v_mfma_f32_16x16x32_bf16 v[104:107], v[138:141], v[198:201], 0
	v_mfma_f32_16x16x32_bf16 v[92:95], v[130:133], v[206:209], 0
	v_mfma_f32_16x16x32_bf16 v[88:91], v[138:141], v[206:209], 0
	v_mfma_f32_16x16x32_bf16 v[76:79], v[130:133], v[240:243], 0
	v_mfma_f32_16x16x32_bf16 v[72:75], v[138:141], v[240:243], 0
	v_mfma_f32_16x16x32_bf16 v[120:123], v[134:137], v[194:197], v[120:123]
	v_mfma_f32_16x16x32_bf16 v[124:127], v[142:145], v[194:197], v[124:127]
	v_mfma_f32_16x16x32_bf16 v[108:111], v[134:137], v[202:205], v[108:111]
	v_mfma_f32_16x16x32_bf16 v[104:107], v[142:145], v[202:205], v[104:107]
	v_mfma_f32_16x16x32_bf16 v[92:95], v[134:137], v[210:213], v[92:95]
	v_mfma_f32_16x16x32_bf16 v[88:91], v[142:145], v[210:213], v[88:91]
	v_mfma_f32_16x16x32_bf16 v[76:79], v[134:137], v[244:247], v[76:79]
	v_mfma_f32_16x16x32_bf16 v[72:75], v[142:145], v[244:247], v[72:75]
	s_setprio 0
	s_setprio 1
	v_mfma_f32_16x16x32_bf16 v[116:119], v[146:149], v[190:193], 0
	v_mfma_f32_16x16x32_bf16 v[112:115], v[154:157], v[190:193], 0
	v_mfma_f32_16x16x32_bf16 v[100:103], v[146:149], v[198:201], 0
	v_mfma_f32_16x16x32_bf16 v[96:99], v[154:157], v[198:201], 0
	v_mfma_f32_16x16x32_bf16 v[84:87], v[146:149], v[206:209], 0
	v_mfma_f32_16x16x32_bf16 v[80:83], v[154:157], v[206:209], 0
	v_mfma_f32_16x16x32_bf16 v[68:71], v[146:149], v[240:243], 0
	v_mfma_f32_16x16x32_bf16 v[64:67], v[154:157], v[240:243], 0
	v_mfma_f32_16x16x32_bf16 v[116:119], v[150:153], v[194:197], v[116:119]
	v_mfma_f32_16x16x32_bf16 v[112:115], v[186:189], v[194:197], v[112:115]
	v_mfma_f32_16x16x32_bf16 v[100:103], v[150:153], v[202:205], v[100:103]
	v_mfma_f32_16x16x32_bf16 v[96:99], v[186:189], v[202:205], v[96:99]
	v_mfma_f32_16x16x32_bf16 v[84:87], v[150:153], v[210:213], v[84:87]
	v_mfma_f32_16x16x32_bf16 v[80:83], v[186:189], v[210:213], v[80:83]
	v_mfma_f32_16x16x32_bf16 v[68:71], v[150:153], v[244:247], v[68:71]
	v_mfma_f32_16x16x32_bf16 v[64:67], v[186:189], v[244:247], v[64:67]
	s_barrier
	s_setprio 0
	s_add_i32 s72, s33, s52
	v_lshl_add_u64 v[166:167], s[70:71], 0, v[180:181]
	s_mov_b32 m0, s72
	ds_read_b128 v[190:193], v219 offset:16384
	ds_read_b128 v[194:197], v219 offset:17408
	ds_read_b128 v[198:201], v219 offset:18432
	ds_read_b128 v[202:205], v219 offset:19456
	ds_read_b128 v[206:209], v219 offset:20480
	ds_read_b128 v[210:213], v219 offset:21504
	ds_read_b128 v[240:243], v219 offset:22528
	ds_read_b128 v[244:247], v219 offset:23552
	global_load_lds_dwordx4 v[166:167], off
	s_add_i32 m0, s72, 0x2000
	v_lshl_add_u64 v[214:215], s[70:71], 0, v[184:185]
	s_add_u32 s70, s70, s49
	s_addc_u32 s71, s71, 0
	s_add_i32 s46, s46, s52
	global_load_lds_dwordx4 v[214:215], off
	v_lshl_add_u64 v[220:221], s[70:71], 0, v[180:181]
	s_mov_b32 m0, s46
	v_lshl_add_u64 v[226:227], s[70:71], 0, v[184:185]
	global_load_lds_dwordx4 v[220:221], off
	s_add_i32 m0, s46, 0x2000
	v_lshl_add_u64 v[248:249], v[158:159], 0, v[178:179]
	global_load_lds_dwordx4 v[226:227], off
	s_mov_b32 m0, s53
	v_lshl_add_u64 v[250:251], v[158:159], 0, v[182:183]
	global_load_lds_dwordx4 v[248:249], off
	s_mov_b32 m0, s54
	s_nop 0
	global_load_lds_dwordx4 v[250:251], off
	s_waitcnt vmcnt(8)
	s_waitcnt lgkmcnt(0)
	s_setprio 1
	s_barrier
; #define PG8_STAGE(bufoff, gbase, voff) do { _Pragma("unroll") for (int _i = 0; _i < 2; ++_i) \
;         __builtin_amdgcn_global_load_lds((const unsigned*)((const char*)(gbase) + (voff)[_i]), (LAS unsigned*)(lds + (bufoff) + ldsw + _i * 8192), 16, 0, 0); } while (0)
; #define PG8_LDA(dst, b, h) do { _Pragma("unroll") for (int m = 0; m < 4; ++m) _Pragma("unroll") for (int k = 0; k < 2; ++k) dst[m][k] = *(const LAS bf16x8*)(lds + PG8_SA(b, h) + aoff + m * 2048 + k * 1024); } while (0)
; #define PG8_LDB(dst, b, h) do { _Pragma("unroll") for (int n = 0; n < 2; ++n) _Pragma("unroll") for (int k = 0; k < 2; ++k) dst[n][k] = *(const LAS bf16x8*)(lds + PG8_SB(b, h) + boff + n * 2048 + k * 1024); } while (0)
; #define PG8_MMA(ai, bj, At, Bt) do { __builtin_amdgcn_s_setprio(1); _Pragma("unroll") for (int k = 0; k < 2; ++k) _Pragma("unroll") for (int m = 0; m < 4; ++m) _Pragma("unroll") for (int n = 0; n < 2; ++n) \
;         acc[ai][bj][m][n] = __builtin_amdgcn_mfma_f32_16x16x32_bf16(Bt[n][k], At[m][k], acc[ai][bj][m][n], 0, 0, 0); __builtin_amdgcn_s_setprio(0); } while (0)
; #define PG8_WAIT_V(n) asm volatile("s_waitcnt vmcnt(" #n ")" ::: "memory")
; #define PG8_WAIT_L(n) asm volatile("s_waitcnt lgkmcnt(" #n ")" ::: "memory")
; #define PG8_BAR __builtin_amdgcn_s_barrier()
; #define PG8_SCHED __builtin_amdgcn_sched_barrier(0)
; template <class Epi, bool ALIGN_EPI>
; __device__ __forceinline__ void gemm_phase(LAS unsigned char* lds, const Gemm g, const StaticOrder& S, const Epi& E, const int tid) {
;     ...
;             PG8_WAIT_V(8); PG8_WAIT_L(0); PG8_BAR; PG8_MMA(1, 0, At, B0); PG8_MMA(1, 1, At, B1); PG8_BAR; PG8_SCHED;
;             PG8_LDB(B0, 1, 0); PG8_LDB(B1, 1, 1); PG8_SCHED; PG8_LDA(At, 1, 0); PG8_STAGE(PG8_SA(0, 1), a2 + hA, voffA);
;             PG8_WAIT_V(8); PG8_WAIT_L(0); PG8_BAR; PG8_MMA(0, 0, At, B0); PG8_MMA(0, 1, At, B1); PG8_BAR; PG8_SCHED;
;             PG8_LDA(At, 1, 1); PG8_STAGE(PG8_SB(1, 0), b3, voffB); PG8_STAGE(PG8_SB(1, 1), b3 + hB, voffB); PG8_STAGE(PG8_SA(1, 0), a3, voffA);
	s_waitcnt lgkmcnt(0)
	v_mfma_f32_16x16x32_bf16 v[60:63], v[130:133], v[190:193], 0
	v_mfma_f32_16x16x32_bf16 v[56:59], v[138:141], v[190:193], 0
	v_mfma_f32_16x16x32_bf16 v[44:47], v[130:133], v[198:201], 0
	v_mfma_f32_16x16x32_bf16 v[40:43], v[138:141], v[198:201], 0
	v_mfma_f32_16x16x32_bf16 v[28:31], v[130:133], v[206:209], 0
	v_mfma_f32_16x16x32_bf16 v[24:27], v[138:141], v[206:209], 0
	v_mfma_f32_16x16x32_bf16 v[12:15], v[130:133], v[240:243], 0
	v_mfma_f32_16x16x32_bf16 v[8:11], v[138:141], v[240:243], 0
	v_mfma_f32_16x16x32_bf16 v[60:63], v[134:137], v[194:197], v[60:63]
	v_mfma_f32_16x16x32_bf16 v[56:59], v[142:145], v[194:197], v[56:59]
	v_mfma_f32_16x16x32_bf16 v[44:47], v[134:137], v[202:205], v[44:47]
	v_mfma_f32_16x16x32_bf16 v[40:43], v[142:145], v[202:205], v[40:43]
	v_mfma_f32_16x16x32_bf16 v[28:31], v[134:137], v[210:213], v[28:31]
	v_mfma_f32_16x16x32_bf16 v[24:27], v[142:145], v[210:213], v[24:27]
	v_mfma_f32_16x16x32_bf16 v[12:15], v[134:137], v[244:247], v[12:15]
	v_mfma_f32_16x16x32_bf16 v[8:11], v[142:145], v[244:247], v[8:11]
	s_setprio 0
	s_setprio 1
	v_mfma_f32_16x16x32_bf16 v[52:55], v[146:149], v[190:193], 0
	v_mfma_f32_16x16x32_bf16 v[48:51], v[154:157], v[190:193], 0
	v_mfma_f32_16x16x32_bf16 v[36:39], v[146:149], v[198:201], 0
	v_mfma_f32_16x16x32_bf16 v[32:35], v[154:157], v[198:201], 0
	v_mfma_f32_16x16x32_bf16 v[20:23], v[146:149], v[206:209], 0
	v_mfma_f32_16x16x32_bf16 v[16:19], v[154:157], v[206:209], 0
	v_mfma_f32_16x16x32_bf16 v[4:7], v[146:149], v[240:243], 0
	v_mfma_f32_16x16x32_bf16 v[0:3], v[154:157], v[240:243], 0
	v_mfma_f32_16x16x32_bf16 v[52:55], v[150:153], v[194:197], v[52:55]
	v_mfma_f32_16x16x32_bf16 v[48:51], v[186:189], v[194:197], v[48:51]
	v_mfma_f32_16x16x32_bf16 v[36:39], v[150:153], v[202:205], v[36:39]
	v_mfma_f32_16x16x32_bf16 v[32:35], v[186:189], v[202:205], v[32:35]
	v_mfma_f32_16x16x32_bf16 v[20:23], v[150:153], v[210:213], v[20:23]
	v_mfma_f32_16x16x32_bf16 v[16:19], v[186:189], v[210:213], v[16:19]
	v_mfma_f32_16x16x32_bf16 v[4:7], v[150:153], v[244:247], v[4:7]
	v_mfma_f32_16x16x32_bf16 v[0:3], v[186:189], v[244:247], v[0:3]
	s_barrier
	s_setprio 0
	s_add_i32 s46, 0, 0x18000
	s_add_i32 s70, 0, 0x1c000
	v_add_u32_e32 v142, s46, v218
	v_add_u32_e32 v168, s70, v218
	ds_read_b128 v[130:133], v142
	ds_read_b128 v[134:137], v142 offset:1024
	ds_read_b128 v[138:141], v142 offset:2048
	ds_read_b128 v[142:145], v142 offset:3072
	ds_read_b128 v[146:149], v168
	ds_read_b128 v[150:153], v168 offset:1024
	ds_read_b128 v[154:157], v168 offset:2048
	ds_read_b128 v[186:189], v168 offset:3072
	v_lshl_add_u64 v[158:159], v[158:159], 0, s[94:95]
	s_mov_b32 m0, s55
	v_lshl_add_u64 v[252:253], v[158:159], 0, v[178:179]
	ds_read_b128 v[190:193], v219 offset:32768
	ds_read_b128 v[194:197], v219 offset:33792
	ds_read_b128 v[198:201], v219 offset:34816
	ds_read_b128 v[202:205], v219 offset:35840
	ds_read_b128 v[206:209], v219 offset:36864
	ds_read_b128 v[210:213], v219 offset:37888
	ds_read_b128 v[240:243], v219 offset:38912
	ds_read_b128 v[244:247], v219 offset:39936
	global_load_lds_dwordx4 v[252:253], off
	v_lshl_add_u64 v[158:159], v[158:159], 0, v[182:183]
	s_mov_b32 m0, s56
	s_nop 0
	global_load_lds_dwordx4 v[158:159], off
	s_waitcnt vmcnt(8)
	s_waitcnt lgkmcnt(0)
	s_setprio 1
	s_barrier
	s_waitcnt lgkmcnt(0)
	v_mfma_f32_16x16x32_bf16 v[120:123], v[130:133], v[190:193], v[120:123]
	v_mfma_f32_16x16x32_bf16 v[124:127], v[138:141], v[190:193], v[124:127]
	v_mfma_f32_16x16x32_bf16 v[108:111], v[130:133], v[198:201], v[108:111]
	v_mfma_f32_16x16x32_bf16 v[104:107], v[138:141], v[198:201], v[104:107]
	v_mfma_f32_16x16x32_bf16 v[92:95], v[130:133], v[206:209], v[92:95]
	v_mfma_f32_16x16x32_bf16 v[88:91], v[138:141], v[206:209], v[88:91]
	v_mfma_f32_16x16x32_bf16 v[76:79], v[130:133], v[240:243], v[76:79]
	v_mfma_f32_16x16x32_bf16 v[72:75], v[138:141], v[240:243], v[72:75]
	v_mfma_f32_16x16x32_bf16 v[120:123], v[134:137], v[194:197], v[120:123]
	v_mfma_f32_16x16x32_bf16 v[124:127], v[142:145], v[194:197], v[124:127]
	v_mfma_f32_16x16x32_bf16 v[108:111], v[134:137], v[202:205], v[108:111]
	v_mfma_f32_16x16x32_bf16 v[104:107], v[142:145], v[202:205], v[104:107]
	v_mfma_f32_16x16x32_bf16 v[92:95], v[134:137], v[210:213], v[92:95]
	v_mfma_f32_16x16x32_bf16 v[88:91], v[142:145], v[210:213], v[88:91]
	v_mfma_f32_16x16x32_bf16 v[76:79], v[134:137], v[244:247], v[76:79]
	v_mfma_f32_16x16x32_bf16 v[72:75], v[142:145], v[244:247], v[72:75]
	s_setprio 0
	s_setprio 1
	v_mfma_f32_16x16x32_bf16 v[116:119], v[146:149], v[190:193], v[116:119]
	v_mfma_f32_16x16x32_bf16 v[112:115], v[154:157], v[190:193], v[112:115]
	v_mfma_f32_16x16x32_bf16 v[100:103], v[146:149], v[198:201], v[100:103]
	v_mfma_f32_16x16x32_bf16 v[96:99], v[154:157], v[198:201], v[96:99]
	v_mfma_f32_16x16x32_bf16 v[84:87], v[146:149], v[206:209], v[84:87]
	v_mfma_f32_16x16x32_bf16 v[80:83], v[154:157], v[206:209], v[80:83]
	v_mfma_f32_16x16x32_bf16 v[68:71], v[146:149], v[240:243], v[68:71]
	v_mfma_f32_16x16x32_bf16 v[64:67], v[154:157], v[240:243], v[64:67]
	v_mfma_f32_16x16x32_bf16 v[116:119], v[150:153], v[194:197], v[116:119]
	v_mfma_f32_16x16x32_bf16 v[112:115], v[186:189], v[194:197], v[112:115]
	v_mfma_f32_16x16x32_bf16 v[100:103], v[150:153], v[202:205], v[100:103]
	v_mfma_f32_16x16x32_bf16 v[96:99], v[186:189], v[202:205], v[96:99]
	v_mfma_f32_16x16x32_bf16 v[84:87], v[150:153], v[210:213], v[84:87]
	v_mfma_f32_16x16x32_bf16 v[80:83], v[186:189], v[210:213], v[80:83]
	v_mfma_f32_16x16x32_bf16 v[68:71], v[150:153], v[244:247], v[68:71]
	v_mfma_f32_16x16x32_bf16 v[64:67], v[186:189], v[244:247], v[64:67]
	s_barrier
; #define PG8_STAGE(bufoff, gbase, voff) do { _Pragma("unroll") for (int _i = 0; _i < 2; ++_i) \
;         __builtin_amdgcn_global_load_lds((const unsigned*)((const char*)(gbase) + (voff)[_i]), (LAS unsigned*)(lds + (bufoff) + ldsw + _i * 8192), 16, 0, 0); } while (0)
; #define PG8_LDA(dst, b, h) do { _Pragma("unroll") for (int m = 0; m < 4; ++m) _Pragma("unroll") for (int k = 0; k < 2; ++k) dst[m][k] = *(const LAS bf16x8*)(lds + PG8_SA(b, h) + aoff + m * 2048 + k * 1024); } while (0)
; #define PG8_LDB(dst, b, h) do { _Pragma("unroll") for (int n = 0; n < 2; ++n) _Pragma("unroll") for (int k = 0; k < 2; ++k) dst[n][k] = *(const LAS bf16x8*)(lds + PG8_SB(b, h) + boff + n * 2048 + k * 1024); } while (0)
; #define PG8_MMA(ai, bj, At, Bt) do { __builtin_amdgcn_s_setprio(1); _Pragma("unroll") for (int k = 0; k < 2; ++k) _Pragma("unroll") for (int m = 0; m < 4; ++m) _Pragma("unroll") for (int n = 0; n < 2; ++n) \
;         acc[ai][bj][m][n] = __builtin_amdgcn_mfma_f32_16x16x32_bf16(Bt[n][k], At[m][k], acc[ai][bj][m][n], 0, 0, 0); __builtin_amdgcn_s_setprio(0); } while (0)
; #define PG8_WAIT_V(n) asm volatile("s_waitcnt vmcnt(" #n ")" ::: "memory")
; #define PG8_WAIT_L(n) asm volatile("s_waitcnt lgkmcnt(" #n ")" ::: "memory")
; #define PG8_BAR __builtin_amdgcn_s_barrier()
; #define PG8_SCHED __builtin_amdgcn_sched_barrier(0)
; template <class Epi, bool ALIGN_EPI>
; __device__ __forceinline__ void gemm_phase(LAS unsigned char* lds, const Gemm g, const StaticOrder& S, const Epi& E, const int tid) {
;     ...
;             PG8_LDB(B0, 0, 0); PG8_LDB(B1, 0, 1); PG8_SCHED; PG8_LDA(At, 0, 0); PG8_STAGE(PG8_SA(1, 1), a1 + hA, voffA);
;             PG8_WAIT_V(8); PG8_WAIT_L(0); PG8_BAR; PG8_MMA(0, 0, At, B0); PG8_MMA(0, 1, At, B1); PG8_BAR; PG8_SCHED;
;     ...
;             PG8_LDA(At, 1, 1); PG8_STAGE(PG8_SB(1, 0), b3, voffB); PG8_STAGE(PG8_SB(1, 1), b3 + hB, voffB); PG8_STAGE(PG8_SA(1, 0), a3, voffA);
;             PG8_WAIT_V(8); PG8_WAIT_L(0); PG8_BAR; PG8_MMA(1, 0, At, B0); PG8_MMA(1, 1, At, B1); PG8_BAR; PG8_SCHED;
	s_setprio 0
	s_add_i32 s46, s46, s52
	v_lshl_add_u64 v[158:159], v[166:167], 0, s[92:93]
	s_mov_b32 m0, s46
	ds_read_b128 v[190:193], v219 offset:49152
	ds_read_b128 v[194:197], v219 offset:50176
	ds_read_b128 v[198:201], v219 offset:51200
	ds_read_b128 v[202:205], v219 offset:52224
	ds_read_b128 v[206:209], v219 offset:53248
	ds_read_b128 v[210:213], v219 offset:54272
	ds_read_b128 v[240:243], v219 offset:55296
	ds_read_b128 v[244:247], v219 offset:56320
	global_load_lds_dwordx4 v[158:159], off
	v_lshl_add_u64 v[158:159], v[214:215], 0, s[92:93]
	s_add_i32 m0, s46, 0x2000
	s_add_i32 s46, s70, s52
	global_load_lds_dwordx4 v[158:159], off
	v_lshl_add_u64 v[158:159], v[220:221], 0, s[92:93]
	s_mov_b32 m0, s46
	s_nop 0
	global_load_lds_dwordx4 v[158:159], off
	v_lshl_add_u64 v[158:159], v[226:227], 0, s[92:93]
	s_add_i32 m0, s46, 0x2000
	s_nop 0
	global_load_lds_dwordx4 v[158:159], off
	v_lshl_add_u64 v[158:159], v[248:249], 0, s[92:93]
	s_mov_b32 m0, s57
	s_nop 0
	global_load_lds_dwordx4 v[158:159], off
	v_lshl_add_u64 v[158:159], v[250:251], 0, s[92:93]
	s_mov_b32 m0, s58
	s_nop 0
	global_load_lds_dwordx4 v[158:159], off
	s_waitcnt vmcnt(8)
	s_waitcnt lgkmcnt(0)
	s_setprio 1
	s_barrier
	s_waitcnt lgkmcnt(0)
	v_mfma_f32_16x16x32_bf16 v[60:63], v[130:133], v[190:193], v[60:63]
	v_mfma_f32_16x16x32_bf16 v[56:59], v[138:141], v[190:193], v[56:59]
	v_mfma_f32_16x16x32_bf16 v[44:47], v[130:133], v[198:201], v[44:47]
	v_mfma_f32_16x16x32_bf16 v[40:43], v[138:141], v[198:201], v[40:43]
	v_mfma_f32_16x16x32_bf16 v[28:31], v[130:133], v[206:209], v[28:31]
	v_mfma_f32_16x16x32_bf16 v[24:27], v[138:141], v[206:209], v[24:27]
	v_mfma_f32_16x16x32_bf16 v[12:15], v[130:133], v[240:243], v[12:15]
	v_mfma_f32_16x16x32_bf16 v[8:11], v[138:141], v[240:243], v[8:11]
	v_mfma_f32_16x16x32_bf16 v[60:63], v[134:137], v[194:197], v[60:63]
	v_mfma_f32_16x16x32_bf16 v[56:59], v[142:145], v[194:197], v[56:59]
	v_mfma_f32_16x16x32_bf16 v[44:47], v[134:137], v[202:205], v[44:47]
	v_mfma_f32_16x16x32_bf16 v[40:43], v[142:145], v[202:205], v[40:43]
	v_mfma_f32_16x16x32_bf16 v[28:31], v[134:137], v[210:213], v[28:31]
	v_mfma_f32_16x16x32_bf16 v[24:27], v[142:145], v[210:213], v[24:27]
	v_mfma_f32_16x16x32_bf16 v[12:15], v[134:137], v[244:247], v[12:15]
	v_mfma_f32_16x16x32_bf16 v[8:11], v[142:145], v[244:247], v[8:11]
	s_setprio 0
	s_setprio 1
	v_mfma_f32_16x16x32_bf16 v[52:55], v[146:149], v[190:193], v[52:55]
	v_mfma_f32_16x16x32_bf16 v[48:51], v[154:157], v[190:193], v[48:51]
	v_mfma_f32_16x16x32_bf16 v[36:39], v[146:149], v[198:201], v[36:39]
	v_mfma_f32_16x16x32_bf16 v[32:35], v[154:157], v[198:201], v[32:35]
	v_mfma_f32_16x16x32_bf16 v[20:23], v[146:149], v[206:209], v[20:23]
	v_mfma_f32_16x16x32_bf16 v[16:19], v[154:157], v[206:209], v[16:19]
	v_mfma_f32_16x16x32_bf16 v[4:7], v[146:149], v[240:243], v[4:7]
	v_mfma_f32_16x16x32_bf16 v[0:3], v[154:157], v[240:243], v[0:3]
	v_mfma_f32_16x16x32_bf16 v[52:55], v[150:153], v[194:197], v[52:55]
	v_mfma_f32_16x16x32_bf16 v[48:51], v[186:189], v[194:197], v[48:51]
	v_mfma_f32_16x16x32_bf16 v[36:39], v[150:153], v[202:205], v[36:39]
	v_mfma_f32_16x16x32_bf16 v[32:35], v[186:189], v[202:205], v[32:35]
	v_mfma_f32_16x16x32_bf16 v[20:23], v[150:153], v[210:213], v[20:23]
	v_mfma_f32_16x16x32_bf16 v[16:19], v[186:189], v[210:213], v[16:19]
	v_mfma_f32_16x16x32_bf16 v[4:7], v[150:153], v[244:247], v[4:7]
	v_mfma_f32_16x16x32_bf16 v[0:3], v[186:189], v[244:247], v[0:3]
	s_barrier
	s_setprio 0
	s_add_u32 s12, s12, 0x100
	s_addc_u32 s13, s13, 0
	v_lshl_add_u64 v[128:129], v[128:129], 0, s[80:81]
	s_cmp_ge_u32 s47, s48
	s_mov_b32 s46, s47
	s_cbranch_scc1 .Lpl1_after
.LBB0_236:
	s_add_i32 s47, s46, 2
	s_cmp_eq_u32 s60, s46
	s_cselect_b64 vcc, -1, 0
	s_cselect_b32 s71, s15, s13
	s_cselect_b32 s70, s14, s12
	s_add_i32 s46, 0, 0x14000
	v_lshl_add_u64 v[130:131], v[128:129], 0, s[92:93]
	v_add_u32_e32 v142, s33, v218
	v_add_u32_e32 v166, s46, v218
	v_cndmask_b32_e32 v159, v131, v165, vcc
	v_cndmask_b32_e32 v158, v130, v164, vcc
	ds_read_b128 v[130:133], v142
	ds_read_b128 v[134:137], v142 offset:1024
	ds_read_b128 v[138:141], v142 offset:2048
	ds_read_b128 v[142:145], v142 offset:3072
	ds_read_b128 v[146:149], v166
	ds_read_b128 v[150:153], v166 offset:1024
	ds_read_b128 v[154:157], v166 offset:2048
	ds_read_b128 v[186:189], v166 offset:3072
	v_lshl_add_u64 v[166:167], v[128:129], 0, v[160:161]
	s_add_i32 m0, s53, 0xc000
	ds_read_b128 v[190:193], v219
	ds_read_b128 v[194:197], v219 offset:1024
	ds_read_b128 v[198:201], v219 offset:2048
	ds_read_b128 v[202:205], v219 offset:3072
	ds_read_b128 v[206:209], v219 offset:4096
	ds_read_b128 v[210:213], v219 offset:5120
	ds_read_b128 v[240:243], v219 offset:6144
	ds_read_b128 v[244:247], v219 offset:7168
	global_load_lds_dwordx4 v[166:167], off
	v_lshl_add_u64 v[166:167], v[128:129], 0, v[162:163]
	s_add_i32 m0, s53, 0xe000
	s_nop 0
	global_load_lds_dwordx4 v[166:167], off
	s_waitcnt vmcnt(8)
	s_waitcnt lgkmcnt(0)
	s_setprio 1
	s_barrier
; #define PG8_STAGE(bufoff, gbase, voff) do { _Pragma("unroll") for (int _i = 0; _i < 2; ++_i) \
;         __builtin_amdgcn_global_load_lds((const unsigned*)((const char*)(gbase) + (voff)[_i]), (LAS unsigned*)(lds + (bufoff) + ldsw + _i * 8192), 16, 0, 0); } while (0)
; #define PG8_LDA(dst, b, h) do { _Pragma("unroll") for (int m = 0; m < 4; ++m) _Pragma("unroll") for (int k = 0; k < 2; ++k) dst[m][k] = *(const LAS bf16x8*)(lds + PG8_SA(b, h) + aoff + m * 2048 + k * 1024); } while (0)
; #define PG8_LDB(dst, b, h) do { _Pragma("unroll") for (int n = 0; n < 2; ++n) _Pragma("unroll") for (int k = 0; k < 2; ++k) dst[n][k] = *(const LAS bf16x8*)(lds + PG8_SB(b, h) + boff + n * 2048 + k * 1024); } while (0)
; #define PG8_MMA(ai, bj, At, Bt) do { __builtin_amdgcn_s_setprio(1); _Pragma("unroll") for (int k = 0; k < 2; ++k) _Pragma("unroll") for (int m = 0; m < 4; ++m) _Pragma("unroll") for (int n = 0; n < 2; ++n) \
;         acc[ai][bj][m][n] = __builtin_amdgcn_mfma_f32_16x16x32_bf16(Bt[n][k], At[m][k], acc[ai][bj][m][n], 0, 0, 0); __builtin_amdgcn_s_setprio(0); } while (0)
; #define PG8_WAIT_V(n) asm volatile("s_waitcnt vmcnt(" #n ")" ::: "memory")
; #define PG8_WAIT_L(n) asm volatile("s_waitcnt lgkmcnt(" #n ")" ::: "memory")
; #define PG8_BAR __builtin_amdgcn_s_barrier()
; #define PG8_SCHED __builtin_amdgcn_sched_barrier(0)
; template <class Epi, bool ALIGN_EPI>
; __device__ __forceinline__ void gemm_phase(LAS unsigned char* lds, const Gemm g, const StaticOrder& S, const Epi& E, const int tid) {
;     ...
;             PG8_WAIT_V(8); PG8_WAIT_L(0); PG8_BAR; PG8_MMA(0, 0, At, B0); PG8_MMA(0, 1, At, B1); PG8_BAR; PG8_SCHED;
;             PG8_LDA(At, 0, 1); PG8_STAGE(PG8_SB(0, 0), b2, voffB); PG8_STAGE(PG8_SB(0, 1), b2 + hB, voffB); PG8_STAGE(PG8_SA(0, 0), a2, voffA);
;             PG8_WAIT_V(8); PG8_WAIT_L(0); PG8_BAR; PG8_MMA(1, 0, At, B0); PG8_MMA(1, 1, At, B1); PG8_BAR; PG8_SCHED;
;             PG8_LDB(B0, 1, 0); PG8_LDB(B1, 1, 1); PG8_SCHED; PG8_LDA(At, 1, 0); PG8_STAGE(PG8_SA(0, 1), a2 + hA, voffA);
;             PG8_WAIT_V(8); PG8_WAIT_L(0); PG8_BAR; PG8_MMA(0, 0, At, B0); PG8_MMA(0, 1, At, B1); PG8_BAR; PG8_SCHED;
	s_waitcnt lgkmcnt(0)
	v_mfma_f32_16x16x32_bf16 v[120:123], v[130:133], v[190:193], v[120:123]
	v_mfma_f32_16x16x32_bf16 v[124:127], v[138:141], v[190:193], v[124:127]
	v_mfma_f32_16x16x32_bf16 v[108:111], v[130:133], v[198:201], v[108:111]
	v_mfma_f32_16x16x32_bf16 v[104:107], v[138:141], v[198:201], v[104:107]
	v_mfma_f32_16x16x32_bf16 v[92:95], v[130:133], v[206:209], v[92:95]
	v_mfma_f32_16x16x32_bf16 v[88:91], v[138:141], v[206:209], v[88:91]
	v_mfma_f32_16x16x32_bf16 v[76:79], v[130:133], v[240:243], v[76:79]
	v_mfma_f32_16x16x32_bf16 v[72:75], v[138:141], v[240:243], v[72:75]
	v_mfma_f32_16x16x32_bf16 v[120:123], v[134:137], v[194:197], v[120:123]
	v_mfma_f32_16x16x32_bf16 v[124:127], v[142:145], v[194:197], v[124:127]
	v_mfma_f32_16x16x32_bf16 v[108:111], v[134:137], v[202:205], v[108:111]
	v_mfma_f32_16x16x32_bf16 v[104:107], v[142:145], v[202:205], v[104:107]
	v_mfma_f32_16x16x32_bf16 v[92:95], v[134:137], v[210:213], v[92:95]
	v_mfma_f32_16x16x32_bf16 v[88:91], v[142:145], v[210:213], v[88:91]
	v_mfma_f32_16x16x32_bf16 v[76:79], v[134:137], v[244:247], v[76:79]
	v_mfma_f32_16x16x32_bf16 v[72:75], v[142:145], v[244:247], v[72:75]
	s_setprio 0
	s_setprio 1
	v_mfma_f32_16x16x32_bf16 v[116:119], v[146:149], v[190:193], v[116:119]
	v_mfma_f32_16x16x32_bf16 v[112:115], v[154:157], v[190:193], v[112:115]
	v_mfma_f32_16x16x32_bf16 v[100:103], v[146:149], v[198:201], v[100:103]
	v_mfma_f32_16x16x32_bf16 v[96:99], v[154:157], v[198:201], v[96:99]
	v_mfma_f32_16x16x32_bf16 v[84:87], v[146:149], v[206:209], v[84:87]
	v_mfma_f32_16x16x32_bf16 v[80:83], v[154:157], v[206:209], v[80:83]
	v_mfma_f32_16x16x32_bf16 v[68:71], v[146:149], v[240:243], v[68:71]
	v_mfma_f32_16x16x32_bf16 v[64:67], v[154:157], v[240:243], v[64:67]
	v_mfma_f32_16x16x32_bf16 v[116:119], v[150:153], v[194:197], v[116:119]
	v_mfma_f32_16x16x32_bf16 v[112:115], v[186:189], v[194:197], v[112:115]
	v_mfma_f32_16x16x32_bf16 v[100:103], v[150:153], v[202:205], v[100:103]
	v_mfma_f32_16x16x32_bf16 v[96:99], v[186:189], v[202:205], v[96:99]
	v_mfma_f32_16x16x32_bf16 v[84:87], v[150:153], v[210:213], v[84:87]
	v_mfma_f32_16x16x32_bf16 v[80:83], v[186:189], v[210:213], v[80:83]
	v_mfma_f32_16x16x32_bf16 v[68:71], v[150:153], v[244:247], v[68:71]
	v_mfma_f32_16x16x32_bf16 v[64:67], v[186:189], v[244:247], v[64:67]
	s_barrier
	s_setprio 0
	s_add_i32 s72, s33, s52
	v_lshl_add_u64 v[166:167], s[70:71], 0, v[180:181]
	s_mov_b32 m0, s72
	ds_read_b128 v[190:193], v219 offset:16384
	ds_read_b128 v[194:197], v219 offset:17408
	ds_read_b128 v[198:201], v219 offset:18432
	ds_read_b128 v[202:205], v219 offset:19456
	ds_read_b128 v[206:209], v219 offset:20480
	ds_read_b128 v[210:213], v219 offset:21504
	ds_read_b128 v[240:243], v219 offset:22528
	ds_read_b128 v[244:247], v219 offset:23552
	global_load_lds_dwordx4 v[166:167], off
	s_add_i32 m0, s72, 0x2000
	v_lshl_add_u64 v[214:215], s[70:71], 0, v[184:185]
	s_add_u32 s70, s70, s49
	s_addc_u32 s71, s71, 0
	s_add_i32 s46, s46, s52
	global_load_lds_dwordx4 v[214:215], off
	v_lshl_add_u64 v[220:221], s[70:71], 0, v[180:181]
	s_mov_b32 m0, s46
	v_lshl_add_u64 v[226:227], s[70:71], 0, v[184:185]
	global_load_lds_dwordx4 v[220:221], off
	s_add_i32 m0, s46, 0x2000
	v_lshl_add_u64 v[248:249], v[158:159], 0, v[178:179]
	global_load_lds_dwordx4 v[226:227], off
	s_mov_b32 m0, s53
	v_lshl_add_u64 v[250:251], v[158:159], 0, v[182:183]
	global_load_lds_dwordx4 v[248:249], off
	s_mov_b32 m0, s54
	s_nop 0
	global_load_lds_dwordx4 v[250:251], off
	s_waitcnt vmcnt(8)
	s_waitcnt lgkmcnt(0)
	s_setprio 1
	s_barrier
	s_waitcnt lgkmcnt(0)
	v_mfma_f32_16x16x32_bf16 v[60:63], v[130:133], v[190:193], v[60:63]
	v_mfma_f32_16x16x32_bf16 v[56:59], v[138:141], v[190:193], v[56:59]
	v_mfma_f32_16x16x32_bf16 v[44:47], v[130:133], v[198:201], v[44:47]
	v_mfma_f32_16x16x32_bf16 v[40:43], v[138:141], v[198:201], v[40:43]
	v_mfma_f32_16x16x32_bf16 v[28:31], v[130:133], v[206:209], v[28:31]
	v_mfma_f32_16x16x32_bf16 v[24:27], v[138:141], v[206:209], v[24:27]
	v_mfma_f32_16x16x32_bf16 v[12:15], v[130:133], v[240:243], v[12:15]
	v_mfma_f32_16x16x32_bf16 v[8:11], v[138:141], v[240:243], v[8:11]
	v_mfma_f32_16x16x32_bf16 v[60:63], v[134:137], v[194:197], v[60:63]
	v_mfma_f32_16x16x32_bf16 v[56:59], v[142:145], v[194:197], v[56:59]
	v_mfma_f32_16x16x32_bf16 v[44:47], v[134:137], v[202:205], v[44:47]
	v_mfma_f32_16x16x32_bf16 v[40:43], v[142:145], v[202:205], v[40:43]
	v_mfma_f32_16x16x32_bf16 v[28:31], v[134:137], v[210:213], v[28:31]
	v_mfma_f32_16x16x32_bf16 v[24:27], v[142:145], v[210:213], v[24:27]
	v_mfma_f32_16x16x32_bf16 v[12:15], v[134:137], v[244:247], v[12:15]
	v_mfma_f32_16x16x32_bf16 v[8:11], v[142:145], v[244:247], v[8:11]
	s_setprio 0
	s_setprio 1
	v_mfma_f32_16x16x32_bf16 v[52:55], v[146:149], v[190:193], v[52:55]
	v_mfma_f32_16x16x32_bf16 v[48:51], v[154:157], v[190:193], v[48:51]
	v_mfma_f32_16x16x32_bf16 v[36:39], v[146:149], v[198:201], v[36:39]
	v_mfma_f32_16x16x32_bf16 v[32:35], v[154:157], v[198:201], v[32:35]
	v_mfma_f32_16x16x32_bf16 v[20:23], v[146:149], v[206:209], v[20:23]
	v_mfma_f32_16x16x32_bf16 v[16:19], v[154:157], v[206:209], v[16:19]
	v_mfma_f32_16x16x32_bf16 v[4:7], v[146:149], v[240:243], v[4:7]
	v_mfma_f32_16x16x32_bf16 v[0:3], v[154:157], v[240:243], v[0:3]
	v_mfma_f32_16x16x32_bf16 v[52:55], v[150:153], v[194:197], v[52:55]
	v_mfma_f32_16x16x32_bf16 v[48:51], v[186:189], v[194:197], v[48:51]
	v_mfma_f32_16x16x32_bf16 v[36:39], v[150:153], v[202:205], v[36:39]
	v_mfma_f32_16x16x32_bf16 v[32:35], v[186:189], v[202:205], v[32:35]
	v_mfma_f32_16x16x32_bf16 v[20:23], v[150:153], v[210:213], v[20:23]
	v_mfma_f32_16x16x32_bf16 v[16:19], v[186:189], v[210:213], v[16:19]
	v_mfma_f32_16x16x32_bf16 v[4:7], v[150:153], v[244:247], v[4:7]
	v_mfma_f32_16x16x32_bf16 v[0:3], v[186:189], v[244:247], v[0:3]
	s_barrier
; #define PG8_STAGE(bufoff, gbase, voff) do { _Pragma("unroll") for (int _i = 0; _i < 2; ++_i) \
;         __builtin_amdgcn_global_load_lds((const unsigned*)((const char*)(gbase) + (voff)[_i]), (LAS unsigned*)(lds + (bufoff) + ldsw + _i * 8192), 16, 0, 0); } while (0)
; #define PG8_LDA(dst, b, h) do { _Pragma("unroll") for (int m = 0; m < 4; ++m) _Pragma("unroll") for (int k = 0; k < 2; ++k) dst[m][k] = *(const LAS bf16x8*)(lds + PG8_SA(b, h) + aoff + m * 2048 + k * 1024); } while (0)
; #define PG8_LDB(dst, b, h) do { _Pragma("unroll") for (int n = 0; n < 2; ++n) _Pragma("unroll") for (int k = 0; k < 2; ++k) dst[n][k] = *(const LAS bf16x8*)(lds + PG8_SB(b, h) + boff + n * 2048 + k * 1024); } while (0)
; #define PG8_MMA(ai, bj, At, Bt) do { __builtin_amdgcn_s_setprio(1); _Pragma("unroll") for (int k = 0; k < 2; ++k) _Pragma("unroll") for (int m = 0; m < 4; ++m) _Pragma("unroll") for (int n = 0; n < 2; ++n) \
;         acc[ai][bj][m][n] = __builtin_amdgcn_mfma_f32_16x16x32_bf16(Bt[n][k], At[m][k], acc[ai][bj][m][n], 0, 0, 0); __builtin_amdgcn_s_setprio(0); } while (0)
; #define PG8_WAIT_V(n) asm volatile("s_waitcnt vmcnt(" #n ")" ::: "memory")
; #define PG8_WAIT_L(n) asm volatile("s_waitcnt lgkmcnt(" #n ")" ::: "memory")
; #define PG8_BAR __builtin_amdgcn_s_barrier()
; #define PG8_SCHED __builtin_amdgcn_sched_barrier(0)
; template <class Epi, bool ALIGN_EPI>
; __device__ __forceinline__ void gemm_phase(LAS unsigned char* lds, const Gemm g, const StaticOrder& S, const Epi& E, const int tid) {
;     ...
;             PG8_LDB(B0, 1, 0); PG8_LDB(B1, 1, 1); PG8_SCHED; PG8_LDA(At, 1, 0); PG8_STAGE(PG8_SA(0, 1), a2 + hA, voffA);
;             PG8_WAIT_V(8); PG8_WAIT_L(0); PG8_BAR; PG8_MMA(0, 0, At, B0); PG8_MMA(0, 1, At, B1); PG8_BAR; PG8_SCHED;
;             PG8_LDA(At, 1, 1); PG8_STAGE(PG8_SB(1, 0), b3, voffB); PG8_STAGE(PG8_SB(1, 1), b3 + hB, voffB); PG8_STAGE(PG8_SA(1, 0), a3, voffA);
	s_setprio 0
	s_add_i32 s46, 0, 0x18000
	s_add_i32 s70, 0, 0x1c000
	v_add_u32_e32 v142, s46, v218
	v_add_u32_e32 v168, s70, v218
	ds_read_b128 v[130:133], v142
	ds_read_b128 v[134:137], v142 offset:1024
	ds_read_b128 v[138:141], v142 offset:2048
	ds_read_b128 v[142:145], v142 offset:3072
	ds_read_b128 v[146:149], v168
	ds_read_b128 v[150:153], v168 offset:1024
	ds_read_b128 v[154:157], v168 offset:2048
	ds_read_b128 v[186:189], v168 offset:3072
	v_lshl_add_u64 v[158:159], v[158:159], 0, s[94:95]
	s_mov_b32 m0, s55
	v_lshl_add_u64 v[252:253], v[158:159], 0, v[178:179]
	ds_read_b128 v[190:193], v219 offset:32768
	ds_read_b128 v[194:197], v219 offset:33792
	ds_read_b128 v[198:201], v219 offset:34816
	ds_read_b128 v[202:205], v219 offset:35840
	ds_read_b128 v[206:209], v219 offset:36864
	ds_read_b128 v[210:213], v219 offset:37888
	ds_read_b128 v[240:243], v219 offset:38912
	ds_read_b128 v[244:247], v219 offset:39936
	global_load_lds_dwordx4 v[252:253], off
	v_lshl_add_u64 v[158:159], v[158:159], 0, v[182:183]
	s_mov_b32 m0, s56
	s_nop 0
	global_load_lds_dwordx4 v[158:159], off
	s_waitcnt vmcnt(8)
	s_waitcnt lgkmcnt(0)
	s_setprio 1
	s_barrier
	s_waitcnt lgkmcnt(0)
	v_mfma_f32_16x16x32_bf16 v[120:123], v[130:133], v[190:193], v[120:123]
	v_mfma_f32_16x16x32_bf16 v[124:127], v[138:141], v[190:193], v[124:127]
	v_mfma_f32_16x16x32_bf16 v[108:111], v[130:133], v[198:201], v[108:111]
	v_mfma_f32_16x16x32_bf16 v[104:107], v[138:141], v[198:201], v[104:107]
	v_mfma_f32_16x16x32_bf16 v[92:95], v[130:133], v[206:209], v[92:95]
	v_mfma_f32_16x16x32_bf16 v[88:91], v[138:141], v[206:209], v[88:91]
	v_mfma_f32_16x16x32_bf16 v[76:79], v[130:133], v[240:243], v[76:79]
	v_mfma_f32_16x16x32_bf16 v[72:75], v[138:141], v[240:243], v[72:75]
	v_mfma_f32_16x16x32_bf16 v[120:123], v[134:137], v[194:197], v[120:123]
	v_mfma_f32_16x16x32_bf16 v[124:127], v[142:145], v[194:197], v[124:127]
	v_mfma_f32_16x16x32_bf16 v[108:111], v[134:137], v[202:205], v[108:111]
	v_mfma_f32_16x16x32_bf16 v[104:107], v[142:145], v[202:205], v[104:107]
	v_mfma_f32_16x16x32_bf16 v[92:95], v[134:137], v[210:213], v[92:95]
	v_mfma_f32_16x16x32_bf16 v[88:91], v[142:145], v[210:213], v[88:91]
	v_mfma_f32_16x16x32_bf16 v[76:79], v[134:137], v[244:247], v[76:79]
	v_mfma_f32_16x16x32_bf16 v[72:75], v[142:145], v[244:247], v[72:75]
	s_setprio 0
	s_setprio 1
	v_mfma_f32_16x16x32_bf16 v[116:119], v[146:149], v[190:193], v[116:119]
	v_mfma_f32_16x16x32_bf16 v[112:115], v[154:157], v[190:193], v[112:115]
	v_mfma_f32_16x16x32_bf16 v[100:103], v[146:149], v[198:201], v[100:103]
	v_mfma_f32_16x16x32_bf16 v[96:99], v[154:157], v[198:201], v[96:99]
	v_mfma_f32_16x16x32_bf16 v[84:87], v[146:149], v[206:209], v[84:87]
	v_mfma_f32_16x16x32_bf16 v[80:83], v[154:157], v[206:209], v[80:83]
	v_mfma_f32_16x16x32_bf16 v[68:71], v[146:149], v[240:243], v[68:71]
	v_mfma_f32_16x16x32_bf16 v[64:67], v[154:157], v[240:243], v[64:67]
	v_mfma_f32_16x16x32_bf16 v[116:119], v[150:153], v[194:197], v[116:119]
	v_mfma_f32_16x16x32_bf16 v[112:115], v[186:189], v[194:197], v[112:115]
	v_mfma_f32_16x16x32_bf16 v[100:103], v[150:153], v[202:205], v[100:103]
	v_mfma_f32_16x16x32_bf16 v[96:99], v[186:189], v[202:205], v[96:99]
	v_mfma_f32_16x16x32_bf16 v[84:87], v[150:153], v[210:213], v[84:87]
	v_mfma_f32_16x16x32_bf16 v[80:83], v[186:189], v[210:213], v[80:83]
	v_mfma_f32_16x16x32_bf16 v[68:71], v[150:153], v[244:247], v[68:71]
	v_mfma_f32_16x16x32_bf16 v[64:67], v[186:189], v[244:247], v[64:67]
	s_barrier
; #define PG8_STAGE(bufoff, gbase, voff) do { _Pragma("unroll") for (int _i = 0; _i < 2; ++_i) \
;         __builtin_amdgcn_global_load_lds((const unsigned*)((const char*)(gbase) + (voff)[_i]), (LAS unsigned*)(lds + (bufoff) + ldsw + _i * 8192), 16, 0, 0); } while (0)
; #define PG8_LDA(dst, b, h) do { _Pragma("unroll") for (int m = 0; m < 4; ++m) _Pragma("unroll") for (int k = 0; k < 2; ++k) dst[m][k] = *(const LAS bf16x8*)(lds + PG8_SA(b, h) + aoff + m * 2048 + k * 1024); } while (0)
; #define PG8_MMA(ai, bj, At, Bt) do { __builtin_amdgcn_s_setprio(1); _Pragma("unroll") for (int k = 0; k < 2; ++k) _Pragma("unroll") for (int m = 0; m < 4; ++m) _Pragma("unroll") for (int n = 0; n < 2; ++n) \
;         acc[ai][bj][m][n] = __builtin_amdgcn_mfma_f32_16x16x32_bf16(Bt[n][k], At[m][k], acc[ai][bj][m][n], 0, 0, 0); __builtin_amdgcn_s_setprio(0); } while (0)
; #define PG8_WAIT_V(n) asm volatile("s_waitcnt vmcnt(" #n ")" ::: "memory")
; #define PG8_WAIT_L(n) asm volatile("s_waitcnt lgkmcnt(" #n ")" ::: "memory")
; #define PG8_BAR __builtin_amdgcn_s_barrier()
; #define PG8_SCHED __builtin_amdgcn_sched_barrier(0)
; template <class Epi, bool ALIGN_EPI>
; __device__ __forceinline__ void gemm_phase(LAS unsigned char* lds, const Gemm g, const StaticOrder& S, const Epi& E, const int tid) {
;     ...
;             PG8_LDA(At, 1, 1); PG8_STAGE(PG8_SB(1, 0), b3, voffB); PG8_STAGE(PG8_SB(1, 1), b3 + hB, voffB); PG8_STAGE(PG8_SA(1, 0), a3, voffA);
;             PG8_WAIT_V(8); PG8_WAIT_L(0); PG8_BAR; PG8_MMA(1, 0, At, B0); PG8_MMA(1, 1, At, B1); PG8_BAR; PG8_SCHED;
;         }
	s_setprio 0
	s_add_i32 s46, s46, s52
	v_lshl_add_u64 v[158:159], v[166:167], 0, s[92:93]
	s_mov_b32 m0, s46
	ds_read_b128 v[190:193], v219 offset:49152
	ds_read_b128 v[194:197], v219 offset:50176
	ds_read_b128 v[198:201], v219 offset:51200
	ds_read_b128 v[202:205], v219 offset:52224
	ds_read_b128 v[206:209], v219 offset:53248
	ds_read_b128 v[210:213], v219 offset:54272
	ds_read_b128 v[240:243], v219 offset:55296
	ds_read_b128 v[244:247], v219 offset:56320
	global_load_lds_dwordx4 v[158:159], off
	v_lshl_add_u64 v[158:159], v[214:215], 0, s[92:93]
	s_add_i32 m0, s46, 0x2000
	s_add_i32 s46, s70, s52
	global_load_lds_dwordx4 v[158:159], off
	v_lshl_add_u64 v[158:159], v[220:221], 0, s[92:93]
	s_mov_b32 m0, s46
	s_nop 0
	global_load_lds_dwordx4 v[158:159], off
	v_lshl_add_u64 v[158:159], v[226:227], 0, s[92:93]
	s_add_i32 m0, s46, 0x2000
	s_nop 0
	global_load_lds_dwordx4 v[158:159], off
	v_lshl_add_u64 v[158:159], v[248:249], 0, s[92:93]
	s_mov_b32 m0, s57
	s_nop 0
	global_load_lds_dwordx4 v[158:159], off
	v_lshl_add_u64 v[158:159], v[250:251], 0, s[92:93]
	s_mov_b32 m0, s58
	s_nop 0
	global_load_lds_dwordx4 v[158:159], off
	s_waitcnt vmcnt(8)
	s_waitcnt lgkmcnt(0)
	s_setprio 1
	s_barrier
	s_waitcnt lgkmcnt(0)
	v_mfma_f32_16x16x32_bf16 v[60:63], v[130:133], v[190:193], v[60:63]
	v_mfma_f32_16x16x32_bf16 v[56:59], v[138:141], v[190:193], v[56:59]
	v_mfma_f32_16x16x32_bf16 v[44:47], v[130:133], v[198:201], v[44:47]
	v_mfma_f32_16x16x32_bf16 v[40:43], v[138:141], v[198:201], v[40:43]
	v_mfma_f32_16x16x32_bf16 v[28:31], v[130:133], v[206:209], v[28:31]
	v_mfma_f32_16x16x32_bf16 v[24:27], v[138:141], v[206:209], v[24:27]
	v_mfma_f32_16x16x32_bf16 v[12:15], v[130:133], v[240:243], v[12:15]
	v_mfma_f32_16x16x32_bf16 v[8:11], v[138:141], v[240:243], v[8:11]
	v_mfma_f32_16x16x32_bf16 v[60:63], v[134:137], v[194:197], v[60:63]
	v_mfma_f32_16x16x32_bf16 v[56:59], v[142:145], v[194:197], v[56:59]
	v_mfma_f32_16x16x32_bf16 v[44:47], v[134:137], v[202:205], v[44:47]
	v_mfma_f32_16x16x32_bf16 v[40:43], v[142:145], v[202:205], v[40:43]
	v_mfma_f32_16x16x32_bf16 v[28:31], v[134:137], v[210:213], v[28:31]
	v_mfma_f32_16x16x32_bf16 v[24:27], v[142:145], v[210:213], v[24:27]
	v_mfma_f32_16x16x32_bf16 v[12:15], v[134:137], v[244:247], v[12:15]
	v_mfma_f32_16x16x32_bf16 v[8:11], v[142:145], v[244:247], v[8:11]
	s_setprio 0
	s_setprio 1
	v_mfma_f32_16x16x32_bf16 v[52:55], v[146:149], v[190:193], v[52:55]
	v_mfma_f32_16x16x32_bf16 v[48:51], v[154:157], v[190:193], v[48:51]
	v_mfma_f32_16x16x32_bf16 v[36:39], v[146:149], v[198:201], v[36:39]
	v_mfma_f32_16x16x32_bf16 v[32:35], v[154:157], v[198:201], v[32:35]
	v_mfma_f32_16x16x32_bf16 v[20:23], v[146:149], v[206:209], v[20:23]
	v_mfma_f32_16x16x32_bf16 v[16:19], v[154:157], v[206:209], v[16:19]
	v_mfma_f32_16x16x32_bf16 v[4:7], v[146:149], v[240:243], v[4:7]
	v_mfma_f32_16x16x32_bf16 v[0:3], v[154:157], v[240:243], v[0:3]
	v_mfma_f32_16x16x32_bf16 v[52:55], v[150:153], v[194:197], v[52:55]
	v_mfma_f32_16x16x32_bf16 v[48:51], v[186:189], v[194:197], v[48:51]
	v_mfma_f32_16x16x32_bf16 v[36:39], v[150:153], v[202:205], v[36:39]
	v_mfma_f32_16x16x32_bf16 v[32:35], v[186:189], v[202:205], v[32:35]
	v_mfma_f32_16x16x32_bf16 v[20:23], v[150:153], v[210:213], v[20:23]
	v_mfma_f32_16x16x32_bf16 v[16:19], v[186:189], v[210:213], v[16:19]
	v_mfma_f32_16x16x32_bf16 v[4:7], v[150:153], v[244:247], v[4:7]
	v_mfma_f32_16x16x32_bf16 v[0:3], v[186:189], v[244:247], v[0:3]
	s_barrier
	s_setprio 0
	s_add_u32 s12, s12, 0x100
	s_addc_u32 s13, s13, 0
	v_lshl_add_u64 v[128:129], v[128:129], 0, s[80:81]
	s_cmp_ge_u32 s47, s48
	s_mov_b32 s46, s47
	s_cbranch_scc0 .LBB0_236

; #define PG8_STAGE(bufoff, gbase, voff) do { _Pragma("unroll") for (int _i = 0; _i < 2; ++_i) \
;         __builtin_amdgcn_global_load_lds((const unsigned*)((const char*)(gbase) + (voff)[_i]), (LAS unsigned*)(lds + (bufoff) + ldsw + _i * 8192), 16, 0, 0); } while (0)
; #define PG8_LDA(dst, b, h) do { _Pragma("unroll") for (int m = 0; m < 4; ++m) _Pragma("unroll") for (int k = 0; k < 2; ++k) dst[m][k] = *(const LAS bf16x8*)(lds + PG8_SA(b, h) + aoff + m * 2048 + k * 1024); } while (0)
; #define PG8_LDB(dst, b, h) do { _Pragma("unroll") for (int n = 0; n < 2; ++n) _Pragma("unroll") for (int k = 0; k < 2; ++k) dst[n][k] = *(const LAS bf16x8*)(lds + PG8_SB(b, h) + boff + n * 2048 + k * 1024); } while (0)
; #define PG8_MMA(ai, bj, At, Bt) do { __builtin_amdgcn_s_setprio(1); _Pragma("unroll") for (int k = 0; k < 2; ++k) _Pragma("unroll") for (int m = 0; m < 4; ++m) _Pragma("unroll") for (int n = 0; n < 2; ++n) \
;         acc[ai][bj][m][n] = __builtin_amdgcn_mfma_f32_16x16x32_bf16(Bt[n][k], At[m][k], acc[ai][bj][m][n], 0, 0, 0); __builtin_amdgcn_s_setprio(0); } while (0)
; template <class Epi, bool ALIGN_EPI>
; __device__ __forceinline__ void gemm_phase(LAS unsigned char* lds, const Gemm g, const StaticOrder& S, const Epi& E, const int tid) {
;     ...
;         for (int t = 0; t < nt; t += 2) {
;             const bool last = (t == nt - 2);
;             const char* a1 = cA + (size_t)(t + 1) * kstep;
;             const char* a2 = last ? nA : cA + (size_t)(t + 2) * kstep; const char* b2 = last ? nB : cB + (size_t)(t + 2) * kstep;
;             const char* a3 = a2 + kstep; const char* b3 = b2 + kstep;
;             PG8_LDB(B0, 0, 0); PG8_LDB(B1, 0, 1); PG8_SCHED; PG8_LDA(At, 0, 0); PG8_STAGE(PG8_SA(1, 1), a1 + hA, voffA);
;             PG8_WAIT_V(8); PG8_WAIT_L(0); PG8_BAR; PG8_MMA(0, 0, At, B0); PG8_MMA(0, 1, At, B1); PG8_BAR; PG8_SCHED;
;             PG8_LDA(At, 0, 1); PG8_STAGE(PG8_SB(0, 0), b2, voffB); PG8_STAGE(PG8_SB(0, 1), b2 + hB, voffB); PG8_STAGE(PG8_SA(0, 0), a2, voffA);
;             PG8_WAIT_V(8); PG8_WAIT_L(0); PG8_BAR; PG8_MMA(1, 0, At, B0); PG8_MMA(1, 1, At, B1); PG8_BAR; PG8_SCHED;
;             PG8_LDB(B0, 1, 0); PG8_LDB(B1, 1, 1); PG8_SCHED; PG8_LDA(At, 1, 0); PG8_STAGE(PG8_SA(0, 1), a2 + hA, voffA);
;             PG8_WAIT_V(8); PG8_WAIT_L(0); PG8_BAR; PG8_MMA(0, 0, At, B0); PG8_MMA(0, 1, At, B1); PG8_BAR; PG8_SCHED;
.LBB0_272:
	s_andn2_b64 vcc, exec, s[36:37]
	s_cbranch_vccnz .LBB0_276
	s_add_u32 s10, s14, 0x100
	v_lshl_add_u64 v[128:129], v[128:129], 0, s[92:93]
	s_addc_u32 s11, s15, 0
	s_mov_b32 s14, 0
	s_add_i32 s15, s14, 2
	s_cmp_eq_u32 s57, s14
	s_cselect_b64 vcc, -1, 0
	s_cselect_b32 s69, s13, s11
	s_cselect_b32 s68, s12, s10
	s_add_i32 s14, 0, 0x14000
	v_lshl_add_u64 v[130:131], v[128:129], 0, s[92:93]
	v_add_u32_e32 v142, s33, v239
	v_add_u32_e32 v158, s14, v239
	v_cndmask_b32_e32 v167, v131, v191, vcc
	v_cndmask_b32_e32 v166, v130, v190, vcc
	ds_read_b128 v[130:133], v142
	ds_read_b128 v[134:137], v142 offset:1024
	ds_read_b128 v[138:141], v142 offset:2048
	ds_read_b128 v[142:145], v142 offset:3072
	ds_read_b128 v[146:149], v158
	ds_read_b128 v[150:153], v158 offset:1024
	ds_read_b128 v[154:157], v158 offset:2048
	ds_read_b128 v[158:161], v158 offset:3072
	v_lshl_add_u64 v[220:221], v[128:129], 0, v[186:187]
	s_add_i32 m0, s51, 0xc000
	ds_read_b128 v[162:165], v171
	ds_read_b128 v[192:195], v171 offset:1024
	ds_read_b128 v[196:199], v171 offset:2048
	ds_read_b128 v[200:203], v171 offset:3072
	ds_read_b128 v[204:207], v171 offset:4096
	ds_read_b128 v[208:211], v171 offset:5120
	ds_read_b128 v[212:215], v171 offset:6144
	ds_read_b128 v[216:219], v171 offset:7168
	global_load_lds_dwordx4 v[220:221], off
	v_lshl_add_u64 v[220:221], v[128:129], 0, v[188:189]
	s_add_i32 m0, s51, 0xe000
	s_nop 0
	global_load_lds_dwordx4 v[220:221], off
	s_waitcnt vmcnt(8)
	s_waitcnt lgkmcnt(0)
	s_setprio 1
	s_barrier
	s_waitcnt lgkmcnt(0)
	v_mfma_f32_16x16x32_bf16 v[124:127], v[130:133], v[162:165], 0
	v_mfma_f32_16x16x32_bf16 v[120:123], v[138:141], v[162:165], 0
	v_mfma_f32_16x16x32_bf16 v[108:111], v[130:133], v[196:199], 0
	v_mfma_f32_16x16x32_bf16 v[104:107], v[138:141], v[196:199], 0
	v_mfma_f32_16x16x32_bf16 v[92:95], v[130:133], v[204:207], 0
	v_mfma_f32_16x16x32_bf16 v[88:91], v[138:141], v[204:207], 0
	v_mfma_f32_16x16x32_bf16 v[76:79], v[130:133], v[212:215], 0
	v_mfma_f32_16x16x32_bf16 v[72:75], v[138:141], v[212:215], 0
	v_mfma_f32_16x16x32_bf16 v[124:127], v[134:137], v[192:195], v[124:127]
	v_mfma_f32_16x16x32_bf16 v[120:123], v[142:145], v[192:195], v[120:123]
	v_mfma_f32_16x16x32_bf16 v[108:111], v[134:137], v[200:203], v[108:111]
	v_mfma_f32_16x16x32_bf16 v[104:107], v[142:145], v[200:203], v[104:107]
	v_mfma_f32_16x16x32_bf16 v[92:95], v[134:137], v[208:211], v[92:95]
	v_mfma_f32_16x16x32_bf16 v[88:91], v[142:145], v[208:211], v[88:91]
	v_mfma_f32_16x16x32_bf16 v[76:79], v[134:137], v[216:219], v[76:79]
	v_mfma_f32_16x16x32_bf16 v[72:75], v[142:145], v[216:219], v[72:75]
	s_setprio 0
	s_setprio 1
	v_mfma_f32_16x16x32_bf16 v[116:119], v[146:149], v[162:165], 0
	v_mfma_f32_16x16x32_bf16 v[112:115], v[154:157], v[162:165], 0
	v_mfma_f32_16x16x32_bf16 v[100:103], v[146:149], v[196:199], 0
	v_mfma_f32_16x16x32_bf16 v[96:99], v[154:157], v[196:199], 0
	v_mfma_f32_16x16x32_bf16 v[84:87], v[146:149], v[204:207], 0
	v_mfma_f32_16x16x32_bf16 v[80:83], v[154:157], v[204:207], 0
	v_mfma_f32_16x16x32_bf16 v[68:71], v[146:149], v[212:215], 0
	v_mfma_f32_16x16x32_bf16 v[64:67], v[154:157], v[212:215], 0
	v_mfma_f32_16x16x32_bf16 v[116:119], v[150:153], v[192:195], v[116:119]
	v_mfma_f32_16x16x32_bf16 v[112:115], v[158:161], v[192:195], v[112:115]
	v_mfma_f32_16x16x32_bf16 v[100:103], v[150:153], v[200:203], v[100:103]
	v_mfma_f32_16x16x32_bf16 v[96:99], v[158:161], v[200:203], v[96:99]
	v_mfma_f32_16x16x32_bf16 v[84:87], v[150:153], v[208:211], v[84:87]
	v_mfma_f32_16x16x32_bf16 v[80:83], v[158:161], v[208:211], v[80:83]
	v_mfma_f32_16x16x32_bf16 v[68:71], v[150:153], v[216:219], v[68:71]
	v_mfma_f32_16x16x32_bf16 v[64:67], v[158:161], v[216:219], v[64:67]
	s_barrier
	s_setprio 0
	s_add_i32 s70, s33, s47
	v_lshl_add_u64 v[220:221], s[68:69], 0, v[180:181]
	s_mov_b32 m0, s70
	ds_read_b128 v[162:165], v171 offset:16384
	ds_read_b128 v[192:195], v171 offset:17408
	ds_read_b128 v[196:199], v171 offset:18432
	ds_read_b128 v[200:203], v171 offset:19456
	ds_read_b128 v[204:207], v171 offset:20480
	ds_read_b128 v[208:211], v171 offset:21504
	ds_read_b128 v[212:215], v171 offset:22528
	ds_read_b128 v[216:219], v171 offset:23552
	global_load_lds_dwordx4 v[220:221], off
	s_add_i32 m0, s70, 0x2000
	v_lshl_add_u64 v[226:227], s[68:69], 0, v[184:185]
	s_add_u32 s68, s68, s49
	s_addc_u32 s69, s69, 0
	s_add_i32 s14, s14, s47
	global_load_lds_dwordx4 v[226:227], off
	v_lshl_add_u64 v[240:241], s[68:69], 0, v[180:181]
	s_mov_b32 m0, s14
	v_lshl_add_u64 v[242:243], s[68:69], 0, v[184:185]
	global_load_lds_dwordx4 v[240:241], off
	s_add_i32 m0, s14, 0x2000
	v_lshl_add_u64 v[244:245], v[166:167], 0, v[178:179]
	global_load_lds_dwordx4 v[242:243], off
	s_mov_b32 m0, s51
	v_lshl_add_u64 v[246:247], v[166:167], 0, v[182:183]
	global_load_lds_dwordx4 v[244:245], off
	s_mov_b32 m0, s52
	s_nop 0
	global_load_lds_dwordx4 v[246:247], off
	s_waitcnt vmcnt(8)
	s_waitcnt lgkmcnt(0)
	s_setprio 1
	s_barrier
; #define PG8_STAGE(bufoff, gbase, voff) do { _Pragma("unroll") for (int _i = 0; _i < 2; ++_i) \
;         __builtin_amdgcn_global_load_lds((const unsigned*)((const char*)(gbase) + (voff)[_i]), (LAS unsigned*)(lds + (bufoff) + ldsw + _i * 8192), 16, 0, 0); } while (0)
; #define PG8_LDA(dst, b, h) do { _Pragma("unroll") for (int m = 0; m < 4; ++m) _Pragma("unroll") for (int k = 0; k < 2; ++k) dst[m][k] = *(const LAS bf16x8*)(lds + PG8_SA(b, h) + aoff + m * 2048 + k * 1024); } while (0)
; #define PG8_LDB(dst, b, h) do { _Pragma("unroll") for (int n = 0; n < 2; ++n) _Pragma("unroll") for (int k = 0; k < 2; ++k) dst[n][k] = *(const LAS bf16x8*)(lds + PG8_SB(b, h) + boff + n * 2048 + k * 1024); } while (0)
; #define PG8_MMA(ai, bj, At, Bt) do { __builtin_amdgcn_s_setprio(1); _Pragma("unroll") for (int k = 0; k < 2; ++k) _Pragma("unroll") for (int m = 0; m < 4; ++m) _Pragma("unroll") for (int n = 0; n < 2; ++n) \
;         acc[ai][bj][m][n] = __builtin_amdgcn_mfma_f32_16x16x32_bf16(Bt[n][k], At[m][k], acc[ai][bj][m][n], 0, 0, 0); __builtin_amdgcn_s_setprio(0); } while (0)
; #define PG8_WAIT_V(n) asm volatile("s_waitcnt vmcnt(" #n ")" ::: "memory")
; #define PG8_WAIT_L(n) asm volatile("s_waitcnt lgkmcnt(" #n ")" ::: "memory")
; #define PG8_BAR __builtin_amdgcn_s_barrier()
; #define PG8_SCHED __builtin_amdgcn_sched_barrier(0)
; template <class Epi, bool ALIGN_EPI>
; __device__ __forceinline__ void gemm_phase(LAS unsigned char* lds, const Gemm g, const StaticOrder& S, const Epi& E, const int tid) {
;     ...
;             PG8_WAIT_V(8); PG8_WAIT_L(0); PG8_BAR; PG8_MMA(1, 0, At, B0); PG8_MMA(1, 1, At, B1); PG8_BAR; PG8_SCHED;
;             PG8_LDB(B0, 1, 0); PG8_LDB(B1, 1, 1); PG8_SCHED; PG8_LDA(At, 1, 0); PG8_STAGE(PG8_SA(0, 1), a2 + hA, voffA);
;             PG8_WAIT_V(8); PG8_WAIT_L(0); PG8_BAR; PG8_MMA(0, 0, At, B0); PG8_MMA(0, 1, At, B1); PG8_BAR; PG8_SCHED;
	s_waitcnt lgkmcnt(0)
	v_mfma_f32_16x16x32_bf16 v[60:63], v[130:133], v[162:165], 0
	v_mfma_f32_16x16x32_bf16 v[56:59], v[138:141], v[162:165], 0
	v_mfma_f32_16x16x32_bf16 v[44:47], v[130:133], v[196:199], 0
	v_mfma_f32_16x16x32_bf16 v[40:43], v[138:141], v[196:199], 0
	v_mfma_f32_16x16x32_bf16 v[28:31], v[130:133], v[204:207], 0
	v_mfma_f32_16x16x32_bf16 v[24:27], v[138:141], v[204:207], 0
	v_mfma_f32_16x16x32_bf16 v[12:15], v[130:133], v[212:215], 0
	v_mfma_f32_16x16x32_bf16 v[8:11], v[138:141], v[212:215], 0
	v_mfma_f32_16x16x32_bf16 v[60:63], v[134:137], v[192:195], v[60:63]
	v_mfma_f32_16x16x32_bf16 v[56:59], v[142:145], v[192:195], v[56:59]
	v_mfma_f32_16x16x32_bf16 v[44:47], v[134:137], v[200:203], v[44:47]
	v_mfma_f32_16x16x32_bf16 v[40:43], v[142:145], v[200:203], v[40:43]
	v_mfma_f32_16x16x32_bf16 v[28:31], v[134:137], v[208:211], v[28:31]
	v_mfma_f32_16x16x32_bf16 v[24:27], v[142:145], v[208:211], v[24:27]
	v_mfma_f32_16x16x32_bf16 v[12:15], v[134:137], v[216:219], v[12:15]
	v_mfma_f32_16x16x32_bf16 v[8:11], v[142:145], v[216:219], v[8:11]
	s_setprio 0
	s_setprio 1
	v_mfma_f32_16x16x32_bf16 v[52:55], v[146:149], v[162:165], 0
	v_mfma_f32_16x16x32_bf16 v[48:51], v[154:157], v[162:165], 0
	v_mfma_f32_16x16x32_bf16 v[36:39], v[146:149], v[196:199], 0
	v_mfma_f32_16x16x32_bf16 v[32:35], v[154:157], v[196:199], 0
	v_mfma_f32_16x16x32_bf16 v[20:23], v[146:149], v[204:207], 0
	v_mfma_f32_16x16x32_bf16 v[16:19], v[154:157], v[204:207], 0
	v_mfma_f32_16x16x32_bf16 v[4:7], v[146:149], v[212:215], 0
	v_mfma_f32_16x16x32_bf16 v[0:3], v[154:157], v[212:215], 0
	v_mfma_f32_16x16x32_bf16 v[52:55], v[150:153], v[192:195], v[52:55]
	v_mfma_f32_16x16x32_bf16 v[48:51], v[158:161], v[192:195], v[48:51]
	v_mfma_f32_16x16x32_bf16 v[36:39], v[150:153], v[200:203], v[36:39]
	v_mfma_f32_16x16x32_bf16 v[32:35], v[158:161], v[200:203], v[32:35]
	v_mfma_f32_16x16x32_bf16 v[20:23], v[150:153], v[208:211], v[20:23]
	v_mfma_f32_16x16x32_bf16 v[16:19], v[158:161], v[208:211], v[16:19]
	v_mfma_f32_16x16x32_bf16 v[4:7], v[150:153], v[216:219], v[4:7]
	v_mfma_f32_16x16x32_bf16 v[0:3], v[158:161], v[216:219], v[0:3]
	s_barrier
	s_setprio 0
	s_add_i32 s14, 0, 0x18000
	s_add_i32 s68, 0, 0x1c000
	v_add_u32_e32 v142, s14, v239
	v_add_u32_e32 v158, s68, v239
	ds_read_b128 v[130:133], v142
	ds_read_b128 v[134:137], v142 offset:1024
	ds_read_b128 v[138:141], v142 offset:2048
	ds_read_b128 v[142:145], v142 offset:3072
	ds_read_b128 v[146:149], v158
	ds_read_b128 v[150:153], v158 offset:1024
	ds_read_b128 v[154:157], v158 offset:2048
	ds_read_b128 v[158:161], v158 offset:3072
	v_lshl_add_u64 v[166:167], v[166:167], 0, s[94:95]
	s_mov_b32 m0, s53
	v_lshl_add_u64 v[248:249], v[166:167], 0, v[178:179]
	ds_read_b128 v[162:165], v171 offset:32768
	ds_read_b128 v[192:195], v171 offset:33792
	ds_read_b128 v[196:199], v171 offset:34816
	ds_read_b128 v[200:203], v171 offset:35840
	ds_read_b128 v[204:207], v171 offset:36864
	ds_read_b128 v[208:211], v171 offset:37888
	ds_read_b128 v[212:215], v171 offset:38912
	ds_read_b128 v[216:219], v171 offset:39936
	global_load_lds_dwordx4 v[248:249], off
	v_lshl_add_u64 v[166:167], v[166:167], 0, v[182:183]
	s_mov_b32 m0, s54
	s_nop 0
	global_load_lds_dwordx4 v[166:167], off
	s_waitcnt vmcnt(8)
	s_waitcnt lgkmcnt(0)
	s_setprio 1
	s_barrier
	s_waitcnt lgkmcnt(0)
	v_mfma_f32_16x16x32_bf16 v[124:127], v[130:133], v[162:165], v[124:127]
	v_mfma_f32_16x16x32_bf16 v[120:123], v[138:141], v[162:165], v[120:123]
	v_mfma_f32_16x16x32_bf16 v[108:111], v[130:133], v[196:199], v[108:111]
	v_mfma_f32_16x16x32_bf16 v[104:107], v[138:141], v[196:199], v[104:107]
	v_mfma_f32_16x16x32_bf16 v[92:95], v[130:133], v[204:207], v[92:95]
	v_mfma_f32_16x16x32_bf16 v[88:91], v[138:141], v[204:207], v[88:91]
	v_mfma_f32_16x16x32_bf16 v[76:79], v[130:133], v[212:215], v[76:79]
	v_mfma_f32_16x16x32_bf16 v[72:75], v[138:141], v[212:215], v[72:75]
	v_mfma_f32_16x16x32_bf16 v[124:127], v[134:137], v[192:195], v[124:127]
	v_mfma_f32_16x16x32_bf16 v[120:123], v[142:145], v[192:195], v[120:123]
	v_mfma_f32_16x16x32_bf16 v[108:111], v[134:137], v[200:203], v[108:111]
	v_mfma_f32_16x16x32_bf16 v[104:107], v[142:145], v[200:203], v[104:107]
	v_mfma_f32_16x16x32_bf16 v[92:95], v[134:137], v[208:211], v[92:95]
	v_mfma_f32_16x16x32_bf16 v[88:91], v[142:145], v[208:211], v[88:91]
	v_mfma_f32_16x16x32_bf16 v[76:79], v[134:137], v[216:219], v[76:79]
	v_mfma_f32_16x16x32_bf16 v[72:75], v[142:145], v[216:219], v[72:75]
	s_setprio 0
	s_setprio 1
	v_mfma_f32_16x16x32_bf16 v[116:119], v[146:149], v[162:165], v[116:119]
	v_mfma_f32_16x16x32_bf16 v[112:115], v[154:157], v[162:165], v[112:115]
	v_mfma_f32_16x16x32_bf16 v[100:103], v[146:149], v[196:199], v[100:103]
	v_mfma_f32_16x16x32_bf16 v[96:99], v[154:157], v[196:199], v[96:99]
	v_mfma_f32_16x16x32_bf16 v[84:87], v[146:149], v[204:207], v[84:87]
	v_mfma_f32_16x16x32_bf16 v[80:83], v[154:157], v[204:207], v[80:83]
	v_mfma_f32_16x16x32_bf16 v[68:71], v[146:149], v[212:215], v[68:71]
	v_mfma_f32_16x16x32_bf16 v[64:67], v[154:157], v[212:215], v[64:67]
	v_mfma_f32_16x16x32_bf16 v[116:119], v[150:153], v[192:195], v[116:119]
	v_mfma_f32_16x16x32_bf16 v[112:115], v[158:161], v[192:195], v[112:115]
	v_mfma_f32_16x16x32_bf16 v[100:103], v[150:153], v[200:203], v[100:103]
	v_mfma_f32_16x16x32_bf16 v[96:99], v[158:161], v[200:203], v[96:99]
	v_mfma_f32_16x16x32_bf16 v[84:87], v[150:153], v[208:211], v[84:87]
	v_mfma_f32_16x16x32_bf16 v[80:83], v[158:161], v[208:211], v[80:83]
	v_mfma_f32_16x16x32_bf16 v[68:71], v[150:153], v[216:219], v[68:71]
	v_mfma_f32_16x16x32_bf16 v[64:67], v[158:161], v[216:219], v[64:67]
	s_barrier
; #define PG8_STAGE(bufoff, gbase, voff) do { _Pragma("unroll") for (int _i = 0; _i < 2; ++_i) \
;         __builtin_amdgcn_global_load_lds((const unsigned*)((const char*)(gbase) + (voff)[_i]), (LAS unsigned*)(lds + (bufoff) + ldsw + _i * 8192), 16, 0, 0); } while (0)
; #define PG8_LDA(dst, b, h) do { _Pragma("unroll") for (int m = 0; m < 4; ++m) _Pragma("unroll") for (int k = 0; k < 2; ++k) dst[m][k] = *(const LAS bf16x8*)(lds + PG8_SA(b, h) + aoff + m * 2048 + k * 1024); } while (0)
; #define PG8_LDB(dst, b, h) do { _Pragma("unroll") for (int n = 0; n < 2; ++n) _Pragma("unroll") for (int k = 0; k < 2; ++k) dst[n][k] = *(const LAS bf16x8*)(lds + PG8_SB(b, h) + boff + n * 2048 + k * 1024); } while (0)
; #define PG8_MMA(ai, bj, At, Bt) do { __builtin_amdgcn_s_setprio(1); _Pragma("unroll") for (int k = 0; k < 2; ++k) _Pragma("unroll") for (int m = 0; m < 4; ++m) _Pragma("unroll") for (int n = 0; n < 2; ++n) \
;         acc[ai][bj][m][n] = __builtin_amdgcn_mfma_f32_16x16x32_bf16(Bt[n][k], At[m][k], acc[ai][bj][m][n], 0, 0, 0); __builtin_amdgcn_s_setprio(0); } while (0)
; #define PG8_WAIT_V(n) asm volatile("s_waitcnt vmcnt(" #n ")" ::: "memory")
; #define PG8_BAR __builtin_amdgcn_s_barrier()
; template <class Epi, bool ALIGN_EPI>
; __device__ __forceinline__ void gemm_phase(LAS unsigned char* lds, const Gemm g, const StaticOrder& S, const Epi& E, const int tid) {
;     ...
;             PG8_LDB(B0, 0, 0); PG8_LDB(B1, 0, 1); PG8_SCHED; PG8_LDA(At, 0, 0); PG8_STAGE(PG8_SA(1, 1), a1 + hA, voffA);
;             PG8_WAIT_V(8); PG8_WAIT_L(0); PG8_BAR; PG8_MMA(0, 0, At, B0); PG8_MMA(0, 1, At, B1); PG8_BAR; PG8_SCHED;
;             PG8_LDA(At, 0, 1); PG8_STAGE(PG8_SB(0, 0), b2, voffB); PG8_STAGE(PG8_SB(0, 1), b2 + hB, voffB); PG8_STAGE(PG8_SA(0, 0), a2, voffA);
;             PG8_WAIT_V(8); PG8_WAIT_L(0); PG8_BAR; PG8_MMA(1, 0, At, B0); PG8_MMA(1, 1, At, B1); PG8_BAR; PG8_SCHED;
;             PG8_LDB(B0, 1, 0); PG8_LDB(B1, 1, 1); PG8_SCHED; PG8_LDA(At, 1, 0); PG8_STAGE(PG8_SA(0, 1), a2 + hA, voffA);
;             PG8_WAIT_V(8); PG8_WAIT_L(0); PG8_BAR; PG8_MMA(0, 0, At, B0); PG8_MMA(0, 1, At, B1); PG8_BAR; PG8_SCHED;
;             PG8_LDA(At, 1, 1); PG8_STAGE(PG8_SB(1, 0), b3, voffB); PG8_STAGE(PG8_SB(1, 1), b3 + hB, voffB); PG8_STAGE(PG8_SA(1, 0), a3, voffA);
;             PG8_WAIT_V(8); PG8_WAIT_L(0); PG8_BAR; PG8_MMA(1, 0, At, B0); PG8_MMA(1, 1, At, B1); PG8_BAR; PG8_SCHED;
	s_setprio 0
	s_add_i32 s14, s14, s47
	v_lshl_add_u64 v[166:167], v[220:221], 0, s[92:93]
	s_mov_b32 m0, s14
	ds_read_b128 v[162:165], v171 offset:49152
	ds_read_b128 v[192:195], v171 offset:50176
	ds_read_b128 v[196:199], v171 offset:51200
	ds_read_b128 v[200:203], v171 offset:52224
	ds_read_b128 v[204:207], v171 offset:53248
	ds_read_b128 v[208:211], v171 offset:54272
	ds_read_b128 v[212:215], v171 offset:55296
	ds_read_b128 v[216:219], v171 offset:56320
	global_load_lds_dwordx4 v[166:167], off
	v_lshl_add_u64 v[166:167], v[226:227], 0, s[92:93]
	s_add_i32 m0, s14, 0x2000
	s_add_i32 s14, s68, s47
	global_load_lds_dwordx4 v[166:167], off
	v_lshl_add_u64 v[166:167], v[240:241], 0, s[92:93]
	s_mov_b32 m0, s14
	s_nop 0
	global_load_lds_dwordx4 v[166:167], off
	v_lshl_add_u64 v[166:167], v[242:243], 0, s[92:93]
	s_add_i32 m0, s14, 0x2000
	s_nop 0
	global_load_lds_dwordx4 v[166:167], off
	v_lshl_add_u64 v[166:167], v[244:245], 0, s[92:93]
	s_mov_b32 m0, s55
	s_nop 0
	global_load_lds_dwordx4 v[166:167], off
	v_lshl_add_u64 v[166:167], v[246:247], 0, s[92:93]
	s_mov_b32 m0, s56
	s_nop 0
	global_load_lds_dwordx4 v[166:167], off
	s_waitcnt vmcnt(8)
	s_waitcnt lgkmcnt(0)
	s_setprio 1
	s_barrier
	s_waitcnt lgkmcnt(0)
	v_mfma_f32_16x16x32_bf16 v[60:63], v[130:133], v[162:165], v[60:63]
	v_mfma_f32_16x16x32_bf16 v[56:59], v[138:141], v[162:165], v[56:59]
	v_mfma_f32_16x16x32_bf16 v[44:47], v[130:133], v[196:199], v[44:47]
	v_mfma_f32_16x16x32_bf16 v[40:43], v[138:141], v[196:199], v[40:43]
	v_mfma_f32_16x16x32_bf16 v[28:31], v[130:133], v[204:207], v[28:31]
	v_mfma_f32_16x16x32_bf16 v[24:27], v[138:141], v[204:207], v[24:27]
	v_mfma_f32_16x16x32_bf16 v[12:15], v[130:133], v[212:215], v[12:15]
	v_mfma_f32_16x16x32_bf16 v[8:11], v[138:141], v[212:215], v[8:11]
	v_mfma_f32_16x16x32_bf16 v[60:63], v[134:137], v[192:195], v[60:63]
	v_mfma_f32_16x16x32_bf16 v[56:59], v[142:145], v[192:195], v[56:59]
	v_mfma_f32_16x16x32_bf16 v[44:47], v[134:137], v[200:203], v[44:47]
	v_mfma_f32_16x16x32_bf16 v[40:43], v[142:145], v[200:203], v[40:43]
	v_mfma_f32_16x16x32_bf16 v[28:31], v[134:137], v[208:211], v[28:31]
	v_mfma_f32_16x16x32_bf16 v[24:27], v[142:145], v[208:211], v[24:27]
	v_mfma_f32_16x16x32_bf16 v[12:15], v[134:137], v[216:219], v[12:15]
	v_mfma_f32_16x16x32_bf16 v[8:11], v[142:145], v[216:219], v[8:11]
	s_setprio 0
	s_setprio 1
	v_mfma_f32_16x16x32_bf16 v[52:55], v[146:149], v[162:165], v[52:55]
	v_mfma_f32_16x16x32_bf16 v[48:51], v[154:157], v[162:165], v[48:51]
	v_mfma_f32_16x16x32_bf16 v[36:39], v[146:149], v[196:199], v[36:39]
	v_mfma_f32_16x16x32_bf16 v[32:35], v[154:157], v[196:199], v[32:35]
	v_mfma_f32_16x16x32_bf16 v[20:23], v[146:149], v[204:207], v[20:23]
	v_mfma_f32_16x16x32_bf16 v[16:19], v[154:157], v[204:207], v[16:19]
	v_mfma_f32_16x16x32_bf16 v[4:7], v[146:149], v[212:215], v[4:7]
	v_mfma_f32_16x16x32_bf16 v[0:3], v[154:157], v[212:215], v[0:3]
	v_mfma_f32_16x16x32_bf16 v[52:55], v[150:153], v[192:195], v[52:55]
	v_mfma_f32_16x16x32_bf16 v[48:51], v[158:161], v[192:195], v[48:51]
	v_mfma_f32_16x16x32_bf16 v[36:39], v[150:153], v[200:203], v[36:39]
	v_mfma_f32_16x16x32_bf16 v[32:35], v[158:161], v[200:203], v[32:35]
	v_mfma_f32_16x16x32_bf16 v[20:23], v[150:153], v[208:211], v[20:23]
	v_mfma_f32_16x16x32_bf16 v[16:19], v[158:161], v[208:211], v[16:19]
	v_mfma_f32_16x16x32_bf16 v[4:7], v[150:153], v[216:219], v[4:7]
	v_mfma_f32_16x16x32_bf16 v[0:3], v[158:161], v[216:219], v[0:3]
	s_barrier
	s_setprio 0
	s_add_u32 s10, s10, 0x100
	s_addc_u32 s11, s11, 0
	v_lshl_add_u64 v[128:129], v[128:129], 0, s[80:81]
	s_cmp_ge_u32 s15, s48
	s_mov_b32 s14, s15
	s_cbranch_scc1 .Lpl2_after
.LBB0_274:
	s_add_i32 s15, s14, 2
	s_cmp_eq_u32 s57, s14
	s_cselect_b64 vcc, -1, 0
	s_cselect_b32 s69, s13, s11
	s_cselect_b32 s68, s12, s10
	s_add_i32 s14, 0, 0x14000
	v_lshl_add_u64 v[130:131], v[128:129], 0, s[92:93]
	v_add_u32_e32 v142, s33, v239
	v_add_u32_e32 v158, s14, v239
	v_cndmask_b32_e32 v167, v131, v191, vcc
	v_cndmask_b32_e32 v166, v130, v190, vcc
	ds_read_b128 v[130:133], v142
	ds_read_b128 v[134:137], v142 offset:1024
	ds_read_b128 v[138:141], v142 offset:2048
	ds_read_b128 v[142:145], v142 offset:3072
	ds_read_b128 v[146:149], v158
	ds_read_b128 v[150:153], v158 offset:1024
	ds_read_b128 v[154:157], v158 offset:2048
	ds_read_b128 v[158:161], v158 offset:3072
	v_lshl_add_u64 v[220:221], v[128:129], 0, v[186:187]
	s_add_i32 m0, s51, 0xc000
	ds_read_b128 v[162:165], v171
	ds_read_b128 v[192:195], v171 offset:1024
	ds_read_b128 v[196:199], v171 offset:2048
	ds_read_b128 v[200:203], v171 offset:3072
	ds_read_b128 v[204:207], v171 offset:4096
	ds_read_b128 v[208:211], v171 offset:5120
	ds_read_b128 v[212:215], v171 offset:6144
	ds_read_b128 v[216:219], v171 offset:7168
	global_load_lds_dwordx4 v[220:221], off
	v_lshl_add_u64 v[220:221], v[128:129], 0, v[188:189]
	s_add_i32 m0, s51, 0xe000
	s_nop 0
	global_load_lds_dwordx4 v[220:221], off
	s_waitcnt vmcnt(8)
	s_waitcnt lgkmcnt(0)
	s_setprio 1
	s_barrier
; #define PG8_STAGE(bufoff, gbase, voff) do { _Pragma("unroll") for (int _i = 0; _i < 2; ++_i) \
;         __builtin_amdgcn_global_load_lds((const unsigned*)((const char*)(gbase) + (voff)[_i]), (LAS unsigned*)(lds + (bufoff) + ldsw + _i * 8192), 16, 0, 0); } while (0)
; #define PG8_LDA(dst, b, h) do { _Pragma("unroll") for (int m = 0; m < 4; ++m) _Pragma("unroll") for (int k = 0; k < 2; ++k) dst[m][k] = *(const LAS bf16x8*)(lds + PG8_SA(b, h) + aoff + m * 2048 + k * 1024); } while (0)
; #define PG8_LDB(dst, b, h) do { _Pragma("unroll") for (int n = 0; n < 2; ++n) _Pragma("unroll") for (int k = 0; k < 2; ++k) dst[n][k] = *(const LAS bf16x8*)(lds + PG8_SB(b, h) + boff + n * 2048 + k * 1024); } while (0)
; #define PG8_MMA(ai, bj, At, Bt) do { __builtin_amdgcn_s_setprio(1); _Pragma("unroll") for (int k = 0; k < 2; ++k) _Pragma("unroll") for (int m = 0; m < 4; ++m) _Pragma("unroll") for (int n = 0; n < 2; ++n) \
;         acc[ai][bj][m][n] = __builtin_amdgcn_mfma_f32_16x16x32_bf16(Bt[n][k], At[m][k], acc[ai][bj][m][n], 0, 0, 0); __builtin_amdgcn_s_setprio(0); } while (0)
; #define PG8_WAIT_V(n) asm volatile("s_waitcnt vmcnt(" #n ")" ::: "memory")
; #define PG8_WAIT_L(n) asm volatile("s_waitcnt lgkmcnt(" #n ")" ::: "memory")
; #define PG8_BAR __builtin_amdgcn_s_barrier()
; #define PG8_SCHED __builtin_amdgcn_sched_barrier(0)
; template <class Epi, bool ALIGN_EPI>
; __device__ __forceinline__ void gemm_phase(LAS unsigned char* lds, const Gemm g, const StaticOrder& S, const Epi& E, const int tid) {
;     ...
;             PG8_WAIT_V(8); PG8_WAIT_L(0); PG8_BAR; PG8_MMA(0, 0, At, B0); PG8_MMA(0, 1, At, B1); PG8_BAR; PG8_SCHED;
;             PG8_LDA(At, 0, 1); PG8_STAGE(PG8_SB(0, 0), b2, voffB); PG8_STAGE(PG8_SB(0, 1), b2 + hB, voffB); PG8_STAGE(PG8_SA(0, 0), a2, voffA);
;             PG8_WAIT_V(8); PG8_WAIT_L(0); PG8_BAR; PG8_MMA(1, 0, At, B0); PG8_MMA(1, 1, At, B1); PG8_BAR; PG8_SCHED;
;             PG8_LDB(B0, 1, 0); PG8_LDB(B1, 1, 1); PG8_SCHED; PG8_LDA(At, 1, 0); PG8_STAGE(PG8_SA(0, 1), a2 + hA, voffA);
;             PG8_WAIT_V(8); PG8_WAIT_L(0); PG8_BAR; PG8_MMA(0, 0, At, B0); PG8_MMA(0, 1, At, B1); PG8_BAR; PG8_SCHED;
	s_waitcnt lgkmcnt(0)
	v_mfma_f32_16x16x32_bf16 v[124:127], v[130:133], v[162:165], v[124:127]
	v_mfma_f32_16x16x32_bf16 v[120:123], v[138:141], v[162:165], v[120:123]
	v_mfma_f32_16x16x32_bf16 v[108:111], v[130:133], v[196:199], v[108:111]
	v_mfma_f32_16x16x32_bf16 v[104:107], v[138:141], v[196:199], v[104:107]
	v_mfma_f32_16x16x32_bf16 v[92:95], v[130:133], v[204:207], v[92:95]
	v_mfma_f32_16x16x32_bf16 v[88:91], v[138:141], v[204:207], v[88:91]
	v_mfma_f32_16x16x32_bf16 v[76:79], v[130:133], v[212:215], v[76:79]
	v_mfma_f32_16x16x32_bf16 v[72:75], v[138:141], v[212:215], v[72:75]
	v_mfma_f32_16x16x32_bf16 v[124:127], v[134:137], v[192:195], v[124:127]
	v_mfma_f32_16x16x32_bf16 v[120:123], v[142:145], v[192:195], v[120:123]
	v_mfma_f32_16x16x32_bf16 v[108:111], v[134:137], v[200:203], v[108:111]
	v_mfma_f32_16x16x32_bf16 v[104:107], v[142:145], v[200:203], v[104:107]
	v_mfma_f32_16x16x32_bf16 v[92:95], v[134:137], v[208:211], v[92:95]
	v_mfma_f32_16x16x32_bf16 v[88:91], v[142:145], v[208:211], v[88:91]
	v_mfma_f32_16x16x32_bf16 v[76:79], v[134:137], v[216:219], v[76:79]
	v_mfma_f32_16x16x32_bf16 v[72:75], v[142:145], v[216:219], v[72:75]
	s_setprio 0
	s_setprio 1
	v_mfma_f32_16x16x32_bf16 v[116:119], v[146:149], v[162:165], v[116:119]
	v_mfma_f32_16x16x32_bf16 v[112:115], v[154:157], v[162:165], v[112:115]
	v_mfma_f32_16x16x32_bf16 v[100:103], v[146:149], v[196:199], v[100:103]
	v_mfma_f32_16x16x32_bf16 v[96:99], v[154:157], v[196:199], v[96:99]
	v_mfma_f32_16x16x32_bf16 v[84:87], v[146:149], v[204:207], v[84:87]
	v_mfma_f32_16x16x32_bf16 v[80:83], v[154:157], v[204:207], v[80:83]
	v_mfma_f32_16x16x32_bf16 v[68:71], v[146:149], v[212:215], v[68:71]
	v_mfma_f32_16x16x32_bf16 v[64:67], v[154:157], v[212:215], v[64:67]
	v_mfma_f32_16x16x32_bf16 v[116:119], v[150:153], v[192:195], v[116:119]
	v_mfma_f32_16x16x32_bf16 v[112:115], v[158:161], v[192:195], v[112:115]
	v_mfma_f32_16x16x32_bf16 v[100:103], v[150:153], v[200:203], v[100:103]
	v_mfma_f32_16x16x32_bf16 v[96:99], v[158:161], v[200:203], v[96:99]
	v_mfma_f32_16x16x32_bf16 v[84:87], v[150:153], v[208:211], v[84:87]
	v_mfma_f32_16x16x32_bf16 v[80:83], v[158:161], v[208:211], v[80:83]
	v_mfma_f32_16x16x32_bf16 v[68:71], v[150:153], v[216:219], v[68:71]
	v_mfma_f32_16x16x32_bf16 v[64:67], v[158:161], v[216:219], v[64:67]
	s_barrier
	s_setprio 0
	s_add_i32 s70, s33, s47
	v_lshl_add_u64 v[220:221], s[68:69], 0, v[180:181]
	s_mov_b32 m0, s70
	ds_read_b128 v[162:165], v171 offset:16384
	ds_read_b128 v[192:195], v171 offset:17408
	ds_read_b128 v[196:199], v171 offset:18432
	ds_read_b128 v[200:203], v171 offset:19456
	ds_read_b128 v[204:207], v171 offset:20480
	ds_read_b128 v[208:211], v171 offset:21504
	ds_read_b128 v[212:215], v171 offset:22528
	ds_read_b128 v[216:219], v171 offset:23552
	global_load_lds_dwordx4 v[220:221], off
	s_add_i32 m0, s70, 0x2000
	v_lshl_add_u64 v[226:227], s[68:69], 0, v[184:185]
	s_add_u32 s68, s68, s49
	s_addc_u32 s69, s69, 0
	s_add_i32 s14, s14, s47
	global_load_lds_dwordx4 v[226:227], off
	v_lshl_add_u64 v[240:241], s[68:69], 0, v[180:181]
	s_mov_b32 m0, s14
	v_lshl_add_u64 v[242:243], s[68:69], 0, v[184:185]
	global_load_lds_dwordx4 v[240:241], off
	s_add_i32 m0, s14, 0x2000
	v_lshl_add_u64 v[244:245], v[166:167], 0, v[178:179]
	global_load_lds_dwordx4 v[242:243], off
	s_mov_b32 m0, s51
	v_lshl_add_u64 v[246:247], v[166:167], 0, v[182:183]
	global_load_lds_dwordx4 v[244:245], off
	s_mov_b32 m0, s52
	s_nop 0
	global_load_lds_dwordx4 v[246:247], off
	s_waitcnt vmcnt(8)
	s_waitcnt lgkmcnt(0)
	s_setprio 1
	s_barrier
	s_waitcnt lgkmcnt(0)
	v_mfma_f32_16x16x32_bf16 v[60:63], v[130:133], v[162:165], v[60:63]
	v_mfma_f32_16x16x32_bf16 v[56:59], v[138:141], v[162:165], v[56:59]
	v_mfma_f32_16x16x32_bf16 v[44:47], v[130:133], v[196:199], v[44:47]
	v_mfma_f32_16x16x32_bf16 v[40:43], v[138:141], v[196:199], v[40:43]
	v_mfma_f32_16x16x32_bf16 v[28:31], v[130:133], v[204:207], v[28:31]
	v_mfma_f32_16x16x32_bf16 v[24:27], v[138:141], v[204:207], v[24:27]
	v_mfma_f32_16x16x32_bf16 v[12:15], v[130:133], v[212:215], v[12:15]
	v_mfma_f32_16x16x32_bf16 v[8:11], v[138:141], v[212:215], v[8:11]
	v_mfma_f32_16x16x32_bf16 v[60:63], v[134:137], v[192:195], v[60:63]
	v_mfma_f32_16x16x32_bf16 v[56:59], v[142:145], v[192:195], v[56:59]
	v_mfma_f32_16x16x32_bf16 v[44:47], v[134:137], v[200:203], v[44:47]
	v_mfma_f32_16x16x32_bf16 v[40:43], v[142:145], v[200:203], v[40:43]
	v_mfma_f32_16x16x32_bf16 v[28:31], v[134:137], v[208:211], v[28:31]
	v_mfma_f32_16x16x32_bf16 v[24:27], v[142:145], v[208:211], v[24:27]
	v_mfma_f32_16x16x32_bf16 v[12:15], v[134:137], v[216:219], v[12:15]
	v_mfma_f32_16x16x32_bf16 v[8:11], v[142:145], v[216:219], v[8:11]
	s_setprio 0
	s_setprio 1
	v_mfma_f32_16x16x32_bf16 v[52:55], v[146:149], v[162:165], v[52:55]
	v_mfma_f32_16x16x32_bf16 v[48:51], v[154:157], v[162:165], v[48:51]
	v_mfma_f32_16x16x32_bf16 v[36:39], v[146:149], v[196:199], v[36:39]
	v_mfma_f32_16x16x32_bf16 v[32:35], v[154:157], v[196:199], v[32:35]
	v_mfma_f32_16x16x32_bf16 v[20:23], v[146:149], v[204:207], v[20:23]
	v_mfma_f32_16x16x32_bf16 v[16:19], v[154:157], v[204:207], v[16:19]
	v_mfma_f32_16x16x32_bf16 v[4:7], v[146:149], v[212:215], v[4:7]
	v_mfma_f32_16x16x32_bf16 v[0:3], v[154:157], v[212:215], v[0:3]
	v_mfma_f32_16x16x32_bf16 v[52:55], v[150:153], v[192:195], v[52:55]
	v_mfma_f32_16x16x32_bf16 v[48:51], v[158:161], v[192:195], v[48:51]
	v_mfma_f32_16x16x32_bf16 v[36:39], v[150:153], v[200:203], v[36:39]
	v_mfma_f32_16x16x32_bf16 v[32:35], v[158:161], v[200:203], v[32:35]
	v_mfma_f32_16x16x32_bf16 v[20:23], v[150:153], v[208:211], v[20:23]
	v_mfma_f32_16x16x32_bf16 v[16:19], v[158:161], v[208:211], v[16:19]
	v_mfma_f32_16x16x32_bf16 v[4:7], v[150:153], v[216:219], v[4:7]
	v_mfma_f32_16x16x32_bf16 v[0:3], v[158:161], v[216:219], v[0:3]
	s_barrier
; #define PG8_STAGE(bufoff, gbase, voff) do { _Pragma("unroll") for (int _i = 0; _i < 2; ++_i) \
;         __builtin_amdgcn_global_load_lds((const unsigned*)((const char*)(gbase) + (voff)[_i]), (LAS unsigned*)(lds + (bufoff) + ldsw + _i * 8192), 16, 0, 0); } while (0)
; #define PG8_LDA(dst, b, h) do { _Pragma("unroll") for (int m = 0; m < 4; ++m) _Pragma("unroll") for (int k = 0; k < 2; ++k) dst[m][k] = *(const LAS bf16x8*)(lds + PG8_SA(b, h) + aoff + m * 2048 + k * 1024); } while (0)
; #define PG8_LDB(dst, b, h) do { _Pragma("unroll") for (int n = 0; n < 2; ++n) _Pragma("unroll") for (int k = 0; k < 2; ++k) dst[n][k] = *(const LAS bf16x8*)(lds + PG8_SB(b, h) + boff + n * 2048 + k * 1024); } while (0)
; #define PG8_MMA(ai, bj, At, Bt) do { __builtin_amdgcn_s_setprio(1); _Pragma("unroll") for (int k = 0; k < 2; ++k) _Pragma("unroll") for (int m = 0; m < 4; ++m) _Pragma("unroll") for (int n = 0; n < 2; ++n) \
;         acc[ai][bj][m][n] = __builtin_amdgcn_mfma_f32_16x16x32_bf16(Bt[n][k], At[m][k], acc[ai][bj][m][n], 0, 0, 0); __builtin_amdgcn_s_setprio(0); } while (0)
; #define PG8_WAIT_V(n) asm volatile("s_waitcnt vmcnt(" #n ")" ::: "memory")
; #define PG8_WAIT_L(n) asm volatile("s_waitcnt lgkmcnt(" #n ")" ::: "memory")
; #define PG8_BAR __builtin_amdgcn_s_barrier()
; #define PG8_SCHED __builtin_amdgcn_sched_barrier(0)
; template <class Epi, bool ALIGN_EPI>
; __device__ __forceinline__ void gemm_phase(LAS unsigned char* lds, const Gemm g, const StaticOrder& S, const Epi& E, const int tid) {
;     ...
;             PG8_LDB(B0, 1, 0); PG8_LDB(B1, 1, 1); PG8_SCHED; PG8_LDA(At, 1, 0); PG8_STAGE(PG8_SA(0, 1), a2 + hA, voffA);
;             PG8_WAIT_V(8); PG8_WAIT_L(0); PG8_BAR; PG8_MMA(0, 0, At, B0); PG8_MMA(0, 1, At, B1); PG8_BAR; PG8_SCHED;
;             PG8_LDA(At, 1, 1); PG8_STAGE(PG8_SB(1, 0), b3, voffB); PG8_STAGE(PG8_SB(1, 1), b3 + hB, voffB); PG8_STAGE(PG8_SA(1, 0), a3, voffA);
;             PG8_WAIT_V(8); PG8_WAIT_L(0); PG8_BAR; PG8_MMA(1, 0, At, B0); PG8_MMA(1, 1, At, B1); PG8_BAR; PG8_SCHED;
	s_setprio 0
	s_add_i32 s14, 0, 0x18000
	s_add_i32 s68, 0, 0x1c000
	v_add_u32_e32 v142, s14, v239
	v_add_u32_e32 v158, s68, v239
	ds_read_b128 v[130:133], v142
	ds_read_b128 v[134:137], v142 offset:1024
	ds_read_b128 v[138:141], v142 offset:2048
	ds_read_b128 v[142:145], v142 offset:3072
	ds_read_b128 v[146:149], v158
	ds_read_b128 v[150:153], v158 offset:1024
	ds_read_b128 v[154:157], v158 offset:2048
	ds_read_b128 v[158:161], v158 offset:3072
	v_lshl_add_u64 v[166:167], v[166:167], 0, s[94:95]
	s_mov_b32 m0, s53
	v_lshl_add_u64 v[248:249], v[166:167], 0, v[178:179]
	ds_read_b128 v[162:165], v171 offset:32768
	ds_read_b128 v[192:195], v171 offset:33792
	ds_read_b128 v[196:199], v171 offset:34816
	ds_read_b128 v[200:203], v171 offset:35840
	ds_read_b128 v[204:207], v171 offset:36864
	ds_read_b128 v[208:211], v171 offset:37888
	ds_read_b128 v[212:215], v171 offset:38912
	ds_read_b128 v[216:219], v171 offset:39936
	global_load_lds_dwordx4 v[248:249], off
	v_lshl_add_u64 v[166:167], v[166:167], 0, v[182:183]
	s_mov_b32 m0, s54
	s_nop 0
	global_load_lds_dwordx4 v[166:167], off
	s_waitcnt vmcnt(8)
	s_waitcnt lgkmcnt(0)
	s_setprio 1
	s_barrier
	s_waitcnt lgkmcnt(0)
	v_mfma_f32_16x16x32_bf16 v[124:127], v[130:133], v[162:165], v[124:127]
	v_mfma_f32_16x16x32_bf16 v[120:123], v[138:141], v[162:165], v[120:123]
	v_mfma_f32_16x16x32_bf16 v[108:111], v[130:133], v[196:199], v[108:111]
	v_mfma_f32_16x16x32_bf16 v[104:107], v[138:141], v[196:199], v[104:107]
	v_mfma_f32_16x16x32_bf16 v[92:95], v[130:133], v[204:207], v[92:95]
	v_mfma_f32_16x16x32_bf16 v[88:91], v[138:141], v[204:207], v[88:91]
	v_mfma_f32_16x16x32_bf16 v[76:79], v[130:133], v[212:215], v[76:79]
	v_mfma_f32_16x16x32_bf16 v[72:75], v[138:141], v[212:215], v[72:75]
	v_mfma_f32_16x16x32_bf16 v[124:127], v[134:137], v[192:195], v[124:127]
	v_mfma_f32_16x16x32_bf16 v[120:123], v[142:145], v[192:195], v[120:123]
	v_mfma_f32_16x16x32_bf16 v[108:111], v[134:137], v[200:203], v[108:111]
	v_mfma_f32_16x16x32_bf16 v[104:107], v[142:145], v[200:203], v[104:107]
	v_mfma_f32_16x16x32_bf16 v[92:95], v[134:137], v[208:211], v[92:95]
	v_mfma_f32_16x16x32_bf16 v[88:91], v[142:145], v[208:211], v[88:91]
	v_mfma_f32_16x16x32_bf16 v[76:79], v[134:137], v[216:219], v[76:79]
	v_mfma_f32_16x16x32_bf16 v[72:75], v[142:145], v[216:219], v[72:75]
	s_setprio 0
	s_setprio 1
	v_mfma_f32_16x16x32_bf16 v[116:119], v[146:149], v[162:165], v[116:119]
	v_mfma_f32_16x16x32_bf16 v[112:115], v[154:157], v[162:165], v[112:115]
	v_mfma_f32_16x16x32_bf16 v[100:103], v[146:149], v[196:199], v[100:103]
	v_mfma_f32_16x16x32_bf16 v[96:99], v[154:157], v[196:199], v[96:99]
	v_mfma_f32_16x16x32_bf16 v[84:87], v[146:149], v[204:207], v[84:87]
	v_mfma_f32_16x16x32_bf16 v[80:83], v[154:157], v[204:207], v[80:83]
	v_mfma_f32_16x16x32_bf16 v[68:71], v[146:149], v[212:215], v[68:71]
	v_mfma_f32_16x16x32_bf16 v[64:67], v[154:157], v[212:215], v[64:67]
	v_mfma_f32_16x16x32_bf16 v[116:119], v[150:153], v[192:195], v[116:119]
	v_mfma_f32_16x16x32_bf16 v[112:115], v[158:161], v[192:195], v[112:115]
	v_mfma_f32_16x16x32_bf16 v[100:103], v[150:153], v[200:203], v[100:103]
	v_mfma_f32_16x16x32_bf16 v[96:99], v[158:161], v[200:203], v[96:99]
	v_mfma_f32_16x16x32_bf16 v[84:87], v[150:153], v[208:211], v[84:87]
	v_mfma_f32_16x16x32_bf16 v[80:83], v[158:161], v[208:211], v[80:83]
	v_mfma_f32_16x16x32_bf16 v[68:71], v[150:153], v[216:219], v[68:71]
	v_mfma_f32_16x16x32_bf16 v[64:67], v[158:161], v[216:219], v[64:67]
	s_barrier
; #define PG8_STAGE(bufoff, gbase, voff) do { _Pragma("unroll") for (int _i = 0; _i < 2; ++_i) \
;         __builtin_amdgcn_global_load_lds((const unsigned*)((const char*)(gbase) + (voff)[_i]), (LAS unsigned*)(lds + (bufoff) + ldsw + _i * 8192), 16, 0, 0); } while (0)
; #define PG8_LDA(dst, b, h) do { _Pragma("unroll") for (int m = 0; m < 4; ++m) _Pragma("unroll") for (int k = 0; k < 2; ++k) dst[m][k] = *(const LAS bf16x8*)(lds + PG8_SA(b, h) + aoff + m * 2048 + k * 1024); } while (0)
; #define PG8_MMA(ai, bj, At, Bt) do { __builtin_amdgcn_s_setprio(1); _Pragma("unroll") for (int k = 0; k < 2; ++k) _Pragma("unroll") for (int m = 0; m < 4; ++m) _Pragma("unroll") for (int n = 0; n < 2; ++n) \
;         acc[ai][bj][m][n] = __builtin_amdgcn_mfma_f32_16x16x32_bf16(Bt[n][k], At[m][k], acc[ai][bj][m][n], 0, 0, 0); __builtin_amdgcn_s_setprio(0); } while (0)
; #define PG8_WAIT_V(n) asm volatile("s_waitcnt vmcnt(" #n ")" ::: "memory")
; #define PG8_WAIT_L(n) asm volatile("s_waitcnt lgkmcnt(" #n ")" ::: "memory")
; #define PG8_BAR __builtin_amdgcn_s_barrier()
; #define PG8_SCHED __builtin_amdgcn_sched_barrier(0)
; template <class Epi, bool ALIGN_EPI>
; __device__ __forceinline__ void gemm_phase(LAS unsigned char* lds, const Gemm g, const StaticOrder& S, const Epi& E, const int tid) {
;     ...
;             PG8_LDA(At, 1, 1); PG8_STAGE(PG8_SB(1, 0), b3, voffB); PG8_STAGE(PG8_SB(1, 1), b3 + hB, voffB); PG8_STAGE(PG8_SA(1, 0), a3, voffA);
;             PG8_WAIT_V(8); PG8_WAIT_L(0); PG8_BAR; PG8_MMA(1, 0, At, B0); PG8_MMA(1, 1, At, B1); PG8_BAR; PG8_SCHED;
;         }
	s_setprio 0
	s_add_i32 s14, s14, s47
	v_lshl_add_u64 v[166:167], v[220:221], 0, s[92:93]
	s_mov_b32 m0, s14
	ds_read_b128 v[162:165], v171 offset:49152
	ds_read_b128 v[192:195], v171 offset:50176
	ds_read_b128 v[196:199], v171 offset:51200
	ds_read_b128 v[200:203], v171 offset:52224
	ds_read_b128 v[204:207], v171 offset:53248
	ds_read_b128 v[208:211], v171 offset:54272
	ds_read_b128 v[212:215], v171 offset:55296
	ds_read_b128 v[216:219], v171 offset:56320
	global_load_lds_dwordx4 v[166:167], off
	v_lshl_add_u64 v[166:167], v[226:227], 0, s[92:93]
	s_add_i32 m0, s14, 0x2000
	s_add_i32 s14, s68, s47
	global_load_lds_dwordx4 v[166:167], off
	v_lshl_add_u64 v[166:167], v[240:241], 0, s[92:93]
	s_mov_b32 m0, s14
	s_nop 0
	global_load_lds_dwordx4 v[166:167], off
	v_lshl_add_u64 v[166:167], v[242:243], 0, s[92:93]
	s_add_i32 m0, s14, 0x2000
	s_nop 0
	global_load_lds_dwordx4 v[166:167], off
	v_lshl_add_u64 v[166:167], v[244:245], 0, s[92:93]
	s_mov_b32 m0, s55
	s_nop 0
	global_load_lds_dwordx4 v[166:167], off
	v_lshl_add_u64 v[166:167], v[246:247], 0, s[92:93]
	s_mov_b32 m0, s56
	s_nop 0
	global_load_lds_dwordx4 v[166:167], off
	s_waitcnt vmcnt(8)
	s_waitcnt lgkmcnt(0)
	s_setprio 1
	s_barrier
	s_waitcnt lgkmcnt(0)
	v_mfma_f32_16x16x32_bf16 v[60:63], v[130:133], v[162:165], v[60:63]
	v_mfma_f32_16x16x32_bf16 v[56:59], v[138:141], v[162:165], v[56:59]
	v_mfma_f32_16x16x32_bf16 v[44:47], v[130:133], v[196:199], v[44:47]
	v_mfma_f32_16x16x32_bf16 v[40:43], v[138:141], v[196:199], v[40:43]
	v_mfma_f32_16x16x32_bf16 v[28:31], v[130:133], v[204:207], v[28:31]
	v_mfma_f32_16x16x32_bf16 v[24:27], v[138:141], v[204:207], v[24:27]
	v_mfma_f32_16x16x32_bf16 v[12:15], v[130:133], v[212:215], v[12:15]
	v_mfma_f32_16x16x32_bf16 v[8:11], v[138:141], v[212:215], v[8:11]
	v_mfma_f32_16x16x32_bf16 v[60:63], v[134:137], v[192:195], v[60:63]
	v_mfma_f32_16x16x32_bf16 v[56:59], v[142:145], v[192:195], v[56:59]
	v_mfma_f32_16x16x32_bf16 v[44:47], v[134:137], v[200:203], v[44:47]
	v_mfma_f32_16x16x32_bf16 v[40:43], v[142:145], v[200:203], v[40:43]
	v_mfma_f32_16x16x32_bf16 v[28:31], v[134:137], v[208:211], v[28:31]
	v_mfma_f32_16x16x32_bf16 v[24:27], v[142:145], v[208:211], v[24:27]
	v_mfma_f32_16x16x32_bf16 v[12:15], v[134:137], v[216:219], v[12:15]
	v_mfma_f32_16x16x32_bf16 v[8:11], v[142:145], v[216:219], v[8:11]
	s_setprio 0
	s_setprio 1
	v_mfma_f32_16x16x32_bf16 v[52:55], v[146:149], v[162:165], v[52:55]
	v_mfma_f32_16x16x32_bf16 v[48:51], v[154:157], v[162:165], v[48:51]
	v_mfma_f32_16x16x32_bf16 v[36:39], v[146:149], v[196:199], v[36:39]
	v_mfma_f32_16x16x32_bf16 v[32:35], v[154:157], v[196:199], v[32:35]
	v_mfma_f32_16x16x32_bf16 v[20:23], v[146:149], v[204:207], v[20:23]
	v_mfma_f32_16x16x32_bf16 v[16:19], v[154:157], v[204:207], v[16:19]
	v_mfma_f32_16x16x32_bf16 v[4:7], v[146:149], v[212:215], v[4:7]
	v_mfma_f32_16x16x32_bf16 v[0:3], v[154:157], v[212:215], v[0:3]
	v_mfma_f32_16x16x32_bf16 v[52:55], v[150:153], v[192:195], v[52:55]
	v_mfma_f32_16x16x32_bf16 v[48:51], v[158:161], v[192:195], v[48:51]
	v_mfma_f32_16x16x32_bf16 v[36:39], v[150:153], v[200:203], v[36:39]
	v_mfma_f32_16x16x32_bf16 v[32:35], v[158:161], v[200:203], v[32:35]
	v_mfma_f32_16x16x32_bf16 v[20:23], v[150:153], v[208:211], v[20:23]
	v_mfma_f32_16x16x32_bf16 v[16:19], v[158:161], v[208:211], v[16:19]
	v_mfma_f32_16x16x32_bf16 v[4:7], v[150:153], v[216:219], v[4:7]
	v_mfma_f32_16x16x32_bf16 v[0:3], v[158:161], v[216:219], v[0:3]
	s_barrier
	s_setprio 0
	s_add_u32 s10, s10, 0x100
	s_addc_u32 s11, s11, 0
	v_lshl_add_u64 v[128:129], v[128:129], 0, s[80:81]
	s_cmp_ge_u32 s15, s48
	s_mov_b32 s14, s15
	s_cbranch_scc0 .LBB0_274

; __device__ __forceinline__ unsigned cvt_pk_bf16(float lo, float hi) { unsigned r; asm volatile("v_cvt_pk_bf16_f32 %0, %1, %2" : "=v"(r) : "v"(lo), "v"(hi)); return r; }
; __device__ __forceinline__ float siluf_(float x) { return x * sigmoidf_(x); }
; #define PG8_STAGE(bufoff, gbase, voff) do { _Pragma("unroll") for (int _i = 0; _i < 2; ++_i) \
;         __builtin_amdgcn_global_load_lds((const unsigned*)((const char*)(gbase) + (voff)[_i]), (LAS unsigned*)(lds + (bufoff) + ldsw + _i * 8192), 16, 0, 0); } while (0)
; #define PG8_LDA(dst, b, h) do { _Pragma("unroll") for (int m = 0; m < 4; ++m) _Pragma("unroll") for (int k = 0; k < 2; ++k) dst[m][k] = *(const LAS bf16x8*)(lds + PG8_SA(b, h) + aoff + m * 2048 + k * 1024); } while (0)
; #define PG8_LDB(dst, b, h) do { _Pragma("unroll") for (int n = 0; n < 2; ++n) _Pragma("unroll") for (int k = 0; k < 2; ++k) dst[n][k] = *(const LAS bf16x8*)(lds + PG8_SB(b, h) + boff + n * 2048 + k * 1024); } while (0)
; #define PG8_WAIT_V(n) asm volatile("s_waitcnt vmcnt(" #n ")" ::: "memory")
; #define PG8_WAIT_L(n) asm volatile("s_waitcnt lgkmcnt(" #n ")" ::: "memory")
; #define PG8_BAR __builtin_amdgcn_s_barrier()
;     __device__ __forceinline__ void operator()(const f32x4 (&acc)[2][2][4][2], const Unit& u, int wr, int wc, int fr, int fq) const {
;     ...
;         for (int ai = 0; ai < 2; ++ai)
; #pragma unroll
;             for (int m = 0; m < 4; ++m) { const int row = row0 + ai * HALF + m * 16; bf16_t* rowp = O + (size_t)row * ldc + col0; const float rs = rsv[ai][m];
;                 f32x4 v0, v1;
; #pragma unroll
;                 for (int j = 0; j < 4; ++j) { v0[j] = siluf_(acc[ai][0][m][0][j] * rs) * (acc[ai][1][m][0][j] * rs); v1[j] = siluf_(acc[ai][0][m][1][j] * rs) * (acc[ai][1][m][1][j] * rs); }
;                 u32x4 w; w.x = cvt_pk_bf16(v0[0], v0[1]); w.y = cvt_pk_bf16(v0[2], v0[3]); w.z = cvt_pk_bf16(v1[0], v1[1]); w.w = cvt_pk_bf16(v1[2], v1[3]);
;                 *(u32x4*)rowp = w; }
; template <class Epi, bool ALIGN_EPI>
; __device__ __forceinline__ void gemm_phase(LAS unsigned char* lds, const Gemm g, const StaticOrder& S, const Epi& E, const int tid) {
;     ...
;             PG8_LDB(B0, 0, 0); PG8_LDB(B1, 0, 1); PG8_SCHED; PG8_LDA(At, 0, 0); PG8_STAGE(PG8_SA(1, 1), a1 + hA, voffA);
;             PG8_WAIT_V(8); PG8_WAIT_L(0); PG8_BAR; PG8_MMA(0, 0, At, B0); PG8_MMA(0, 1, At, B1); PG8_BAR; PG8_SCHED;
.Lgu_first_epi:
	s_add_i32 s11, s10, 2
	s_cmp_eq_u32 s58, s10
	v_lshl_add_u64 v[146:147], v[142:143], 0, s[92:93]
	s_cselect_b64 vcc, -1, 0
	v_add_u32_e32 v150, s33, v151
	s_add_i32 s10, 0, 0x14000
	v_cndmask_b32_e32 v167, v147, v139, vcc
	v_cndmask_b32_e32 v166, v146, v138, vcc
	ds_read_b128 v[146:149], v150
	ds_read_b128 v[154:157], v150 offset:1024
	ds_read_b128 v[158:161], v150 offset:2048
	ds_read_b128 v[162:165], v150 offset:3072
	v_add_u32_e32 v150, s10, v151
	ds_read_b128 v[176:179], v150
	ds_read_b128 v[180:183], v150 offset:1024
	ds_read_b128 v[184:187], v150 offset:2048
	ds_read_b128 v[188:191], v150 offset:3072
	v_cndmask_b32_e32 v221, v145, v141, vcc
	v_cndmask_b32_e32 v220, v144, v140, vcc
	v_lshl_add_u64 v[226:227], v[142:143], 0, v[134:135]
	s_add_i32 m0, s51, 0xc000
	ds_read_b128 v[192:195], v153
	ds_read_b128 v[196:199], v153 offset:1024
	ds_read_b128 v[200:203], v153 offset:2048
	ds_read_b128 v[204:207], v153 offset:3072
	ds_read_b128 v[208:211], v153 offset:4096
	ds_read_b128 v[212:215], v153 offset:5120
	ds_read_b128 v[216:219], v153 offset:6144
	ds_read_b128 v[240:243], v153 offset:7168
	global_load_lds_dwordx4 v[226:227], off
	v_lshl_add_u64 v[226:227], v[142:143], 0, v[136:137]
	s_add_i32 m0, s51, 0xe000
	s_nop 0
	global_load_lds_dwordx4 v[226:227], off
	s_waitcnt vmcnt(12)
	s_waitcnt lgkmcnt(0)
	s_setprio 1
	s_barrier
	s_waitcnt lgkmcnt(0)
	v_mfma_f32_16x16x32_bf16 v[120:123], v[146:149], v[192:195], 0
	s_lshl_b32 s98, s28, 5
	s_mov_b32 s99, 0
	s_mov_b32 s100, 0xbfb8aa3b
	s_mov_b32 s101, 0xbfb8aa3b
	v_mul_f32_e32 v56, v238, v56
	v_mul_f32_e32 v57, v238, v57
	v_mul_f32_e32 v58, v238, v58
	v_mul_f32_e32 v59, v238, v59
	v_mul_f32_e32 v60, v238, v60
	v_mul_f32_e32 v61, v238, v61
	v_mfma_f32_16x16x32_bf16 v[112:115], v[158:161], v[192:195], 0
	v_mul_f32_e32 v62, v238, v62
	v_mul_f32_e32 v63, v238, v63
	v_mul_f32_e32 v224, s100, v56
	v_mul_f32_e32 v225, s101, v57
	v_mul_f32_e32 v228, s100, v58
	v_mul_f32_e32 v229, s101, v59
	v_exp_f32_e32 v224, v224
	v_exp_f32_e32 v225, v225
	v_exp_f32_e32 v228, v228
	v_exp_f32_e32 v229, v229
	v_mfma_f32_16x16x32_bf16 v[104:107], v[146:149], v[200:203], 0
	v_add_f32_e32 v224, 1.0, v224
	v_add_f32_e32 v225, 1.0, v225
	v_add_f32_e32 v228, 1.0, v228
	v_add_f32_e32 v229, 1.0, v229
	v_rcp_f32_e32 v224, v224
	v_rcp_f32_e32 v225, v225
	v_rcp_f32_e32 v228, v228
	v_rcp_f32_e32 v229, v229
	v_nop
	v_mul_f32_e32 v56, v224, v56
	v_mfma_f32_16x16x32_bf16 v[96:99], v[158:161], v[200:203], 0
	v_mul_f32_e32 v57, v225, v57
	v_mul_f32_e32 v58, v228, v58
	v_mul_f32_e32 v59, v229, v59
	v_mul_f32_e32 v56, v60, v56
	v_mul_f32_e32 v57, v61, v57
	v_mul_f32_e32 v58, v62, v58
	v_mul_f32_e32 v59, v63, v59
	v_mul_f32_e32 v48, v238, v48
	v_mul_f32_e32 v49, v238, v49
	v_mul_f32_e32 v50, v238, v50
	v_mfma_f32_16x16x32_bf16 v[88:91], v[146:149], v[208:211], 0
	v_mul_f32_e32 v51, v238, v51
	v_mul_f32_e32 v52, v238, v52
	v_mul_f32_e32 v53, v238, v53
	v_mul_f32_e32 v54, v238, v54
	v_mul_f32_e32 v55, v238, v55
	v_mul_f32_e32 v224, s100, v48
	v_mul_f32_e32 v225, s101, v49
	v_mul_f32_e32 v228, s100, v50
	v_mul_f32_e32 v229, s101, v51
	v_exp_f32_e32 v224, v224
	v_mfma_f32_16x16x32_bf16 v[80:83], v[158:161], v[208:211], 0
	v_exp_f32_e32 v225, v225
	v_exp_f32_e32 v228, v228
	v_exp_f32_e32 v229, v229
	v_add_f32_e32 v224, 1.0, v224
	v_add_f32_e32 v225, 1.0, v225
	v_add_f32_e32 v228, 1.0, v228
	v_add_f32_e32 v229, 1.0, v229
	v_rcp_f32_e32 v224, v224
	v_rcp_f32_e32 v225, v225
	v_rcp_f32_e32 v228, v228
	v_mfma_f32_16x16x32_bf16 v[72:75], v[146:149], v[216:219], 0
	v_rcp_f32_e32 v229, v229
	v_nop
	v_mul_f32_e32 v48, v224, v48
	v_mul_f32_e32 v49, v225, v49
	v_mul_f32_e32 v50, v228, v50
	v_mul_f32_e32 v51, v229, v51
	v_mul_f32_e32 v48, v52, v48
	v_mul_f32_e32 v49, v53, v49
	v_mul_f32_e32 v50, v54, v50
	v_mul_f32_e32 v51, v55, v51
	v_mfma_f32_16x16x32_bf16 v[64:67], v[158:161], v[216:219], 0
	v_cvt_pk_bf16_f32 v56, v56, v57
	v_cvt_pk_bf16_f32 v57, v58, v59
	v_cvt_pk_bf16_f32 v58, v48, v49
	v_cvt_pk_bf16_f32 v59, v50, v51
	global_store_dwordx4 v[232:233], v[56:59], off
	v_lshl_add_u64 v[232:233], v[232:233], 0, s[98:99]
	v_mul_f32_e32 v40, v239, v40
	v_mul_f32_e32 v41, v239, v41
	v_mul_f32_e32 v42, v239, v42
	v_mul_f32_e32 v43, v239, v43
	v_mfma_f32_16x16x32_bf16 v[120:123], v[154:157], v[196:199], v[120:123]
	v_mul_f32_e32 v44, v239, v44
	v_mul_f32_e32 v45, v239, v45
	v_mul_f32_e32 v46, v239, v46
	v_mul_f32_e32 v47, v239, v47
	v_mul_f32_e32 v224, s100, v40
	v_mul_f32_e32 v225, s101, v41
	v_mul_f32_e32 v228, s100, v42
	v_mul_f32_e32 v229, s101, v43
	v_exp_f32_e32 v224, v224
	v_exp_f32_e32 v225, v225
	v_mfma_f32_16x16x32_bf16 v[112:115], v[162:165], v[196:199], v[112:115]
	v_exp_f32_e32 v228, v228
	v_exp_f32_e32 v229, v229
	v_add_f32_e32 v224, 1.0, v224
	v_add_f32_e32 v225, 1.0, v225
	v_add_f32_e32 v228, 1.0, v228
	v_add_f32_e32 v229, 1.0, v229
	v_rcp_f32_e32 v224, v224
	v_rcp_f32_e32 v225, v225
	v_rcp_f32_e32 v228, v228
	v_rcp_f32_e32 v229, v229
	v_mfma_f32_16x16x32_bf16 v[104:107], v[154:157], v[204:207], v[104:107]
	v_nop
	v_mul_f32_e32 v40, v224, v40
	v_mul_f32_e32 v41, v225, v41
	v_mul_f32_e32 v42, v228, v42
	v_mul_f32_e32 v43, v229, v43
	v_mul_f32_e32 v40, v44, v40
	v_mul_f32_e32 v41, v45, v41
	v_mul_f32_e32 v42, v46, v42
	v_mul_f32_e32 v43, v47, v43
	v_mul_f32_e32 v32, v239, v32
	v_mfma_f32_16x16x32_bf16 v[96:99], v[162:165], v[204:207], v[96:99]
	v_mul_f32_e32 v33, v239, v33
	v_mul_f32_e32 v34, v239, v34
	v_mul_f32_e32 v35, v239, v35
	v_mul_f32_e32 v36, v239, v36
	v_mul_f32_e32 v37, v239, v37
	v_mul_f32_e32 v38, v239, v38
	v_mul_f32_e32 v39, v239, v39
	v_mul_f32_e32 v224, s100, v32
	v_mul_f32_e32 v225, s101, v33
; __device__ __forceinline__ unsigned cvt_pk_bf16(float lo, float hi) { unsigned r; asm volatile("v_cvt_pk_bf16_f32 %0, %1, %2" : "=v"(r) : "v"(lo), "v"(hi)); return r; }
; __device__ __forceinline__ float siluf_(float x) { return x * sigmoidf_(x); }
; #define PG8_MMA(ai, bj, At, Bt) do { __builtin_amdgcn_s_setprio(1); _Pragma("unroll") for (int k = 0; k < 2; ++k) _Pragma("unroll") for (int m = 0; m < 4; ++m) _Pragma("unroll") for (int n = 0; n < 2; ++n) \
;         acc[ai][bj][m][n] = __builtin_amdgcn_mfma_f32_16x16x32_bf16(Bt[n][k], At[m][k], acc[ai][bj][m][n], 0, 0, 0); __builtin_amdgcn_s_setprio(0); } while (0)
; #define PG8_WAIT_V(n) asm volatile("s_waitcnt vmcnt(" #n ")" ::: "memory")
; #define PG8_WAIT_L(n) asm volatile("s_waitcnt lgkmcnt(" #n ")" ::: "memory")
; #define PG8_BAR __builtin_amdgcn_s_barrier()
; #define PG8_SCHED __builtin_amdgcn_sched_barrier(0)
;     __device__ __forceinline__ void operator()(const f32x4 (&acc)[2][2][4][2], const Unit& u, int wr, int wc, int fr, int fq) const {
;     ...
;         for (int ai = 0; ai < 2; ++ai)
; #pragma unroll
;             for (int m = 0; m < 4; ++m) { const int row = row0 + ai * HALF + m * 16; bf16_t* rowp = O + (size_t)row * ldc + col0; const float rs = rsv[ai][m];
;                 f32x4 v0, v1;
; #pragma unroll
;                 for (int j = 0; j < 4; ++j) { v0[j] = siluf_(acc[ai][0][m][0][j] * rs) * (acc[ai][1][m][0][j] * rs); v1[j] = siluf_(acc[ai][0][m][1][j] * rs) * (acc[ai][1][m][1][j] * rs); }
;                 u32x4 w; w.x = cvt_pk_bf16(v0[0], v0[1]); w.y = cvt_pk_bf16(v0[2], v0[3]); w.z = cvt_pk_bf16(v1[0], v1[1]); w.w = cvt_pk_bf16(v1[2], v1[3]);
;                 *(u32x4*)rowp = w; }
; template <class Epi, bool ALIGN_EPI>
; __device__ __forceinline__ void gemm_phase(LAS unsigned char* lds, const Gemm g, const StaticOrder& S, const Epi& E, const int tid) {
;     ...
;             PG8_WAIT_V(8); PG8_WAIT_L(0); PG8_BAR; PG8_MMA(0, 0, At, B0); PG8_MMA(0, 1, At, B1); PG8_BAR; PG8_SCHED;
	v_mul_f32_e32 v228, s100, v34
	v_mfma_f32_16x16x32_bf16 v[88:91], v[154:157], v[212:215], v[88:91]
	v_mul_f32_e32 v229, s101, v35
	v_exp_f32_e32 v224, v224
	v_exp_f32_e32 v225, v225
	v_exp_f32_e32 v228, v228
	v_exp_f32_e32 v229, v229
	v_add_f32_e32 v224, 1.0, v224
	v_add_f32_e32 v225, 1.0, v225
	v_add_f32_e32 v228, 1.0, v228
	v_add_f32_e32 v229, 1.0, v229
	v_rcp_f32_e32 v224, v224
	v_mfma_f32_16x16x32_bf16 v[80:83], v[162:165], v[212:215], v[80:83]
	v_rcp_f32_e32 v225, v225
	v_rcp_f32_e32 v228, v228
	v_rcp_f32_e32 v229, v229
	v_nop
	v_mul_f32_e32 v32, v224, v32
	v_mul_f32_e32 v33, v225, v33
	v_mul_f32_e32 v34, v228, v34
	v_mul_f32_e32 v35, v229, v35
	v_mul_f32_e32 v32, v36, v32
	v_mul_f32_e32 v33, v37, v33
	v_mfma_f32_16x16x32_bf16 v[72:75], v[154:157], v[240:243], v[72:75]
	v_mul_f32_e32 v34, v38, v34
	v_mul_f32_e32 v35, v39, v35
	v_cvt_pk_bf16_f32 v40, v40, v41
	v_cvt_pk_bf16_f32 v41, v42, v43
	v_cvt_pk_bf16_f32 v42, v32, v33
	v_cvt_pk_bf16_f32 v43, v34, v35
	global_store_dwordx4 v[232:233], v[40:43], off
	v_lshl_add_u64 v[232:233], v[232:233], 0, s[98:99]
	v_mul_f32_e32 v24, v230, v24
	v_mul_f32_e32 v25, v230, v25
	v_mfma_f32_16x16x32_bf16 v[64:67], v[162:165], v[240:243], v[64:67]
	v_mul_f32_e32 v26, v230, v26
	v_mul_f32_e32 v27, v230, v27
	v_mul_f32_e32 v28, v230, v28
	v_mul_f32_e32 v29, v230, v29
	v_mul_f32_e32 v30, v230, v30
	v_mul_f32_e32 v31, v230, v31
	v_mul_f32_e32 v224, s100, v24
	v_mul_f32_e32 v225, s101, v25
	v_mul_f32_e32 v228, s100, v26
	v_mul_f32_e32 v229, s101, v27
	s_setprio 0
	s_setprio 1
	v_mfma_f32_16x16x32_bf16 v[124:127], v[176:179], v[192:195], 0
	v_exp_f32_e32 v224, v224
	v_exp_f32_e32 v225, v225
	v_exp_f32_e32 v228, v228
	v_exp_f32_e32 v229, v229
	v_add_f32_e32 v224, 1.0, v224
	v_add_f32_e32 v225, 1.0, v225
	v_add_f32_e32 v228, 1.0, v228
	v_add_f32_e32 v229, 1.0, v229
	v_rcp_f32_e32 v224, v224
	v_rcp_f32_e32 v225, v225
	v_mfma_f32_16x16x32_bf16 v[116:119], v[184:187], v[192:195], 0
	v_rcp_f32_e32 v228, v228
	v_rcp_f32_e32 v229, v229
	v_nop
	v_mul_f32_e32 v24, v224, v24
	v_mul_f32_e32 v25, v225, v25
	v_mul_f32_e32 v26, v228, v26
	v_mul_f32_e32 v27, v229, v27
	v_mul_f32_e32 v24, v28, v24
	v_mul_f32_e32 v25, v29, v25
	v_mul_f32_e32 v26, v30, v26
	v_mfma_f32_16x16x32_bf16 v[108:111], v[176:179], v[200:203], 0
	v_mul_f32_e32 v27, v31, v27
	v_mul_f32_e32 v16, v230, v16
	v_mul_f32_e32 v17, v230, v17
	v_mul_f32_e32 v18, v230, v18
	v_mul_f32_e32 v19, v230, v19
	v_mul_f32_e32 v20, v230, v20
	v_mul_f32_e32 v21, v230, v21
	v_mul_f32_e32 v22, v230, v22
	v_mul_f32_e32 v23, v230, v23
	v_mul_f32_e32 v224, s100, v16
	v_mfma_f32_16x16x32_bf16 v[100:103], v[184:187], v[200:203], 0
	v_mul_f32_e32 v225, s101, v17
	v_mul_f32_e32 v228, s100, v18
	v_mul_f32_e32 v229, s101, v19
	v_exp_f32_e32 v224, v224
	v_exp_f32_e32 v225, v225
	v_exp_f32_e32 v228, v228
	v_exp_f32_e32 v229, v229
	v_add_f32_e32 v224, 1.0, v224
	v_add_f32_e32 v225, 1.0, v225
	v_add_f32_e32 v228, 1.0, v228
	v_mfma_f32_16x16x32_bf16 v[92:95], v[176:179], v[208:211], 0
	v_add_f32_e32 v229, 1.0, v229
	v_rcp_f32_e32 v224, v224
	v_rcp_f32_e32 v225, v225
	v_rcp_f32_e32 v228, v228
	v_rcp_f32_e32 v229, v229
	v_nop
	v_mul_f32_e32 v16, v224, v16
	v_mul_f32_e32 v17, v225, v17
	v_mul_f32_e32 v18, v228, v18
	v_mul_f32_e32 v19, v229, v19
	v_mfma_f32_16x16x32_bf16 v[84:87], v[184:187], v[208:211], 0
	v_mul_f32_e32 v16, v20, v16
	v_mul_f32_e32 v17, v21, v17
	v_mul_f32_e32 v18, v22, v18
	v_mul_f32_e32 v19, v23, v19
	v_cvt_pk_bf16_f32 v24, v24, v25
	v_cvt_pk_bf16_f32 v25, v26, v27
	v_cvt_pk_bf16_f32 v26, v16, v17
	v_cvt_pk_bf16_f32 v27, v18, v19
	global_store_dwordx4 v[232:233], v[24:27], off
	v_lshl_add_u64 v[232:233], v[232:233], 0, s[98:99]
	v_mfma_f32_16x16x32_bf16 v[76:79], v[176:179], v[216:219], 0
	v_mul_f32_e32 v8, v231, v8
	v_mul_f32_e32 v9, v231, v9
	v_mul_f32_e32 v10, v231, v10
	v_mul_f32_e32 v11, v231, v11
	v_mul_f32_e32 v12, v231, v12
	v_mul_f32_e32 v13, v231, v13
	v_mul_f32_e32 v14, v231, v14
	v_mul_f32_e32 v15, v231, v15
	v_mul_f32_e32 v224, s100, v8
	v_mul_f32_e32 v225, s101, v9
	v_mfma_f32_16x16x32_bf16 v[68:71], v[184:187], v[216:219], 0
	v_mul_f32_e32 v228, s100, v10
	v_mul_f32_e32 v229, s101, v11
	v_exp_f32_e32 v224, v224
	v_exp_f32_e32 v225, v225
	v_exp_f32_e32 v228, v228
	v_exp_f32_e32 v229, v229
	v_add_f32_e32 v224, 1.0, v224
	v_add_f32_e32 v225, 1.0, v225
	v_add_f32_e32 v228, 1.0, v228
	v_add_f32_e32 v229, 1.0, v229
	v_mfma_f32_16x16x32_bf16 v[124:127], v[180:183], v[196:199], v[124:127]
	v_rcp_f32_e32 v224, v224
	v_rcp_f32_e32 v225, v225
	v_rcp_f32_e32 v228, v228
	v_rcp_f32_e32 v229, v229
	v_nop
	v_mul_f32_e32 v8, v224, v8
	v_mul_f32_e32 v9, v225, v9
	v_mul_f32_e32 v10, v228, v10
	v_mul_f32_e32 v11, v229, v11
	v_mul_f32_e32 v8, v12, v8
	v_mfma_f32_16x16x32_bf16 v[116:119], v[188:191], v[196:199], v[116:119]
	v_mul_f32_e32 v9, v13, v9
	v_mul_f32_e32 v10, v14, v10
	v_mul_f32_e32 v11, v15, v11
	v_mul_f32_e32 v4, v231, v4
	v_mul_f32_e32 v5, v231, v5
	v_mul_f32_e32 v6, v231, v6
	v_mul_f32_e32 v7, v231, v7
	v_mul_f32_e32 v0, v231, v0
	v_mul_f32_e32 v1, v231, v1
	v_mul_f32_e32 v2, v231, v2
	v_mfma_f32_16x16x32_bf16 v[108:111], v[180:183], v[204:207], v[108:111]
	v_mul_f32_e32 v3, v231, v3
	v_mul_f32_e32 v224, s100, v4
	v_mul_f32_e32 v225, s101, v5
	v_mul_f32_e32 v228, s100, v6
	v_mul_f32_e32 v229, s101, v7
	v_exp_f32_e32 v224, v224
	v_exp_f32_e32 v225, v225
	v_exp_f32_e32 v228, v228
	v_exp_f32_e32 v229, v229
	v_add_f32_e32 v224, 1.0, v224
	v_mfma_f32_16x16x32_bf16 v[100:103], v[188:191], v[204:207], v[100:103]
	v_add_f32_e32 v225, 1.0, v225
	v_add_f32_e32 v228, 1.0, v228
	v_add_f32_e32 v229, 1.0, v229
	v_rcp_f32_e32 v224, v224
	v_rcp_f32_e32 v225, v225
	v_rcp_f32_e32 v228, v228
	v_rcp_f32_e32 v229, v229
	v_nop
	v_mul_f32_e32 v4, v224, v4
	v_mul_f32_e32 v5, v225, v5
	v_mfma_f32_16x16x32_bf16 v[92:95], v[180:183], v[212:215], v[92:95]
	v_mul_f32_e32 v6, v228, v6
	v_mul_f32_e32 v7, v229, v7
	v_mul_f32_e32 v4, v0, v4
	v_mul_f32_e32 v5, v1, v5
	v_mul_f32_e32 v6, v2, v6
	v_mul_f32_e32 v7, v3, v7
	v_cvt_pk_bf16_f32 v8, v8, v9
	v_cvt_pk_bf16_f32 v9, v10, v11
	v_cvt_pk_bf16_f32 v10, v4, v5
	v_cvt_pk_bf16_f32 v11, v6, v7
	v_mfma_f32_16x16x32_bf16 v[84:87], v[188:191], v[212:215], v[84:87]
	global_store_dwordx4 v[232:233], v[8:11], off
	v_mfma_f32_16x16x32_bf16 v[76:79], v[180:183], v[240:243], v[76:79]
	v_mfma_f32_16x16x32_bf16 v[68:71], v[188:191], v[240:243], v[68:71]
	s_barrier
; #define PG8_STAGE(bufoff, gbase, voff) do { _Pragma("unroll") for (int _i = 0; _i < 2; ++_i) \
;         __builtin_amdgcn_global_load_lds((const unsigned*)((const char*)(gbase) + (voff)[_i]), (LAS unsigned*)(lds + (bufoff) + ldsw + _i * 8192), 16, 0, 0); } while (0)
; #define PG8_LDA(dst, b, h) do { _Pragma("unroll") for (int m = 0; m < 4; ++m) _Pragma("unroll") for (int k = 0; k < 2; ++k) dst[m][k] = *(const LAS bf16x8*)(lds + PG8_SA(b, h) + aoff + m * 2048 + k * 1024); } while (0)
; #define PG8_LDB(dst, b, h) do { _Pragma("unroll") for (int n = 0; n < 2; ++n) _Pragma("unroll") for (int k = 0; k < 2; ++k) dst[n][k] = *(const LAS bf16x8*)(lds + PG8_SB(b, h) + boff + n * 2048 + k * 1024); } while (0)
; #define PG8_MMA(ai, bj, At, Bt) do { __builtin_amdgcn_s_setprio(1); _Pragma("unroll") for (int k = 0; k < 2; ++k) _Pragma("unroll") for (int m = 0; m < 4; ++m) _Pragma("unroll") for (int n = 0; n < 2; ++n) \
;         acc[ai][bj][m][n] = __builtin_amdgcn_mfma_f32_16x16x32_bf16(Bt[n][k], At[m][k], acc[ai][bj][m][n], 0, 0, 0); __builtin_amdgcn_s_setprio(0); } while (0)
; #define PG8_WAIT_V(n) asm volatile("s_waitcnt vmcnt(" #n ")" ::: "memory")
; #define PG8_WAIT_L(n) asm volatile("s_waitcnt lgkmcnt(" #n ")" ::: "memory")
; #define PG8_BAR __builtin_amdgcn_s_barrier()
; #define PG8_SCHED __builtin_amdgcn_sched_barrier(0)
; template <class Epi, bool ALIGN_EPI>
; __device__ __forceinline__ void gemm_phase(LAS unsigned char* lds, const Gemm g, const StaticOrder& S, const Epi& E, const int tid) {
;     ...
;             PG8_LDA(At, 0, 1); PG8_STAGE(PG8_SB(0, 0), b2, voffB); PG8_STAGE(PG8_SB(0, 1), b2 + hB, voffB); PG8_STAGE(PG8_SA(0, 0), a2, voffA);
;             PG8_WAIT_V(8); PG8_WAIT_L(0); PG8_BAR; PG8_MMA(1, 0, At, B0); PG8_MMA(1, 1, At, B1); PG8_BAR; PG8_SCHED;
;             PG8_LDB(B0, 1, 0); PG8_LDB(B1, 1, 1); PG8_SCHED; PG8_LDA(At, 1, 0); PG8_STAGE(PG8_SA(0, 1), a2 + hA, voffA);
;             PG8_WAIT_V(8); PG8_WAIT_L(0); PG8_BAR; PG8_MMA(0, 0, At, B0); PG8_MMA(0, 1, At, B1); PG8_BAR; PG8_SCHED;
	s_setprio 0
	s_add_i32 s65, s33, s45
	v_lshl_add_u64 v[226:227], v[220:221], 0, v[168:169]
	s_mov_b32 m0, s65
	ds_read_b128 v[192:195], v153 offset:16384
	ds_read_b128 v[196:199], v153 offset:17408
	ds_read_b128 v[200:203], v153 offset:18432
	ds_read_b128 v[204:207], v153 offset:19456
	ds_read_b128 v[208:211], v153 offset:20480
	ds_read_b128 v[212:215], v153 offset:21504
	ds_read_b128 v[216:219], v153 offset:22528
	ds_read_b128 v[240:243], v153 offset:23552
	global_load_lds_dwordx4 v[226:227], off
	v_lshl_add_u64 v[244:245], v[220:221], 0, v[128:129]
	s_add_i32 m0, s65, 0x2000
	v_lshl_add_u64 v[220:221], v[220:221], 0, s[12:13]
	s_add_i32 s10, s10, s45
	global_load_lds_dwordx4 v[244:245], off
	v_lshl_add_u64 v[246:247], v[220:221], 0, v[168:169]
	s_mov_b32 m0, s10
	v_lshl_add_u64 v[220:221], v[220:221], 0, v[128:129]
	global_load_lds_dwordx4 v[246:247], off
	s_add_i32 m0, s10, 0x2000
	v_lshl_add_u64 v[248:249], v[166:167], 0, v[132:133]
	global_load_lds_dwordx4 v[220:221], off
	s_mov_b32 m0, s51
	v_lshl_add_u64 v[250:251], v[166:167], 0, v[130:131]
	global_load_lds_dwordx4 v[248:249], off
	s_mov_b32 m0, s52
	s_nop 0
	global_load_lds_dwordx4 v[250:251], off
	s_waitcnt vmcnt(16)
	s_waitcnt lgkmcnt(0)
	s_setprio 1
	s_barrier
	s_waitcnt lgkmcnt(0)
	v_mfma_f32_16x16x32_bf16 v[56:59], v[146:149], v[192:195], 0
	v_mfma_f32_16x16x32_bf16 v[48:51], v[158:161], v[192:195], 0
	v_mfma_f32_16x16x32_bf16 v[40:43], v[146:149], v[200:203], 0
	v_mfma_f32_16x16x32_bf16 v[32:35], v[158:161], v[200:203], 0
	v_mfma_f32_16x16x32_bf16 v[24:27], v[146:149], v[208:211], 0
	v_mfma_f32_16x16x32_bf16 v[16:19], v[158:161], v[208:211], 0
	v_mfma_f32_16x16x32_bf16 v[8:11], v[146:149], v[216:219], 0
	v_mfma_f32_16x16x32_bf16 v[4:7], v[158:161], v[216:219], 0
	v_mfma_f32_16x16x32_bf16 v[56:59], v[154:157], v[196:199], v[56:59]
	v_mfma_f32_16x16x32_bf16 v[48:51], v[162:165], v[196:199], v[48:51]
	v_mfma_f32_16x16x32_bf16 v[40:43], v[154:157], v[204:207], v[40:43]
	v_mfma_f32_16x16x32_bf16 v[32:35], v[162:165], v[204:207], v[32:35]
	v_mfma_f32_16x16x32_bf16 v[24:27], v[154:157], v[212:215], v[24:27]
	v_mfma_f32_16x16x32_bf16 v[16:19], v[162:165], v[212:215], v[16:19]
	v_mfma_f32_16x16x32_bf16 v[8:11], v[154:157], v[240:243], v[8:11]
	v_mfma_f32_16x16x32_bf16 v[4:7], v[162:165], v[240:243], v[4:7]
	s_setprio 0
	s_setprio 1
	v_mfma_f32_16x16x32_bf16 v[60:63], v[176:179], v[192:195], 0
	v_mfma_f32_16x16x32_bf16 v[52:55], v[184:187], v[192:195], 0
	v_mfma_f32_16x16x32_bf16 v[44:47], v[176:179], v[200:203], 0
	v_mfma_f32_16x16x32_bf16 v[36:39], v[184:187], v[200:203], 0
	v_mfma_f32_16x16x32_bf16 v[28:31], v[176:179], v[208:211], 0
	v_mfma_f32_16x16x32_bf16 v[20:23], v[184:187], v[208:211], 0
	v_mfma_f32_16x16x32_bf16 v[12:15], v[176:179], v[216:219], 0
	v_mfma_f32_16x16x32_bf16 v[0:3], v[184:187], v[216:219], 0
	v_mfma_f32_16x16x32_bf16 v[60:63], v[180:183], v[196:199], v[60:63]
	v_mfma_f32_16x16x32_bf16 v[52:55], v[188:191], v[196:199], v[52:55]
	v_mfma_f32_16x16x32_bf16 v[44:47], v[180:183], v[204:207], v[44:47]
	v_mfma_f32_16x16x32_bf16 v[36:39], v[188:191], v[204:207], v[36:39]
	v_mfma_f32_16x16x32_bf16 v[28:31], v[180:183], v[212:215], v[28:31]
	v_mfma_f32_16x16x32_bf16 v[20:23], v[188:191], v[212:215], v[20:23]
	v_mfma_f32_16x16x32_bf16 v[12:15], v[180:183], v[240:243], v[12:15]
	v_mfma_f32_16x16x32_bf16 v[0:3], v[188:191], v[240:243], v[0:3]
	s_barrier
	s_setprio 0
	s_add_i32 s10, 0, 0x18000
	v_add_u32_e32 v150, s10, v151
	s_add_i32 s65, 0, 0x1c000
	ds_read_b128 v[146:149], v150
	ds_read_b128 v[154:157], v150 offset:1024
	ds_read_b128 v[158:161], v150 offset:2048
	ds_read_b128 v[162:165], v150 offset:3072
	v_add_u32_e32 v150, s65, v151
	ds_read_b128 v[176:179], v150
	ds_read_b128 v[180:183], v150 offset:1024
	ds_read_b128 v[184:187], v150 offset:2048
	ds_read_b128 v[188:191], v150 offset:3072
	v_lshl_add_u64 v[166:167], v[166:167], 0, s[94:95]
	s_mov_b32 m0, s53
	v_lshl_add_u64 v[252:253], v[166:167], 0, v[132:133]
	ds_read_b128 v[192:195], v153 offset:32768
	ds_read_b128 v[196:199], v153 offset:33792
	ds_read_b128 v[200:203], v153 offset:34816
	ds_read_b128 v[204:207], v153 offset:35840
	ds_read_b128 v[208:211], v153 offset:36864
	ds_read_b128 v[212:215], v153 offset:37888
	ds_read_b128 v[216:219], v153 offset:38912
	ds_read_b128 v[240:243], v153 offset:39936
	global_load_lds_dwordx4 v[252:253], off
	v_lshl_add_u64 v[166:167], v[166:167], 0, v[130:131]
	s_mov_b32 m0, s54
	s_nop 0
	global_load_lds_dwordx4 v[166:167], off
	s_waitcnt vmcnt(12)
	s_waitcnt lgkmcnt(0)
	s_setprio 1
	s_barrier
; #define PG8_STAGE(bufoff, gbase, voff) do { _Pragma("unroll") for (int _i = 0; _i < 2; ++_i) \
;         __builtin_amdgcn_global_load_lds((const unsigned*)((const char*)(gbase) + (voff)[_i]), (LAS unsigned*)(lds + (bufoff) + ldsw + _i * 8192), 16, 0, 0); } while (0)
; #define PG8_LDA(dst, b, h) do { _Pragma("unroll") for (int m = 0; m < 4; ++m) _Pragma("unroll") for (int k = 0; k < 2; ++k) dst[m][k] = *(const LAS bf16x8*)(lds + PG8_SA(b, h) + aoff + m * 2048 + k * 1024); } while (0)
; #define PG8_MMA(ai, bj, At, Bt) do { __builtin_amdgcn_s_setprio(1); _Pragma("unroll") for (int k = 0; k < 2; ++k) _Pragma("unroll") for (int m = 0; m < 4; ++m) _Pragma("unroll") for (int n = 0; n < 2; ++n) \
;         acc[ai][bj][m][n] = __builtin_amdgcn_mfma_f32_16x16x32_bf16(Bt[n][k], At[m][k], acc[ai][bj][m][n], 0, 0, 0); __builtin_amdgcn_s_setprio(0); } while (0)
; #define PG8_WAIT_V(n) asm volatile("s_waitcnt vmcnt(" #n ")" ::: "memory")
; #define PG8_WAIT_L(n) asm volatile("s_waitcnt lgkmcnt(" #n ")" ::: "memory")
; #define PG8_BAR __builtin_amdgcn_s_barrier()
; #define PG8_SCHED __builtin_amdgcn_sched_barrier(0)
; template <class Epi, bool ALIGN_EPI>
; __device__ __forceinline__ void gemm_phase(LAS unsigned char* lds, const Gemm g, const StaticOrder& S, const Epi& E, const int tid) {
;     ...
;             PG8_WAIT_V(8); PG8_WAIT_L(0); PG8_BAR; PG8_MMA(0, 0, At, B0); PG8_MMA(0, 1, At, B1); PG8_BAR; PG8_SCHED;
;             PG8_LDA(At, 1, 1); PG8_STAGE(PG8_SB(1, 0), b3, voffB); PG8_STAGE(PG8_SB(1, 1), b3 + hB, voffB); PG8_STAGE(PG8_SA(1, 0), a3, voffA);
;             PG8_WAIT_V(8); PG8_WAIT_L(0); PG8_BAR; PG8_MMA(1, 0, At, B0); PG8_MMA(1, 1, At, B1); PG8_BAR; PG8_SCHED;
;         }
	s_waitcnt lgkmcnt(0)
	v_mfma_f32_16x16x32_bf16 v[120:123], v[146:149], v[192:195], v[120:123]
	v_mfma_f32_16x16x32_bf16 v[112:115], v[158:161], v[192:195], v[112:115]
	v_mfma_f32_16x16x32_bf16 v[104:107], v[146:149], v[200:203], v[104:107]
	v_mfma_f32_16x16x32_bf16 v[96:99], v[158:161], v[200:203], v[96:99]
	v_mfma_f32_16x16x32_bf16 v[88:91], v[146:149], v[208:211], v[88:91]
	v_mfma_f32_16x16x32_bf16 v[80:83], v[158:161], v[208:211], v[80:83]
	v_mfma_f32_16x16x32_bf16 v[72:75], v[146:149], v[216:219], v[72:75]
	v_mfma_f32_16x16x32_bf16 v[64:67], v[158:161], v[216:219], v[64:67]
	v_mfma_f32_16x16x32_bf16 v[120:123], v[154:157], v[196:199], v[120:123]
	v_mfma_f32_16x16x32_bf16 v[112:115], v[162:165], v[196:199], v[112:115]
	v_mfma_f32_16x16x32_bf16 v[104:107], v[154:157], v[204:207], v[104:107]
	v_mfma_f32_16x16x32_bf16 v[96:99], v[162:165], v[204:207], v[96:99]
	v_mfma_f32_16x16x32_bf16 v[88:91], v[154:157], v[212:215], v[88:91]
	v_mfma_f32_16x16x32_bf16 v[80:83], v[162:165], v[212:215], v[80:83]
	v_mfma_f32_16x16x32_bf16 v[72:75], v[154:157], v[240:243], v[72:75]
	v_mfma_f32_16x16x32_bf16 v[64:67], v[162:165], v[240:243], v[64:67]
	s_setprio 0
	s_setprio 1
	v_mfma_f32_16x16x32_bf16 v[124:127], v[176:179], v[192:195], v[124:127]
	v_mfma_f32_16x16x32_bf16 v[116:119], v[184:187], v[192:195], v[116:119]
	v_mfma_f32_16x16x32_bf16 v[108:111], v[176:179], v[200:203], v[108:111]
	v_mfma_f32_16x16x32_bf16 v[100:103], v[184:187], v[200:203], v[100:103]
	v_mfma_f32_16x16x32_bf16 v[92:95], v[176:179], v[208:211], v[92:95]
	v_mfma_f32_16x16x32_bf16 v[84:87], v[184:187], v[208:211], v[84:87]
	v_mfma_f32_16x16x32_bf16 v[76:79], v[176:179], v[216:219], v[76:79]
	v_mfma_f32_16x16x32_bf16 v[68:71], v[184:187], v[216:219], v[68:71]
	v_mfma_f32_16x16x32_bf16 v[124:127], v[180:183], v[196:199], v[124:127]
	v_mfma_f32_16x16x32_bf16 v[116:119], v[188:191], v[196:199], v[116:119]
	v_mfma_f32_16x16x32_bf16 v[108:111], v[180:183], v[204:207], v[108:111]
	v_mfma_f32_16x16x32_bf16 v[100:103], v[188:191], v[204:207], v[100:103]
	v_mfma_f32_16x16x32_bf16 v[92:95], v[180:183], v[212:215], v[92:95]
	v_mfma_f32_16x16x32_bf16 v[84:87], v[188:191], v[212:215], v[84:87]
	v_mfma_f32_16x16x32_bf16 v[76:79], v[180:183], v[240:243], v[76:79]
	v_mfma_f32_16x16x32_bf16 v[68:71], v[188:191], v[240:243], v[68:71]
	s_barrier
	s_setprio 0
	s_add_i32 s10, s10, s45
	v_lshl_add_u64 v[166:167], v[226:227], 0, s[92:93]
	s_mov_b32 m0, s10
	ds_read_b128 v[192:195], v153 offset:49152
	ds_read_b128 v[196:199], v153 offset:50176
	ds_read_b128 v[200:203], v153 offset:51200
	ds_read_b128 v[204:207], v153 offset:52224
	ds_read_b128 v[208:211], v153 offset:53248
	ds_read_b128 v[212:215], v153 offset:54272
	ds_read_b128 v[216:219], v153 offset:55296
	ds_read_b128 v[240:243], v153 offset:56320
	global_load_lds_dwordx4 v[166:167], off
	v_lshl_add_u64 v[166:167], v[244:245], 0, s[92:93]
	s_add_i32 m0, s10, 0x2000
	s_add_i32 s10, s65, s45
	global_load_lds_dwordx4 v[166:167], off
	v_lshl_add_u64 v[166:167], v[246:247], 0, s[92:93]
	s_mov_b32 m0, s10
	s_nop 0
	global_load_lds_dwordx4 v[166:167], off
	v_lshl_add_u64 v[166:167], v[220:221], 0, s[92:93]
	s_add_i32 m0, s10, 0x2000
	s_nop 0
	global_load_lds_dwordx4 v[166:167], off
	v_lshl_add_u64 v[166:167], v[248:249], 0, s[92:93]
	s_mov_b32 m0, s56
	s_nop 0
	global_load_lds_dwordx4 v[166:167], off
	v_lshl_add_u64 v[166:167], v[250:251], 0, s[92:93]
	s_mov_b32 m0, s57
	s_nop 0
	global_load_lds_dwordx4 v[166:167], off
	s_waitcnt vmcnt(8)
	s_waitcnt lgkmcnt(0)
	s_setprio 1
	s_barrier
	s_waitcnt lgkmcnt(0)
	v_mfma_f32_16x16x32_bf16 v[56:59], v[146:149], v[192:195], v[56:59]
	v_mfma_f32_16x16x32_bf16 v[48:51], v[158:161], v[192:195], v[48:51]
	v_mfma_f32_16x16x32_bf16 v[40:43], v[146:149], v[200:203], v[40:43]
	v_mfma_f32_16x16x32_bf16 v[32:35], v[158:161], v[200:203], v[32:35]
	v_mfma_f32_16x16x32_bf16 v[24:27], v[146:149], v[208:211], v[24:27]
	v_mfma_f32_16x16x32_bf16 v[16:19], v[158:161], v[208:211], v[16:19]
	v_mfma_f32_16x16x32_bf16 v[8:11], v[146:149], v[216:219], v[8:11]
	v_mfma_f32_16x16x32_bf16 v[4:7], v[158:161], v[216:219], v[4:7]
	v_mfma_f32_16x16x32_bf16 v[56:59], v[154:157], v[196:199], v[56:59]
	v_mfma_f32_16x16x32_bf16 v[48:51], v[162:165], v[196:199], v[48:51]
	v_mfma_f32_16x16x32_bf16 v[40:43], v[154:157], v[204:207], v[40:43]
	v_mfma_f32_16x16x32_bf16 v[32:35], v[162:165], v[204:207], v[32:35]
	v_mfma_f32_16x16x32_bf16 v[24:27], v[154:157], v[212:215], v[24:27]
	v_mfma_f32_16x16x32_bf16 v[16:19], v[162:165], v[212:215], v[16:19]
	v_mfma_f32_16x16x32_bf16 v[8:11], v[154:157], v[240:243], v[8:11]
	v_mfma_f32_16x16x32_bf16 v[4:7], v[162:165], v[240:243], v[4:7]
	s_setprio 0
	s_setprio 1
	v_mfma_f32_16x16x32_bf16 v[60:63], v[176:179], v[192:195], v[60:63]
	v_mfma_f32_16x16x32_bf16 v[52:55], v[184:187], v[192:195], v[52:55]
	v_mfma_f32_16x16x32_bf16 v[44:47], v[176:179], v[200:203], v[44:47]
	v_mfma_f32_16x16x32_bf16 v[36:39], v[184:187], v[200:203], v[36:39]
	v_mfma_f32_16x16x32_bf16 v[28:31], v[176:179], v[208:211], v[28:31]
	v_mfma_f32_16x16x32_bf16 v[20:23], v[184:187], v[208:211], v[20:23]
	v_mfma_f32_16x16x32_bf16 v[12:15], v[176:179], v[216:219], v[12:15]
	v_mfma_f32_16x16x32_bf16 v[0:3], v[184:187], v[216:219], v[0:3]
	v_mfma_f32_16x16x32_bf16 v[60:63], v[180:183], v[196:199], v[60:63]
	v_mfma_f32_16x16x32_bf16 v[52:55], v[188:191], v[196:199], v[52:55]
	v_mfma_f32_16x16x32_bf16 v[44:47], v[180:183], v[204:207], v[44:47]
	v_mfma_f32_16x16x32_bf16 v[36:39], v[188:191], v[204:207], v[36:39]
	v_mfma_f32_16x16x32_bf16 v[28:31], v[180:183], v[212:215], v[28:31]
	v_mfma_f32_16x16x32_bf16 v[20:23], v[188:191], v[212:215], v[20:23]
	v_mfma_f32_16x16x32_bf16 v[12:15], v[180:183], v[240:243], v[12:15]
	v_mfma_f32_16x16x32_bf16 v[0:3], v[188:191], v[240:243], v[0:3]
	s_barrier
	s_setprio 0
	v_lshl_add_u64 v[142:143], v[142:143], 0, s[80:81]
	v_lshl_add_u64 v[144:145], v[144:145], 0, s[80:81]
	s_mov_b32 s10, s11
	s_cmp_eq_u32 s10, s58
	s_cbranch_scc1 .Lgu_last
	s_branch .LBB0_308
; #define PG8_STAGE(bufoff, gbase, voff) do { _Pragma("unroll") for (int _i = 0; _i < 2; ++_i) \
;         __builtin_amdgcn_global_load_lds((const unsigned*)((const char*)(gbase) + (voff)[_i]), (LAS unsigned*)(lds + (bufoff) + ldsw + _i * 8192), 16, 0, 0); } while (0)
; #define PG8_LDA(dst, b, h) do { _Pragma("unroll") for (int m = 0; m < 4; ++m) _Pragma("unroll") for (int k = 0; k < 2; ++k) dst[m][k] = *(const LAS bf16x8*)(lds + PG8_SA(b, h) + aoff + m * 2048 + k * 1024); } while (0)
; #define PG8_LDB(dst, b, h) do { _Pragma("unroll") for (int n = 0; n < 2; ++n) _Pragma("unroll") for (int k = 0; k < 2; ++k) dst[n][k] = *(const LAS bf16x8*)(lds + PG8_SB(b, h) + boff + n * 2048 + k * 1024); } while (0)
; #define PG8_MMA(ai, bj, At, Bt) do { __builtin_amdgcn_s_setprio(1); _Pragma("unroll") for (int k = 0; k < 2; ++k) _Pragma("unroll") for (int m = 0; m < 4; ++m) _Pragma("unroll") for (int n = 0; n < 2; ++n) \
;         acc[ai][bj][m][n] = __builtin_amdgcn_mfma_f32_16x16x32_bf16(Bt[n][k], At[m][k], acc[ai][bj][m][n], 0, 0, 0); __builtin_amdgcn_s_setprio(0); } while (0)
; #define PG8_WAIT_V(n) asm volatile("s_waitcnt vmcnt(" #n ")" ::: "memory")
; #define PG8_WAIT_L(n) asm volatile("s_waitcnt lgkmcnt(" #n ")" ::: "memory")
; #define PG8_BAR __builtin_amdgcn_s_barrier()
; #define PG8_SCHED __builtin_amdgcn_sched_barrier(0)
; template <class Epi, bool ALIGN_EPI>
; __device__ __forceinline__ void gemm_phase(LAS unsigned char* lds, const Gemm g, const StaticOrder& S, const Epi& E, const int tid) {
;     ...
;             PG8_LDB(B0, 0, 0); PG8_LDB(B1, 0, 1); PG8_SCHED; PG8_LDA(At, 0, 0); PG8_STAGE(PG8_SA(1, 1), a1 + hA, voffA);
;             PG8_WAIT_V(8); PG8_WAIT_L(0); PG8_BAR; PG8_MMA(0, 0, At, B0); PG8_MMA(0, 1, At, B1); PG8_BAR; PG8_SCHED;
;             PG8_LDA(At, 0, 1); PG8_STAGE(PG8_SB(0, 0), b2, voffB); PG8_STAGE(PG8_SB(0, 1), b2 + hB, voffB); PG8_STAGE(PG8_SA(0, 0), a2, voffA);
;             PG8_WAIT_V(8); PG8_WAIT_L(0); PG8_BAR; PG8_MMA(1, 0, At, B0); PG8_MMA(1, 1, At, B1); PG8_BAR; PG8_SCHED;
.Lgu_first:
	s_add_i32 s11, s10, 2
	s_cmp_eq_u32 s58, s10
	v_lshl_add_u64 v[146:147], v[142:143], 0, s[92:93]
	s_cselect_b64 vcc, -1, 0
	v_add_u32_e32 v150, s33, v151
	s_add_i32 s10, 0, 0x14000
	v_cndmask_b32_e32 v167, v147, v139, vcc
	v_cndmask_b32_e32 v166, v146, v138, vcc
	ds_read_b128 v[146:149], v150
	ds_read_b128 v[154:157], v150 offset:1024
	ds_read_b128 v[158:161], v150 offset:2048
	ds_read_b128 v[162:165], v150 offset:3072
	v_add_u32_e32 v150, s10, v151
	ds_read_b128 v[176:179], v150
	ds_read_b128 v[180:183], v150 offset:1024
	ds_read_b128 v[184:187], v150 offset:2048
	ds_read_b128 v[188:191], v150 offset:3072
	v_cndmask_b32_e32 v221, v145, v141, vcc
	v_cndmask_b32_e32 v220, v144, v140, vcc
	v_lshl_add_u64 v[226:227], v[142:143], 0, v[134:135]
	s_add_i32 m0, s51, 0xc000
	ds_read_b128 v[192:195], v153
	ds_read_b128 v[196:199], v153 offset:1024
	ds_read_b128 v[200:203], v153 offset:2048
	ds_read_b128 v[204:207], v153 offset:3072
	ds_read_b128 v[208:211], v153 offset:4096
	ds_read_b128 v[212:215], v153 offset:5120
	ds_read_b128 v[216:219], v153 offset:6144
	ds_read_b128 v[240:243], v153 offset:7168
	global_load_lds_dwordx4 v[226:227], off
	v_lshl_add_u64 v[226:227], v[142:143], 0, v[136:137]
	s_add_i32 m0, s51, 0xe000
	s_nop 0
	global_load_lds_dwordx4 v[226:227], off
	s_waitcnt vmcnt(8)
	s_waitcnt lgkmcnt(0)
	s_setprio 1
	s_barrier
	s_waitcnt lgkmcnt(0)
	v_mfma_f32_16x16x32_bf16 v[120:123], v[146:149], v[192:195], 0
	v_mfma_f32_16x16x32_bf16 v[112:115], v[158:161], v[192:195], 0
	v_mfma_f32_16x16x32_bf16 v[104:107], v[146:149], v[200:203], 0
	v_mfma_f32_16x16x32_bf16 v[96:99], v[158:161], v[200:203], 0
	v_mfma_f32_16x16x32_bf16 v[88:91], v[146:149], v[208:211], 0
	v_mfma_f32_16x16x32_bf16 v[80:83], v[158:161], v[208:211], 0
	v_mfma_f32_16x16x32_bf16 v[72:75], v[146:149], v[216:219], 0
	v_mfma_f32_16x16x32_bf16 v[64:67], v[158:161], v[216:219], 0
	v_mfma_f32_16x16x32_bf16 v[120:123], v[154:157], v[196:199], v[120:123]
	v_mfma_f32_16x16x32_bf16 v[112:115], v[162:165], v[196:199], v[112:115]
	v_mfma_f32_16x16x32_bf16 v[104:107], v[154:157], v[204:207], v[104:107]
	v_mfma_f32_16x16x32_bf16 v[96:99], v[162:165], v[204:207], v[96:99]
	v_mfma_f32_16x16x32_bf16 v[88:91], v[154:157], v[212:215], v[88:91]
	v_mfma_f32_16x16x32_bf16 v[80:83], v[162:165], v[212:215], v[80:83]
	v_mfma_f32_16x16x32_bf16 v[72:75], v[154:157], v[240:243], v[72:75]
	v_mfma_f32_16x16x32_bf16 v[64:67], v[162:165], v[240:243], v[64:67]
	s_setprio 0
	s_setprio 1
	v_mfma_f32_16x16x32_bf16 v[124:127], v[176:179], v[192:195], 0
	v_mfma_f32_16x16x32_bf16 v[116:119], v[184:187], v[192:195], 0
	v_mfma_f32_16x16x32_bf16 v[108:111], v[176:179], v[200:203], 0
	v_mfma_f32_16x16x32_bf16 v[100:103], v[184:187], v[200:203], 0
	v_mfma_f32_16x16x32_bf16 v[92:95], v[176:179], v[208:211], 0
	v_mfma_f32_16x16x32_bf16 v[84:87], v[184:187], v[208:211], 0
	v_mfma_f32_16x16x32_bf16 v[76:79], v[176:179], v[216:219], 0
	v_mfma_f32_16x16x32_bf16 v[68:71], v[184:187], v[216:219], 0
	v_mfma_f32_16x16x32_bf16 v[124:127], v[180:183], v[196:199], v[124:127]
	v_mfma_f32_16x16x32_bf16 v[116:119], v[188:191], v[196:199], v[116:119]
	v_mfma_f32_16x16x32_bf16 v[108:111], v[180:183], v[204:207], v[108:111]
	v_mfma_f32_16x16x32_bf16 v[100:103], v[188:191], v[204:207], v[100:103]
	v_mfma_f32_16x16x32_bf16 v[92:95], v[180:183], v[212:215], v[92:95]
	v_mfma_f32_16x16x32_bf16 v[84:87], v[188:191], v[212:215], v[84:87]
	v_mfma_f32_16x16x32_bf16 v[76:79], v[180:183], v[240:243], v[76:79]
	v_mfma_f32_16x16x32_bf16 v[68:71], v[188:191], v[240:243], v[68:71]
	s_barrier
	s_setprio 0
	s_add_i32 s65, s33, s45
	v_lshl_add_u64 v[226:227], v[220:221], 0, v[168:169]
	s_mov_b32 m0, s65
	ds_read_b128 v[192:195], v153 offset:16384
	ds_read_b128 v[196:199], v153 offset:17408
	ds_read_b128 v[200:203], v153 offset:18432
	ds_read_b128 v[204:207], v153 offset:19456
	ds_read_b128 v[208:211], v153 offset:20480
	ds_read_b128 v[212:215], v153 offset:21504
	ds_read_b128 v[216:219], v153 offset:22528
	ds_read_b128 v[240:243], v153 offset:23552
	global_load_lds_dwordx4 v[226:227], off
	v_lshl_add_u64 v[244:245], v[220:221], 0, v[128:129]
	s_add_i32 m0, s65, 0x2000
	v_lshl_add_u64 v[220:221], v[220:221], 0, s[12:13]
	s_add_i32 s10, s10, s45
	global_load_lds_dwordx4 v[244:245], off
	v_lshl_add_u64 v[246:247], v[220:221], 0, v[168:169]
	s_mov_b32 m0, s10
	v_lshl_add_u64 v[220:221], v[220:221], 0, v[128:129]
	global_load_lds_dwordx4 v[246:247], off
	s_add_i32 m0, s10, 0x2000
	v_lshl_add_u64 v[248:249], v[166:167], 0, v[132:133]
	global_load_lds_dwordx4 v[220:221], off
	s_mov_b32 m0, s51
	v_lshl_add_u64 v[250:251], v[166:167], 0, v[130:131]
	global_load_lds_dwordx4 v[248:249], off
	s_mov_b32 m0, s52
	s_nop 0
	global_load_lds_dwordx4 v[250:251], off
	s_waitcnt vmcnt(8)
	s_waitcnt lgkmcnt(0)
	s_setprio 1
	s_barrier
; #define PG8_STAGE(bufoff, gbase, voff) do { _Pragma("unroll") for (int _i = 0; _i < 2; ++_i) \
;         __builtin_amdgcn_global_load_lds((const unsigned*)((const char*)(gbase) + (voff)[_i]), (LAS unsigned*)(lds + (bufoff) + ldsw + _i * 8192), 16, 0, 0); } while (0)
; #define PG8_LDA(dst, b, h) do { _Pragma("unroll") for (int m = 0; m < 4; ++m) _Pragma("unroll") for (int k = 0; k < 2; ++k) dst[m][k] = *(const LAS bf16x8*)(lds + PG8_SA(b, h) + aoff + m * 2048 + k * 1024); } while (0)
; #define PG8_LDB(dst, b, h) do { _Pragma("unroll") for (int n = 0; n < 2; ++n) _Pragma("unroll") for (int k = 0; k < 2; ++k) dst[n][k] = *(const LAS bf16x8*)(lds + PG8_SB(b, h) + boff + n * 2048 + k * 1024); } while (0)
; #define PG8_MMA(ai, bj, At, Bt) do { __builtin_amdgcn_s_setprio(1); _Pragma("unroll") for (int k = 0; k < 2; ++k) _Pragma("unroll") for (int m = 0; m < 4; ++m) _Pragma("unroll") for (int n = 0; n < 2; ++n) \
;         acc[ai][bj][m][n] = __builtin_amdgcn_mfma_f32_16x16x32_bf16(Bt[n][k], At[m][k], acc[ai][bj][m][n], 0, 0, 0); __builtin_amdgcn_s_setprio(0); } while (0)
; #define PG8_WAIT_V(n) asm volatile("s_waitcnt vmcnt(" #n ")" ::: "memory")
; #define PG8_WAIT_L(n) asm volatile("s_waitcnt lgkmcnt(" #n ")" ::: "memory")
; #define PG8_BAR __builtin_amdgcn_s_barrier()
; #define PG8_SCHED __builtin_amdgcn_sched_barrier(0)
; template <class Epi, bool ALIGN_EPI>
; __device__ __forceinline__ void gemm_phase(LAS unsigned char* lds, const Gemm g, const StaticOrder& S, const Epi& E, const int tid) {
;     ...
;             PG8_WAIT_V(8); PG8_WAIT_L(0); PG8_BAR; PG8_MMA(1, 0, At, B0); PG8_MMA(1, 1, At, B1); PG8_BAR; PG8_SCHED;
;             PG8_LDB(B0, 1, 0); PG8_LDB(B1, 1, 1); PG8_SCHED; PG8_LDA(At, 1, 0); PG8_STAGE(PG8_SA(0, 1), a2 + hA, voffA);
;             PG8_WAIT_V(8); PG8_WAIT_L(0); PG8_BAR; PG8_MMA(0, 0, At, B0); PG8_MMA(0, 1, At, B1); PG8_BAR; PG8_SCHED;
	s_waitcnt lgkmcnt(0)
	v_mfma_f32_16x16x32_bf16 v[56:59], v[146:149], v[192:195], 0
	v_mfma_f32_16x16x32_bf16 v[48:51], v[158:161], v[192:195], 0
	v_mfma_f32_16x16x32_bf16 v[40:43], v[146:149], v[200:203], 0
	v_mfma_f32_16x16x32_bf16 v[32:35], v[158:161], v[200:203], 0
	v_mfma_f32_16x16x32_bf16 v[24:27], v[146:149], v[208:211], 0
	v_mfma_f32_16x16x32_bf16 v[16:19], v[158:161], v[208:211], 0
	v_mfma_f32_16x16x32_bf16 v[8:11], v[146:149], v[216:219], 0
	v_mfma_f32_16x16x32_bf16 v[4:7], v[158:161], v[216:219], 0
	v_mfma_f32_16x16x32_bf16 v[56:59], v[154:157], v[196:199], v[56:59]
	v_mfma_f32_16x16x32_bf16 v[48:51], v[162:165], v[196:199], v[48:51]
	v_mfma_f32_16x16x32_bf16 v[40:43], v[154:157], v[204:207], v[40:43]
	v_mfma_f32_16x16x32_bf16 v[32:35], v[162:165], v[204:207], v[32:35]
	v_mfma_f32_16x16x32_bf16 v[24:27], v[154:157], v[212:215], v[24:27]
	v_mfma_f32_16x16x32_bf16 v[16:19], v[162:165], v[212:215], v[16:19]
	v_mfma_f32_16x16x32_bf16 v[8:11], v[154:157], v[240:243], v[8:11]
	v_mfma_f32_16x16x32_bf16 v[4:7], v[162:165], v[240:243], v[4:7]
	s_setprio 0
	s_setprio 1
	v_mfma_f32_16x16x32_bf16 v[60:63], v[176:179], v[192:195], 0
	v_mfma_f32_16x16x32_bf16 v[52:55], v[184:187], v[192:195], 0
	v_mfma_f32_16x16x32_bf16 v[44:47], v[176:179], v[200:203], 0
	v_mfma_f32_16x16x32_bf16 v[36:39], v[184:187], v[200:203], 0
	v_mfma_f32_16x16x32_bf16 v[28:31], v[176:179], v[208:211], 0
	v_mfma_f32_16x16x32_bf16 v[20:23], v[184:187], v[208:211], 0
	v_mfma_f32_16x16x32_bf16 v[12:15], v[176:179], v[216:219], 0
	v_mfma_f32_16x16x32_bf16 v[0:3], v[184:187], v[216:219], 0
	v_mfma_f32_16x16x32_bf16 v[60:63], v[180:183], v[196:199], v[60:63]
	v_mfma_f32_16x16x32_bf16 v[52:55], v[188:191], v[196:199], v[52:55]
	v_mfma_f32_16x16x32_bf16 v[44:47], v[180:183], v[204:207], v[44:47]
	v_mfma_f32_16x16x32_bf16 v[36:39], v[188:191], v[204:207], v[36:39]
	v_mfma_f32_16x16x32_bf16 v[28:31], v[180:183], v[212:215], v[28:31]
	v_mfma_f32_16x16x32_bf16 v[20:23], v[188:191], v[212:215], v[20:23]
	v_mfma_f32_16x16x32_bf16 v[12:15], v[180:183], v[240:243], v[12:15]
	v_mfma_f32_16x16x32_bf16 v[0:3], v[188:191], v[240:243], v[0:3]
	s_barrier
	s_setprio 0
	s_add_i32 s10, 0, 0x18000
	v_add_u32_e32 v150, s10, v151
	s_add_i32 s65, 0, 0x1c000
	ds_read_b128 v[146:149], v150
	ds_read_b128 v[154:157], v150 offset:1024
	ds_read_b128 v[158:161], v150 offset:2048
	ds_read_b128 v[162:165], v150 offset:3072
	v_add_u32_e32 v150, s65, v151
	ds_read_b128 v[176:179], v150
	ds_read_b128 v[180:183], v150 offset:1024
	ds_read_b128 v[184:187], v150 offset:2048
	ds_read_b128 v[188:191], v150 offset:3072
	v_lshl_add_u64 v[166:167], v[166:167], 0, s[94:95]
	s_mov_b32 m0, s53
	v_lshl_add_u64 v[252:253], v[166:167], 0, v[132:133]
	ds_read_b128 v[192:195], v153 offset:32768
	ds_read_b128 v[196:199], v153 offset:33792
	ds_read_b128 v[200:203], v153 offset:34816
	ds_read_b128 v[204:207], v153 offset:35840
	ds_read_b128 v[208:211], v153 offset:36864
	ds_read_b128 v[212:215], v153 offset:37888
	ds_read_b128 v[216:219], v153 offset:38912
	ds_read_b128 v[240:243], v153 offset:39936
	global_load_lds_dwordx4 v[252:253], off
	v_lshl_add_u64 v[166:167], v[166:167], 0, v[130:131]
	s_mov_b32 m0, s54
	s_nop 0
	global_load_lds_dwordx4 v[166:167], off
	s_waitcnt vmcnt(8)
	s_waitcnt lgkmcnt(0)
	s_setprio 1
	s_barrier
	s_waitcnt lgkmcnt(0)
	v_mfma_f32_16x16x32_bf16 v[120:123], v[146:149], v[192:195], v[120:123]
	v_mfma_f32_16x16x32_bf16 v[112:115], v[158:161], v[192:195], v[112:115]
	v_mfma_f32_16x16x32_bf16 v[104:107], v[146:149], v[200:203], v[104:107]
	v_mfma_f32_16x16x32_bf16 v[96:99], v[158:161], v[200:203], v[96:99]
	v_mfma_f32_16x16x32_bf16 v[88:91], v[146:149], v[208:211], v[88:91]
	v_mfma_f32_16x16x32_bf16 v[80:83], v[158:161], v[208:211], v[80:83]
	v_mfma_f32_16x16x32_bf16 v[72:75], v[146:149], v[216:219], v[72:75]
	v_mfma_f32_16x16x32_bf16 v[64:67], v[158:161], v[216:219], v[64:67]
	v_mfma_f32_16x16x32_bf16 v[120:123], v[154:157], v[196:199], v[120:123]
	v_mfma_f32_16x16x32_bf16 v[112:115], v[162:165], v[196:199], v[112:115]
	v_mfma_f32_16x16x32_bf16 v[104:107], v[154:157], v[204:207], v[104:107]
	v_mfma_f32_16x16x32_bf16 v[96:99], v[162:165], v[204:207], v[96:99]
	v_mfma_f32_16x16x32_bf16 v[88:91], v[154:157], v[212:215], v[88:91]
	v_mfma_f32_16x16x32_bf16 v[80:83], v[162:165], v[212:215], v[80:83]
	v_mfma_f32_16x16x32_bf16 v[72:75], v[154:157], v[240:243], v[72:75]
	v_mfma_f32_16x16x32_bf16 v[64:67], v[162:165], v[240:243], v[64:67]
	s_setprio 0
	s_setprio 1
	v_mfma_f32_16x16x32_bf16 v[124:127], v[176:179], v[192:195], v[124:127]
	v_mfma_f32_16x16x32_bf16 v[116:119], v[184:187], v[192:195], v[116:119]
	v_mfma_f32_16x16x32_bf16 v[108:111], v[176:179], v[200:203], v[108:111]
	v_mfma_f32_16x16x32_bf16 v[100:103], v[184:187], v[200:203], v[100:103]
	v_mfma_f32_16x16x32_bf16 v[92:95], v[176:179], v[208:211], v[92:95]
	v_mfma_f32_16x16x32_bf16 v[84:87], v[184:187], v[208:211], v[84:87]
	v_mfma_f32_16x16x32_bf16 v[76:79], v[176:179], v[216:219], v[76:79]
	v_mfma_f32_16x16x32_bf16 v[68:71], v[184:187], v[216:219], v[68:71]
	v_mfma_f32_16x16x32_bf16 v[124:127], v[180:183], v[196:199], v[124:127]
	v_mfma_f32_16x16x32_bf16 v[116:119], v[188:191], v[196:199], v[116:119]
	v_mfma_f32_16x16x32_bf16 v[108:111], v[180:183], v[204:207], v[108:111]
	v_mfma_f32_16x16x32_bf16 v[100:103], v[188:191], v[204:207], v[100:103]
	v_mfma_f32_16x16x32_bf16 v[92:95], v[180:183], v[212:215], v[92:95]
	v_mfma_f32_16x16x32_bf16 v[84:87], v[188:191], v[212:215], v[84:87]
	v_mfma_f32_16x16x32_bf16 v[76:79], v[180:183], v[240:243], v[76:79]
	v_mfma_f32_16x16x32_bf16 v[68:71], v[188:191], v[240:243], v[68:71]
	s_barrier
; #define PG8_STAGE(bufoff, gbase, voff) do { _Pragma("unroll") for (int _i = 0; _i < 2; ++_i) \
;         __builtin_amdgcn_global_load_lds((const unsigned*)((const char*)(gbase) + (voff)[_i]), (LAS unsigned*)(lds + (bufoff) + ldsw + _i * 8192), 16, 0, 0); } while (0)
; #define PG8_LDA(dst, b, h) do { _Pragma("unroll") for (int m = 0; m < 4; ++m) _Pragma("unroll") for (int k = 0; k < 2; ++k) dst[m][k] = *(const LAS bf16x8*)(lds + PG8_SA(b, h) + aoff + m * 2048 + k * 1024); } while (0)
; #define PG8_LDB(dst, b, h) do { _Pragma("unroll") for (int n = 0; n < 2; ++n) _Pragma("unroll") for (int k = 0; k < 2; ++k) dst[n][k] = *(const LAS bf16x8*)(lds + PG8_SB(b, h) + boff + n * 2048 + k * 1024); } while (0)
; #define PG8_MMA(ai, bj, At, Bt) do { __builtin_amdgcn_s_setprio(1); _Pragma("unroll") for (int k = 0; k < 2; ++k) _Pragma("unroll") for (int m = 0; m < 4; ++m) _Pragma("unroll") for (int n = 0; n < 2; ++n) \
;         acc[ai][bj][m][n] = __builtin_amdgcn_mfma_f32_16x16x32_bf16(Bt[n][k], At[m][k], acc[ai][bj][m][n], 0, 0, 0); __builtin_amdgcn_s_setprio(0); } while (0)
; #define PG8_WAIT_V(n) asm volatile("s_waitcnt vmcnt(" #n ")" ::: "memory")
; #define PG8_BAR __builtin_amdgcn_s_barrier()
; template <class Epi, bool ALIGN_EPI>
; __device__ __forceinline__ void gemm_phase(LAS unsigned char* lds, const Gemm g, const StaticOrder& S, const Epi& E, const int tid) {
;     ...
;             PG8_LDB(B0, 0, 0); PG8_LDB(B1, 0, 1); PG8_SCHED; PG8_LDA(At, 0, 0); PG8_STAGE(PG8_SA(1, 1), a1 + hA, voffA);
;             PG8_WAIT_V(8); PG8_WAIT_L(0); PG8_BAR; PG8_MMA(0, 0, At, B0); PG8_MMA(0, 1, At, B1); PG8_BAR; PG8_SCHED;
;             PG8_LDA(At, 0, 1); PG8_STAGE(PG8_SB(0, 0), b2, voffB); PG8_STAGE(PG8_SB(0, 1), b2 + hB, voffB); PG8_STAGE(PG8_SA(0, 0), a2, voffA);
;             PG8_WAIT_V(8); PG8_WAIT_L(0); PG8_BAR; PG8_MMA(1, 0, At, B0); PG8_MMA(1, 1, At, B1); PG8_BAR; PG8_SCHED;
;             PG8_LDB(B0, 1, 0); PG8_LDB(B1, 1, 1); PG8_SCHED; PG8_LDA(At, 1, 0); PG8_STAGE(PG8_SA(0, 1), a2 + hA, voffA);
;             PG8_WAIT_V(8); PG8_WAIT_L(0); PG8_BAR; PG8_MMA(0, 0, At, B0); PG8_MMA(0, 1, At, B1); PG8_BAR; PG8_SCHED;
;             PG8_LDA(At, 1, 1); PG8_STAGE(PG8_SB(1, 0), b3, voffB); PG8_STAGE(PG8_SB(1, 1), b3 + hB, voffB); PG8_STAGE(PG8_SA(1, 0), a3, voffA);
;             PG8_WAIT_V(8); PG8_WAIT_L(0); PG8_BAR; PG8_MMA(1, 0, At, B0); PG8_MMA(1, 1, At, B1); PG8_BAR; PG8_SCHED;
	s_setprio 0
	s_add_i32 s10, s10, s45
	v_lshl_add_u64 v[166:167], v[226:227], 0, s[92:93]
	s_mov_b32 m0, s10
	ds_read_b128 v[192:195], v153 offset:49152
	ds_read_b128 v[196:199], v153 offset:50176
	ds_read_b128 v[200:203], v153 offset:51200
	ds_read_b128 v[204:207], v153 offset:52224
	ds_read_b128 v[208:211], v153 offset:53248
	ds_read_b128 v[212:215], v153 offset:54272
	ds_read_b128 v[216:219], v153 offset:55296
	ds_read_b128 v[240:243], v153 offset:56320
	global_load_lds_dwordx4 v[166:167], off
	v_lshl_add_u64 v[166:167], v[244:245], 0, s[92:93]
	s_add_i32 m0, s10, 0x2000
	s_add_i32 s10, s65, s45
	global_load_lds_dwordx4 v[166:167], off
	v_lshl_add_u64 v[166:167], v[246:247], 0, s[92:93]
	s_mov_b32 m0, s10
	s_nop 0
	global_load_lds_dwordx4 v[166:167], off
	v_lshl_add_u64 v[166:167], v[220:221], 0, s[92:93]
	s_add_i32 m0, s10, 0x2000
	s_nop 0
	global_load_lds_dwordx4 v[166:167], off
	v_lshl_add_u64 v[166:167], v[248:249], 0, s[92:93]
	s_mov_b32 m0, s56
	s_nop 0
	global_load_lds_dwordx4 v[166:167], off
	v_lshl_add_u64 v[166:167], v[250:251], 0, s[92:93]
	s_mov_b32 m0, s57
	s_nop 0
	global_load_lds_dwordx4 v[166:167], off
	s_waitcnt vmcnt(8)
	s_waitcnt lgkmcnt(0)
	s_setprio 1
	s_barrier
	s_waitcnt lgkmcnt(0)
	v_mfma_f32_16x16x32_bf16 v[56:59], v[146:149], v[192:195], v[56:59]
	v_mfma_f32_16x16x32_bf16 v[48:51], v[158:161], v[192:195], v[48:51]
	v_mfma_f32_16x16x32_bf16 v[40:43], v[146:149], v[200:203], v[40:43]
	v_mfma_f32_16x16x32_bf16 v[32:35], v[158:161], v[200:203], v[32:35]
	v_mfma_f32_16x16x32_bf16 v[24:27], v[146:149], v[208:211], v[24:27]
	v_mfma_f32_16x16x32_bf16 v[16:19], v[158:161], v[208:211], v[16:19]
	v_mfma_f32_16x16x32_bf16 v[8:11], v[146:149], v[216:219], v[8:11]
	v_mfma_f32_16x16x32_bf16 v[4:7], v[158:161], v[216:219], v[4:7]
	v_mfma_f32_16x16x32_bf16 v[56:59], v[154:157], v[196:199], v[56:59]
	v_mfma_f32_16x16x32_bf16 v[48:51], v[162:165], v[196:199], v[48:51]
	v_mfma_f32_16x16x32_bf16 v[40:43], v[154:157], v[204:207], v[40:43]
	v_mfma_f32_16x16x32_bf16 v[32:35], v[162:165], v[204:207], v[32:35]
	v_mfma_f32_16x16x32_bf16 v[24:27], v[154:157], v[212:215], v[24:27]
	v_mfma_f32_16x16x32_bf16 v[16:19], v[162:165], v[212:215], v[16:19]
	v_mfma_f32_16x16x32_bf16 v[8:11], v[154:157], v[240:243], v[8:11]
	v_mfma_f32_16x16x32_bf16 v[4:7], v[162:165], v[240:243], v[4:7]
	s_setprio 0
	s_setprio 1
	v_mfma_f32_16x16x32_bf16 v[60:63], v[176:179], v[192:195], v[60:63]
	v_mfma_f32_16x16x32_bf16 v[52:55], v[184:187], v[192:195], v[52:55]
	v_mfma_f32_16x16x32_bf16 v[44:47], v[176:179], v[200:203], v[44:47]
	v_mfma_f32_16x16x32_bf16 v[36:39], v[184:187], v[200:203], v[36:39]
	v_mfma_f32_16x16x32_bf16 v[28:31], v[176:179], v[208:211], v[28:31]
	v_mfma_f32_16x16x32_bf16 v[20:23], v[184:187], v[208:211], v[20:23]
	v_mfma_f32_16x16x32_bf16 v[12:15], v[176:179], v[216:219], v[12:15]
	v_mfma_f32_16x16x32_bf16 v[0:3], v[184:187], v[216:219], v[0:3]
	v_mfma_f32_16x16x32_bf16 v[60:63], v[180:183], v[196:199], v[60:63]
	v_mfma_f32_16x16x32_bf16 v[52:55], v[188:191], v[196:199], v[52:55]
	v_mfma_f32_16x16x32_bf16 v[44:47], v[180:183], v[204:207], v[44:47]
	v_mfma_f32_16x16x32_bf16 v[36:39], v[188:191], v[204:207], v[36:39]
	v_mfma_f32_16x16x32_bf16 v[28:31], v[180:183], v[212:215], v[28:31]
	v_mfma_f32_16x16x32_bf16 v[20:23], v[188:191], v[212:215], v[20:23]
	v_mfma_f32_16x16x32_bf16 v[12:15], v[180:183], v[240:243], v[12:15]
	v_mfma_f32_16x16x32_bf16 v[0:3], v[188:191], v[240:243], v[0:3]
	s_barrier
	s_setprio 0
	v_lshl_add_u64 v[142:143], v[142:143], 0, s[80:81]
	v_lshl_add_u64 v[144:145], v[144:145], 0, s[80:81]
	s_mov_b32 s10, s11
	s_cmp_eq_u32 s10, s58
	s_cbranch_scc1 .Lgu_last
.LBB0_308:
	s_add_i32 s11, s10, 2
	s_cmp_eq_u32 s58, s10
	v_lshl_add_u64 v[146:147], v[142:143], 0, s[92:93]
	s_cselect_b64 vcc, -1, 0
	v_add_u32_e32 v150, s33, v151
	s_add_i32 s10, 0, 0x14000
	v_cndmask_b32_e32 v167, v147, v139, vcc
	v_cndmask_b32_e32 v166, v146, v138, vcc
	ds_read_b128 v[146:149], v150
	ds_read_b128 v[154:157], v150 offset:1024
	ds_read_b128 v[158:161], v150 offset:2048
	ds_read_b128 v[162:165], v150 offset:3072
	v_add_u32_e32 v150, s10, v151
	ds_read_b128 v[176:179], v150
	ds_read_b128 v[180:183], v150 offset:1024
	ds_read_b128 v[184:187], v150 offset:2048
	ds_read_b128 v[188:191], v150 offset:3072
	v_cndmask_b32_e32 v221, v145, v141, vcc
	v_cndmask_b32_e32 v220, v144, v140, vcc
	v_lshl_add_u64 v[226:227], v[142:143], 0, v[134:135]
	s_add_i32 m0, s51, 0xc000
	ds_read_b128 v[192:195], v153
	ds_read_b128 v[196:199], v153 offset:1024
	ds_read_b128 v[200:203], v153 offset:2048
	ds_read_b128 v[204:207], v153 offset:3072
	ds_read_b128 v[208:211], v153 offset:4096
	ds_read_b128 v[212:215], v153 offset:5120
	ds_read_b128 v[216:219], v153 offset:6144
	ds_read_b128 v[240:243], v153 offset:7168
	global_load_lds_dwordx4 v[226:227], off
	v_lshl_add_u64 v[226:227], v[142:143], 0, v[136:137]
	s_add_i32 m0, s51, 0xe000
	s_nop 0
	global_load_lds_dwordx4 v[226:227], off
	s_waitcnt vmcnt(8)
	s_waitcnt lgkmcnt(0)
	s_setprio 1
	s_barrier
; #define PG8_STAGE(bufoff, gbase, voff) do { _Pragma("unroll") for (int _i = 0; _i < 2; ++_i) \
;         __builtin_amdgcn_global_load_lds((const unsigned*)((const char*)(gbase) + (voff)[_i]), (LAS unsigned*)(lds + (bufoff) + ldsw + _i * 8192), 16, 0, 0); } while (0)
; #define PG8_LDA(dst, b, h) do { _Pragma("unroll") for (int m = 0; m < 4; ++m) _Pragma("unroll") for (int k = 0; k < 2; ++k) dst[m][k] = *(const LAS bf16x8*)(lds + PG8_SA(b, h) + aoff + m * 2048 + k * 1024); } while (0)
; #define PG8_MMA(ai, bj, At, Bt) do { __builtin_amdgcn_s_setprio(1); _Pragma("unroll") for (int k = 0; k < 2; ++k) _Pragma("unroll") for (int m = 0; m < 4; ++m) _Pragma("unroll") for (int n = 0; n < 2; ++n) \
;         acc[ai][bj][m][n] = __builtin_amdgcn_mfma_f32_16x16x32_bf16(Bt[n][k], At[m][k], acc[ai][bj][m][n], 0, 0, 0); __builtin_amdgcn_s_setprio(0); } while (0)
; #define PG8_WAIT_V(n) asm volatile("s_waitcnt vmcnt(" #n ")" ::: "memory")
; #define PG8_WAIT_L(n) asm volatile("s_waitcnt lgkmcnt(" #n ")" ::: "memory")
; #define PG8_BAR __builtin_amdgcn_s_barrier()
; #define PG8_SCHED __builtin_amdgcn_sched_barrier(0)
; template <class Epi, bool ALIGN_EPI>
; __device__ __forceinline__ void gemm_phase(LAS unsigned char* lds, const Gemm g, const StaticOrder& S, const Epi& E, const int tid) {
;     ...
;             PG8_WAIT_V(8); PG8_WAIT_L(0); PG8_BAR; PG8_MMA(0, 0, At, B0); PG8_MMA(0, 1, At, B1); PG8_BAR; PG8_SCHED;
;             PG8_LDA(At, 0, 1); PG8_STAGE(PG8_SB(0, 0), b2, voffB); PG8_STAGE(PG8_SB(0, 1), b2 + hB, voffB); PG8_STAGE(PG8_SA(0, 0), a2, voffA);
;             PG8_WAIT_V(8); PG8_WAIT_L(0); PG8_BAR; PG8_MMA(1, 0, At, B0); PG8_MMA(1, 1, At, B1); PG8_BAR; PG8_SCHED;
	s_waitcnt lgkmcnt(0)
	v_mfma_f32_16x16x32_bf16 v[120:123], v[146:149], v[192:195], v[120:123]
	v_mfma_f32_16x16x32_bf16 v[112:115], v[158:161], v[192:195], v[112:115]
	v_mfma_f32_16x16x32_bf16 v[104:107], v[146:149], v[200:203], v[104:107]
	v_mfma_f32_16x16x32_bf16 v[96:99], v[158:161], v[200:203], v[96:99]
	v_mfma_f32_16x16x32_bf16 v[88:91], v[146:149], v[208:211], v[88:91]
	v_mfma_f32_16x16x32_bf16 v[80:83], v[158:161], v[208:211], v[80:83]
	v_mfma_f32_16x16x32_bf16 v[72:75], v[146:149], v[216:219], v[72:75]
	v_mfma_f32_16x16x32_bf16 v[64:67], v[158:161], v[216:219], v[64:67]
	v_mfma_f32_16x16x32_bf16 v[120:123], v[154:157], v[196:199], v[120:123]
	v_mfma_f32_16x16x32_bf16 v[112:115], v[162:165], v[196:199], v[112:115]
	v_mfma_f32_16x16x32_bf16 v[104:107], v[154:157], v[204:207], v[104:107]
	v_mfma_f32_16x16x32_bf16 v[96:99], v[162:165], v[204:207], v[96:99]
	v_mfma_f32_16x16x32_bf16 v[88:91], v[154:157], v[212:215], v[88:91]
	v_mfma_f32_16x16x32_bf16 v[80:83], v[162:165], v[212:215], v[80:83]
	v_mfma_f32_16x16x32_bf16 v[72:75], v[154:157], v[240:243], v[72:75]
	v_mfma_f32_16x16x32_bf16 v[64:67], v[162:165], v[240:243], v[64:67]
	s_setprio 0
	s_setprio 1
	v_mfma_f32_16x16x32_bf16 v[124:127], v[176:179], v[192:195], v[124:127]
	v_mfma_f32_16x16x32_bf16 v[116:119], v[184:187], v[192:195], v[116:119]
	v_mfma_f32_16x16x32_bf16 v[108:111], v[176:179], v[200:203], v[108:111]
	v_mfma_f32_16x16x32_bf16 v[100:103], v[184:187], v[200:203], v[100:103]
	v_mfma_f32_16x16x32_bf16 v[92:95], v[176:179], v[208:211], v[92:95]
	v_mfma_f32_16x16x32_bf16 v[84:87], v[184:187], v[208:211], v[84:87]
	v_mfma_f32_16x16x32_bf16 v[76:79], v[176:179], v[216:219], v[76:79]
	v_mfma_f32_16x16x32_bf16 v[68:71], v[184:187], v[216:219], v[68:71]
	v_mfma_f32_16x16x32_bf16 v[124:127], v[180:183], v[196:199], v[124:127]
	v_mfma_f32_16x16x32_bf16 v[116:119], v[188:191], v[196:199], v[116:119]
	v_mfma_f32_16x16x32_bf16 v[108:111], v[180:183], v[204:207], v[108:111]
	v_mfma_f32_16x16x32_bf16 v[100:103], v[188:191], v[204:207], v[100:103]
	v_mfma_f32_16x16x32_bf16 v[92:95], v[180:183], v[212:215], v[92:95]
	v_mfma_f32_16x16x32_bf16 v[84:87], v[188:191], v[212:215], v[84:87]
	v_mfma_f32_16x16x32_bf16 v[76:79], v[180:183], v[240:243], v[76:79]
	v_mfma_f32_16x16x32_bf16 v[68:71], v[188:191], v[240:243], v[68:71]
	s_barrier
	s_setprio 0
	s_add_i32 s65, s33, s45
	v_lshl_add_u64 v[226:227], v[220:221], 0, v[168:169]
	s_mov_b32 m0, s65
	ds_read_b128 v[192:195], v153 offset:16384
	ds_read_b128 v[196:199], v153 offset:17408
	ds_read_b128 v[200:203], v153 offset:18432
	ds_read_b128 v[204:207], v153 offset:19456
	ds_read_b128 v[208:211], v153 offset:20480
	ds_read_b128 v[212:215], v153 offset:21504
	ds_read_b128 v[216:219], v153 offset:22528
	ds_read_b128 v[240:243], v153 offset:23552
	global_load_lds_dwordx4 v[226:227], off
	v_lshl_add_u64 v[244:245], v[220:221], 0, v[128:129]
	s_add_i32 m0, s65, 0x2000
	v_lshl_add_u64 v[220:221], v[220:221], 0, s[12:13]
	s_add_i32 s10, s10, s45
	global_load_lds_dwordx4 v[244:245], off
	v_lshl_add_u64 v[246:247], v[220:221], 0, v[168:169]
	s_mov_b32 m0, s10
	v_lshl_add_u64 v[220:221], v[220:221], 0, v[128:129]
	global_load_lds_dwordx4 v[246:247], off
	s_add_i32 m0, s10, 0x2000
	v_lshl_add_u64 v[248:249], v[166:167], 0, v[132:133]
	global_load_lds_dwordx4 v[220:221], off
	s_mov_b32 m0, s51
	v_lshl_add_u64 v[250:251], v[166:167], 0, v[130:131]
	global_load_lds_dwordx4 v[248:249], off
	s_mov_b32 m0, s52
	s_nop 0
	global_load_lds_dwordx4 v[250:251], off
	s_waitcnt vmcnt(8)
	s_waitcnt lgkmcnt(0)
	s_setprio 1
	s_barrier
	s_waitcnt lgkmcnt(0)
	v_mfma_f32_16x16x32_bf16 v[56:59], v[146:149], v[192:195], v[56:59]
	v_mfma_f32_16x16x32_bf16 v[48:51], v[158:161], v[192:195], v[48:51]
	v_mfma_f32_16x16x32_bf16 v[40:43], v[146:149], v[200:203], v[40:43]
	v_mfma_f32_16x16x32_bf16 v[32:35], v[158:161], v[200:203], v[32:35]
	v_mfma_f32_16x16x32_bf16 v[24:27], v[146:149], v[208:211], v[24:27]
	v_mfma_f32_16x16x32_bf16 v[16:19], v[158:161], v[208:211], v[16:19]
	v_mfma_f32_16x16x32_bf16 v[8:11], v[146:149], v[216:219], v[8:11]
	v_mfma_f32_16x16x32_bf16 v[4:7], v[158:161], v[216:219], v[4:7]
	v_mfma_f32_16x16x32_bf16 v[56:59], v[154:157], v[196:199], v[56:59]
	v_mfma_f32_16x16x32_bf16 v[48:51], v[162:165], v[196:199], v[48:51]
	v_mfma_f32_16x16x32_bf16 v[40:43], v[154:157], v[204:207], v[40:43]
	v_mfma_f32_16x16x32_bf16 v[32:35], v[162:165], v[204:207], v[32:35]
	v_mfma_f32_16x16x32_bf16 v[24:27], v[154:157], v[212:215], v[24:27]
	v_mfma_f32_16x16x32_bf16 v[16:19], v[162:165], v[212:215], v[16:19]
	v_mfma_f32_16x16x32_bf16 v[8:11], v[154:157], v[240:243], v[8:11]
	v_mfma_f32_16x16x32_bf16 v[4:7], v[162:165], v[240:243], v[4:7]
	s_setprio 0
	s_setprio 1
	v_mfma_f32_16x16x32_bf16 v[60:63], v[176:179], v[192:195], v[60:63]
	v_mfma_f32_16x16x32_bf16 v[52:55], v[184:187], v[192:195], v[52:55]
	v_mfma_f32_16x16x32_bf16 v[44:47], v[176:179], v[200:203], v[44:47]
	v_mfma_f32_16x16x32_bf16 v[36:39], v[184:187], v[200:203], v[36:39]
	v_mfma_f32_16x16x32_bf16 v[28:31], v[176:179], v[208:211], v[28:31]
	v_mfma_f32_16x16x32_bf16 v[20:23], v[184:187], v[208:211], v[20:23]
	v_mfma_f32_16x16x32_bf16 v[12:15], v[176:179], v[216:219], v[12:15]
	v_mfma_f32_16x16x32_bf16 v[0:3], v[184:187], v[216:219], v[0:3]
	v_mfma_f32_16x16x32_bf16 v[60:63], v[180:183], v[196:199], v[60:63]
	v_mfma_f32_16x16x32_bf16 v[52:55], v[188:191], v[196:199], v[52:55]
	v_mfma_f32_16x16x32_bf16 v[44:47], v[180:183], v[204:207], v[44:47]
	v_mfma_f32_16x16x32_bf16 v[36:39], v[188:191], v[204:207], v[36:39]
	v_mfma_f32_16x16x32_bf16 v[28:31], v[180:183], v[212:215], v[28:31]
	v_mfma_f32_16x16x32_bf16 v[20:23], v[188:191], v[212:215], v[20:23]
	v_mfma_f32_16x16x32_bf16 v[12:15], v[180:183], v[240:243], v[12:15]
	v_mfma_f32_16x16x32_bf16 v[0:3], v[188:191], v[240:243], v[0:3]
	s_barrier
; #define PG8_STAGE(bufoff, gbase, voff) do { _Pragma("unroll") for (int _i = 0; _i < 2; ++_i) \
;         __builtin_amdgcn_global_load_lds((const unsigned*)((const char*)(gbase) + (voff)[_i]), (LAS unsigned*)(lds + (bufoff) + ldsw + _i * 8192), 16, 0, 0); } while (0)
; #define PG8_LDA(dst, b, h) do { _Pragma("unroll") for (int m = 0; m < 4; ++m) _Pragma("unroll") for (int k = 0; k < 2; ++k) dst[m][k] = *(const LAS bf16x8*)(lds + PG8_SA(b, h) + aoff + m * 2048 + k * 1024); } while (0)
; #define PG8_LDB(dst, b, h) do { _Pragma("unroll") for (int n = 0; n < 2; ++n) _Pragma("unroll") for (int k = 0; k < 2; ++k) dst[n][k] = *(const LAS bf16x8*)(lds + PG8_SB(b, h) + boff + n * 2048 + k * 1024); } while (0)
; #define PG8_MMA(ai, bj, At, Bt) do { __builtin_amdgcn_s_setprio(1); _Pragma("unroll") for (int k = 0; k < 2; ++k) _Pragma("unroll") for (int m = 0; m < 4; ++m) _Pragma("unroll") for (int n = 0; n < 2; ++n) \
;         acc[ai][bj][m][n] = __builtin_amdgcn_mfma_f32_16x16x32_bf16(Bt[n][k], At[m][k], acc[ai][bj][m][n], 0, 0, 0); __builtin_amdgcn_s_setprio(0); } while (0)
; #define PG8_WAIT_V(n) asm volatile("s_waitcnt vmcnt(" #n ")" ::: "memory")
; #define PG8_WAIT_L(n) asm volatile("s_waitcnt lgkmcnt(" #n ")" ::: "memory")
; #define PG8_BAR __builtin_amdgcn_s_barrier()
; #define PG8_SCHED __builtin_amdgcn_sched_barrier(0)
; template <class Epi, bool ALIGN_EPI>
; __device__ __forceinline__ void gemm_phase(LAS unsigned char* lds, const Gemm g, const StaticOrder& S, const Epi& E, const int tid) {
;     ...
;             PG8_LDB(B0, 1, 0); PG8_LDB(B1, 1, 1); PG8_SCHED; PG8_LDA(At, 1, 0); PG8_STAGE(PG8_SA(0, 1), a2 + hA, voffA);
;             PG8_WAIT_V(8); PG8_WAIT_L(0); PG8_BAR; PG8_MMA(0, 0, At, B0); PG8_MMA(0, 1, At, B1); PG8_BAR; PG8_SCHED;
;             PG8_LDA(At, 1, 1); PG8_STAGE(PG8_SB(1, 0), b3, voffB); PG8_STAGE(PG8_SB(1, 1), b3 + hB, voffB); PG8_STAGE(PG8_SA(1, 0), a3, voffA);
;             PG8_WAIT_V(8); PG8_WAIT_L(0); PG8_BAR; PG8_MMA(1, 0, At, B0); PG8_MMA(1, 1, At, B1); PG8_BAR; PG8_SCHED;
	s_setprio 0
	s_add_i32 s10, 0, 0x18000
	v_add_u32_e32 v150, s10, v151
	s_add_i32 s65, 0, 0x1c000
	ds_read_b128 v[146:149], v150
	ds_read_b128 v[154:157], v150 offset:1024
	ds_read_b128 v[158:161], v150 offset:2048
	ds_read_b128 v[162:165], v150 offset:3072
	v_add_u32_e32 v150, s65, v151
	ds_read_b128 v[176:179], v150
	ds_read_b128 v[180:183], v150 offset:1024
	ds_read_b128 v[184:187], v150 offset:2048
	ds_read_b128 v[188:191], v150 offset:3072
	v_lshl_add_u64 v[166:167], v[166:167], 0, s[94:95]
	s_mov_b32 m0, s53
	v_lshl_add_u64 v[252:253], v[166:167], 0, v[132:133]
	ds_read_b128 v[192:195], v153 offset:32768
	ds_read_b128 v[196:199], v153 offset:33792
	ds_read_b128 v[200:203], v153 offset:34816
	ds_read_b128 v[204:207], v153 offset:35840
	ds_read_b128 v[208:211], v153 offset:36864
	ds_read_b128 v[212:215], v153 offset:37888
	ds_read_b128 v[216:219], v153 offset:38912
	ds_read_b128 v[240:243], v153 offset:39936
	global_load_lds_dwordx4 v[252:253], off
	v_lshl_add_u64 v[166:167], v[166:167], 0, v[130:131]
	s_mov_b32 m0, s54
	s_nop 0
	global_load_lds_dwordx4 v[166:167], off
	s_waitcnt vmcnt(8)
	s_waitcnt lgkmcnt(0)
	s_setprio 1
	s_barrier
	s_waitcnt lgkmcnt(0)
	v_mfma_f32_16x16x32_bf16 v[120:123], v[146:149], v[192:195], v[120:123]
	v_mfma_f32_16x16x32_bf16 v[112:115], v[158:161], v[192:195], v[112:115]
	v_mfma_f32_16x16x32_bf16 v[104:107], v[146:149], v[200:203], v[104:107]
	v_mfma_f32_16x16x32_bf16 v[96:99], v[158:161], v[200:203], v[96:99]
	v_mfma_f32_16x16x32_bf16 v[88:91], v[146:149], v[208:211], v[88:91]
	v_mfma_f32_16x16x32_bf16 v[80:83], v[158:161], v[208:211], v[80:83]
	v_mfma_f32_16x16x32_bf16 v[72:75], v[146:149], v[216:219], v[72:75]
	v_mfma_f32_16x16x32_bf16 v[64:67], v[158:161], v[216:219], v[64:67]
	v_mfma_f32_16x16x32_bf16 v[120:123], v[154:157], v[196:199], v[120:123]
	v_mfma_f32_16x16x32_bf16 v[112:115], v[162:165], v[196:199], v[112:115]
	v_mfma_f32_16x16x32_bf16 v[104:107], v[154:157], v[204:207], v[104:107]
	v_mfma_f32_16x16x32_bf16 v[96:99], v[162:165], v[204:207], v[96:99]
	v_mfma_f32_16x16x32_bf16 v[88:91], v[154:157], v[212:215], v[88:91]
	v_mfma_f32_16x16x32_bf16 v[80:83], v[162:165], v[212:215], v[80:83]
	v_mfma_f32_16x16x32_bf16 v[72:75], v[154:157], v[240:243], v[72:75]
	v_mfma_f32_16x16x32_bf16 v[64:67], v[162:165], v[240:243], v[64:67]
	s_setprio 0
	s_setprio 1
	v_mfma_f32_16x16x32_bf16 v[124:127], v[176:179], v[192:195], v[124:127]
	v_mfma_f32_16x16x32_bf16 v[116:119], v[184:187], v[192:195], v[116:119]
	v_mfma_f32_16x16x32_bf16 v[108:111], v[176:179], v[200:203], v[108:111]
	v_mfma_f32_16x16x32_bf16 v[100:103], v[184:187], v[200:203], v[100:103]
	v_mfma_f32_16x16x32_bf16 v[92:95], v[176:179], v[208:211], v[92:95]
	v_mfma_f32_16x16x32_bf16 v[84:87], v[184:187], v[208:211], v[84:87]
	v_mfma_f32_16x16x32_bf16 v[76:79], v[176:179], v[216:219], v[76:79]
	v_mfma_f32_16x16x32_bf16 v[68:71], v[184:187], v[216:219], v[68:71]
	v_mfma_f32_16x16x32_bf16 v[124:127], v[180:183], v[196:199], v[124:127]
	v_mfma_f32_16x16x32_bf16 v[116:119], v[188:191], v[196:199], v[116:119]
	v_mfma_f32_16x16x32_bf16 v[108:111], v[180:183], v[204:207], v[108:111]
	v_mfma_f32_16x16x32_bf16 v[100:103], v[188:191], v[204:207], v[100:103]
	v_mfma_f32_16x16x32_bf16 v[92:95], v[180:183], v[212:215], v[92:95]
	v_mfma_f32_16x16x32_bf16 v[84:87], v[188:191], v[212:215], v[84:87]
	v_mfma_f32_16x16x32_bf16 v[76:79], v[180:183], v[240:243], v[76:79]
	v_mfma_f32_16x16x32_bf16 v[68:71], v[188:191], v[240:243], v[68:71]
	s_barrier
	s_setprio 0
	s_add_i32 s10, s10, s45
	v_lshl_add_u64 v[166:167], v[226:227], 0, s[92:93]
	s_mov_b32 m0, s10
	ds_read_b128 v[192:195], v153 offset:49152
	ds_read_b128 v[196:199], v153 offset:50176
	ds_read_b128 v[200:203], v153 offset:51200
	ds_read_b128 v[204:207], v153 offset:52224
	ds_read_b128 v[208:211], v153 offset:53248
	ds_read_b128 v[212:215], v153 offset:54272
	ds_read_b128 v[216:219], v153 offset:55296
	ds_read_b128 v[240:243], v153 offset:56320
	global_load_lds_dwordx4 v[166:167], off
	v_lshl_add_u64 v[166:167], v[244:245], 0, s[92:93]
	s_add_i32 m0, s10, 0x2000
	s_add_i32 s10, s65, s45
	global_load_lds_dwordx4 v[166:167], off
	v_lshl_add_u64 v[166:167], v[246:247], 0, s[92:93]
	s_mov_b32 m0, s10
	s_nop 0
	global_load_lds_dwordx4 v[166:167], off
	v_lshl_add_u64 v[166:167], v[220:221], 0, s[92:93]
	s_add_i32 m0, s10, 0x2000
	s_nop 0
	global_load_lds_dwordx4 v[166:167], off
	v_lshl_add_u64 v[166:167], v[248:249], 0, s[92:93]
	s_mov_b32 m0, s56
	s_nop 0
	global_load_lds_dwordx4 v[166:167], off
	v_lshl_add_u64 v[166:167], v[250:251], 0, s[92:93]
	s_mov_b32 m0, s57
	s_nop 0
	global_load_lds_dwordx4 v[166:167], off
	s_waitcnt vmcnt(8)
	s_waitcnt lgkmcnt(0)
	s_setprio 1
	s_barrier
; #define PG8_STAGE(bufoff, gbase, voff) do { _Pragma("unroll") for (int _i = 0; _i < 2; ++_i) \
;         __builtin_amdgcn_global_load_lds((const unsigned*)((const char*)(gbase) + (voff)[_i]), (LAS unsigned*)(lds + (bufoff) + ldsw + _i * 8192), 16, 0, 0); } while (0)
; #define PG8_LDA(dst, b, h) do { _Pragma("unroll") for (int m = 0; m < 4; ++m) _Pragma("unroll") for (int k = 0; k < 2; ++k) dst[m][k] = *(const LAS bf16x8*)(lds + PG8_SA(b, h) + aoff + m * 2048 + k * 1024); } while (0)
; #define PG8_LDB(dst, b, h) do { _Pragma("unroll") for (int n = 0; n < 2; ++n) _Pragma("unroll") for (int k = 0; k < 2; ++k) dst[n][k] = *(const LAS bf16x8*)(lds + PG8_SB(b, h) + boff + n * 2048 + k * 1024); } while (0)
; #define PG8_MMA(ai, bj, At, Bt) do { __builtin_amdgcn_s_setprio(1); _Pragma("unroll") for (int k = 0; k < 2; ++k) _Pragma("unroll") for (int m = 0; m < 4; ++m) _Pragma("unroll") for (int n = 0; n < 2; ++n) \
;         acc[ai][bj][m][n] = __builtin_amdgcn_mfma_f32_16x16x32_bf16(Bt[n][k], At[m][k], acc[ai][bj][m][n], 0, 0, 0); __builtin_amdgcn_s_setprio(0); } while (0)
; #define PG8_WAIT_V(n) asm volatile("s_waitcnt vmcnt(" #n ")" ::: "memory")
; #define PG8_BAR __builtin_amdgcn_s_barrier()
; template <class Epi, bool ALIGN_EPI>
; __device__ __forceinline__ void gemm_phase(LAS unsigned char* lds, const Gemm g, const StaticOrder& S, const Epi& E, const int tid) {
;     ...
;             PG8_LDB(B0, 0, 0); PG8_LDB(B1, 0, 1); PG8_SCHED; PG8_LDA(At, 0, 0); PG8_STAGE(PG8_SA(1, 1), a1 + hA, voffA);
;             PG8_WAIT_V(8); PG8_WAIT_L(0); PG8_BAR; PG8_MMA(0, 0, At, B0); PG8_MMA(0, 1, At, B1); PG8_BAR; PG8_SCHED;
;             PG8_LDA(At, 0, 1); PG8_STAGE(PG8_SB(0, 0), b2, voffB); PG8_STAGE(PG8_SB(0, 1), b2 + hB, voffB); PG8_STAGE(PG8_SA(0, 0), a2, voffA);
;             PG8_WAIT_V(8); PG8_WAIT_L(0); PG8_BAR; PG8_MMA(1, 0, At, B0); PG8_MMA(1, 1, At, B1); PG8_BAR; PG8_SCHED;
;             PG8_LDB(B0, 1, 0); PG8_LDB(B1, 1, 1); PG8_SCHED; PG8_LDA(At, 1, 0); PG8_STAGE(PG8_SA(0, 1), a2 + hA, voffA);
;             PG8_WAIT_V(8); PG8_WAIT_L(0); PG8_BAR; PG8_MMA(0, 0, At, B0); PG8_MMA(0, 1, At, B1); PG8_BAR; PG8_SCHED;
;             PG8_LDA(At, 1, 1); PG8_STAGE(PG8_SB(1, 0), b3, voffB); PG8_STAGE(PG8_SB(1, 1), b3 + hB, voffB); PG8_STAGE(PG8_SA(1, 0), a3, voffA);
;             PG8_WAIT_V(8); PG8_WAIT_L(0); PG8_BAR; PG8_MMA(1, 0, At, B0); PG8_MMA(1, 1, At, B1); PG8_BAR; PG8_SCHED;
	s_waitcnt lgkmcnt(0)
	v_mfma_f32_16x16x32_bf16 v[56:59], v[146:149], v[192:195], v[56:59]
	v_mfma_f32_16x16x32_bf16 v[48:51], v[158:161], v[192:195], v[48:51]
	v_mfma_f32_16x16x32_bf16 v[40:43], v[146:149], v[200:203], v[40:43]
	v_mfma_f32_16x16x32_bf16 v[32:35], v[158:161], v[200:203], v[32:35]
	v_mfma_f32_16x16x32_bf16 v[24:27], v[146:149], v[208:211], v[24:27]
	v_mfma_f32_16x16x32_bf16 v[16:19], v[158:161], v[208:211], v[16:19]
	v_mfma_f32_16x16x32_bf16 v[8:11], v[146:149], v[216:219], v[8:11]
	v_mfma_f32_16x16x32_bf16 v[4:7], v[158:161], v[216:219], v[4:7]
	v_mfma_f32_16x16x32_bf16 v[56:59], v[154:157], v[196:199], v[56:59]
	v_mfma_f32_16x16x32_bf16 v[48:51], v[162:165], v[196:199], v[48:51]
	v_mfma_f32_16x16x32_bf16 v[40:43], v[154:157], v[204:207], v[40:43]
	v_mfma_f32_16x16x32_bf16 v[32:35], v[162:165], v[204:207], v[32:35]
	v_mfma_f32_16x16x32_bf16 v[24:27], v[154:157], v[212:215], v[24:27]
	v_mfma_f32_16x16x32_bf16 v[16:19], v[162:165], v[212:215], v[16:19]
	v_mfma_f32_16x16x32_bf16 v[8:11], v[154:157], v[240:243], v[8:11]
	v_mfma_f32_16x16x32_bf16 v[4:7], v[162:165], v[240:243], v[4:7]
	s_setprio 0
	s_setprio 1
	v_mfma_f32_16x16x32_bf16 v[60:63], v[176:179], v[192:195], v[60:63]
	v_mfma_f32_16x16x32_bf16 v[52:55], v[184:187], v[192:195], v[52:55]
	v_mfma_f32_16x16x32_bf16 v[44:47], v[176:179], v[200:203], v[44:47]
	v_mfma_f32_16x16x32_bf16 v[36:39], v[184:187], v[200:203], v[36:39]
	v_mfma_f32_16x16x32_bf16 v[28:31], v[176:179], v[208:211], v[28:31]
	v_mfma_f32_16x16x32_bf16 v[20:23], v[184:187], v[208:211], v[20:23]
	v_mfma_f32_16x16x32_bf16 v[12:15], v[176:179], v[216:219], v[12:15]
	v_mfma_f32_16x16x32_bf16 v[0:3], v[184:187], v[216:219], v[0:3]
	v_mfma_f32_16x16x32_bf16 v[60:63], v[180:183], v[196:199], v[60:63]
	v_mfma_f32_16x16x32_bf16 v[52:55], v[188:191], v[196:199], v[52:55]
	v_mfma_f32_16x16x32_bf16 v[44:47], v[180:183], v[204:207], v[44:47]
	v_mfma_f32_16x16x32_bf16 v[36:39], v[188:191], v[204:207], v[36:39]
	v_mfma_f32_16x16x32_bf16 v[28:31], v[180:183], v[212:215], v[28:31]
	v_mfma_f32_16x16x32_bf16 v[20:23], v[188:191], v[212:215], v[20:23]
	v_mfma_f32_16x16x32_bf16 v[12:15], v[180:183], v[240:243], v[12:15]
	v_mfma_f32_16x16x32_bf16 v[0:3], v[188:191], v[240:243], v[0:3]
	s_barrier
	s_setprio 0
	v_lshl_add_u64 v[142:143], v[142:143], 0, s[80:81]
	v_lshl_add_u64 v[144:145], v[144:145], 0, s[80:81]
	s_mov_b32 s10, s11
	s_cmp_lg_u32 s10, s58
	s_cbranch_scc1 .LBB0_308
.Lgu_last:
	s_add_i32 s11, s10, 2
	s_cmp_eq_u32 s58, s10
	v_lshl_add_u64 v[146:147], v[142:143], 0, s[92:93]
	s_cselect_b64 vcc, -1, 0
	v_add_u32_e32 v150, s33, v151
	s_add_i32 s10, 0, 0x14000
	v_cndmask_b32_e32 v167, v147, v139, vcc
	v_cndmask_b32_e32 v166, v146, v138, vcc
	ds_read_b128 v[146:149], v150
	ds_read_b128 v[154:157], v150 offset:1024
	ds_read_b128 v[158:161], v150 offset:2048
	ds_read_b128 v[162:165], v150 offset:3072
	v_add_u32_e32 v150, s10, v151
	ds_read_b128 v[176:179], v150
	ds_read_b128 v[180:183], v150 offset:1024
	ds_read_b128 v[184:187], v150 offset:2048
	ds_read_b128 v[188:191], v150 offset:3072
	v_cndmask_b32_e32 v221, v145, v141, vcc
	v_cndmask_b32_e32 v220, v144, v140, vcc
	v_lshl_add_u64 v[226:227], v[142:143], 0, v[134:135]
	s_add_i32 m0, s51, 0xc000
	ds_read_b128 v[192:195], v153
	ds_read_b128 v[196:199], v153 offset:1024
	ds_read_b128 v[200:203], v153 offset:2048
	ds_read_b128 v[204:207], v153 offset:3072
	ds_read_b128 v[208:211], v153 offset:4096
	ds_read_b128 v[212:215], v153 offset:5120
	ds_read_b128 v[216:219], v153 offset:6144
	ds_read_b128 v[240:243], v153 offset:7168
	global_load_lds_dwordx4 v[226:227], off
	v_lshl_add_u64 v[226:227], v[142:143], 0, v[136:137]
	s_add_i32 m0, s51, 0xe000
	s_nop 0
	global_load_lds_dwordx4 v[226:227], off
	s_waitcnt vmcnt(8)
	s_waitcnt lgkmcnt(0)
	s_setprio 1
	s_barrier
	s_waitcnt lgkmcnt(0)
	v_mfma_f32_16x16x32_bf16 v[120:123], v[146:149], v[192:195], v[120:123]
	v_mfma_f32_16x16x32_bf16 v[112:115], v[158:161], v[192:195], v[112:115]
	v_mfma_f32_16x16x32_bf16 v[104:107], v[146:149], v[200:203], v[104:107]
	v_mfma_f32_16x16x32_bf16 v[96:99], v[158:161], v[200:203], v[96:99]
	v_mfma_f32_16x16x32_bf16 v[88:91], v[146:149], v[208:211], v[88:91]
	v_mfma_f32_16x16x32_bf16 v[80:83], v[158:161], v[208:211], v[80:83]
	v_mfma_f32_16x16x32_bf16 v[72:75], v[146:149], v[216:219], v[72:75]
	v_mfma_f32_16x16x32_bf16 v[64:67], v[158:161], v[216:219], v[64:67]
	v_mfma_f32_16x16x32_bf16 v[120:123], v[154:157], v[196:199], v[120:123]
	v_mfma_f32_16x16x32_bf16 v[112:115], v[162:165], v[196:199], v[112:115]
	v_mfma_f32_16x16x32_bf16 v[104:107], v[154:157], v[204:207], v[104:107]
	v_mfma_f32_16x16x32_bf16 v[96:99], v[162:165], v[204:207], v[96:99]
	v_mfma_f32_16x16x32_bf16 v[88:91], v[154:157], v[212:215], v[88:91]
	v_mfma_f32_16x16x32_bf16 v[80:83], v[162:165], v[212:215], v[80:83]
	v_mfma_f32_16x16x32_bf16 v[72:75], v[154:157], v[240:243], v[72:75]
	v_mfma_f32_16x16x32_bf16 v[64:67], v[162:165], v[240:243], v[64:67]
	s_setprio 0
	s_setprio 1
	v_mfma_f32_16x16x32_bf16 v[124:127], v[176:179], v[192:195], v[124:127]
	v_mfma_f32_16x16x32_bf16 v[116:119], v[184:187], v[192:195], v[116:119]
	v_mfma_f32_16x16x32_bf16 v[108:111], v[176:179], v[200:203], v[108:111]
	v_mfma_f32_16x16x32_bf16 v[100:103], v[184:187], v[200:203], v[100:103]
	v_mfma_f32_16x16x32_bf16 v[92:95], v[176:179], v[208:211], v[92:95]
	v_mfma_f32_16x16x32_bf16 v[84:87], v[184:187], v[208:211], v[84:87]
	v_mfma_f32_16x16x32_bf16 v[76:79], v[176:179], v[216:219], v[76:79]
	v_mfma_f32_16x16x32_bf16 v[68:71], v[184:187], v[216:219], v[68:71]
	v_mfma_f32_16x16x32_bf16 v[124:127], v[180:183], v[196:199], v[124:127]
	v_mfma_f32_16x16x32_bf16 v[116:119], v[188:191], v[196:199], v[116:119]
	v_mfma_f32_16x16x32_bf16 v[108:111], v[180:183], v[204:207], v[108:111]
	v_mfma_f32_16x16x32_bf16 v[100:103], v[188:191], v[204:207], v[100:103]
	v_mfma_f32_16x16x32_bf16 v[92:95], v[180:183], v[212:215], v[92:95]
	v_mfma_f32_16x16x32_bf16 v[84:87], v[188:191], v[212:215], v[84:87]
	v_mfma_f32_16x16x32_bf16 v[76:79], v[180:183], v[240:243], v[76:79]
	v_mfma_f32_16x16x32_bf16 v[68:71], v[188:191], v[240:243], v[68:71]
	s_barrier
; #define PG8_STAGE(bufoff, gbase, voff) do { _Pragma("unroll") for (int _i = 0; _i < 2; ++_i) \
;         __builtin_amdgcn_global_load_lds((const unsigned*)((const char*)(gbase) + (voff)[_i]), (LAS unsigned*)(lds + (bufoff) + ldsw + _i * 8192), 16, 0, 0); } while (0)
; #define PG8_LDA(dst, b, h) do { _Pragma("unroll") for (int m = 0; m < 4; ++m) _Pragma("unroll") for (int k = 0; k < 2; ++k) dst[m][k] = *(const LAS bf16x8*)(lds + PG8_SA(b, h) + aoff + m * 2048 + k * 1024); } while (0)
; #define PG8_LDB(dst, b, h) do { _Pragma("unroll") for (int n = 0; n < 2; ++n) _Pragma("unroll") for (int k = 0; k < 2; ++k) dst[n][k] = *(const LAS bf16x8*)(lds + PG8_SB(b, h) + boff + n * 2048 + k * 1024); } while (0)
; #define PG8_MMA(ai, bj, At, Bt) do { __builtin_amdgcn_s_setprio(1); _Pragma("unroll") for (int k = 0; k < 2; ++k) _Pragma("unroll") for (int m = 0; m < 4; ++m) _Pragma("unroll") for (int n = 0; n < 2; ++n) \
;         acc[ai][bj][m][n] = __builtin_amdgcn_mfma_f32_16x16x32_bf16(Bt[n][k], At[m][k], acc[ai][bj][m][n], 0, 0, 0); __builtin_amdgcn_s_setprio(0); } while (0)
; #define PG8_WAIT_V(n) asm volatile("s_waitcnt vmcnt(" #n ")" ::: "memory")
; #define PG8_WAIT_L(n) asm volatile("s_waitcnt lgkmcnt(" #n ")" ::: "memory")
; #define PG8_BAR __builtin_amdgcn_s_barrier()
; #define PG8_SCHED __builtin_amdgcn_sched_barrier(0)
; template <class Epi, bool ALIGN_EPI>
; __device__ __forceinline__ void gemm_phase(LAS unsigned char* lds, const Gemm g, const StaticOrder& S, const Epi& E, const int tid) {
;     ...
;             PG8_WAIT_V(8); PG8_WAIT_L(0); PG8_BAR; PG8_MMA(0, 0, At, B0); PG8_MMA(0, 1, At, B1); PG8_BAR; PG8_SCHED;
;             PG8_LDA(At, 0, 1); PG8_STAGE(PG8_SB(0, 0), b2, voffB); PG8_STAGE(PG8_SB(0, 1), b2 + hB, voffB); PG8_STAGE(PG8_SA(0, 0), a2, voffA);
;             PG8_WAIT_V(8); PG8_WAIT_L(0); PG8_BAR; PG8_MMA(1, 0, At, B0); PG8_MMA(1, 1, At, B1); PG8_BAR; PG8_SCHED;
;             PG8_LDB(B0, 1, 0); PG8_LDB(B1, 1, 1); PG8_SCHED; PG8_LDA(At, 1, 0); PG8_STAGE(PG8_SA(0, 1), a2 + hA, voffA);
	s_setprio 0
	s_add_i32 s65, s33, s45
	v_lshl_add_u64 v[226:227], v[220:221], 0, v[168:169]
	s_mov_b32 m0, s65
	ds_read_b128 v[192:195], v153 offset:16384
	ds_read_b128 v[196:199], v153 offset:17408
	ds_read_b128 v[200:203], v153 offset:18432
	ds_read_b128 v[204:207], v153 offset:19456
	ds_read_b128 v[208:211], v153 offset:20480
	ds_read_b128 v[212:215], v153 offset:21504
	ds_read_b128 v[216:219], v153 offset:22528
	ds_read_b128 v[240:243], v153 offset:23552
	global_load_lds_dwordx4 v[226:227], off
	v_lshl_add_u64 v[244:245], v[220:221], 0, v[128:129]
	s_add_i32 m0, s65, 0x2000
	v_lshl_add_u64 v[220:221], v[220:221], 0, s[12:13]
	s_add_i32 s10, s10, s45
	global_load_lds_dwordx4 v[244:245], off
	v_lshl_add_u64 v[246:247], v[220:221], 0, v[168:169]
	s_mov_b32 m0, s10
	v_lshl_add_u64 v[220:221], v[220:221], 0, v[128:129]
	global_load_lds_dwordx4 v[246:247], off
	s_add_i32 m0, s10, 0x2000
	v_lshl_add_u64 v[248:249], v[166:167], 0, v[132:133]
	global_load_lds_dwordx4 v[220:221], off
	s_mov_b32 m0, s51
	v_lshl_add_u64 v[250:251], v[166:167], 0, v[130:131]
	global_load_lds_dwordx4 v[248:249], off
	s_mov_b32 m0, s52
	s_nop 0
	global_load_lds_dwordx4 v[250:251], off
	s_waitcnt vmcnt(8)
	s_waitcnt lgkmcnt(0)
	s_setprio 1
	s_barrier
	s_waitcnt lgkmcnt(0)
	v_mfma_f32_16x16x32_bf16 v[56:59], v[146:149], v[192:195], v[56:59]
	v_mfma_f32_16x16x32_bf16 v[48:51], v[158:161], v[192:195], v[48:51]
	v_mfma_f32_16x16x32_bf16 v[40:43], v[146:149], v[200:203], v[40:43]
	v_mfma_f32_16x16x32_bf16 v[32:35], v[158:161], v[200:203], v[32:35]
	v_mfma_f32_16x16x32_bf16 v[24:27], v[146:149], v[208:211], v[24:27]
	v_mfma_f32_16x16x32_bf16 v[16:19], v[158:161], v[208:211], v[16:19]
	v_mfma_f32_16x16x32_bf16 v[8:11], v[146:149], v[216:219], v[8:11]
	v_mfma_f32_16x16x32_bf16 v[4:7], v[158:161], v[216:219], v[4:7]
	v_mfma_f32_16x16x32_bf16 v[56:59], v[154:157], v[196:199], v[56:59]
	v_mfma_f32_16x16x32_bf16 v[48:51], v[162:165], v[196:199], v[48:51]
	v_mfma_f32_16x16x32_bf16 v[40:43], v[154:157], v[204:207], v[40:43]
	v_mfma_f32_16x16x32_bf16 v[32:35], v[162:165], v[204:207], v[32:35]
	v_mfma_f32_16x16x32_bf16 v[24:27], v[154:157], v[212:215], v[24:27]
	v_mfma_f32_16x16x32_bf16 v[16:19], v[162:165], v[212:215], v[16:19]
	v_mfma_f32_16x16x32_bf16 v[8:11], v[154:157], v[240:243], v[8:11]
	v_mfma_f32_16x16x32_bf16 v[4:7], v[162:165], v[240:243], v[4:7]
	s_setprio 0
	s_setprio 1
	v_mfma_f32_16x16x32_bf16 v[60:63], v[176:179], v[192:195], v[60:63]
	v_mfma_f32_16x16x32_bf16 v[52:55], v[184:187], v[192:195], v[52:55]
	v_mfma_f32_16x16x32_bf16 v[44:47], v[176:179], v[200:203], v[44:47]
	v_mfma_f32_16x16x32_bf16 v[36:39], v[184:187], v[200:203], v[36:39]
	v_mfma_f32_16x16x32_bf16 v[28:31], v[176:179], v[208:211], v[28:31]
	v_mfma_f32_16x16x32_bf16 v[20:23], v[184:187], v[208:211], v[20:23]
	v_mfma_f32_16x16x32_bf16 v[12:15], v[176:179], v[216:219], v[12:15]
	v_mfma_f32_16x16x32_bf16 v[0:3], v[184:187], v[216:219], v[0:3]
	v_mfma_f32_16x16x32_bf16 v[60:63], v[180:183], v[196:199], v[60:63]
	v_mfma_f32_16x16x32_bf16 v[52:55], v[188:191], v[196:199], v[52:55]
	v_mfma_f32_16x16x32_bf16 v[44:47], v[180:183], v[204:207], v[44:47]
	v_mfma_f32_16x16x32_bf16 v[36:39], v[188:191], v[204:207], v[36:39]
	v_mfma_f32_16x16x32_bf16 v[28:31], v[180:183], v[212:215], v[28:31]
	v_mfma_f32_16x16x32_bf16 v[20:23], v[188:191], v[212:215], v[20:23]
	v_mfma_f32_16x16x32_bf16 v[12:15], v[180:183], v[240:243], v[12:15]
	v_mfma_f32_16x16x32_bf16 v[0:3], v[188:191], v[240:243], v[0:3]
	s_barrier
	s_setprio 0
	s_add_i32 s10, 0, 0x18000
	v_add_u32_e32 v150, s10, v151
	s_add_i32 s65, 0, 0x1c000
	ds_read_b128 v[146:149], v150
	ds_read_b128 v[154:157], v150 offset:1024
	ds_read_b128 v[158:161], v150 offset:2048
	ds_read_b128 v[162:165], v150 offset:3072
	v_add_u32_e32 v150, s65, v151
	ds_read_b128 v[176:179], v150
	ds_read_b128 v[180:183], v150 offset:1024
	ds_read_b128 v[184:187], v150 offset:2048
	ds_read_b128 v[188:191], v150 offset:3072
	v_lshl_add_u64 v[166:167], v[166:167], 0, s[94:95]
	s_mov_b32 m0, s53
	v_lshl_add_u64 v[252:253], v[166:167], 0, v[132:133]
	ds_read_b128 v[192:195], v153 offset:32768
	ds_read_b128 v[196:199], v153 offset:33792
	ds_read_b128 v[200:203], v153 offset:34816
	ds_read_b128 v[204:207], v153 offset:35840
	ds_read_b128 v[208:211], v153 offset:36864
	ds_read_b128 v[212:215], v153 offset:37888
	ds_read_b128 v[216:219], v153 offset:38912
	ds_read_b128 v[240:243], v153 offset:39936
	global_load_lds_dwordx4 v[252:253], off
	v_lshl_add_u64 v[166:167], v[166:167], 0, v[130:131]
	s_mov_b32 m0, s54
	s_nop 0
	global_load_lds_dwordx4 v[166:167], off
	s_waitcnt vmcnt(8)
	s_waitcnt lgkmcnt(0)
	s_setprio 1
	s_barrier
; __device__ __forceinline__ unsigned cvt_pk_bf16(float lo, float hi) { unsigned r; asm volatile("v_cvt_pk_bf16_f32 %0, %1, %2" : "=v"(r) : "v"(lo), "v"(hi)); return r; }
; __device__ __forceinline__ float siluf_(float x) { return x * sigmoidf_(x); }
; #define PG8_STAGE(bufoff, gbase, voff) do { _Pragma("unroll") for (int _i = 0; _i < 2; ++_i) \
;         __builtin_amdgcn_global_load_lds((const unsigned*)((const char*)(gbase) + (voff)[_i]), (LAS unsigned*)(lds + (bufoff) + ldsw + _i * 8192), 16, 0, 0); } while (0)
; #define PG8_LDA(dst, b, h) do { _Pragma("unroll") for (int m = 0; m < 4; ++m) _Pragma("unroll") for (int k = 0; k < 2; ++k) dst[m][k] = *(const LAS bf16x8*)(lds + PG8_SA(b, h) + aoff + m * 2048 + k * 1024); } while (0)
; #define PG8_WAIT_V(n) asm volatile("s_waitcnt vmcnt(" #n ")" ::: "memory")
; #define PG8_BAR __builtin_amdgcn_s_barrier()
;     __device__ __forceinline__ void operator()(const f32x4 (&acc)[2][2][4][2], const Unit& u, int wr, int wc, int fr, int fq) const {
;         const int row0 = u.pm * BM + wr * 64 + fr, col0 = u.pn * HALF + wc * 32 + 8 * fq;
;         float rsv[2][4]; load_rstd(rsv, ssq, row0);
; #pragma unroll
;         for (int ai = 0; ai < 2; ++ai)
; #pragma unroll
;             for (int m = 0; m < 4; ++m) { const int row = row0 + ai * HALF + m * 16; bf16_t* rowp = O + (size_t)row * ldc + col0; const float rs = rsv[ai][m];
;                 f32x4 v0, v1;
; #pragma unroll
;                 for (int j = 0; j < 4; ++j) { v0[j] = siluf_(acc[ai][0][m][0][j] * rs) * (acc[ai][1][m][0][j] * rs); v1[j] = siluf_(acc[ai][0][m][1][j] * rs) * (acc[ai][1][m][1][j] * rs); }
;                 u32x4 w; w.x = cvt_pk_bf16(v0[0], v0[1]); w.y = cvt_pk_bf16(v0[2], v0[3]); w.z = cvt_pk_bf16(v1[0], v1[1]); w.w = cvt_pk_bf16(v1[2], v1[3]);
;                 *(u32x4*)rowp = w; }
; template <class Epi, bool ALIGN_EPI>
; __device__ __forceinline__ void gemm_phase(LAS unsigned char* lds, const Gemm g, const StaticOrder& S, const Epi& E, const int tid) {
;     ...
;             PG8_WAIT_V(8); PG8_WAIT_L(0); PG8_BAR; PG8_MMA(0, 0, At, B0); PG8_MMA(0, 1, At, B1); PG8_BAR; PG8_SCHED;
;             PG8_LDA(At, 1, 1); PG8_STAGE(PG8_SB(1, 0), b3, voffB); PG8_STAGE(PG8_SB(1, 1), b3 + hB, voffB); PG8_STAGE(PG8_SA(1, 0), a3, voffA);
;             PG8_WAIT_V(8); PG8_WAIT_L(0); PG8_BAR; PG8_MMA(1, 0, At, B0); PG8_MMA(1, 1, At, B1); PG8_BAR; PG8_SCHED;
	s_waitcnt lgkmcnt(0)
	v_mfma_f32_16x16x32_bf16 v[120:123], v[146:149], v[192:195], v[120:123]
	v_mfma_f32_16x16x32_bf16 v[112:115], v[158:161], v[192:195], v[112:115]
	v_mfma_f32_16x16x32_bf16 v[104:107], v[146:149], v[200:203], v[104:107]
	v_mfma_f32_16x16x32_bf16 v[96:99], v[158:161], v[200:203], v[96:99]
	v_mfma_f32_16x16x32_bf16 v[88:91], v[146:149], v[208:211], v[88:91]
	v_mfma_f32_16x16x32_bf16 v[80:83], v[158:161], v[208:211], v[80:83]
	v_mfma_f32_16x16x32_bf16 v[72:75], v[146:149], v[216:219], v[72:75]
	v_mfma_f32_16x16x32_bf16 v[64:67], v[158:161], v[216:219], v[64:67]
	v_mfma_f32_16x16x32_bf16 v[120:123], v[154:157], v[196:199], v[120:123]
	v_mfma_f32_16x16x32_bf16 v[112:115], v[162:165], v[196:199], v[112:115]
	v_mfma_f32_16x16x32_bf16 v[104:107], v[154:157], v[204:207], v[104:107]
	v_mfma_f32_16x16x32_bf16 v[96:99], v[162:165], v[204:207], v[96:99]
	v_mfma_f32_16x16x32_bf16 v[88:91], v[154:157], v[212:215], v[88:91]
	v_mfma_f32_16x16x32_bf16 v[80:83], v[162:165], v[212:215], v[80:83]
	v_mfma_f32_16x16x32_bf16 v[72:75], v[154:157], v[240:243], v[72:75]
	v_mfma_f32_16x16x32_bf16 v[64:67], v[162:165], v[240:243], v[64:67]
	s_setprio 0
	s_setprio 1
	v_mfma_f32_16x16x32_bf16 v[124:127], v[176:179], v[192:195], v[124:127]
	v_mfma_f32_16x16x32_bf16 v[116:119], v[184:187], v[192:195], v[116:119]
	v_mfma_f32_16x16x32_bf16 v[108:111], v[176:179], v[200:203], v[108:111]
	v_mfma_f32_16x16x32_bf16 v[100:103], v[184:187], v[200:203], v[100:103]
	v_mfma_f32_16x16x32_bf16 v[92:95], v[176:179], v[208:211], v[92:95]
	v_mfma_f32_16x16x32_bf16 v[84:87], v[184:187], v[208:211], v[84:87]
	v_mfma_f32_16x16x32_bf16 v[76:79], v[176:179], v[216:219], v[76:79]
	v_mfma_f32_16x16x32_bf16 v[68:71], v[184:187], v[216:219], v[68:71]
	v_mfma_f32_16x16x32_bf16 v[124:127], v[180:183], v[196:199], v[124:127]
	v_mfma_f32_16x16x32_bf16 v[116:119], v[188:191], v[196:199], v[116:119]
	v_mfma_f32_16x16x32_bf16 v[108:111], v[180:183], v[204:207], v[108:111]
	v_mfma_f32_16x16x32_bf16 v[100:103], v[188:191], v[204:207], v[100:103]
	v_mfma_f32_16x16x32_bf16 v[92:95], v[180:183], v[212:215], v[92:95]
	v_mfma_f32_16x16x32_bf16 v[84:87], v[188:191], v[212:215], v[84:87]
	v_mfma_f32_16x16x32_bf16 v[76:79], v[180:183], v[240:243], v[76:79]
	v_mfma_f32_16x16x32_bf16 v[68:71], v[188:191], v[240:243], v[68:71]
	s_barrier
	s_setprio 0
	s_add_i32 s10, s10, s45
	v_lshl_add_u64 v[166:167], v[226:227], 0, s[92:93]
	s_mov_b32 m0, s10
	ds_read_b128 v[192:195], v153 offset:49152
	ds_read_b128 v[196:199], v153 offset:50176
	ds_read_b128 v[200:203], v153 offset:51200
	ds_read_b128 v[204:207], v153 offset:52224
	ds_read_b128 v[208:211], v153 offset:53248
	ds_read_b128 v[212:215], v153 offset:54272
	ds_read_b128 v[216:219], v153 offset:55296
	ds_read_b128 v[240:243], v153 offset:56320
	global_load_lds_dwordx4 v[166:167], off
	v_lshl_add_u64 v[166:167], v[244:245], 0, s[92:93]
	s_add_i32 m0, s10, 0x2000
	s_add_i32 s10, s65, s45
	global_load_lds_dwordx4 v[166:167], off
	v_lshl_add_u64 v[166:167], v[246:247], 0, s[92:93]
	s_mov_b32 m0, s10
	s_nop 0
	global_load_lds_dwordx4 v[166:167], off
	v_lshl_add_u64 v[166:167], v[220:221], 0, s[92:93]
	s_add_i32 m0, s10, 0x2000
	s_nop 0
	global_load_lds_dwordx4 v[166:167], off
	v_lshl_add_u64 v[166:167], v[248:249], 0, s[92:93]
	s_mov_b32 m0, s56
	s_nop 0
	global_load_lds_dwordx4 v[166:167], off
	v_lshl_add_u64 v[166:167], v[250:251], 0, s[92:93]
	s_mov_b32 m0, s57
	s_nop 0
	global_load_lds_dwordx4 v[166:167], off
	s_waitcnt vmcnt(8)
	s_waitcnt lgkmcnt(0)
	s_setprio 1
	s_barrier
	s_waitcnt lgkmcnt(0)
	v_mfma_f32_16x16x32_bf16 v[56:59], v[146:149], v[192:195], v[56:59]
	v_lshrrev_b32_e32 v171, 8, v170
	v_and_b32_e32 v234, 15, v170
	v_lshl_add_u32 v171, v171, 6, v234
	s_lshl_b32 s98, s64, 8
	v_add_u32_e32 v171, s98, v171
	v_mul_lo_u32 v171, v171, s28
	v_bfe_u32 v234, v170, 6, 2
	v_bfe_u32 v224, v170, 4, 2
	v_lshlrev_b32_e32 v234, 5, v234
	v_lshl_or_b32 v234, v224, 3, v234
	v_mfma_f32_16x16x32_bf16 v[48:51], v[158:161], v[192:195], v[48:51]
	s_lshl_b32 s98, s63, 7
	v_add_u32_e32 v234, s98, v234
	v_add_lshl_u32 v232, v171, v234, 1
	v_mov_b32_e32 v233, 0
	v_lshl_add_u64 v[232:233], v[232:233], 0, s[30:31]
	s_lshl_b32 s98, s28, 5
	s_mov_b32 s99, 0
	s_mov_b32 s100, 0xbfb8aa3b
	s_mov_b32 s101, 0xbfb8aa3b
	v_mul_f32_e32 v120, v172, v120
	v_mfma_f32_16x16x32_bf16 v[40:43], v[146:149], v[200:203], v[40:43]
	v_mul_f32_e32 v121, v172, v121
	v_mul_f32_e32 v122, v172, v122
	v_mul_f32_e32 v123, v172, v123
	v_mul_f32_e32 v124, v172, v124
	v_mul_f32_e32 v125, v172, v125
	v_mul_f32_e32 v126, v172, v126
	v_mul_f32_e32 v127, v172, v127
	v_mul_f32_e32 v224, s100, v120
	v_mul_f32_e32 v225, s101, v121
	v_mul_f32_e32 v228, s100, v122
	v_mfma_f32_16x16x32_bf16 v[32:35], v[158:161], v[200:203], v[32:35]
	v_mul_f32_e32 v229, s101, v123
	v_exp_f32_e32 v224, v224
	v_exp_f32_e32 v225, v225
	v_exp_f32_e32 v228, v228
	v_exp_f32_e32 v229, v229
	v_add_f32_e32 v224, 1.0, v224
	v_add_f32_e32 v225, 1.0, v225
	v_add_f32_e32 v228, 1.0, v228
	v_add_f32_e32 v229, 1.0, v229
	v_rcp_f32_e32 v224, v224
	v_mfma_f32_16x16x32_bf16 v[24:27], v[146:149], v[208:211], v[24:27]
	v_rcp_f32_e32 v225, v225
	v_rcp_f32_e32 v228, v228
	v_rcp_f32_e32 v229, v229
	v_nop
	v_mul_f32_e32 v120, v224, v120
	v_mul_f32_e32 v121, v225, v121
	v_mul_f32_e32 v122, v228, v122
	v_mul_f32_e32 v123, v229, v123
	v_mul_f32_e32 v120, v124, v120
	v_mul_f32_e32 v121, v125, v121
	v_mfma_f32_16x16x32_bf16 v[16:19], v[158:161], v[208:211], v[16:19]
	v_mul_f32_e32 v122, v126, v122
	v_mul_f32_e32 v123, v127, v123
	v_mul_f32_e32 v112, v172, v112
	v_mul_f32_e32 v113, v172, v113
	v_mul_f32_e32 v114, v172, v114
	v_mul_f32_e32 v115, v172, v115
; __device__ __forceinline__ unsigned cvt_pk_bf16(float lo, float hi) { unsigned r; asm volatile("v_cvt_pk_bf16_f32 %0, %1, %2" : "=v"(r) : "v"(lo), "v"(hi)); return r; }
; __device__ __forceinline__ float siluf_(float x) { return x * sigmoidf_(x); }
;     __device__ __forceinline__ void operator()(const f32x4 (&acc)[2][2][4][2], const Unit& u, int wr, int wc, int fr, int fq) const {
;     ...
;         for (int ai = 0; ai < 2; ++ai)
; #pragma unroll
;             for (int m = 0; m < 4; ++m) { const int row = row0 + ai * HALF + m * 16; bf16_t* rowp = O + (size_t)row * ldc + col0; const float rs = rsv[ai][m];
;                 f32x4 v0, v1;
; #pragma unroll
;                 for (int j = 0; j < 4; ++j) { v0[j] = siluf_(acc[ai][0][m][0][j] * rs) * (acc[ai][1][m][0][j] * rs); v1[j] = siluf_(acc[ai][0][m][1][j] * rs) * (acc[ai][1][m][1][j] * rs); }
;                 u32x4 w; w.x = cvt_pk_bf16(v0[0], v0[1]); w.y = cvt_pk_bf16(v0[2], v0[3]); w.z = cvt_pk_bf16(v1[0], v1[1]); w.w = cvt_pk_bf16(v1[2], v1[3]);
;                 *(u32x4*)rowp = w; }
	v_mul_f32_e32 v116, v172, v116
	v_mul_f32_e32 v117, v172, v117
	v_mul_f32_e32 v118, v172, v118
	v_mul_f32_e32 v119, v172, v119
	v_mfma_f32_16x16x32_bf16 v[8:11], v[146:149], v[216:219], v[8:11]
	v_mul_f32_e32 v224, s100, v112
	v_mul_f32_e32 v225, s101, v113
	v_mul_f32_e32 v228, s100, v114
	v_mul_f32_e32 v229, s101, v115
	v_exp_f32_e32 v224, v224
	v_exp_f32_e32 v225, v225
	v_exp_f32_e32 v228, v228
	v_exp_f32_e32 v229, v229
	v_add_f32_e32 v224, 1.0, v224
	v_add_f32_e32 v225, 1.0, v225
	v_mfma_f32_16x16x32_bf16 v[4:7], v[158:161], v[216:219], v[4:7]
	v_add_f32_e32 v228, 1.0, v228
	v_add_f32_e32 v229, 1.0, v229
	v_rcp_f32_e32 v224, v224
	v_rcp_f32_e32 v225, v225
	v_rcp_f32_e32 v228, v228
	v_rcp_f32_e32 v229, v229
	v_nop
	v_mul_f32_e32 v112, v224, v112
	v_mul_f32_e32 v113, v225, v113
	v_mul_f32_e32 v114, v228, v114
	v_mfma_f32_16x16x32_bf16 v[56:59], v[154:157], v[196:199], v[56:59]
	v_mul_f32_e32 v115, v229, v115
	v_mul_f32_e32 v112, v116, v112
	v_mul_f32_e32 v113, v117, v113
	v_mul_f32_e32 v114, v118, v114
	v_mul_f32_e32 v115, v119, v115
	v_cvt_pk_bf16_f32 v120, v120, v121
	v_cvt_pk_bf16_f32 v121, v122, v123
	v_cvt_pk_bf16_f32 v122, v112, v113
	v_cvt_pk_bf16_f32 v123, v114, v115
	global_store_dwordx4 v[232:233], v[120:123], off
	v_mfma_f32_16x16x32_bf16 v[48:51], v[162:165], v[196:199], v[48:51]
	v_lshl_add_u64 v[232:233], v[232:233], 0, s[98:99]
	v_mul_f32_e32 v104, v173, v104
	v_mul_f32_e32 v105, v173, v105
	v_mul_f32_e32 v106, v173, v106
	v_mul_f32_e32 v107, v173, v107
	v_mul_f32_e32 v108, v173, v108
	v_mul_f32_e32 v109, v173, v109
	v_mul_f32_e32 v110, v173, v110
	v_mul_f32_e32 v111, v173, v111
	v_mul_f32_e32 v224, s100, v104
	v_mfma_f32_16x16x32_bf16 v[40:43], v[154:157], v[204:207], v[40:43]
	v_mul_f32_e32 v225, s101, v105
	v_mul_f32_e32 v228, s100, v106
	v_mul_f32_e32 v229, s101, v107
	v_exp_f32_e32 v224, v224
	v_exp_f32_e32 v225, v225
	v_exp_f32_e32 v228, v228
	v_exp_f32_e32 v229, v229
	v_add_f32_e32 v224, 1.0, v224
	v_add_f32_e32 v225, 1.0, v225
	v_add_f32_e32 v228, 1.0, v228
	v_mfma_f32_16x16x32_bf16 v[32:35], v[162:165], v[204:207], v[32:35]
	v_add_f32_e32 v229, 1.0, v229
	v_rcp_f32_e32 v224, v224
	v_rcp_f32_e32 v225, v225
	v_rcp_f32_e32 v228, v228
	v_rcp_f32_e32 v229, v229
	v_nop
	v_mul_f32_e32 v104, v224, v104
	v_mul_f32_e32 v105, v225, v105
	v_mul_f32_e32 v106, v228, v106
	v_mul_f32_e32 v107, v229, v107
	v_mfma_f32_16x16x32_bf16 v[24:27], v[154:157], v[212:215], v[24:27]
	v_mul_f32_e32 v104, v108, v104
	v_mul_f32_e32 v105, v109, v105
	v_mul_f32_e32 v106, v110, v106
	v_mul_f32_e32 v107, v111, v107
	v_mul_f32_e32 v96, v173, v96
	v_mul_f32_e32 v97, v173, v97
	v_mul_f32_e32 v98, v173, v98
	v_mul_f32_e32 v99, v173, v99
	v_mul_f32_e32 v100, v173, v100
	v_mul_f32_e32 v101, v173, v101
	v_mfma_f32_16x16x32_bf16 v[16:19], v[162:165], v[212:215], v[16:19]
	v_mul_f32_e32 v102, v173, v102
	v_mul_f32_e32 v103, v173, v103
	v_mul_f32_e32 v224, s100, v96
	v_mul_f32_e32 v225, s101, v97
	v_mul_f32_e32 v228, s100, v98
	v_mul_f32_e32 v229, s101, v99
	v_exp_f32_e32 v224, v224
	v_exp_f32_e32 v225, v225
	v_exp_f32_e32 v228, v228
	v_exp_f32_e32 v229, v229
	v_mfma_f32_16x16x32_bf16 v[8:11], v[154:157], v[240:243], v[8:11]
	v_add_f32_e32 v224, 1.0, v224
	v_add_f32_e32 v225, 1.0, v225
	v_add_f32_e32 v228, 1.0, v228
	v_add_f32_e32 v229, 1.0, v229
	v_rcp_f32_e32 v224, v224
	v_rcp_f32_e32 v225, v225
	v_rcp_f32_e32 v228, v228
	v_rcp_f32_e32 v229, v229
	v_nop
	v_mul_f32_e32 v96, v224, v96
	v_mfma_f32_16x16x32_bf16 v[4:7], v[162:165], v[240:243], v[4:7]
	v_mul_f32_e32 v97, v225, v97
	v_mul_f32_e32 v98, v228, v98
	v_mul_f32_e32 v99, v229, v99
	v_mul_f32_e32 v96, v100, v96
	v_mul_f32_e32 v97, v101, v97
	v_mul_f32_e32 v98, v102, v98
	v_mul_f32_e32 v99, v103, v99
	v_cvt_pk_bf16_f32 v104, v104, v105
	v_cvt_pk_bf16_f32 v105, v106, v107
	v_cvt_pk_bf16_f32 v106, v96, v97
	s_setprio 0
	s_setprio 1
	v_mfma_f32_16x16x32_bf16 v[60:63], v[176:179], v[192:195], v[60:63]
	v_cvt_pk_bf16_f32 v107, v98, v99
	global_store_dwordx4 v[232:233], v[104:107], off
	v_lshl_add_u64 v[232:233], v[232:233], 0, s[98:99]
	v_mul_f32_e32 v88, v236, v88
	v_mul_f32_e32 v89, v236, v89
	v_mul_f32_e32 v90, v236, v90
	v_mul_f32_e32 v91, v236, v91
	v_mul_f32_e32 v92, v236, v92
	v_mul_f32_e32 v93, v236, v93
	v_mul_f32_e32 v94, v236, v94
	v_mfma_f32_16x16x32_bf16 v[52:55], v[184:187], v[192:195], v[52:55]
	v_mul_f32_e32 v95, v236, v95
	v_mul_f32_e32 v224, s100, v88
	v_mul_f32_e32 v225, s101, v89
	v_mul_f32_e32 v228, s100, v90
	v_mul_f32_e32 v229, s101, v91
	v_exp_f32_e32 v224, v224
	v_exp_f32_e32 v225, v225
	v_exp_f32_e32 v228, v228
	v_exp_f32_e32 v229, v229
	v_add_f32_e32 v224, 1.0, v224
	v_mfma_f32_16x16x32_bf16 v[44:47], v[176:179], v[200:203], v[44:47]
	v_add_f32_e32 v225, 1.0, v225
	v_add_f32_e32 v228, 1.0, v228
	v_add_f32_e32 v229, 1.0, v229
	v_rcp_f32_e32 v224, v224
	v_rcp_f32_e32 v225, v225
	v_rcp_f32_e32 v228, v228
	v_rcp_f32_e32 v229, v229
	v_nop
	v_mul_f32_e32 v88, v224, v88
	v_mul_f32_e32 v89, v225, v89
; __device__ __forceinline__ unsigned cvt_pk_bf16(float lo, float hi) { unsigned r; asm volatile("v_cvt_pk_bf16_f32 %0, %1, %2" : "=v"(r) : "v"(lo), "v"(hi)); return r; }
; __device__ __forceinline__ float siluf_(float x) { return x * sigmoidf_(x); }
; #define PG8_BAR __builtin_amdgcn_s_barrier()
;     __device__ __forceinline__ void operator()(const f32x4 (&acc)[2][2][4][2], const Unit& u, int wr, int wc, int fr, int fq) const {
;     ...
;             for (int m = 0; m < 4; ++m) { const int row = row0 + ai * HALF + m * 16; bf16_t* rowp = O + (size_t)row * ldc + col0; const float rs = rsv[ai][m];
;                 f32x4 v0, v1;
; #pragma unroll
;                 for (int j = 0; j < 4; ++j) { v0[j] = siluf_(acc[ai][0][m][0][j] * rs) * (acc[ai][1][m][0][j] * rs); v1[j] = siluf_(acc[ai][0][m][1][j] * rs) * (acc[ai][1][m][1][j] * rs); }
;                 u32x4 w; w.x = cvt_pk_bf16(v0[0], v0[1]); w.y = cvt_pk_bf16(v0[2], v0[3]); w.z = cvt_pk_bf16(v1[0], v1[1]); w.w = cvt_pk_bf16(v1[2], v1[3]);
;                 *(u32x4*)rowp = w; }
; template <class Epi, bool ALIGN_EPI>
; __device__ __forceinline__ void gemm_phase(LAS unsigned char* lds, const Gemm g, const StaticOrder& S, const Epi& E, const int tid) {
;     ...
;         { int t2 = tid; asm volatile("" : "+v"(t2)); const int l2 = t2 & 63, w2 = __builtin_amdgcn_readfirstlane(t2 >> 6); E(acc, cur, w2 >> 2, w2 & 3, l2 & 15, l2 >> 4); }
;         if (!has_next) break;
; #pragma unroll
;         for (int a = 0; a < 2; ++a)
; #pragma unroll
;             for (int b = 0; b < 2; ++b)
; #pragma unroll
;                 for (int m = 0; m < 4; ++m)
; #pragma unroll
;                     for (int n = 0; n < 2; ++n) acc[a][b][m][n] = (f32x4){0.f, 0.f, 0.f, 0.f};
;         cur = nxt; cA = nA; cB = nB; ++ui;
;         if constexpr (ALIGN_EPI) { if (wr == 1) PG8_BAR; }
	v_mfma_f32_16x16x32_bf16 v[36:39], v[184:187], v[200:203], v[36:39]
	v_mul_f32_e32 v90, v228, v90
	v_mul_f32_e32 v91, v229, v91
	v_mul_f32_e32 v88, v92, v88
	v_mul_f32_e32 v89, v93, v89
	v_mul_f32_e32 v90, v94, v90
	v_mul_f32_e32 v91, v95, v91
	v_mul_f32_e32 v80, v236, v80
	v_mul_f32_e32 v81, v236, v81
	v_mul_f32_e32 v82, v236, v82
	v_mul_f32_e32 v83, v236, v83
	v_mfma_f32_16x16x32_bf16 v[28:31], v[176:179], v[208:211], v[28:31]
	v_mul_f32_e32 v84, v236, v84
	v_mul_f32_e32 v85, v236, v85
	v_mul_f32_e32 v86, v236, v86
	v_mul_f32_e32 v87, v236, v87
	v_mul_f32_e32 v224, s100, v80
	v_mul_f32_e32 v225, s101, v81
	v_mul_f32_e32 v228, s100, v82
	v_mul_f32_e32 v229, s101, v83
	v_exp_f32_e32 v224, v224
	v_exp_f32_e32 v225, v225
	v_mfma_f32_16x16x32_bf16 v[20:23], v[184:187], v[208:211], v[20:23]
	v_exp_f32_e32 v228, v228
	v_exp_f32_e32 v229, v229
	v_add_f32_e32 v224, 1.0, v224
	v_add_f32_e32 v225, 1.0, v225
	v_add_f32_e32 v228, 1.0, v228
	v_add_f32_e32 v229, 1.0, v229
	v_rcp_f32_e32 v224, v224
	v_rcp_f32_e32 v225, v225
	v_rcp_f32_e32 v228, v228
	v_rcp_f32_e32 v229, v229
	v_mfma_f32_16x16x32_bf16 v[12:15], v[176:179], v[216:219], v[12:15]
	v_nop
	v_mul_f32_e32 v80, v224, v80
	v_mul_f32_e32 v81, v225, v81
	v_mul_f32_e32 v82, v228, v82
	v_mul_f32_e32 v83, v229, v83
	v_mul_f32_e32 v80, v84, v80
	v_mul_f32_e32 v81, v85, v81
	v_mul_f32_e32 v82, v86, v82
	v_mul_f32_e32 v83, v87, v83
	v_cvt_pk_bf16_f32 v88, v88, v89
	v_mfma_f32_16x16x32_bf16 v[0:3], v[184:187], v[216:219], v[0:3]
	v_cvt_pk_bf16_f32 v89, v90, v91
	v_cvt_pk_bf16_f32 v90, v80, v81
	v_cvt_pk_bf16_f32 v91, v82, v83
	global_store_dwordx4 v[232:233], v[88:91], off
	v_lshl_add_u64 v[232:233], v[232:233], 0, s[98:99]
	v_mul_f32_e32 v72, v237, v72
	v_mul_f32_e32 v73, v237, v73
	v_mul_f32_e32 v74, v237, v74
	v_mul_f32_e32 v75, v237, v75
	v_mul_f32_e32 v76, v237, v76
	v_mfma_f32_16x16x32_bf16 v[60:63], v[180:183], v[196:199], v[60:63]
	v_mul_f32_e32 v77, v237, v77
	v_mul_f32_e32 v78, v237, v78
	v_mul_f32_e32 v79, v237, v79
	v_mul_f32_e32 v224, s100, v72
	v_mul_f32_e32 v225, s101, v73
	v_mul_f32_e32 v228, s100, v74
	v_mul_f32_e32 v229, s101, v75
	v_exp_f32_e32 v224, v224
	v_exp_f32_e32 v225, v225
	v_exp_f32_e32 v228, v228
	v_mfma_f32_16x16x32_bf16 v[52:55], v[188:191], v[196:199], v[52:55]
	v_exp_f32_e32 v229, v229
	v_add_f32_e32 v224, 1.0, v224
	v_add_f32_e32 v225, 1.0, v225
	v_add_f32_e32 v228, 1.0, v228
	v_add_f32_e32 v229, 1.0, v229
	v_rcp_f32_e32 v224, v224
	v_rcp_f32_e32 v225, v225
	v_rcp_f32_e32 v228, v228
	v_rcp_f32_e32 v229, v229
	v_nop
	v_mfma_f32_16x16x32_bf16 v[44:47], v[180:183], v[204:207], v[44:47]
	v_mul_f32_e32 v72, v224, v72
	v_mul_f32_e32 v73, v225, v73
	v_mul_f32_e32 v74, v228, v74
	v_mul_f32_e32 v75, v229, v75
	v_mul_f32_e32 v72, v76, v72
	v_mul_f32_e32 v73, v77, v73
	v_mul_f32_e32 v74, v78, v74
	v_mul_f32_e32 v75, v79, v75
	v_mul_f32_e32 v64, v237, v64
	v_mul_f32_e32 v65, v237, v65
	v_mfma_f32_16x16x32_bf16 v[36:39], v[188:191], v[204:207], v[36:39]
	v_mul_f32_e32 v66, v237, v66
	v_mul_f32_e32 v67, v237, v67
	v_mul_f32_e32 v68, v237, v68
	v_mul_f32_e32 v69, v237, v69
	v_mul_f32_e32 v70, v237, v70
	v_mul_f32_e32 v71, v237, v71
	v_mul_f32_e32 v224, s100, v64
	v_mul_f32_e32 v225, s101, v65
	v_mul_f32_e32 v228, s100, v66
	v_mul_f32_e32 v229, s101, v67
	v_mfma_f32_16x16x32_bf16 v[28:31], v[180:183], v[212:215], v[28:31]
	v_exp_f32_e32 v224, v224
	v_exp_f32_e32 v225, v225
	v_exp_f32_e32 v228, v228
	v_exp_f32_e32 v229, v229
	v_add_f32_e32 v224, 1.0, v224
	v_add_f32_e32 v225, 1.0, v225
	v_add_f32_e32 v228, 1.0, v228
	v_add_f32_e32 v229, 1.0, v229
	v_rcp_f32_e32 v224, v224
	v_rcp_f32_e32 v225, v225
	v_mfma_f32_16x16x32_bf16 v[20:23], v[188:191], v[212:215], v[20:23]
	v_rcp_f32_e32 v228, v228
	v_rcp_f32_e32 v229, v229
	v_nop
	v_mul_f32_e32 v64, v224, v64
	v_mul_f32_e32 v65, v225, v65
	v_mul_f32_e32 v66, v228, v66
	v_mul_f32_e32 v67, v229, v67
	v_mul_f32_e32 v64, v68, v64
	v_mul_f32_e32 v65, v69, v65
	v_mul_f32_e32 v66, v70, v66
	v_mfma_f32_16x16x32_bf16 v[12:15], v[180:183], v[240:243], v[12:15]
	v_mul_f32_e32 v67, v71, v67
	v_cvt_pk_bf16_f32 v72, v72, v73
	v_cvt_pk_bf16_f32 v73, v74, v75
	v_cvt_pk_bf16_f32 v74, v64, v65
	v_cvt_pk_bf16_f32 v75, v66, v67
	global_store_dwordx4 v[232:233], v[72:75], off
	v_lshl_add_u64 v[232:233], v[232:233], 0, s[98:99]
	v_lshl_add_u64 v[232:233], v[232:233], 0, s[98:99]
	v_lshl_add_u64 v[232:233], v[232:233], 0, s[98:99]
	v_lshl_add_u64 v[232:233], v[232:233], 0, s[98:99]
	v_mfma_f32_16x16x32_bf16 v[0:3], v[188:191], v[240:243], v[0:3]
	v_lshl_add_u64 v[232:233], v[232:233], 0, s[98:99]
	s_barrier
	s_setprio 0
	v_lshl_add_u64 v[142:143], v[142:143], 0, s[80:81]
	v_lshl_add_u64 v[144:145], v[144:145], 0, s[80:81]
	s_and_b64 vcc, exec, s[8:9]
	s_cbranch_vccnz .Lgu_notdefer
	s_cmp_lg_u32 s62, s64
	s_cbranch_scc1 .Lgu_notdefer
	s_mov_b32 s101, 1
	s_mov_b32 s63, s61
	s_mov_b32 s64, s62
	v_mov_b64_e32 v[144:145], v[140:141]
	v_mov_b64_e32 v[142:143], v[138:139]
	s_branch .LBB0_300

; #define PG8_STAGE(bufoff, gbase, voff) do { _Pragma("unroll") for (int _i = 0; _i < 2; ++_i) \
;         __builtin_amdgcn_global_load_lds((const unsigned*)((const char*)(gbase) + (voff)[_i]), (LAS unsigned*)(lds + (bufoff) + ldsw + _i * 8192), 16, 0, 0); } while (0)
; #define PG8_LDA(dst, b, h) do { _Pragma("unroll") for (int m = 0; m < 4; ++m) _Pragma("unroll") for (int k = 0; k < 2; ++k) dst[m][k] = *(const LAS bf16x8*)(lds + PG8_SA(b, h) + aoff + m * 2048 + k * 1024); } while (0)
; #define PG8_LDB(dst, b, h) do { _Pragma("unroll") for (int n = 0; n < 2; ++n) _Pragma("unroll") for (int k = 0; k < 2; ++k) dst[n][k] = *(const LAS bf16x8*)(lds + PG8_SB(b, h) + boff + n * 2048 + k * 1024); } while (0)
; #define PG8_MMA(ai, bj, At, Bt) do { __builtin_amdgcn_s_setprio(1); _Pragma("unroll") for (int k = 0; k < 2; ++k) _Pragma("unroll") for (int m = 0; m < 4; ++m) _Pragma("unroll") for (int n = 0; n < 2; ++n) \
;         acc[ai][bj][m][n] = __builtin_amdgcn_mfma_f32_16x16x32_bf16(Bt[n][k], At[m][k], acc[ai][bj][m][n], 0, 0, 0); __builtin_amdgcn_s_setprio(0); } while (0)
; #define PG8_WAIT_V(n) asm volatile("s_waitcnt vmcnt(" #n ")" ::: "memory")
; #define PG8_WAIT_L(n) asm volatile("s_waitcnt lgkmcnt(" #n ")" ::: "memory")
; #define PG8_BAR __builtin_amdgcn_s_barrier()
; #define PG8_SCHED __builtin_amdgcn_sched_barrier(0)
; template <class Epi, bool ALIGN_EPI>
; __device__ __forceinline__ void gemm_phase(LAS unsigned char* lds, const Gemm g, const StaticOrder& S, const Epi& E, const int tid) {
;     ...
;             PG8_LDB(B0, 0, 0); PG8_LDB(B1, 0, 1); PG8_SCHED; PG8_LDA(At, 0, 0); PG8_STAGE(PG8_SA(1, 1), a1 + hA, voffA);
;             PG8_WAIT_V(8); PG8_WAIT_L(0); PG8_BAR; PG8_MMA(0, 0, At, B0); PG8_MMA(0, 1, At, B1); PG8_BAR; PG8_SCHED;
;             PG8_LDA(At, 0, 1); PG8_STAGE(PG8_SB(0, 0), b2, voffB); PG8_STAGE(PG8_SB(0, 1), b2 + hB, voffB); PG8_STAGE(PG8_SA(0, 0), a2, voffA);
;             PG8_WAIT_V(8); PG8_WAIT_L(0); PG8_BAR; PG8_MMA(1, 0, At, B0); PG8_MMA(1, 1, At, B1); PG8_BAR; PG8_SCHED;
.LBB0_329:
	s_andn2_b64 vcc, exec, s[36:37]
	s_cbranch_vccnz .LBB0_332
	v_lshl_add_u64 v[142:143], v[142:143], 0, s[92:93]
	v_lshl_add_u64 v[144:145], v[144:145], 0, s[80:81]
	s_mov_b32 s10, 0
	s_add_i32 s11, s10, 2
	s_cmp_eq_u32 s58, s10
	v_lshl_add_u64 v[146:147], v[142:143], 0, s[92:93]
	s_cselect_b64 vcc, -1, 0
	v_add_u32_e32 v152, s33, v153
	s_add_i32 s10, 0, 0x14000
	v_cndmask_b32_e32 v151, v147, v139, vcc
	v_cndmask_b32_e32 v150, v146, v138, vcc
	ds_read_b128 v[146:149], v152
	ds_read_b128 v[156:159], v152 offset:1024
	ds_read_b128 v[160:163], v152 offset:2048
	ds_read_b128 v[164:167], v152 offset:3072
	v_add_u32_e32 v152, s10, v153
	ds_read_b128 v[176:179], v152
	ds_read_b128 v[180:183], v152 offset:1024
	ds_read_b128 v[184:187], v152 offset:2048
	ds_read_b128 v[188:191], v152 offset:3072
	v_cndmask_b32_e32 v221, v145, v141, vcc
	v_cndmask_b32_e32 v220, v144, v140, vcc
	v_lshl_add_u64 v[226:227], v[142:143], 0, v[134:135]
	s_add_i32 m0, s51, 0xc000
	ds_read_b128 v[192:195], v155
	ds_read_b128 v[196:199], v155 offset:1024
	ds_read_b128 v[200:203], v155 offset:2048
	ds_read_b128 v[204:207], v155 offset:3072
	ds_read_b128 v[208:211], v155 offset:4096
	ds_read_b128 v[212:215], v155 offset:5120
	ds_read_b128 v[216:219], v155 offset:6144
	ds_read_b128 v[240:243], v155 offset:7168
	global_load_lds_dwordx4 v[226:227], off
	v_lshl_add_u64 v[226:227], v[142:143], 0, v[136:137]
	s_add_i32 m0, s51, 0xe000
	s_nop 0
	global_load_lds_dwordx4 v[226:227], off
	s_waitcnt vmcnt(8)
	s_waitcnt lgkmcnt(0)
	s_setprio 1
	s_barrier
	s_waitcnt lgkmcnt(0)
	v_mfma_f32_16x16x32_bf16 v[120:123], v[146:149], v[192:195], 0
	v_mfma_f32_16x16x32_bf16 v[124:127], v[160:163], v[192:195], 0
	v_mfma_f32_16x16x32_bf16 v[108:111], v[146:149], v[200:203], 0
	v_mfma_f32_16x16x32_bf16 v[104:107], v[160:163], v[200:203], 0
	v_mfma_f32_16x16x32_bf16 v[92:95], v[146:149], v[208:211], 0
	v_mfma_f32_16x16x32_bf16 v[88:91], v[160:163], v[208:211], 0
	v_mfma_f32_16x16x32_bf16 v[76:79], v[146:149], v[216:219], 0
	v_mfma_f32_16x16x32_bf16 v[72:75], v[160:163], v[216:219], 0
	v_mfma_f32_16x16x32_bf16 v[120:123], v[156:159], v[196:199], v[120:123]
	v_mfma_f32_16x16x32_bf16 v[124:127], v[164:167], v[196:199], v[124:127]
	v_mfma_f32_16x16x32_bf16 v[108:111], v[156:159], v[204:207], v[108:111]
	v_mfma_f32_16x16x32_bf16 v[104:107], v[164:167], v[204:207], v[104:107]
	v_mfma_f32_16x16x32_bf16 v[92:95], v[156:159], v[212:215], v[92:95]
	v_mfma_f32_16x16x32_bf16 v[88:91], v[164:167], v[212:215], v[88:91]
	v_mfma_f32_16x16x32_bf16 v[76:79], v[156:159], v[240:243], v[76:79]
	v_mfma_f32_16x16x32_bf16 v[72:75], v[164:167], v[240:243], v[72:75]
	s_setprio 0
	s_setprio 1
	v_mfma_f32_16x16x32_bf16 v[116:119], v[176:179], v[192:195], 0
	v_mfma_f32_16x16x32_bf16 v[112:115], v[184:187], v[192:195], 0
	v_mfma_f32_16x16x32_bf16 v[100:103], v[176:179], v[200:203], 0
	v_mfma_f32_16x16x32_bf16 v[96:99], v[184:187], v[200:203], 0
	v_mfma_f32_16x16x32_bf16 v[84:87], v[176:179], v[208:211], 0
	v_mfma_f32_16x16x32_bf16 v[80:83], v[184:187], v[208:211], 0
	v_mfma_f32_16x16x32_bf16 v[68:71], v[176:179], v[216:219], 0
	v_mfma_f32_16x16x32_bf16 v[64:67], v[184:187], v[216:219], 0
	v_mfma_f32_16x16x32_bf16 v[116:119], v[180:183], v[196:199], v[116:119]
	v_mfma_f32_16x16x32_bf16 v[112:115], v[188:191], v[196:199], v[112:115]
	v_mfma_f32_16x16x32_bf16 v[100:103], v[180:183], v[204:207], v[100:103]
	v_mfma_f32_16x16x32_bf16 v[96:99], v[188:191], v[204:207], v[96:99]
	v_mfma_f32_16x16x32_bf16 v[84:87], v[180:183], v[212:215], v[84:87]
	v_mfma_f32_16x16x32_bf16 v[80:83], v[188:191], v[212:215], v[80:83]
	v_mfma_f32_16x16x32_bf16 v[68:71], v[180:183], v[240:243], v[68:71]
	v_mfma_f32_16x16x32_bf16 v[64:67], v[188:191], v[240:243], v[64:67]
	s_barrier
	s_setprio 0
	s_add_i32 s65, s33, s45
	v_lshl_add_u64 v[226:227], v[220:221], 0, v[168:169]
	s_mov_b32 m0, s65
	ds_read_b128 v[192:195], v155 offset:16384
	ds_read_b128 v[196:199], v155 offset:17408
	ds_read_b128 v[200:203], v155 offset:18432
	ds_read_b128 v[204:207], v155 offset:19456
	ds_read_b128 v[208:211], v155 offset:20480
	ds_read_b128 v[212:215], v155 offset:21504
	ds_read_b128 v[216:219], v155 offset:22528
	ds_read_b128 v[240:243], v155 offset:23552
	global_load_lds_dwordx4 v[226:227], off
	v_lshl_add_u64 v[244:245], v[220:221], 0, v[128:129]
	s_add_i32 m0, s65, 0x2000
	v_lshl_add_u64 v[220:221], v[220:221], 0, s[12:13]
	s_add_i32 s10, s10, s45
	global_load_lds_dwordx4 v[244:245], off
	v_lshl_add_u64 v[246:247], v[220:221], 0, v[168:169]
	s_mov_b32 m0, s10
	v_lshl_add_u64 v[220:221], v[220:221], 0, v[128:129]
	global_load_lds_dwordx4 v[246:247], off
	s_add_i32 m0, s10, 0x2000
	v_lshl_add_u64 v[248:249], v[150:151], 0, v[132:133]
	global_load_lds_dwordx4 v[220:221], off
	s_mov_b32 m0, s51
	v_lshl_add_u64 v[250:251], v[150:151], 0, v[130:131]
	global_load_lds_dwordx4 v[248:249], off
	s_mov_b32 m0, s52
	s_nop 0
	global_load_lds_dwordx4 v[250:251], off
	s_waitcnt vmcnt(8)
	s_waitcnt lgkmcnt(0)
	s_setprio 1
	s_barrier
; #define PG8_STAGE(bufoff, gbase, voff) do { _Pragma("unroll") for (int _i = 0; _i < 2; ++_i) \
;         __builtin_amdgcn_global_load_lds((const unsigned*)((const char*)(gbase) + (voff)[_i]), (LAS unsigned*)(lds + (bufoff) + ldsw + _i * 8192), 16, 0, 0); } while (0)
; #define PG8_LDA(dst, b, h) do { _Pragma("unroll") for (int m = 0; m < 4; ++m) _Pragma("unroll") for (int k = 0; k < 2; ++k) dst[m][k] = *(const LAS bf16x8*)(lds + PG8_SA(b, h) + aoff + m * 2048 + k * 1024); } while (0)
; #define PG8_LDB(dst, b, h) do { _Pragma("unroll") for (int n = 0; n < 2; ++n) _Pragma("unroll") for (int k = 0; k < 2; ++k) dst[n][k] = *(const LAS bf16x8*)(lds + PG8_SB(b, h) + boff + n * 2048 + k * 1024); } while (0)
; #define PG8_MMA(ai, bj, At, Bt) do { __builtin_amdgcn_s_setprio(1); _Pragma("unroll") for (int k = 0; k < 2; ++k) _Pragma("unroll") for (int m = 0; m < 4; ++m) _Pragma("unroll") for (int n = 0; n < 2; ++n) \
;         acc[ai][bj][m][n] = __builtin_amdgcn_mfma_f32_16x16x32_bf16(Bt[n][k], At[m][k], acc[ai][bj][m][n], 0, 0, 0); __builtin_amdgcn_s_setprio(0); } while (0)
; #define PG8_WAIT_V(n) asm volatile("s_waitcnt vmcnt(" #n ")" ::: "memory")
; #define PG8_WAIT_L(n) asm volatile("s_waitcnt lgkmcnt(" #n ")" ::: "memory")
; #define PG8_BAR __builtin_amdgcn_s_barrier()
; #define PG8_SCHED __builtin_amdgcn_sched_barrier(0)
; template <class Epi, bool ALIGN_EPI>
; __device__ __forceinline__ void gemm_phase(LAS unsigned char* lds, const Gemm g, const StaticOrder& S, const Epi& E, const int tid) {
;     ...
;             PG8_WAIT_V(8); PG8_WAIT_L(0); PG8_BAR; PG8_MMA(1, 0, At, B0); PG8_MMA(1, 1, At, B1); PG8_BAR; PG8_SCHED;
;             PG8_LDB(B0, 1, 0); PG8_LDB(B1, 1, 1); PG8_SCHED; PG8_LDA(At, 1, 0); PG8_STAGE(PG8_SA(0, 1), a2 + hA, voffA);
;             PG8_WAIT_V(8); PG8_WAIT_L(0); PG8_BAR; PG8_MMA(0, 0, At, B0); PG8_MMA(0, 1, At, B1); PG8_BAR; PG8_SCHED;
	s_waitcnt lgkmcnt(0)
	v_mfma_f32_16x16x32_bf16 v[60:63], v[146:149], v[192:195], 0
	v_mfma_f32_16x16x32_bf16 v[56:59], v[160:163], v[192:195], 0
	v_mfma_f32_16x16x32_bf16 v[44:47], v[146:149], v[200:203], 0
	v_mfma_f32_16x16x32_bf16 v[40:43], v[160:163], v[200:203], 0
	v_mfma_f32_16x16x32_bf16 v[28:31], v[146:149], v[208:211], 0
	v_mfma_f32_16x16x32_bf16 v[24:27], v[160:163], v[208:211], 0
	v_mfma_f32_16x16x32_bf16 v[12:15], v[146:149], v[216:219], 0
	v_mfma_f32_16x16x32_bf16 v[8:11], v[160:163], v[216:219], 0
	v_mfma_f32_16x16x32_bf16 v[60:63], v[156:159], v[196:199], v[60:63]
	v_mfma_f32_16x16x32_bf16 v[56:59], v[164:167], v[196:199], v[56:59]
	v_mfma_f32_16x16x32_bf16 v[44:47], v[156:159], v[204:207], v[44:47]
	v_mfma_f32_16x16x32_bf16 v[40:43], v[164:167], v[204:207], v[40:43]
	v_mfma_f32_16x16x32_bf16 v[28:31], v[156:159], v[212:215], v[28:31]
	v_mfma_f32_16x16x32_bf16 v[24:27], v[164:167], v[212:215], v[24:27]
	v_mfma_f32_16x16x32_bf16 v[12:15], v[156:159], v[240:243], v[12:15]
	v_mfma_f32_16x16x32_bf16 v[8:11], v[164:167], v[240:243], v[8:11]
	s_setprio 0
	s_setprio 1
	v_mfma_f32_16x16x32_bf16 v[52:55], v[176:179], v[192:195], 0
	v_mfma_f32_16x16x32_bf16 v[48:51], v[184:187], v[192:195], 0
	v_mfma_f32_16x16x32_bf16 v[36:39], v[176:179], v[200:203], 0
	v_mfma_f32_16x16x32_bf16 v[32:35], v[184:187], v[200:203], 0
	v_mfma_f32_16x16x32_bf16 v[20:23], v[176:179], v[208:211], 0
	v_mfma_f32_16x16x32_bf16 v[16:19], v[184:187], v[208:211], 0
	v_mfma_f32_16x16x32_bf16 v[4:7], v[176:179], v[216:219], 0
	v_mfma_f32_16x16x32_bf16 v[0:3], v[184:187], v[216:219], 0
	v_mfma_f32_16x16x32_bf16 v[52:55], v[180:183], v[196:199], v[52:55]
	v_mfma_f32_16x16x32_bf16 v[48:51], v[188:191], v[196:199], v[48:51]
	v_mfma_f32_16x16x32_bf16 v[36:39], v[180:183], v[204:207], v[36:39]
	v_mfma_f32_16x16x32_bf16 v[32:35], v[188:191], v[204:207], v[32:35]
	v_mfma_f32_16x16x32_bf16 v[20:23], v[180:183], v[212:215], v[20:23]
	v_mfma_f32_16x16x32_bf16 v[16:19], v[188:191], v[212:215], v[16:19]
	v_mfma_f32_16x16x32_bf16 v[4:7], v[180:183], v[240:243], v[4:7]
	v_mfma_f32_16x16x32_bf16 v[0:3], v[188:191], v[240:243], v[0:3]
	s_barrier
	s_setprio 0
	s_add_i32 s10, 0, 0x18000
	v_add_u32_e32 v152, s10, v153
	s_add_i32 s65, 0, 0x1c000
	ds_read_b128 v[146:149], v152
	ds_read_b128 v[156:159], v152 offset:1024
	ds_read_b128 v[160:163], v152 offset:2048
	ds_read_b128 v[164:167], v152 offset:3072
	v_add_u32_e32 v152, s65, v153
	ds_read_b128 v[176:179], v152
	ds_read_b128 v[180:183], v152 offset:1024
	ds_read_b128 v[184:187], v152 offset:2048
	ds_read_b128 v[188:191], v152 offset:3072
	v_lshl_add_u64 v[150:151], v[150:151], 0, s[94:95]
	s_mov_b32 m0, s53
	v_lshl_add_u64 v[252:253], v[150:151], 0, v[132:133]
	ds_read_b128 v[192:195], v155 offset:32768
	ds_read_b128 v[196:199], v155 offset:33792
	ds_read_b128 v[200:203], v155 offset:34816
	ds_read_b128 v[204:207], v155 offset:35840
	ds_read_b128 v[208:211], v155 offset:36864
	ds_read_b128 v[212:215], v155 offset:37888
	ds_read_b128 v[216:219], v155 offset:38912
	ds_read_b128 v[240:243], v155 offset:39936
	global_load_lds_dwordx4 v[252:253], off
	v_lshl_add_u64 v[150:151], v[150:151], 0, v[130:131]
	s_mov_b32 m0, s54
	s_nop 0
	global_load_lds_dwordx4 v[150:151], off
	s_waitcnt vmcnt(8)
	s_waitcnt lgkmcnt(0)
	s_setprio 1
	s_barrier
	s_waitcnt lgkmcnt(0)
	v_mfma_f32_16x16x32_bf16 v[120:123], v[146:149], v[192:195], v[120:123]
	v_mfma_f32_16x16x32_bf16 v[124:127], v[160:163], v[192:195], v[124:127]
	v_mfma_f32_16x16x32_bf16 v[108:111], v[146:149], v[200:203], v[108:111]
	v_mfma_f32_16x16x32_bf16 v[104:107], v[160:163], v[200:203], v[104:107]
	v_mfma_f32_16x16x32_bf16 v[92:95], v[146:149], v[208:211], v[92:95]
	v_mfma_f32_16x16x32_bf16 v[88:91], v[160:163], v[208:211], v[88:91]
	v_mfma_f32_16x16x32_bf16 v[76:79], v[146:149], v[216:219], v[76:79]
	v_mfma_f32_16x16x32_bf16 v[72:75], v[160:163], v[216:219], v[72:75]
	v_mfma_f32_16x16x32_bf16 v[120:123], v[156:159], v[196:199], v[120:123]
	v_mfma_f32_16x16x32_bf16 v[124:127], v[164:167], v[196:199], v[124:127]
	v_mfma_f32_16x16x32_bf16 v[108:111], v[156:159], v[204:207], v[108:111]
	v_mfma_f32_16x16x32_bf16 v[104:107], v[164:167], v[204:207], v[104:107]
	v_mfma_f32_16x16x32_bf16 v[92:95], v[156:159], v[212:215], v[92:95]
	v_mfma_f32_16x16x32_bf16 v[88:91], v[164:167], v[212:215], v[88:91]
	v_mfma_f32_16x16x32_bf16 v[76:79], v[156:159], v[240:243], v[76:79]
	v_mfma_f32_16x16x32_bf16 v[72:75], v[164:167], v[240:243], v[72:75]
	s_setprio 0
	s_setprio 1
	v_mfma_f32_16x16x32_bf16 v[116:119], v[176:179], v[192:195], v[116:119]
	v_mfma_f32_16x16x32_bf16 v[112:115], v[184:187], v[192:195], v[112:115]
	v_mfma_f32_16x16x32_bf16 v[100:103], v[176:179], v[200:203], v[100:103]
	v_mfma_f32_16x16x32_bf16 v[96:99], v[184:187], v[200:203], v[96:99]
	v_mfma_f32_16x16x32_bf16 v[84:87], v[176:179], v[208:211], v[84:87]
	v_mfma_f32_16x16x32_bf16 v[80:83], v[184:187], v[208:211], v[80:83]
	v_mfma_f32_16x16x32_bf16 v[68:71], v[176:179], v[216:219], v[68:71]
	v_mfma_f32_16x16x32_bf16 v[64:67], v[184:187], v[216:219], v[64:67]
	v_mfma_f32_16x16x32_bf16 v[116:119], v[180:183], v[196:199], v[116:119]
	v_mfma_f32_16x16x32_bf16 v[112:115], v[188:191], v[196:199], v[112:115]
	v_mfma_f32_16x16x32_bf16 v[100:103], v[180:183], v[204:207], v[100:103]
	v_mfma_f32_16x16x32_bf16 v[96:99], v[188:191], v[204:207], v[96:99]
	v_mfma_f32_16x16x32_bf16 v[84:87], v[180:183], v[212:215], v[84:87]
	v_mfma_f32_16x16x32_bf16 v[80:83], v[188:191], v[212:215], v[80:83]
	v_mfma_f32_16x16x32_bf16 v[68:71], v[180:183], v[240:243], v[68:71]
	v_mfma_f32_16x16x32_bf16 v[64:67], v[188:191], v[240:243], v[64:67]
	s_barrier
; #define PG8_STAGE(bufoff, gbase, voff) do { _Pragma("unroll") for (int _i = 0; _i < 2; ++_i) \
;         __builtin_amdgcn_global_load_lds((const unsigned*)((const char*)(gbase) + (voff)[_i]), (LAS unsigned*)(lds + (bufoff) + ldsw + _i * 8192), 16, 0, 0); } while (0)
; #define PG8_LDA(dst, b, h) do { _Pragma("unroll") for (int m = 0; m < 4; ++m) _Pragma("unroll") for (int k = 0; k < 2; ++k) dst[m][k] = *(const LAS bf16x8*)(lds + PG8_SA(b, h) + aoff + m * 2048 + k * 1024); } while (0)
; #define PG8_LDB(dst, b, h) do { _Pragma("unroll") for (int n = 0; n < 2; ++n) _Pragma("unroll") for (int k = 0; k < 2; ++k) dst[n][k] = *(const LAS bf16x8*)(lds + PG8_SB(b, h) + boff + n * 2048 + k * 1024); } while (0)
; #define PG8_MMA(ai, bj, At, Bt) do { __builtin_amdgcn_s_setprio(1); _Pragma("unroll") for (int k = 0; k < 2; ++k) _Pragma("unroll") for (int m = 0; m < 4; ++m) _Pragma("unroll") for (int n = 0; n < 2; ++n) \
;         acc[ai][bj][m][n] = __builtin_amdgcn_mfma_f32_16x16x32_bf16(Bt[n][k], At[m][k], acc[ai][bj][m][n], 0, 0, 0); __builtin_amdgcn_s_setprio(0); } while (0)
; #define PG8_WAIT_V(n) asm volatile("s_waitcnt vmcnt(" #n ")" ::: "memory")
; #define PG8_BAR __builtin_amdgcn_s_barrier()
; template <class Epi, bool ALIGN_EPI>
; __device__ __forceinline__ void gemm_phase(LAS unsigned char* lds, const Gemm g, const StaticOrder& S, const Epi& E, const int tid) {
;     ...
;             PG8_LDB(B0, 0, 0); PG8_LDB(B1, 0, 1); PG8_SCHED; PG8_LDA(At, 0, 0); PG8_STAGE(PG8_SA(1, 1), a1 + hA, voffA);
;             PG8_WAIT_V(8); PG8_WAIT_L(0); PG8_BAR; PG8_MMA(0, 0, At, B0); PG8_MMA(0, 1, At, B1); PG8_BAR; PG8_SCHED;
;             PG8_LDA(At, 0, 1); PG8_STAGE(PG8_SB(0, 0), b2, voffB); PG8_STAGE(PG8_SB(0, 1), b2 + hB, voffB); PG8_STAGE(PG8_SA(0, 0), a2, voffA);
;             PG8_WAIT_V(8); PG8_WAIT_L(0); PG8_BAR; PG8_MMA(1, 0, At, B0); PG8_MMA(1, 1, At, B1); PG8_BAR; PG8_SCHED;
;             PG8_LDB(B0, 1, 0); PG8_LDB(B1, 1, 1); PG8_SCHED; PG8_LDA(At, 1, 0); PG8_STAGE(PG8_SA(0, 1), a2 + hA, voffA);
;             PG8_WAIT_V(8); PG8_WAIT_L(0); PG8_BAR; PG8_MMA(0, 0, At, B0); PG8_MMA(0, 1, At, B1); PG8_BAR; PG8_SCHED;
;             PG8_LDA(At, 1, 1); PG8_STAGE(PG8_SB(1, 0), b3, voffB); PG8_STAGE(PG8_SB(1, 1), b3 + hB, voffB); PG8_STAGE(PG8_SA(1, 0), a3, voffA);
;             PG8_WAIT_V(8); PG8_WAIT_L(0); PG8_BAR; PG8_MMA(1, 0, At, B0); PG8_MMA(1, 1, At, B1); PG8_BAR; PG8_SCHED;
	s_setprio 0
	s_add_i32 s10, s10, s45
	v_lshl_add_u64 v[150:151], v[226:227], 0, s[92:93]
	s_mov_b32 m0, s10
	ds_read_b128 v[192:195], v155 offset:49152
	ds_read_b128 v[196:199], v155 offset:50176
	ds_read_b128 v[200:203], v155 offset:51200
	ds_read_b128 v[204:207], v155 offset:52224
	ds_read_b128 v[208:211], v155 offset:53248
	ds_read_b128 v[212:215], v155 offset:54272
	ds_read_b128 v[216:219], v155 offset:55296
	ds_read_b128 v[240:243], v155 offset:56320
	global_load_lds_dwordx4 v[150:151], off
	v_lshl_add_u64 v[150:151], v[244:245], 0, s[92:93]
	s_add_i32 m0, s10, 0x2000
	s_add_i32 s10, s65, s45
	global_load_lds_dwordx4 v[150:151], off
	v_lshl_add_u64 v[150:151], v[246:247], 0, s[92:93]
	s_mov_b32 m0, s10
	s_nop 0
	global_load_lds_dwordx4 v[150:151], off
	v_lshl_add_u64 v[150:151], v[220:221], 0, s[92:93]
	s_add_i32 m0, s10, 0x2000
	s_nop 0
	global_load_lds_dwordx4 v[150:151], off
	v_lshl_add_u64 v[150:151], v[248:249], 0, s[92:93]
	s_mov_b32 m0, s56
	s_nop 0
	global_load_lds_dwordx4 v[150:151], off
	v_lshl_add_u64 v[150:151], v[250:251], 0, s[92:93]
	s_mov_b32 m0, s57
	s_nop 0
	global_load_lds_dwordx4 v[150:151], off
	s_waitcnt vmcnt(8)
	s_waitcnt lgkmcnt(0)
	s_setprio 1
	s_barrier
	s_waitcnt lgkmcnt(0)
	v_mfma_f32_16x16x32_bf16 v[60:63], v[146:149], v[192:195], v[60:63]
	v_mfma_f32_16x16x32_bf16 v[56:59], v[160:163], v[192:195], v[56:59]
	v_mfma_f32_16x16x32_bf16 v[44:47], v[146:149], v[200:203], v[44:47]
	v_mfma_f32_16x16x32_bf16 v[40:43], v[160:163], v[200:203], v[40:43]
	v_mfma_f32_16x16x32_bf16 v[28:31], v[146:149], v[208:211], v[28:31]
	v_mfma_f32_16x16x32_bf16 v[24:27], v[160:163], v[208:211], v[24:27]
	v_mfma_f32_16x16x32_bf16 v[12:15], v[146:149], v[216:219], v[12:15]
	v_mfma_f32_16x16x32_bf16 v[8:11], v[160:163], v[216:219], v[8:11]
	v_mfma_f32_16x16x32_bf16 v[60:63], v[156:159], v[196:199], v[60:63]
	v_mfma_f32_16x16x32_bf16 v[56:59], v[164:167], v[196:199], v[56:59]
	v_mfma_f32_16x16x32_bf16 v[44:47], v[156:159], v[204:207], v[44:47]
	v_mfma_f32_16x16x32_bf16 v[40:43], v[164:167], v[204:207], v[40:43]
	v_mfma_f32_16x16x32_bf16 v[28:31], v[156:159], v[212:215], v[28:31]
	v_mfma_f32_16x16x32_bf16 v[24:27], v[164:167], v[212:215], v[24:27]
	v_mfma_f32_16x16x32_bf16 v[12:15], v[156:159], v[240:243], v[12:15]
	v_mfma_f32_16x16x32_bf16 v[8:11], v[164:167], v[240:243], v[8:11]
	s_setprio 0
	s_setprio 1
	v_mfma_f32_16x16x32_bf16 v[52:55], v[176:179], v[192:195], v[52:55]
	v_mfma_f32_16x16x32_bf16 v[48:51], v[184:187], v[192:195], v[48:51]
	v_mfma_f32_16x16x32_bf16 v[36:39], v[176:179], v[200:203], v[36:39]
	v_mfma_f32_16x16x32_bf16 v[32:35], v[184:187], v[200:203], v[32:35]
	v_mfma_f32_16x16x32_bf16 v[20:23], v[176:179], v[208:211], v[20:23]
	v_mfma_f32_16x16x32_bf16 v[16:19], v[184:187], v[208:211], v[16:19]
	v_mfma_f32_16x16x32_bf16 v[4:7], v[176:179], v[216:219], v[4:7]
	v_mfma_f32_16x16x32_bf16 v[0:3], v[184:187], v[216:219], v[0:3]
	v_mfma_f32_16x16x32_bf16 v[52:55], v[180:183], v[196:199], v[52:55]
	v_mfma_f32_16x16x32_bf16 v[48:51], v[188:191], v[196:199], v[48:51]
	v_mfma_f32_16x16x32_bf16 v[36:39], v[180:183], v[204:207], v[36:39]
	v_mfma_f32_16x16x32_bf16 v[32:35], v[188:191], v[204:207], v[32:35]
	v_mfma_f32_16x16x32_bf16 v[20:23], v[180:183], v[212:215], v[20:23]
	v_mfma_f32_16x16x32_bf16 v[16:19], v[188:191], v[212:215], v[16:19]
	v_mfma_f32_16x16x32_bf16 v[4:7], v[180:183], v[240:243], v[4:7]
	v_mfma_f32_16x16x32_bf16 v[0:3], v[188:191], v[240:243], v[0:3]
	s_barrier
	s_setprio 0
	v_lshl_add_u64 v[142:143], v[142:143], 0, s[80:81]
	v_lshl_add_u64 v[144:145], v[144:145], 0, s[80:81]
	s_cmp_ge_u32 s11, s55
	s_mov_b32 s10, s11
	s_cbranch_scc1 .Lpl4_after
.LBB0_331:
	s_add_i32 s11, s10, 2
	s_cmp_eq_u32 s58, s10
	v_lshl_add_u64 v[146:147], v[142:143], 0, s[92:93]
	s_cselect_b64 vcc, -1, 0
	v_add_u32_e32 v152, s33, v153
	s_add_i32 s10, 0, 0x14000
	v_cndmask_b32_e32 v151, v147, v139, vcc
	v_cndmask_b32_e32 v150, v146, v138, vcc
	ds_read_b128 v[146:149], v152
	ds_read_b128 v[156:159], v152 offset:1024
	ds_read_b128 v[160:163], v152 offset:2048
	ds_read_b128 v[164:167], v152 offset:3072
	v_add_u32_e32 v152, s10, v153
	ds_read_b128 v[176:179], v152
	ds_read_b128 v[180:183], v152 offset:1024
	ds_read_b128 v[184:187], v152 offset:2048
	ds_read_b128 v[188:191], v152 offset:3072
	v_cndmask_b32_e32 v221, v145, v141, vcc
	v_cndmask_b32_e32 v220, v144, v140, vcc
	v_lshl_add_u64 v[226:227], v[142:143], 0, v[134:135]
	s_add_i32 m0, s51, 0xc000
	ds_read_b128 v[192:195], v155
	ds_read_b128 v[196:199], v155 offset:1024
	ds_read_b128 v[200:203], v155 offset:2048
	ds_read_b128 v[204:207], v155 offset:3072
	ds_read_b128 v[208:211], v155 offset:4096
	ds_read_b128 v[212:215], v155 offset:5120
	ds_read_b128 v[216:219], v155 offset:6144
	ds_read_b128 v[240:243], v155 offset:7168
	global_load_lds_dwordx4 v[226:227], off
	v_lshl_add_u64 v[226:227], v[142:143], 0, v[136:137]
	s_add_i32 m0, s51, 0xe000
	s_nop 0
	global_load_lds_dwordx4 v[226:227], off
	s_waitcnt vmcnt(8)
	s_waitcnt lgkmcnt(0)
	s_setprio 1
	s_barrier
; #define PG8_STAGE(bufoff, gbase, voff) do { _Pragma("unroll") for (int _i = 0; _i < 2; ++_i) \
;         __builtin_amdgcn_global_load_lds((const unsigned*)((const char*)(gbase) + (voff)[_i]), (LAS unsigned*)(lds + (bufoff) + ldsw + _i * 8192), 16, 0, 0); } while (0)
; #define PG8_LDA(dst, b, h) do { _Pragma("unroll") for (int m = 0; m < 4; ++m) _Pragma("unroll") for (int k = 0; k < 2; ++k) dst[m][k] = *(const LAS bf16x8*)(lds + PG8_SA(b, h) + aoff + m * 2048 + k * 1024); } while (0)
; #define PG8_LDB(dst, b, h) do { _Pragma("unroll") for (int n = 0; n < 2; ++n) _Pragma("unroll") for (int k = 0; k < 2; ++k) dst[n][k] = *(const LAS bf16x8*)(lds + PG8_SB(b, h) + boff + n * 2048 + k * 1024); } while (0)
; #define PG8_MMA(ai, bj, At, Bt) do { __builtin_amdgcn_s_setprio(1); _Pragma("unroll") for (int k = 0; k < 2; ++k) _Pragma("unroll") for (int m = 0; m < 4; ++m) _Pragma("unroll") for (int n = 0; n < 2; ++n) \
;         acc[ai][bj][m][n] = __builtin_amdgcn_mfma_f32_16x16x32_bf16(Bt[n][k], At[m][k], acc[ai][bj][m][n], 0, 0, 0); __builtin_amdgcn_s_setprio(0); } while (0)
; #define PG8_WAIT_V(n) asm volatile("s_waitcnt vmcnt(" #n ")" ::: "memory")
; #define PG8_BAR __builtin_amdgcn_s_barrier()
; template <class Epi, bool ALIGN_EPI>
; __device__ __forceinline__ void gemm_phase(LAS unsigned char* lds, const Gemm g, const StaticOrder& S, const Epi& E, const int tid) {
;     ...
;             PG8_LDB(B0, 0, 0); PG8_LDB(B1, 0, 1); PG8_SCHED; PG8_LDA(At, 0, 0); PG8_STAGE(PG8_SA(1, 1), a1 + hA, voffA);
;             PG8_WAIT_V(8); PG8_WAIT_L(0); PG8_BAR; PG8_MMA(0, 0, At, B0); PG8_MMA(0, 1, At, B1); PG8_BAR; PG8_SCHED;
;             PG8_LDA(At, 0, 1); PG8_STAGE(PG8_SB(0, 0), b2, voffB); PG8_STAGE(PG8_SB(0, 1), b2 + hB, voffB); PG8_STAGE(PG8_SA(0, 0), a2, voffA);
;             PG8_WAIT_V(8); PG8_WAIT_L(0); PG8_BAR; PG8_MMA(1, 0, At, B0); PG8_MMA(1, 1, At, B1); PG8_BAR; PG8_SCHED;
;             PG8_LDB(B0, 1, 0); PG8_LDB(B1, 1, 1); PG8_SCHED; PG8_LDA(At, 1, 0); PG8_STAGE(PG8_SA(0, 1), a2 + hA, voffA);
;             PG8_WAIT_V(8); PG8_WAIT_L(0); PG8_BAR; PG8_MMA(0, 0, At, B0); PG8_MMA(0, 1, At, B1); PG8_BAR; PG8_SCHED;
;             PG8_LDA(At, 1, 1); PG8_STAGE(PG8_SB(1, 0), b3, voffB); PG8_STAGE(PG8_SB(1, 1), b3 + hB, voffB); PG8_STAGE(PG8_SA(1, 0), a3, voffA);
;             PG8_WAIT_V(8); PG8_WAIT_L(0); PG8_BAR; PG8_MMA(1, 0, At, B0); PG8_MMA(1, 1, At, B1); PG8_BAR; PG8_SCHED;
	s_waitcnt lgkmcnt(0)
	v_mfma_f32_16x16x32_bf16 v[120:123], v[146:149], v[192:195], v[120:123]
	v_mfma_f32_16x16x32_bf16 v[124:127], v[160:163], v[192:195], v[124:127]
	v_mfma_f32_16x16x32_bf16 v[108:111], v[146:149], v[200:203], v[108:111]
	v_mfma_f32_16x16x32_bf16 v[104:107], v[160:163], v[200:203], v[104:107]
	v_mfma_f32_16x16x32_bf16 v[92:95], v[146:149], v[208:211], v[92:95]
	v_mfma_f32_16x16x32_bf16 v[88:91], v[160:163], v[208:211], v[88:91]
	v_mfma_f32_16x16x32_bf16 v[76:79], v[146:149], v[216:219], v[76:79]
	v_mfma_f32_16x16x32_bf16 v[72:75], v[160:163], v[216:219], v[72:75]
	v_mfma_f32_16x16x32_bf16 v[120:123], v[156:159], v[196:199], v[120:123]
	v_mfma_f32_16x16x32_bf16 v[124:127], v[164:167], v[196:199], v[124:127]
	v_mfma_f32_16x16x32_bf16 v[108:111], v[156:159], v[204:207], v[108:111]
	v_mfma_f32_16x16x32_bf16 v[104:107], v[164:167], v[204:207], v[104:107]
	v_mfma_f32_16x16x32_bf16 v[92:95], v[156:159], v[212:215], v[92:95]
	v_mfma_f32_16x16x32_bf16 v[88:91], v[164:167], v[212:215], v[88:91]
	v_mfma_f32_16x16x32_bf16 v[76:79], v[156:159], v[240:243], v[76:79]
	v_mfma_f32_16x16x32_bf16 v[72:75], v[164:167], v[240:243], v[72:75]
	s_setprio 0
	s_setprio 1
	v_mfma_f32_16x16x32_bf16 v[116:119], v[176:179], v[192:195], v[116:119]
	v_mfma_f32_16x16x32_bf16 v[112:115], v[184:187], v[192:195], v[112:115]
	v_mfma_f32_16x16x32_bf16 v[100:103], v[176:179], v[200:203], v[100:103]
	v_mfma_f32_16x16x32_bf16 v[96:99], v[184:187], v[200:203], v[96:99]
	v_mfma_f32_16x16x32_bf16 v[84:87], v[176:179], v[208:211], v[84:87]
	v_mfma_f32_16x16x32_bf16 v[80:83], v[184:187], v[208:211], v[80:83]
	v_mfma_f32_16x16x32_bf16 v[68:71], v[176:179], v[216:219], v[68:71]
	v_mfma_f32_16x16x32_bf16 v[64:67], v[184:187], v[216:219], v[64:67]
	v_mfma_f32_16x16x32_bf16 v[116:119], v[180:183], v[196:199], v[116:119]
	v_mfma_f32_16x16x32_bf16 v[112:115], v[188:191], v[196:199], v[112:115]
	v_mfma_f32_16x16x32_bf16 v[100:103], v[180:183], v[204:207], v[100:103]
	v_mfma_f32_16x16x32_bf16 v[96:99], v[188:191], v[204:207], v[96:99]
	v_mfma_f32_16x16x32_bf16 v[84:87], v[180:183], v[212:215], v[84:87]
	v_mfma_f32_16x16x32_bf16 v[80:83], v[188:191], v[212:215], v[80:83]
	v_mfma_f32_16x16x32_bf16 v[68:71], v[180:183], v[240:243], v[68:71]
	v_mfma_f32_16x16x32_bf16 v[64:67], v[188:191], v[240:243], v[64:67]
	s_barrier
	s_setprio 0
	s_add_i32 s65, s33, s45
	v_lshl_add_u64 v[226:227], v[220:221], 0, v[168:169]
	s_mov_b32 m0, s65
	ds_read_b128 v[192:195], v155 offset:16384
	ds_read_b128 v[196:199], v155 offset:17408
	ds_read_b128 v[200:203], v155 offset:18432
	ds_read_b128 v[204:207], v155 offset:19456
	ds_read_b128 v[208:211], v155 offset:20480
	ds_read_b128 v[212:215], v155 offset:21504
	ds_read_b128 v[216:219], v155 offset:22528
	ds_read_b128 v[240:243], v155 offset:23552
	global_load_lds_dwordx4 v[226:227], off
	v_lshl_add_u64 v[244:245], v[220:221], 0, v[128:129]
	s_add_i32 m0, s65, 0x2000
	v_lshl_add_u64 v[220:221], v[220:221], 0, s[12:13]
	s_add_i32 s10, s10, s45
	global_load_lds_dwordx4 v[244:245], off
	v_lshl_add_u64 v[246:247], v[220:221], 0, v[168:169]
	s_mov_b32 m0, s10
	v_lshl_add_u64 v[220:221], v[220:221], 0, v[128:129]
	global_load_lds_dwordx4 v[246:247], off
	s_add_i32 m0, s10, 0x2000
	v_lshl_add_u64 v[248:249], v[150:151], 0, v[132:133]
	global_load_lds_dwordx4 v[220:221], off
	s_mov_b32 m0, s51
	v_lshl_add_u64 v[250:251], v[150:151], 0, v[130:131]
	global_load_lds_dwordx4 v[248:249], off
	s_mov_b32 m0, s52
	s_nop 0
	global_load_lds_dwordx4 v[250:251], off
	s_waitcnt vmcnt(8)
	s_waitcnt lgkmcnt(0)
	s_setprio 1
	s_barrier
	s_waitcnt lgkmcnt(0)
	v_mfma_f32_16x16x32_bf16 v[60:63], v[146:149], v[192:195], v[60:63]
	v_mfma_f32_16x16x32_bf16 v[56:59], v[160:163], v[192:195], v[56:59]
	v_mfma_f32_16x16x32_bf16 v[44:47], v[146:149], v[200:203], v[44:47]
	v_mfma_f32_16x16x32_bf16 v[40:43], v[160:163], v[200:203], v[40:43]
	v_mfma_f32_16x16x32_bf16 v[28:31], v[146:149], v[208:211], v[28:31]
	v_mfma_f32_16x16x32_bf16 v[24:27], v[160:163], v[208:211], v[24:27]
	v_mfma_f32_16x16x32_bf16 v[12:15], v[146:149], v[216:219], v[12:15]
	v_mfma_f32_16x16x32_bf16 v[8:11], v[160:163], v[216:219], v[8:11]
	v_mfma_f32_16x16x32_bf16 v[60:63], v[156:159], v[196:199], v[60:63]
	v_mfma_f32_16x16x32_bf16 v[56:59], v[164:167], v[196:199], v[56:59]
	v_mfma_f32_16x16x32_bf16 v[44:47], v[156:159], v[204:207], v[44:47]
	v_mfma_f32_16x16x32_bf16 v[40:43], v[164:167], v[204:207], v[40:43]
	v_mfma_f32_16x16x32_bf16 v[28:31], v[156:159], v[212:215], v[28:31]
	v_mfma_f32_16x16x32_bf16 v[24:27], v[164:167], v[212:215], v[24:27]
	v_mfma_f32_16x16x32_bf16 v[12:15], v[156:159], v[240:243], v[12:15]
	v_mfma_f32_16x16x32_bf16 v[8:11], v[164:167], v[240:243], v[8:11]
	s_setprio 0
	s_setprio 1
	v_mfma_f32_16x16x32_bf16 v[52:55], v[176:179], v[192:195], v[52:55]
	v_mfma_f32_16x16x32_bf16 v[48:51], v[184:187], v[192:195], v[48:51]
	v_mfma_f32_16x16x32_bf16 v[36:39], v[176:179], v[200:203], v[36:39]
	v_mfma_f32_16x16x32_bf16 v[32:35], v[184:187], v[200:203], v[32:35]
	v_mfma_f32_16x16x32_bf16 v[20:23], v[176:179], v[208:211], v[20:23]
	v_mfma_f32_16x16x32_bf16 v[16:19], v[184:187], v[208:211], v[16:19]
	v_mfma_f32_16x16x32_bf16 v[4:7], v[176:179], v[216:219], v[4:7]
	v_mfma_f32_16x16x32_bf16 v[0:3], v[184:187], v[216:219], v[0:3]
	v_mfma_f32_16x16x32_bf16 v[52:55], v[180:183], v[196:199], v[52:55]
	v_mfma_f32_16x16x32_bf16 v[48:51], v[188:191], v[196:199], v[48:51]
	v_mfma_f32_16x16x32_bf16 v[36:39], v[180:183], v[204:207], v[36:39]
	v_mfma_f32_16x16x32_bf16 v[32:35], v[188:191], v[204:207], v[32:35]
	v_mfma_f32_16x16x32_bf16 v[20:23], v[180:183], v[212:215], v[20:23]
	v_mfma_f32_16x16x32_bf16 v[16:19], v[188:191], v[212:215], v[16:19]
	v_mfma_f32_16x16x32_bf16 v[4:7], v[180:183], v[240:243], v[4:7]
	v_mfma_f32_16x16x32_bf16 v[0:3], v[188:191], v[240:243], v[0:3]
	s_barrier
; #define PG8_STAGE(bufoff, gbase, voff) do { _Pragma("unroll") for (int _i = 0; _i < 2; ++_i) \
;         __builtin_amdgcn_global_load_lds((const unsigned*)((const char*)(gbase) + (voff)[_i]), (LAS unsigned*)(lds + (bufoff) + ldsw + _i * 8192), 16, 0, 0); } while (0)
; #define PG8_LDA(dst, b, h) do { _Pragma("unroll") for (int m = 0; m < 4; ++m) _Pragma("unroll") for (int k = 0; k < 2; ++k) dst[m][k] = *(const LAS bf16x8*)(lds + PG8_SA(b, h) + aoff + m * 2048 + k * 1024); } while (0)
; #define PG8_LDB(dst, b, h) do { _Pragma("unroll") for (int n = 0; n < 2; ++n) _Pragma("unroll") for (int k = 0; k < 2; ++k) dst[n][k] = *(const LAS bf16x8*)(lds + PG8_SB(b, h) + boff + n * 2048 + k * 1024); } while (0)
; #define PG8_MMA(ai, bj, At, Bt) do { __builtin_amdgcn_s_setprio(1); _Pragma("unroll") for (int k = 0; k < 2; ++k) _Pragma("unroll") for (int m = 0; m < 4; ++m) _Pragma("unroll") for (int n = 0; n < 2; ++n) \
;         acc[ai][bj][m][n] = __builtin_amdgcn_mfma_f32_16x16x32_bf16(Bt[n][k], At[m][k], acc[ai][bj][m][n], 0, 0, 0); __builtin_amdgcn_s_setprio(0); } while (0)
; #define PG8_WAIT_V(n) asm volatile("s_waitcnt vmcnt(" #n ")" ::: "memory")
; #define PG8_BAR __builtin_amdgcn_s_barrier()
; template <class Epi, bool ALIGN_EPI>
; __device__ __forceinline__ void gemm_phase(LAS unsigned char* lds, const Gemm g, const StaticOrder& S, const Epi& E, const int tid) {
;     ...
;             PG8_LDB(B0, 0, 0); PG8_LDB(B1, 0, 1); PG8_SCHED; PG8_LDA(At, 0, 0); PG8_STAGE(PG8_SA(1, 1), a1 + hA, voffA);
;             PG8_WAIT_V(8); PG8_WAIT_L(0); PG8_BAR; PG8_MMA(0, 0, At, B0); PG8_MMA(0, 1, At, B1); PG8_BAR; PG8_SCHED;
;             PG8_LDA(At, 0, 1); PG8_STAGE(PG8_SB(0, 0), b2, voffB); PG8_STAGE(PG8_SB(0, 1), b2 + hB, voffB); PG8_STAGE(PG8_SA(0, 0), a2, voffA);
;             PG8_WAIT_V(8); PG8_WAIT_L(0); PG8_BAR; PG8_MMA(1, 0, At, B0); PG8_MMA(1, 1, At, B1); PG8_BAR; PG8_SCHED;
;             PG8_LDB(B0, 1, 0); PG8_LDB(B1, 1, 1); PG8_SCHED; PG8_LDA(At, 1, 0); PG8_STAGE(PG8_SA(0, 1), a2 + hA, voffA);
;             PG8_WAIT_V(8); PG8_WAIT_L(0); PG8_BAR; PG8_MMA(0, 0, At, B0); PG8_MMA(0, 1, At, B1); PG8_BAR; PG8_SCHED;
;             PG8_LDA(At, 1, 1); PG8_STAGE(PG8_SB(1, 0), b3, voffB); PG8_STAGE(PG8_SB(1, 1), b3 + hB, voffB); PG8_STAGE(PG8_SA(1, 0), a3, voffA);
;             PG8_WAIT_V(8); PG8_WAIT_L(0); PG8_BAR; PG8_MMA(1, 0, At, B0); PG8_MMA(1, 1, At, B1); PG8_BAR; PG8_SCHED;
	s_setprio 0
	s_add_i32 s10, 0, 0x18000
	v_add_u32_e32 v152, s10, v153
	s_add_i32 s65, 0, 0x1c000
	ds_read_b128 v[146:149], v152
	ds_read_b128 v[156:159], v152 offset:1024
	ds_read_b128 v[160:163], v152 offset:2048
	ds_read_b128 v[164:167], v152 offset:3072
	v_add_u32_e32 v152, s65, v153
	ds_read_b128 v[176:179], v152
	ds_read_b128 v[180:183], v152 offset:1024
	ds_read_b128 v[184:187], v152 offset:2048
	ds_read_b128 v[188:191], v152 offset:3072
	v_lshl_add_u64 v[150:151], v[150:151], 0, s[94:95]
	s_mov_b32 m0, s53
	v_lshl_add_u64 v[252:253], v[150:151], 0, v[132:133]
	ds_read_b128 v[192:195], v155 offset:32768
	ds_read_b128 v[196:199], v155 offset:33792
	ds_read_b128 v[200:203], v155 offset:34816
	ds_read_b128 v[204:207], v155 offset:35840
	ds_read_b128 v[208:211], v155 offset:36864
	ds_read_b128 v[212:215], v155 offset:37888
	ds_read_b128 v[216:219], v155 offset:38912
	ds_read_b128 v[240:243], v155 offset:39936
	global_load_lds_dwordx4 v[252:253], off
	v_lshl_add_u64 v[150:151], v[150:151], 0, v[130:131]
	s_mov_b32 m0, s54
	s_nop 0
	global_load_lds_dwordx4 v[150:151], off
	s_waitcnt vmcnt(8)
	s_waitcnt lgkmcnt(0)
	s_setprio 1
	s_barrier
	s_waitcnt lgkmcnt(0)
	v_mfma_f32_16x16x32_bf16 v[120:123], v[146:149], v[192:195], v[120:123]
	v_mfma_f32_16x16x32_bf16 v[124:127], v[160:163], v[192:195], v[124:127]
	v_mfma_f32_16x16x32_bf16 v[108:111], v[146:149], v[200:203], v[108:111]
	v_mfma_f32_16x16x32_bf16 v[104:107], v[160:163], v[200:203], v[104:107]
	v_mfma_f32_16x16x32_bf16 v[92:95], v[146:149], v[208:211], v[92:95]
	v_mfma_f32_16x16x32_bf16 v[88:91], v[160:163], v[208:211], v[88:91]
	v_mfma_f32_16x16x32_bf16 v[76:79], v[146:149], v[216:219], v[76:79]
	v_mfma_f32_16x16x32_bf16 v[72:75], v[160:163], v[216:219], v[72:75]
	v_mfma_f32_16x16x32_bf16 v[120:123], v[156:159], v[196:199], v[120:123]
	v_mfma_f32_16x16x32_bf16 v[124:127], v[164:167], v[196:199], v[124:127]
	v_mfma_f32_16x16x32_bf16 v[108:111], v[156:159], v[204:207], v[108:111]
	v_mfma_f32_16x16x32_bf16 v[104:107], v[164:167], v[204:207], v[104:107]
	v_mfma_f32_16x16x32_bf16 v[92:95], v[156:159], v[212:215], v[92:95]
	v_mfma_f32_16x16x32_bf16 v[88:91], v[164:167], v[212:215], v[88:91]
	v_mfma_f32_16x16x32_bf16 v[76:79], v[156:159], v[240:243], v[76:79]
	v_mfma_f32_16x16x32_bf16 v[72:75], v[164:167], v[240:243], v[72:75]
	s_setprio 0
	s_setprio 1
	v_mfma_f32_16x16x32_bf16 v[116:119], v[176:179], v[192:195], v[116:119]
	v_mfma_f32_16x16x32_bf16 v[112:115], v[184:187], v[192:195], v[112:115]
	v_mfma_f32_16x16x32_bf16 v[100:103], v[176:179], v[200:203], v[100:103]
	v_mfma_f32_16x16x32_bf16 v[96:99], v[184:187], v[200:203], v[96:99]
	v_mfma_f32_16x16x32_bf16 v[84:87], v[176:179], v[208:211], v[84:87]
	v_mfma_f32_16x16x32_bf16 v[80:83], v[184:187], v[208:211], v[80:83]
	v_mfma_f32_16x16x32_bf16 v[68:71], v[176:179], v[216:219], v[68:71]
	v_mfma_f32_16x16x32_bf16 v[64:67], v[184:187], v[216:219], v[64:67]
	v_mfma_f32_16x16x32_bf16 v[116:119], v[180:183], v[196:199], v[116:119]
	v_mfma_f32_16x16x32_bf16 v[112:115], v[188:191], v[196:199], v[112:115]
	v_mfma_f32_16x16x32_bf16 v[100:103], v[180:183], v[204:207], v[100:103]
	v_mfma_f32_16x16x32_bf16 v[96:99], v[188:191], v[204:207], v[96:99]
	v_mfma_f32_16x16x32_bf16 v[84:87], v[180:183], v[212:215], v[84:87]
	v_mfma_f32_16x16x32_bf16 v[80:83], v[188:191], v[212:215], v[80:83]
	v_mfma_f32_16x16x32_bf16 v[68:71], v[180:183], v[240:243], v[68:71]
	v_mfma_f32_16x16x32_bf16 v[64:67], v[188:191], v[240:243], v[64:67]
	s_barrier
; #define PG8_STAGE(bufoff, gbase, voff) do { _Pragma("unroll") for (int _i = 0; _i < 2; ++_i) \
;         __builtin_amdgcn_global_load_lds((const unsigned*)((const char*)(gbase) + (voff)[_i]), (LAS unsigned*)(lds + (bufoff) + ldsw + _i * 8192), 16, 0, 0); } while (0)
; #define PG8_LDA(dst, b, h) do { _Pragma("unroll") for (int m = 0; m < 4; ++m) _Pragma("unroll") for (int k = 0; k < 2; ++k) dst[m][k] = *(const LAS bf16x8*)(lds + PG8_SA(b, h) + aoff + m * 2048 + k * 1024); } while (0)
; #define PG8_LDB(dst, b, h) do { _Pragma("unroll") for (int n = 0; n < 2; ++n) _Pragma("unroll") for (int k = 0; k < 2; ++k) dst[n][k] = *(const LAS bf16x8*)(lds + PG8_SB(b, h) + boff + n * 2048 + k * 1024); } while (0)
; #define PG8_WAIT_V(n) asm volatile("s_waitcnt vmcnt(" #n ")" ::: "memory")
; #define PG8_BAR __builtin_amdgcn_s_barrier()
; template <class Epi, bool ALIGN_EPI>
; __device__ __forceinline__ void gemm_phase(LAS unsigned char* lds, const Gemm g, const StaticOrder& S, const Epi& E, const int tid) {
;     ...
;         for (int t = 0; t < nt; t += 2) {
;             const bool last = (t == nt - 2);
;             const char* a1 = cA + (size_t)(t + 1) * kstep;
;             const char* a2 = last ? nA : cA + (size_t)(t + 2) * kstep; const char* b2 = last ? nB : cB + (size_t)(t + 2) * kstep;
;             const char* a3 = a2 + kstep; const char* b3 = b2 + kstep;
;             PG8_LDB(B0, 0, 0); PG8_LDB(B1, 0, 1); PG8_SCHED; PG8_LDA(At, 0, 0); PG8_STAGE(PG8_SA(1, 1), a1 + hA, voffA);
;             PG8_WAIT_V(8); PG8_WAIT_L(0); PG8_BAR; PG8_MMA(0, 0, At, B0); PG8_MMA(0, 1, At, B1); PG8_BAR; PG8_SCHED;
;             PG8_LDA(At, 0, 1); PG8_STAGE(PG8_SB(0, 0), b2, voffB); PG8_STAGE(PG8_SB(0, 1), b2 + hB, voffB); PG8_STAGE(PG8_SA(0, 0), a2, voffA);
;             PG8_WAIT_V(8); PG8_WAIT_L(0); PG8_BAR; PG8_MMA(1, 0, At, B0); PG8_MMA(1, 1, At, B1); PG8_BAR; PG8_SCHED;
;             PG8_LDB(B0, 1, 0); PG8_LDB(B1, 1, 1); PG8_SCHED; PG8_LDA(At, 1, 0); PG8_STAGE(PG8_SA(0, 1), a2 + hA, voffA);
;             PG8_WAIT_V(8); PG8_WAIT_L(0); PG8_BAR; PG8_MMA(0, 0, At, B0); PG8_MMA(0, 1, At, B1); PG8_BAR; PG8_SCHED;
;             PG8_LDA(At, 1, 1); PG8_STAGE(PG8_SB(1, 0), b3, voffB); PG8_STAGE(PG8_SB(1, 1), b3 + hB, voffB); PG8_STAGE(PG8_SA(1, 0), a3, voffA);
;             PG8_WAIT_V(8); PG8_WAIT_L(0); PG8_BAR; PG8_MMA(1, 0, At, B0); PG8_MMA(1, 1, At, B1); PG8_BAR; PG8_SCHED;
	s_setprio 0
	s_add_i32 s10, s10, s45
	v_lshl_add_u64 v[150:151], v[226:227], 0, s[92:93]
	s_mov_b32 m0, s10
	ds_read_b128 v[192:195], v155 offset:49152
	ds_read_b128 v[196:199], v155 offset:50176
	ds_read_b128 v[200:203], v155 offset:51200
	ds_read_b128 v[204:207], v155 offset:52224
	ds_read_b128 v[208:211], v155 offset:53248
	ds_read_b128 v[212:215], v155 offset:54272
	ds_read_b128 v[216:219], v155 offset:55296
	ds_read_b128 v[240:243], v155 offset:56320
	global_load_lds_dwordx4 v[150:151], off
	v_lshl_add_u64 v[150:151], v[244:245], 0, s[92:93]
	s_add_i32 m0, s10, 0x2000
	s_add_i32 s10, s65, s45
	global_load_lds_dwordx4 v[150:151], off
	v_lshl_add_u64 v[150:151], v[246:247], 0, s[92:93]
	s_mov_b32 m0, s10
	s_nop 0
	global_load_lds_dwordx4 v[150:151], off
	v_lshl_add_u64 v[150:151], v[220:221], 0, s[92:93]
	s_add_i32 m0, s10, 0x2000
	s_nop 0
	global_load_lds_dwordx4 v[150:151], off
	v_lshl_add_u64 v[150:151], v[248:249], 0, s[92:93]
	s_mov_b32 m0, s56
	s_nop 0
	global_load_lds_dwordx4 v[150:151], off
	v_lshl_add_u64 v[150:151], v[250:251], 0, s[92:93]
	s_mov_b32 m0, s57
	s_nop 0
	global_load_lds_dwordx4 v[150:151], off
	s_waitcnt vmcnt(8)
	s_waitcnt lgkmcnt(0)
	s_setprio 1
	s_barrier
	s_waitcnt lgkmcnt(0)
	v_mfma_f32_16x16x32_bf16 v[60:63], v[146:149], v[192:195], v[60:63]
	v_mfma_f32_16x16x32_bf16 v[56:59], v[160:163], v[192:195], v[56:59]
	v_mfma_f32_16x16x32_bf16 v[44:47], v[146:149], v[200:203], v[44:47]
	v_mfma_f32_16x16x32_bf16 v[40:43], v[160:163], v[200:203], v[40:43]
	v_mfma_f32_16x16x32_bf16 v[28:31], v[146:149], v[208:211], v[28:31]
	v_mfma_f32_16x16x32_bf16 v[24:27], v[160:163], v[208:211], v[24:27]
	v_mfma_f32_16x16x32_bf16 v[12:15], v[146:149], v[216:219], v[12:15]
	v_mfma_f32_16x16x32_bf16 v[8:11], v[160:163], v[216:219], v[8:11]
	v_mfma_f32_16x16x32_bf16 v[60:63], v[156:159], v[196:199], v[60:63]
	v_mfma_f32_16x16x32_bf16 v[56:59], v[164:167], v[196:199], v[56:59]
	v_mfma_f32_16x16x32_bf16 v[44:47], v[156:159], v[204:207], v[44:47]
	v_mfma_f32_16x16x32_bf16 v[40:43], v[164:167], v[204:207], v[40:43]
	v_mfma_f32_16x16x32_bf16 v[28:31], v[156:159], v[212:215], v[28:31]
	v_mfma_f32_16x16x32_bf16 v[24:27], v[164:167], v[212:215], v[24:27]
	v_mfma_f32_16x16x32_bf16 v[12:15], v[156:159], v[240:243], v[12:15]
	v_mfma_f32_16x16x32_bf16 v[8:11], v[164:167], v[240:243], v[8:11]
	s_setprio 0
	s_setprio 1
	v_mfma_f32_16x16x32_bf16 v[52:55], v[176:179], v[192:195], v[52:55]
	v_mfma_f32_16x16x32_bf16 v[48:51], v[184:187], v[192:195], v[48:51]
	v_mfma_f32_16x16x32_bf16 v[36:39], v[176:179], v[200:203], v[36:39]
	v_mfma_f32_16x16x32_bf16 v[32:35], v[184:187], v[200:203], v[32:35]
	v_mfma_f32_16x16x32_bf16 v[20:23], v[176:179], v[208:211], v[20:23]
	v_mfma_f32_16x16x32_bf16 v[16:19], v[184:187], v[208:211], v[16:19]
	v_mfma_f32_16x16x32_bf16 v[4:7], v[176:179], v[216:219], v[4:7]
	v_mfma_f32_16x16x32_bf16 v[0:3], v[184:187], v[216:219], v[0:3]
	v_mfma_f32_16x16x32_bf16 v[52:55], v[180:183], v[196:199], v[52:55]
	v_mfma_f32_16x16x32_bf16 v[48:51], v[188:191], v[196:199], v[48:51]
	v_mfma_f32_16x16x32_bf16 v[36:39], v[180:183], v[204:207], v[36:39]
	v_mfma_f32_16x16x32_bf16 v[32:35], v[188:191], v[204:207], v[32:35]
	v_mfma_f32_16x16x32_bf16 v[20:23], v[180:183], v[212:215], v[20:23]
	v_mfma_f32_16x16x32_bf16 v[16:19], v[188:191], v[212:215], v[16:19]
	v_mfma_f32_16x16x32_bf16 v[4:7], v[180:183], v[240:243], v[4:7]
	v_mfma_f32_16x16x32_bf16 v[0:3], v[188:191], v[240:243], v[0:3]
	s_barrier
	s_setprio 0
	v_lshl_add_u64 v[142:143], v[142:143], 0, s[80:81]
	v_lshl_add_u64 v[144:145], v[144:145], 0, s[80:81]
	s_cmp_ge_u32 s11, s55
	s_mov_b32 s10, s11
	s_cbranch_scc0 .LBB0_331

; __device__ __forceinline__ unsigned cvt_pk_bf16(float lo, float hi) { unsigned r; asm volatile("v_cvt_pk_bf16_f32 %0, %1, %2" : "=v"(r) : "v"(lo), "v"(hi)); return r; }
;     __device__ __forceinline__ void operator()(const f32x4 (&acc)[2][2][4][2], const Unit& u, int wr, int wc, int fr, int fq) const {
;         const int row0 = u.pm * BM + wr * 64 + fr, col0 = u.pn * BM + wc * 32 + 8 * fq;
;         float rsv[2][4]; load_rstd(rsv, ssq, row0);
; #pragma unroll
;         for (int ai = 0; ai < 2; ++ai)
; #pragma unroll
;             for (int m = 0; m < 4; ++m) { const int row = row0 + ai * HALF + m * 16; bf16_t* rowp = O + (size_t)row * ldc + col0; const float rs = rsv[ai][m];
; #pragma unroll
;                 for (int bj = 0; bj < 2; ++bj) { f32x4 v0 = acc[ai][bj][m][0] * rs, v1 = acc[ai][bj][m][1] * rs;
;                     if (ACT == 1) {
; #pragma unroll
;                         for (int j = 0; j < 4; ++j) { v0[j] = gelu_tanh(v0[j]); v1[j] = gelu_tanh(v1[j]); } }
;                     u32x4 w; w.x = cvt_pk_bf16(v0[0], v0[1]); w.y = cvt_pk_bf16(v0[2], v0[3]); w.z = cvt_pk_bf16(v1[0], v1[1]); w.w = cvt_pk_bf16(v1[2], v1[3]);
;                     *(u32x4*)(rowp + bj * HALF) = w; } }
; template <class Epi, bool ALIGN_EPI>
; __device__ __forceinline__ void gemm_phase(LAS unsigned char* lds, const Gemm g, const StaticOrder& S, const Epi& E, const int tid) {
;     ...
;             PG8_LDB(B0, 0, 0); PG8_LDB(B1, 0, 1); PG8_SCHED; PG8_LDA(At, 0, 0); PG8_STAGE(PG8_SA(1, 1), a1 + hA, voffA);
;             PG8_WAIT_V(8); PG8_WAIT_L(0); PG8_BAR; PG8_MMA(0, 0, At, B0); PG8_MMA(0, 1, At, B1); PG8_BAR; PG8_SCHED;
;             PG8_LDA(At, 0, 1); PG8_STAGE(PG8_SB(0, 0), b2, voffB); PG8_STAGE(PG8_SB(0, 1), b2 + hB, voffB); PG8_STAGE(PG8_SA(0, 0), a2, voffA);
;             PG8_WAIT_V(8); PG8_WAIT_L(0); PG8_BAR; PG8_MMA(1, 0, At, B0); PG8_MMA(1, 1, At, B1); PG8_BAR; PG8_SCHED;
;             PG8_LDB(B0, 1, 0); PG8_LDB(B1, 1, 1); PG8_SCHED; PG8_LDA(At, 1, 0); PG8_STAGE(PG8_SA(0, 1), a2 + hA, voffA);
;             PG8_WAIT_V(8); PG8_WAIT_L(0); PG8_BAR; PG8_MMA(0, 0, At, B0); PG8_MMA(0, 1, At, B1); PG8_BAR; PG8_SCHED;
;             PG8_LDA(At, 1, 1); PG8_STAGE(PG8_SB(1, 0), b3, voffB); PG8_STAGE(PG8_SB(1, 1), b3 + hB, voffB); PG8_STAGE(PG8_SA(1, 0), a3, voffA);
;             PG8_WAIT_V(8); PG8_WAIT_L(0); PG8_BAR; PG8_MMA(1, 0, At, B0); PG8_MMA(1, 1, At, B1); PG8_BAR; PG8_SCHED;
.Lq5_first_epi:
	s_add_i32 s11, s10, 2
	s_cmp_eq_u32 s55, s10
	s_cselect_b64 vcc, -1, 0
	v_add_u32_e32 v148, s33, v149
	s_add_i32 s10, 0, 0x14000
	ds_read_b128 v[152:155], v148
	ds_read_b128 v[156:159], v148 offset:1024
	ds_read_b128 v[160:163], v148 offset:2048
	ds_read_b128 v[164:167], v148 offset:3072
	v_add_u32_e32 v148, s10, v149
	ds_read_b128 v[176:179], v148
	ds_read_b128 v[180:183], v148 offset:1024
	ds_read_b128 v[184:187], v148 offset:2048
	ds_read_b128 v[188:191], v148 offset:3072
	v_lshl_add_u64 v[146:147], v[142:143], 0, s[92:93]
	v_cndmask_b32_e32 v147, v147, v139, vcc
	v_cndmask_b32_e32 v146, v146, v138, vcc
	v_cndmask_b32_e32 v221, v145, v141, vcc
	v_cndmask_b32_e32 v220, v144, v140, vcc
	v_lshl_add_u64 v[244:245], v[142:143], 0, v[134:135]
	s_add_i32 m0, s25, 0xc000
	ds_read_b128 v[192:195], v151
	ds_read_b128 v[196:199], v151 offset:1024
	ds_read_b128 v[200:203], v151 offset:2048
	ds_read_b128 v[204:207], v151 offset:3072
	ds_read_b128 v[208:211], v151 offset:4096
	ds_read_b128 v[212:215], v151 offset:5120
	ds_read_b128 v[216:219], v151 offset:6144
	ds_read_b128 v[240:243], v151 offset:7168
	global_load_lds_dwordx4 v[244:245], off
	v_lshl_add_u64 v[244:245], v[142:143], 0, v[136:137]
	s_add_i32 m0, s25, 0xe000
	s_nop 0
	global_load_lds_dwordx4 v[244:245], off
	s_waitcnt vmcnt(16)
	s_waitcnt lgkmcnt(0)
	s_setprio 1
	s_barrier
	s_waitcnt lgkmcnt(0)
	v_mfma_f32_16x16x32_bf16 v[124:127], v[152:155], v[192:195], 0
	s_lshl_b32 s98, s28, 5
	s_mov_b32 s99, 0
	v_mul_f32_e32 v60, v238, v60
	v_mul_f32_e32 v61, v238, v61
	v_mfma_f32_16x16x32_bf16 v[120:123], v[160:163], v[192:195], 0
	v_mul_f32_e32 v62, v238, v62
	v_mul_f32_e32 v63, v238, v63
	v_mul_f32_e32 v56, v238, v56
	v_mul_f32_e32 v57, v238, v57
	v_mfma_f32_16x16x32_bf16 v[108:111], v[152:155], v[200:203], 0
	v_mul_f32_e32 v58, v238, v58
	v_mul_f32_e32 v59, v238, v59
	v_cvt_pk_bf16_f32 v60, v60, v61
	v_cvt_pk_bf16_f32 v61, v62, v63
	v_mfma_f32_16x16x32_bf16 v[104:107], v[160:163], v[200:203], 0
	v_cvt_pk_bf16_f32 v62, v56, v57
	v_cvt_pk_bf16_f32 v63, v58, v59
	global_store_dwordx4 v[232:233], v[60:63], off
	v_mul_f32_e32 v52, v238, v52
	v_mfma_f32_16x16x32_bf16 v[92:95], v[152:155], v[208:211], 0
	v_mul_f32_e32 v53, v238, v53
	v_mul_f32_e32 v54, v238, v54
	v_mul_f32_e32 v55, v238, v55
	v_mul_f32_e32 v48, v238, v48
	v_mfma_f32_16x16x32_bf16 v[88:91], v[160:163], v[208:211], 0
	v_mul_f32_e32 v49, v238, v49
	v_mul_f32_e32 v50, v238, v50
	v_mul_f32_e32 v51, v238, v51
	v_cvt_pk_bf16_f32 v52, v52, v53
	v_mfma_f32_16x16x32_bf16 v[76:79], v[152:155], v[216:219], 0
	v_cvt_pk_bf16_f32 v53, v54, v55
	v_cvt_pk_bf16_f32 v54, v48, v49
	v_cvt_pk_bf16_f32 v55, v50, v51
	global_store_dwordx4 v[232:233], v[52:55], off offset:256
	v_mfma_f32_16x16x32_bf16 v[72:75], v[160:163], v[216:219], 0
	v_lshl_add_u64 v[232:233], v[232:233], 0, s[98:99]
	v_mul_f32_e32 v44, v239, v44
	v_mul_f32_e32 v45, v239, v45
	v_mul_f32_e32 v46, v239, v46
	v_mfma_f32_16x16x32_bf16 v[124:127], v[156:159], v[196:199], v[124:127]
	v_mul_f32_e32 v47, v239, v47
	v_mul_f32_e32 v40, v239, v40
	v_mul_f32_e32 v41, v239, v41
	v_mul_f32_e32 v42, v239, v42
	v_mfma_f32_16x16x32_bf16 v[120:123], v[164:167], v[196:199], v[120:123]
	v_mul_f32_e32 v43, v239, v43
	v_cvt_pk_bf16_f32 v44, v44, v45
	v_cvt_pk_bf16_f32 v45, v46, v47
	v_cvt_pk_bf16_f32 v46, v40, v41
	v_mfma_f32_16x16x32_bf16 v[108:111], v[156:159], v[204:207], v[108:111]
	v_cvt_pk_bf16_f32 v47, v42, v43
	global_store_dwordx4 v[232:233], v[44:47], off
	v_mul_f32_e32 v36, v239, v36
	v_mul_f32_e32 v37, v239, v37
	v_mfma_f32_16x16x32_bf16 v[104:107], v[164:167], v[204:207], v[104:107]
	v_mul_f32_e32 v38, v239, v38
	v_mul_f32_e32 v39, v239, v39
	v_mul_f32_e32 v32, v239, v32
	v_mul_f32_e32 v33, v239, v33
	v_mfma_f32_16x16x32_bf16 v[92:95], v[156:159], v[212:215], v[92:95]
	v_mul_f32_e32 v34, v239, v34
	v_mul_f32_e32 v35, v239, v35
	v_cvt_pk_bf16_f32 v36, v36, v37
	v_cvt_pk_bf16_f32 v37, v38, v39
	v_mfma_f32_16x16x32_bf16 v[88:91], v[164:167], v[212:215], v[88:91]
	v_cvt_pk_bf16_f32 v38, v32, v33
	v_cvt_pk_bf16_f32 v39, v34, v35
	global_store_dwordx4 v[232:233], v[36:39], off offset:256
	v_lshl_add_u64 v[232:233], v[232:233], 0, s[98:99]
	v_mfma_f32_16x16x32_bf16 v[76:79], v[156:159], v[240:243], v[76:79]
	v_mul_f32_e32 v28, v230, v28
	v_mul_f32_e32 v29, v230, v29
	v_mul_f32_e32 v30, v230, v30
	v_mul_f32_e32 v31, v230, v31
	v_mfma_f32_16x16x32_bf16 v[72:75], v[164:167], v[240:243], v[72:75]
	v_mul_f32_e32 v24, v230, v24
	v_mul_f32_e32 v25, v230, v25
	v_mul_f32_e32 v26, v230, v26
	v_mul_f32_e32 v27, v230, v27
	s_setprio 0
	s_setprio 1
	v_mfma_f32_16x16x32_bf16 v[116:119], v[176:179], v[192:195], 0
	v_cvt_pk_bf16_f32 v28, v28, v29
	v_cvt_pk_bf16_f32 v29, v30, v31
	v_cvt_pk_bf16_f32 v30, v24, v25
	v_cvt_pk_bf16_f32 v31, v26, v27
	v_mfma_f32_16x16x32_bf16 v[112:115], v[184:187], v[192:195], 0
	global_store_dwordx4 v[232:233], v[28:31], off
	v_mul_f32_e32 v20, v230, v20
	v_mul_f32_e32 v21, v230, v21
	v_mul_f32_e32 v22, v230, v22
	v_mfma_f32_16x16x32_bf16 v[100:103], v[176:179], v[200:203], 0
	v_mul_f32_e32 v23, v230, v23
	v_mul_f32_e32 v16, v230, v16
	v_mul_f32_e32 v17, v230, v17
	v_mul_f32_e32 v18, v230, v18
	v_mfma_f32_16x16x32_bf16 v[96:99], v[184:187], v[200:203], 0
	v_mul_f32_e32 v19, v230, v19
	v_cvt_pk_bf16_f32 v20, v20, v21
	v_cvt_pk_bf16_f32 v21, v22, v23
	v_cvt_pk_bf16_f32 v22, v16, v17
	v_mfma_f32_16x16x32_bf16 v[84:87], v[176:179], v[208:211], 0
	v_cvt_pk_bf16_f32 v23, v18, v19
	global_store_dwordx4 v[232:233], v[20:23], off offset:256
	v_lshl_add_u64 v[232:233], v[232:233], 0, s[98:99]
	v_mul_f32_e32 v12, v231, v12
	v_mfma_f32_16x16x32_bf16 v[80:83], v[184:187], v[208:211], 0
; __device__ __forceinline__ unsigned cvt_pk_bf16(float lo, float hi) { unsigned r; asm volatile("v_cvt_pk_bf16_f32 %0, %1, %2" : "=v"(r) : "v"(lo), "v"(hi)); return r; }
;     __device__ __forceinline__ void operator()(const f32x4 (&acc)[2][2][4][2], const Unit& u, int wr, int wc, int fr, int fq) const {
;         const int row0 = u.pm * BM + wr * 64 + fr, col0 = u.pn * BM + wc * 32 + 8 * fq;
;         float rsv[2][4]; load_rstd(rsv, ssq, row0);
; #pragma unroll
;         for (int ai = 0; ai < 2; ++ai)
; #pragma unroll
;             for (int m = 0; m < 4; ++m) { const int row = row0 + ai * HALF + m * 16; bf16_t* rowp = O + (size_t)row * ldc + col0; const float rs = rsv[ai][m];
; #pragma unroll
;                 for (int bj = 0; bj < 2; ++bj) { f32x4 v0 = acc[ai][bj][m][0] * rs, v1 = acc[ai][bj][m][1] * rs;
;                     if (ACT == 1) {
; #pragma unroll
;                         for (int j = 0; j < 4; ++j) { v0[j] = gelu_tanh(v0[j]); v1[j] = gelu_tanh(v1[j]); } }
;                     u32x4 w; w.x = cvt_pk_bf16(v0[0], v0[1]); w.y = cvt_pk_bf16(v0[2], v0[3]); w.z = cvt_pk_bf16(v1[0], v1[1]); w.w = cvt_pk_bf16(v1[2], v1[3]);
;                     *(u32x4*)(rowp + bj * HALF) = w; } }
; template <class Epi, bool ALIGN_EPI>
; __device__ __forceinline__ void gemm_phase(LAS unsigned char* lds, const Gemm g, const StaticOrder& S, const Epi& E, const int tid) {
;     ...
;             PG8_LDB(B0, 0, 0); PG8_LDB(B1, 0, 1); PG8_SCHED; PG8_LDA(At, 0, 0); PG8_STAGE(PG8_SA(1, 1), a1 + hA, voffA);
;             PG8_WAIT_V(8); PG8_WAIT_L(0); PG8_BAR; PG8_MMA(0, 0, At, B0); PG8_MMA(0, 1, At, B1); PG8_BAR; PG8_SCHED;
;             PG8_LDA(At, 0, 1); PG8_STAGE(PG8_SB(0, 0), b2, voffB); PG8_STAGE(PG8_SB(0, 1), b2 + hB, voffB); PG8_STAGE(PG8_SA(0, 0), a2, voffA);
;             PG8_WAIT_V(8); PG8_WAIT_L(0); PG8_BAR; PG8_MMA(1, 0, At, B0); PG8_MMA(1, 1, At, B1); PG8_BAR; PG8_SCHED;
;             PG8_LDB(B0, 1, 0); PG8_LDB(B1, 1, 1); PG8_SCHED; PG8_LDA(At, 1, 0); PG8_STAGE(PG8_SA(0, 1), a2 + hA, voffA);
;             PG8_WAIT_V(8); PG8_WAIT_L(0); PG8_BAR; PG8_MMA(0, 0, At, B0); PG8_MMA(0, 1, At, B1); PG8_BAR; PG8_SCHED;
;             PG8_LDA(At, 1, 1); PG8_STAGE(PG8_SB(1, 0), b3, voffB); PG8_STAGE(PG8_SB(1, 1), b3 + hB, voffB); PG8_STAGE(PG8_SA(1, 0), a3, voffA);
;             PG8_WAIT_V(8); PG8_WAIT_L(0); PG8_BAR; PG8_MMA(1, 0, At, B0); PG8_MMA(1, 1, At, B1); PG8_BAR; PG8_SCHED;
	v_mul_f32_e32 v13, v231, v13
	v_mul_f32_e32 v14, v231, v14
	v_mul_f32_e32 v15, v231, v15
	v_mul_f32_e32 v8, v231, v8
	v_mfma_f32_16x16x32_bf16 v[68:71], v[176:179], v[216:219], 0
	v_mul_f32_e32 v9, v231, v9
	v_mul_f32_e32 v10, v231, v10
	v_mul_f32_e32 v11, v231, v11
	v_cvt_pk_bf16_f32 v12, v12, v13
	v_mfma_f32_16x16x32_bf16 v[64:67], v[184:187], v[216:219], 0
	v_cvt_pk_bf16_f32 v13, v14, v15
	v_cvt_pk_bf16_f32 v14, v8, v9
	v_cvt_pk_bf16_f32 v15, v10, v11
	global_store_dwordx4 v[232:233], v[12:15], off
	v_mfma_f32_16x16x32_bf16 v[116:119], v[180:183], v[196:199], v[116:119]
	v_mul_f32_e32 v4, v231, v4
	v_mul_f32_e32 v5, v231, v5
	v_mul_f32_e32 v6, v231, v6
	v_mul_f32_e32 v7, v231, v7
	v_mfma_f32_16x16x32_bf16 v[112:115], v[188:191], v[196:199], v[112:115]
	v_mul_f32_e32 v0, v231, v0
	v_mul_f32_e32 v1, v231, v1
	v_mul_f32_e32 v2, v231, v2
	v_mul_f32_e32 v3, v231, v3
	v_mfma_f32_16x16x32_bf16 v[100:103], v[180:183], v[204:207], v[100:103]
	v_cvt_pk_bf16_f32 v4, v4, v5
	v_cvt_pk_bf16_f32 v5, v6, v7
	v_cvt_pk_bf16_f32 v6, v0, v1
	v_cvt_pk_bf16_f32 v7, v2, v3
	v_mfma_f32_16x16x32_bf16 v[96:99], v[188:191], v[204:207], v[96:99]
	global_store_dwordx4 v[232:233], v[4:7], off offset:256
	v_mfma_f32_16x16x32_bf16 v[84:87], v[180:183], v[212:215], v[84:87]
	v_mfma_f32_16x16x32_bf16 v[80:83], v[188:191], v[212:215], v[80:83]
	v_mfma_f32_16x16x32_bf16 v[68:71], v[180:183], v[240:243], v[68:71]
	v_mfma_f32_16x16x32_bf16 v[64:67], v[188:191], v[240:243], v[64:67]
	s_barrier
	s_setprio 0
	s_add_i32 s62, s33, s45
	v_lshl_add_u64 v[244:245], v[220:221], 0, v[168:169]
	s_mov_b32 m0, s62
	ds_read_b128 v[192:195], v151 offset:16384
	ds_read_b128 v[196:199], v151 offset:17408
	ds_read_b128 v[200:203], v151 offset:18432
	ds_read_b128 v[204:207], v151 offset:19456
	ds_read_b128 v[208:211], v151 offset:20480
	ds_read_b128 v[212:215], v151 offset:21504
	ds_read_b128 v[216:219], v151 offset:22528
	ds_read_b128 v[240:243], v151 offset:23552
	global_load_lds_dwordx4 v[244:245], off
	v_lshl_add_u64 v[246:247], v[220:221], 0, v[128:129]
	s_add_i32 m0, s62, 0x2000
	v_lshl_add_u64 v[220:221], v[220:221], 0, s[12:13]
	s_add_i32 s10, s10, s45
	global_load_lds_dwordx4 v[246:247], off
	v_lshl_add_u64 v[248:249], v[220:221], 0, v[168:169]
	s_mov_b32 m0, s10
	v_lshl_add_u64 v[220:221], v[220:221], 0, v[128:129]
	global_load_lds_dwordx4 v[248:249], off
	s_add_i32 m0, s10, 0x2000
	v_lshl_add_u64 v[250:251], v[146:147], 0, v[132:133]
	global_load_lds_dwordx4 v[220:221], off
	s_mov_b32 m0, s25
	v_lshl_add_u64 v[252:253], v[146:147], 0, v[130:131]
	global_load_lds_dwordx4 v[250:251], off
	s_mov_b32 m0, s50
	s_nop 0
	global_load_lds_dwordx4 v[252:253], off
	s_waitcnt vmcnt(24)
	s_waitcnt lgkmcnt(0)
	s_setprio 1
	s_barrier
	s_waitcnt lgkmcnt(0)
	v_mfma_f32_16x16x32_bf16 v[60:63], v[152:155], v[192:195], 0
	v_mfma_f32_16x16x32_bf16 v[56:59], v[160:163], v[192:195], 0
	v_mfma_f32_16x16x32_bf16 v[44:47], v[152:155], v[200:203], 0
	v_mfma_f32_16x16x32_bf16 v[40:43], v[160:163], v[200:203], 0
	v_mfma_f32_16x16x32_bf16 v[28:31], v[152:155], v[208:211], 0
	v_mfma_f32_16x16x32_bf16 v[24:27], v[160:163], v[208:211], 0
	v_mfma_f32_16x16x32_bf16 v[12:15], v[152:155], v[216:219], 0
	v_mfma_f32_16x16x32_bf16 v[8:11], v[160:163], v[216:219], 0
	v_mfma_f32_16x16x32_bf16 v[60:63], v[156:159], v[196:199], v[60:63]
	v_mfma_f32_16x16x32_bf16 v[56:59], v[164:167], v[196:199], v[56:59]
	v_mfma_f32_16x16x32_bf16 v[44:47], v[156:159], v[204:207], v[44:47]
	v_mfma_f32_16x16x32_bf16 v[40:43], v[164:167], v[204:207], v[40:43]
	v_mfma_f32_16x16x32_bf16 v[28:31], v[156:159], v[212:215], v[28:31]
	v_mfma_f32_16x16x32_bf16 v[24:27], v[164:167], v[212:215], v[24:27]
	v_mfma_f32_16x16x32_bf16 v[12:15], v[156:159], v[240:243], v[12:15]
	v_mfma_f32_16x16x32_bf16 v[8:11], v[164:167], v[240:243], v[8:11]
	s_setprio 0
	s_setprio 1
	v_mfma_f32_16x16x32_bf16 v[52:55], v[176:179], v[192:195], 0
	v_mfma_f32_16x16x32_bf16 v[48:51], v[184:187], v[192:195], 0
	v_mfma_f32_16x16x32_bf16 v[36:39], v[176:179], v[200:203], 0
	v_mfma_f32_16x16x32_bf16 v[32:35], v[184:187], v[200:203], 0
	v_mfma_f32_16x16x32_bf16 v[20:23], v[176:179], v[208:211], 0
	v_mfma_f32_16x16x32_bf16 v[16:19], v[184:187], v[208:211], 0
	v_mfma_f32_16x16x32_bf16 v[4:7], v[176:179], v[216:219], 0
	v_mfma_f32_16x16x32_bf16 v[0:3], v[184:187], v[216:219], 0
	v_mfma_f32_16x16x32_bf16 v[52:55], v[180:183], v[196:199], v[52:55]
	v_mfma_f32_16x16x32_bf16 v[48:51], v[188:191], v[196:199], v[48:51]
	v_mfma_f32_16x16x32_bf16 v[36:39], v[180:183], v[204:207], v[36:39]
	v_mfma_f32_16x16x32_bf16 v[32:35], v[188:191], v[204:207], v[32:35]
	v_mfma_f32_16x16x32_bf16 v[20:23], v[180:183], v[212:215], v[20:23]
	v_mfma_f32_16x16x32_bf16 v[16:19], v[188:191], v[212:215], v[16:19]
	v_mfma_f32_16x16x32_bf16 v[4:7], v[180:183], v[240:243], v[4:7]
	v_mfma_f32_16x16x32_bf16 v[0:3], v[188:191], v[240:243], v[0:3]
	s_barrier
	s_setprio 0
	s_add_i32 s10, 0, 0x18000
	v_add_u32_e32 v148, s10, v149
	s_add_i32 s62, 0, 0x1c000
	ds_read_b128 v[152:155], v148
	ds_read_b128 v[156:159], v148 offset:1024
	ds_read_b128 v[160:163], v148 offset:2048
	ds_read_b128 v[164:167], v148 offset:3072
	v_add_u32_e32 v148, s62, v149
	ds_read_b128 v[176:179], v148
	ds_read_b128 v[180:183], v148 offset:1024
	ds_read_b128 v[184:187], v148 offset:2048
	ds_read_b128 v[188:191], v148 offset:3072
	v_lshl_add_u64 v[146:147], v[146:147], 0, s[94:95]
	s_mov_b32 m0, s51
	v_lshl_add_u64 v[226:227], v[146:147], 0, v[132:133]
	ds_read_b128 v[192:195], v151 offset:32768
	ds_read_b128 v[196:199], v151 offset:33792
	ds_read_b128 v[200:203], v151 offset:34816
	ds_read_b128 v[204:207], v151 offset:35840
	ds_read_b128 v[208:211], v151 offset:36864
	ds_read_b128 v[212:215], v151 offset:37888
	ds_read_b128 v[216:219], v151 offset:38912
	ds_read_b128 v[240:243], v151 offset:39936
	global_load_lds_dwordx4 v[226:227], off
	v_lshl_add_u64 v[146:147], v[146:147], 0, v[130:131]
	s_mov_b32 m0, s52
	s_nop 0
	global_load_lds_dwordx4 v[146:147], off
	s_waitcnt vmcnt(16)
	s_waitcnt lgkmcnt(0)
	s_setprio 1
	s_barrier
; #define PG8_STAGE(bufoff, gbase, voff) do { _Pragma("unroll") for (int _i = 0; _i < 2; ++_i) \
;         __builtin_amdgcn_global_load_lds((const unsigned*)((const char*)(gbase) + (voff)[_i]), (LAS unsigned*)(lds + (bufoff) + ldsw + _i * 8192), 16, 0, 0); } while (0)
; #define PG8_LDA(dst, b, h) do { _Pragma("unroll") for (int m = 0; m < 4; ++m) _Pragma("unroll") for (int k = 0; k < 2; ++k) dst[m][k] = *(const LAS bf16x8*)(lds + PG8_SA(b, h) + aoff + m * 2048 + k * 1024); } while (0)
; #define PG8_LDB(dst, b, h) do { _Pragma("unroll") for (int n = 0; n < 2; ++n) _Pragma("unroll") for (int k = 0; k < 2; ++k) dst[n][k] = *(const LAS bf16x8*)(lds + PG8_SB(b, h) + boff + n * 2048 + k * 1024); } while (0)
; #define PG8_MMA(ai, bj, At, Bt) do { __builtin_amdgcn_s_setprio(1); _Pragma("unroll") for (int k = 0; k < 2; ++k) _Pragma("unroll") for (int m = 0; m < 4; ++m) _Pragma("unroll") for (int n = 0; n < 2; ++n) \
;         acc[ai][bj][m][n] = __builtin_amdgcn_mfma_f32_16x16x32_bf16(Bt[n][k], At[m][k], acc[ai][bj][m][n], 0, 0, 0); __builtin_amdgcn_s_setprio(0); } while (0)
; #define PG8_WAIT_V(n) asm volatile("s_waitcnt vmcnt(" #n ")" ::: "memory")
; #define PG8_BAR __builtin_amdgcn_s_barrier()
; template <class Epi, bool ALIGN_EPI>
; __device__ __forceinline__ void gemm_phase(LAS unsigned char* lds, const Gemm g, const StaticOrder& S, const Epi& E, const int tid) {
;     ...
;             PG8_LDB(B0, 0, 0); PG8_LDB(B1, 0, 1); PG8_SCHED; PG8_LDA(At, 0, 0); PG8_STAGE(PG8_SA(1, 1), a1 + hA, voffA);
;             PG8_WAIT_V(8); PG8_WAIT_L(0); PG8_BAR; PG8_MMA(0, 0, At, B0); PG8_MMA(0, 1, At, B1); PG8_BAR; PG8_SCHED;
;             PG8_LDA(At, 0, 1); PG8_STAGE(PG8_SB(0, 0), b2, voffB); PG8_STAGE(PG8_SB(0, 1), b2 + hB, voffB); PG8_STAGE(PG8_SA(0, 0), a2, voffA);
;             PG8_WAIT_V(8); PG8_WAIT_L(0); PG8_BAR; PG8_MMA(1, 0, At, B0); PG8_MMA(1, 1, At, B1); PG8_BAR; PG8_SCHED;
;             PG8_LDB(B0, 1, 0); PG8_LDB(B1, 1, 1); PG8_SCHED; PG8_LDA(At, 1, 0); PG8_STAGE(PG8_SA(0, 1), a2 + hA, voffA);
;             PG8_WAIT_V(8); PG8_WAIT_L(0); PG8_BAR; PG8_MMA(0, 0, At, B0); PG8_MMA(0, 1, At, B1); PG8_BAR; PG8_SCHED;
;             PG8_LDA(At, 1, 1); PG8_STAGE(PG8_SB(1, 0), b3, voffB); PG8_STAGE(PG8_SB(1, 1), b3 + hB, voffB); PG8_STAGE(PG8_SA(1, 0), a3, voffA);
;             PG8_WAIT_V(8); PG8_WAIT_L(0); PG8_BAR; PG8_MMA(1, 0, At, B0); PG8_MMA(1, 1, At, B1); PG8_BAR; PG8_SCHED;
	s_waitcnt lgkmcnt(0)
	v_mfma_f32_16x16x32_bf16 v[124:127], v[152:155], v[192:195], v[124:127]
	v_mfma_f32_16x16x32_bf16 v[120:123], v[160:163], v[192:195], v[120:123]
	v_mfma_f32_16x16x32_bf16 v[108:111], v[152:155], v[200:203], v[108:111]
	v_mfma_f32_16x16x32_bf16 v[104:107], v[160:163], v[200:203], v[104:107]
	v_mfma_f32_16x16x32_bf16 v[92:95], v[152:155], v[208:211], v[92:95]
	v_mfma_f32_16x16x32_bf16 v[88:91], v[160:163], v[208:211], v[88:91]
	v_mfma_f32_16x16x32_bf16 v[76:79], v[152:155], v[216:219], v[76:79]
	v_mfma_f32_16x16x32_bf16 v[72:75], v[160:163], v[216:219], v[72:75]
	v_mfma_f32_16x16x32_bf16 v[124:127], v[156:159], v[196:199], v[124:127]
	v_mfma_f32_16x16x32_bf16 v[120:123], v[164:167], v[196:199], v[120:123]
	v_mfma_f32_16x16x32_bf16 v[108:111], v[156:159], v[204:207], v[108:111]
	v_mfma_f32_16x16x32_bf16 v[104:107], v[164:167], v[204:207], v[104:107]
	v_mfma_f32_16x16x32_bf16 v[92:95], v[156:159], v[212:215], v[92:95]
	v_mfma_f32_16x16x32_bf16 v[88:91], v[164:167], v[212:215], v[88:91]
	v_mfma_f32_16x16x32_bf16 v[76:79], v[156:159], v[240:243], v[76:79]
	v_mfma_f32_16x16x32_bf16 v[72:75], v[164:167], v[240:243], v[72:75]
	s_setprio 0
	s_setprio 1
	v_mfma_f32_16x16x32_bf16 v[116:119], v[176:179], v[192:195], v[116:119]
	v_mfma_f32_16x16x32_bf16 v[112:115], v[184:187], v[192:195], v[112:115]
	v_mfma_f32_16x16x32_bf16 v[100:103], v[176:179], v[200:203], v[100:103]
	v_mfma_f32_16x16x32_bf16 v[96:99], v[184:187], v[200:203], v[96:99]
	v_mfma_f32_16x16x32_bf16 v[84:87], v[176:179], v[208:211], v[84:87]
	v_mfma_f32_16x16x32_bf16 v[80:83], v[184:187], v[208:211], v[80:83]
	v_mfma_f32_16x16x32_bf16 v[68:71], v[176:179], v[216:219], v[68:71]
	v_mfma_f32_16x16x32_bf16 v[64:67], v[184:187], v[216:219], v[64:67]
	v_mfma_f32_16x16x32_bf16 v[116:119], v[180:183], v[196:199], v[116:119]
	v_mfma_f32_16x16x32_bf16 v[112:115], v[188:191], v[196:199], v[112:115]
	v_mfma_f32_16x16x32_bf16 v[100:103], v[180:183], v[204:207], v[100:103]
	v_mfma_f32_16x16x32_bf16 v[96:99], v[188:191], v[204:207], v[96:99]
	v_mfma_f32_16x16x32_bf16 v[84:87], v[180:183], v[212:215], v[84:87]
	v_mfma_f32_16x16x32_bf16 v[80:83], v[188:191], v[212:215], v[80:83]
	v_mfma_f32_16x16x32_bf16 v[68:71], v[180:183], v[240:243], v[68:71]
	v_mfma_f32_16x16x32_bf16 v[64:67], v[188:191], v[240:243], v[64:67]
	s_barrier
	s_setprio 0
	s_add_i32 s10, s10, s45
	v_lshl_add_u64 v[146:147], v[244:245], 0, s[92:93]
	s_mov_b32 m0, s10
	ds_read_b128 v[192:195], v151 offset:49152
	ds_read_b128 v[196:199], v151 offset:50176
	ds_read_b128 v[200:203], v151 offset:51200
	ds_read_b128 v[204:207], v151 offset:52224
	ds_read_b128 v[208:211], v151 offset:53248
	ds_read_b128 v[212:215], v151 offset:54272
	ds_read_b128 v[216:219], v151 offset:55296
	ds_read_b128 v[240:243], v151 offset:56320
	global_load_lds_dwordx4 v[146:147], off
	v_lshl_add_u64 v[146:147], v[246:247], 0, s[92:93]
	s_add_i32 m0, s10, 0x2000
	s_add_i32 s10, s62, s45
	global_load_lds_dwordx4 v[146:147], off
	v_lshl_add_u64 v[146:147], v[248:249], 0, s[92:93]
	s_mov_b32 m0, s10
	s_nop 0
	global_load_lds_dwordx4 v[146:147], off
	v_lshl_add_u64 v[146:147], v[220:221], 0, s[92:93]
	s_add_i32 m0, s10, 0x2000
	s_nop 0
	global_load_lds_dwordx4 v[146:147], off
	v_lshl_add_u64 v[146:147], v[250:251], 0, s[92:93]
	s_mov_b32 m0, s53
	s_nop 0
	global_load_lds_dwordx4 v[146:147], off
	v_lshl_add_u64 v[146:147], v[252:253], 0, s[92:93]
	s_mov_b32 m0, s54
	s_nop 0
	global_load_lds_dwordx4 v[146:147], off
	s_waitcnt vmcnt(8)
	s_waitcnt lgkmcnt(0)
	s_setprio 1
	s_barrier
	s_waitcnt lgkmcnt(0)
	v_mfma_f32_16x16x32_bf16 v[60:63], v[152:155], v[192:195], v[60:63]
	v_mfma_f32_16x16x32_bf16 v[56:59], v[160:163], v[192:195], v[56:59]
	v_mfma_f32_16x16x32_bf16 v[44:47], v[152:155], v[200:203], v[44:47]
	v_mfma_f32_16x16x32_bf16 v[40:43], v[160:163], v[200:203], v[40:43]
	v_mfma_f32_16x16x32_bf16 v[28:31], v[152:155], v[208:211], v[28:31]
	v_mfma_f32_16x16x32_bf16 v[24:27], v[160:163], v[208:211], v[24:27]
	v_mfma_f32_16x16x32_bf16 v[12:15], v[152:155], v[216:219], v[12:15]
	v_mfma_f32_16x16x32_bf16 v[8:11], v[160:163], v[216:219], v[8:11]
	v_mfma_f32_16x16x32_bf16 v[60:63], v[156:159], v[196:199], v[60:63]
	v_mfma_f32_16x16x32_bf16 v[56:59], v[164:167], v[196:199], v[56:59]
	v_mfma_f32_16x16x32_bf16 v[44:47], v[156:159], v[204:207], v[44:47]
	v_mfma_f32_16x16x32_bf16 v[40:43], v[164:167], v[204:207], v[40:43]
	v_mfma_f32_16x16x32_bf16 v[28:31], v[156:159], v[212:215], v[28:31]
	v_mfma_f32_16x16x32_bf16 v[24:27], v[164:167], v[212:215], v[24:27]
	v_mfma_f32_16x16x32_bf16 v[12:15], v[156:159], v[240:243], v[12:15]
	v_mfma_f32_16x16x32_bf16 v[8:11], v[164:167], v[240:243], v[8:11]
	s_setprio 0
	s_setprio 1
	v_mfma_f32_16x16x32_bf16 v[52:55], v[176:179], v[192:195], v[52:55]
	v_mfma_f32_16x16x32_bf16 v[48:51], v[184:187], v[192:195], v[48:51]
	v_mfma_f32_16x16x32_bf16 v[36:39], v[176:179], v[200:203], v[36:39]
	v_mfma_f32_16x16x32_bf16 v[32:35], v[184:187], v[200:203], v[32:35]
	v_mfma_f32_16x16x32_bf16 v[20:23], v[176:179], v[208:211], v[20:23]
	v_mfma_f32_16x16x32_bf16 v[16:19], v[184:187], v[208:211], v[16:19]
	v_mfma_f32_16x16x32_bf16 v[4:7], v[176:179], v[216:219], v[4:7]
	v_mfma_f32_16x16x32_bf16 v[0:3], v[184:187], v[216:219], v[0:3]
	v_mfma_f32_16x16x32_bf16 v[52:55], v[180:183], v[196:199], v[52:55]
	v_mfma_f32_16x16x32_bf16 v[48:51], v[188:191], v[196:199], v[48:51]
	v_mfma_f32_16x16x32_bf16 v[36:39], v[180:183], v[204:207], v[36:39]
	v_mfma_f32_16x16x32_bf16 v[32:35], v[188:191], v[204:207], v[32:35]
	v_mfma_f32_16x16x32_bf16 v[20:23], v[180:183], v[212:215], v[20:23]
	v_mfma_f32_16x16x32_bf16 v[16:19], v[188:191], v[212:215], v[16:19]
	v_mfma_f32_16x16x32_bf16 v[4:7], v[180:183], v[240:243], v[4:7]
	v_mfma_f32_16x16x32_bf16 v[0:3], v[188:191], v[240:243], v[0:3]
	s_barrier
	s_setprio 0
	v_lshl_add_u64 v[142:143], v[142:143], 0, s[80:81]
	v_lshl_add_u64 v[144:145], v[144:145], 0, s[80:81]
	s_mov_b32 s10, s11
	s_cmp_eq_u32 s10, s55
	s_cbranch_scc1 .Lq5_last
	s_branch .LBB0_354
.Lq5_first:
	s_add_i32 s11, s10, 2
	s_cmp_eq_u32 s55, s10
	s_cselect_b64 vcc, -1, 0
	v_add_u32_e32 v148, s33, v149
	s_add_i32 s10, 0, 0x14000
	ds_read_b128 v[152:155], v148
	ds_read_b128 v[156:159], v148 offset:1024
	ds_read_b128 v[160:163], v148 offset:2048
	ds_read_b128 v[164:167], v148 offset:3072
	v_add_u32_e32 v148, s10, v149
	ds_read_b128 v[176:179], v148
	ds_read_b128 v[180:183], v148 offset:1024
	ds_read_b128 v[184:187], v148 offset:2048
	ds_read_b128 v[188:191], v148 offset:3072
	v_lshl_add_u64 v[146:147], v[142:143], 0, s[92:93]
	v_cndmask_b32_e32 v147, v147, v139, vcc
	v_cndmask_b32_e32 v146, v146, v138, vcc
	v_cndmask_b32_e32 v221, v145, v141, vcc
	v_cndmask_b32_e32 v220, v144, v140, vcc
	v_lshl_add_u64 v[244:245], v[142:143], 0, v[134:135]
	s_add_i32 m0, s25, 0xc000
	ds_read_b128 v[192:195], v151
	ds_read_b128 v[196:199], v151 offset:1024
	ds_read_b128 v[200:203], v151 offset:2048
	ds_read_b128 v[204:207], v151 offset:3072
	ds_read_b128 v[208:211], v151 offset:4096
	ds_read_b128 v[212:215], v151 offset:5120
	ds_read_b128 v[216:219], v151 offset:6144
	ds_read_b128 v[240:243], v151 offset:7168
	global_load_lds_dwordx4 v[244:245], off
	v_lshl_add_u64 v[244:245], v[142:143], 0, v[136:137]
	s_add_i32 m0, s25, 0xe000
	s_nop 0
	global_load_lds_dwordx4 v[244:245], off
	s_waitcnt vmcnt(8)
	s_waitcnt lgkmcnt(0)
	s_setprio 1
	s_barrier
	s_waitcnt lgkmcnt(0)
	v_mfma_f32_16x16x32_bf16 v[124:127], v[152:155], v[192:195], 0
	v_mfma_f32_16x16x32_bf16 v[120:123], v[160:163], v[192:195], 0
	v_mfma_f32_16x16x32_bf16 v[108:111], v[152:155], v[200:203], 0
	v_mfma_f32_16x16x32_bf16 v[104:107], v[160:163], v[200:203], 0
	v_mfma_f32_16x16x32_bf16 v[92:95], v[152:155], v[208:211], 0
	v_mfma_f32_16x16x32_bf16 v[88:91], v[160:163], v[208:211], 0
	v_mfma_f32_16x16x32_bf16 v[76:79], v[152:155], v[216:219], 0
	v_mfma_f32_16x16x32_bf16 v[72:75], v[160:163], v[216:219], 0
	v_mfma_f32_16x16x32_bf16 v[124:127], v[156:159], v[196:199], v[124:127]
	v_mfma_f32_16x16x32_bf16 v[120:123], v[164:167], v[196:199], v[120:123]
	v_mfma_f32_16x16x32_bf16 v[108:111], v[156:159], v[204:207], v[108:111]
	v_mfma_f32_16x16x32_bf16 v[104:107], v[164:167], v[204:207], v[104:107]
	v_mfma_f32_16x16x32_bf16 v[92:95], v[156:159], v[212:215], v[92:95]
	v_mfma_f32_16x16x32_bf16 v[88:91], v[164:167], v[212:215], v[88:91]
	v_mfma_f32_16x16x32_bf16 v[76:79], v[156:159], v[240:243], v[76:79]
	v_mfma_f32_16x16x32_bf16 v[72:75], v[164:167], v[240:243], v[72:75]
	s_setprio 0
	s_setprio 1
	v_mfma_f32_16x16x32_bf16 v[116:119], v[176:179], v[192:195], 0
	v_mfma_f32_16x16x32_bf16 v[112:115], v[184:187], v[192:195], 0
	v_mfma_f32_16x16x32_bf16 v[100:103], v[176:179], v[200:203], 0
	v_mfma_f32_16x16x32_bf16 v[96:99], v[184:187], v[200:203], 0
	v_mfma_f32_16x16x32_bf16 v[84:87], v[176:179], v[208:211], 0
	v_mfma_f32_16x16x32_bf16 v[80:83], v[184:187], v[208:211], 0
	v_mfma_f32_16x16x32_bf16 v[68:71], v[176:179], v[216:219], 0
	v_mfma_f32_16x16x32_bf16 v[64:67], v[184:187], v[216:219], 0
	v_mfma_f32_16x16x32_bf16 v[116:119], v[180:183], v[196:199], v[116:119]
	v_mfma_f32_16x16x32_bf16 v[112:115], v[188:191], v[196:199], v[112:115]
	v_mfma_f32_16x16x32_bf16 v[100:103], v[180:183], v[204:207], v[100:103]
	v_mfma_f32_16x16x32_bf16 v[96:99], v[188:191], v[204:207], v[96:99]
	v_mfma_f32_16x16x32_bf16 v[84:87], v[180:183], v[212:215], v[84:87]
	v_mfma_f32_16x16x32_bf16 v[80:83], v[188:191], v[212:215], v[80:83]
	v_mfma_f32_16x16x32_bf16 v[68:71], v[180:183], v[240:243], v[68:71]
	v_mfma_f32_16x16x32_bf16 v[64:67], v[188:191], v[240:243], v[64:67]
	s_barrier
	s_setprio 0
	s_add_i32 s62, s33, s45
	v_lshl_add_u64 v[244:245], v[220:221], 0, v[168:169]
	s_mov_b32 m0, s62
	ds_read_b128 v[192:195], v151 offset:16384
	ds_read_b128 v[196:199], v151 offset:17408
	ds_read_b128 v[200:203], v151 offset:18432
	ds_read_b128 v[204:207], v151 offset:19456
	ds_read_b128 v[208:211], v151 offset:20480
	ds_read_b128 v[212:215], v151 offset:21504
	ds_read_b128 v[216:219], v151 offset:22528
	ds_read_b128 v[240:243], v151 offset:23552
	global_load_lds_dwordx4 v[244:245], off
	v_lshl_add_u64 v[246:247], v[220:221], 0, v[128:129]
	s_add_i32 m0, s62, 0x2000
	v_lshl_add_u64 v[220:221], v[220:221], 0, s[12:13]
	s_add_i32 s10, s10, s45
	global_load_lds_dwordx4 v[246:247], off
	v_lshl_add_u64 v[248:249], v[220:221], 0, v[168:169]
	s_mov_b32 m0, s10
	v_lshl_add_u64 v[220:221], v[220:221], 0, v[128:129]
	global_load_lds_dwordx4 v[248:249], off
	s_add_i32 m0, s10, 0x2000
	v_lshl_add_u64 v[250:251], v[146:147], 0, v[132:133]
	global_load_lds_dwordx4 v[220:221], off
	s_mov_b32 m0, s25
	v_lshl_add_u64 v[252:253], v[146:147], 0, v[130:131]
	global_load_lds_dwordx4 v[250:251], off
	s_mov_b32 m0, s50
	s_nop 0
	global_load_lds_dwordx4 v[252:253], off
	s_waitcnt vmcnt(8)
	s_waitcnt lgkmcnt(0)
	s_setprio 1
	s_barrier
; #define PG8_STAGE(bufoff, gbase, voff) do { _Pragma("unroll") for (int _i = 0; _i < 2; ++_i) \
;         __builtin_amdgcn_global_load_lds((const unsigned*)((const char*)(gbase) + (voff)[_i]), (LAS unsigned*)(lds + (bufoff) + ldsw + _i * 8192), 16, 0, 0); } while (0)
; #define PG8_LDA(dst, b, h) do { _Pragma("unroll") for (int m = 0; m < 4; ++m) _Pragma("unroll") for (int k = 0; k < 2; ++k) dst[m][k] = *(const LAS bf16x8*)(lds + PG8_SA(b, h) + aoff + m * 2048 + k * 1024); } while (0)
; #define PG8_LDB(dst, b, h) do { _Pragma("unroll") for (int n = 0; n < 2; ++n) _Pragma("unroll") for (int k = 0; k < 2; ++k) dst[n][k] = *(const LAS bf16x8*)(lds + PG8_SB(b, h) + boff + n * 2048 + k * 1024); } while (0)
; #define PG8_MMA(ai, bj, At, Bt) do { __builtin_amdgcn_s_setprio(1); _Pragma("unroll") for (int k = 0; k < 2; ++k) _Pragma("unroll") for (int m = 0; m < 4; ++m) _Pragma("unroll") for (int n = 0; n < 2; ++n) \
;         acc[ai][bj][m][n] = __builtin_amdgcn_mfma_f32_16x16x32_bf16(Bt[n][k], At[m][k], acc[ai][bj][m][n], 0, 0, 0); __builtin_amdgcn_s_setprio(0); } while (0)
; #define PG8_WAIT_V(n) asm volatile("s_waitcnt vmcnt(" #n ")" ::: "memory")
; #define PG8_BAR __builtin_amdgcn_s_barrier()
; template <class Epi, bool ALIGN_EPI>
; __device__ __forceinline__ void gemm_phase(LAS unsigned char* lds, const Gemm g, const StaticOrder& S, const Epi& E, const int tid) {
;     ...
;             PG8_LDB(B0, 0, 0); PG8_LDB(B1, 0, 1); PG8_SCHED; PG8_LDA(At, 0, 0); PG8_STAGE(PG8_SA(1, 1), a1 + hA, voffA);
;             PG8_WAIT_V(8); PG8_WAIT_L(0); PG8_BAR; PG8_MMA(0, 0, At, B0); PG8_MMA(0, 1, At, B1); PG8_BAR; PG8_SCHED;
;             PG8_LDA(At, 0, 1); PG8_STAGE(PG8_SB(0, 0), b2, voffB); PG8_STAGE(PG8_SB(0, 1), b2 + hB, voffB); PG8_STAGE(PG8_SA(0, 0), a2, voffA);
;             PG8_WAIT_V(8); PG8_WAIT_L(0); PG8_BAR; PG8_MMA(1, 0, At, B0); PG8_MMA(1, 1, At, B1); PG8_BAR; PG8_SCHED;
;             PG8_LDB(B0, 1, 0); PG8_LDB(B1, 1, 1); PG8_SCHED; PG8_LDA(At, 1, 0); PG8_STAGE(PG8_SA(0, 1), a2 + hA, voffA);
;             PG8_WAIT_V(8); PG8_WAIT_L(0); PG8_BAR; PG8_MMA(0, 0, At, B0); PG8_MMA(0, 1, At, B1); PG8_BAR; PG8_SCHED;
;             PG8_LDA(At, 1, 1); PG8_STAGE(PG8_SB(1, 0), b3, voffB); PG8_STAGE(PG8_SB(1, 1), b3 + hB, voffB); PG8_STAGE(PG8_SA(1, 0), a3, voffA);
;             PG8_WAIT_V(8); PG8_WAIT_L(0); PG8_BAR; PG8_MMA(1, 0, At, B0); PG8_MMA(1, 1, At, B1); PG8_BAR; PG8_SCHED;
	s_waitcnt lgkmcnt(0)
	v_mfma_f32_16x16x32_bf16 v[60:63], v[152:155], v[192:195], 0
	v_mfma_f32_16x16x32_bf16 v[56:59], v[160:163], v[192:195], 0
	v_mfma_f32_16x16x32_bf16 v[44:47], v[152:155], v[200:203], 0
	v_mfma_f32_16x16x32_bf16 v[40:43], v[160:163], v[200:203], 0
	v_mfma_f32_16x16x32_bf16 v[28:31], v[152:155], v[208:211], 0
	v_mfma_f32_16x16x32_bf16 v[24:27], v[160:163], v[208:211], 0
	v_mfma_f32_16x16x32_bf16 v[12:15], v[152:155], v[216:219], 0
	v_mfma_f32_16x16x32_bf16 v[8:11], v[160:163], v[216:219], 0
	v_mfma_f32_16x16x32_bf16 v[60:63], v[156:159], v[196:199], v[60:63]
	v_mfma_f32_16x16x32_bf16 v[56:59], v[164:167], v[196:199], v[56:59]
	v_mfma_f32_16x16x32_bf16 v[44:47], v[156:159], v[204:207], v[44:47]
	v_mfma_f32_16x16x32_bf16 v[40:43], v[164:167], v[204:207], v[40:43]
	v_mfma_f32_16x16x32_bf16 v[28:31], v[156:159], v[212:215], v[28:31]
	v_mfma_f32_16x16x32_bf16 v[24:27], v[164:167], v[212:215], v[24:27]
	v_mfma_f32_16x16x32_bf16 v[12:15], v[156:159], v[240:243], v[12:15]
	v_mfma_f32_16x16x32_bf16 v[8:11], v[164:167], v[240:243], v[8:11]
	s_setprio 0
	s_setprio 1
	v_mfma_f32_16x16x32_bf16 v[52:55], v[176:179], v[192:195], 0
	v_mfma_f32_16x16x32_bf16 v[48:51], v[184:187], v[192:195], 0
	v_mfma_f32_16x16x32_bf16 v[36:39], v[176:179], v[200:203], 0
	v_mfma_f32_16x16x32_bf16 v[32:35], v[184:187], v[200:203], 0
	v_mfma_f32_16x16x32_bf16 v[20:23], v[176:179], v[208:211], 0
	v_mfma_f32_16x16x32_bf16 v[16:19], v[184:187], v[208:211], 0
	v_mfma_f32_16x16x32_bf16 v[4:7], v[176:179], v[216:219], 0
	v_mfma_f32_16x16x32_bf16 v[0:3], v[184:187], v[216:219], 0
	v_mfma_f32_16x16x32_bf16 v[52:55], v[180:183], v[196:199], v[52:55]
	v_mfma_f32_16x16x32_bf16 v[48:51], v[188:191], v[196:199], v[48:51]
	v_mfma_f32_16x16x32_bf16 v[36:39], v[180:183], v[204:207], v[36:39]
	v_mfma_f32_16x16x32_bf16 v[32:35], v[188:191], v[204:207], v[32:35]
	v_mfma_f32_16x16x32_bf16 v[20:23], v[180:183], v[212:215], v[20:23]
	v_mfma_f32_16x16x32_bf16 v[16:19], v[188:191], v[212:215], v[16:19]
	v_mfma_f32_16x16x32_bf16 v[4:7], v[180:183], v[240:243], v[4:7]
	v_mfma_f32_16x16x32_bf16 v[0:3], v[188:191], v[240:243], v[0:3]
	s_barrier
	s_setprio 0
	s_add_i32 s10, 0, 0x18000
	v_add_u32_e32 v148, s10, v149
	s_add_i32 s62, 0, 0x1c000
	ds_read_b128 v[152:155], v148
	ds_read_b128 v[156:159], v148 offset:1024
	ds_read_b128 v[160:163], v148 offset:2048
	ds_read_b128 v[164:167], v148 offset:3072
	v_add_u32_e32 v148, s62, v149
	ds_read_b128 v[176:179], v148
	ds_read_b128 v[180:183], v148 offset:1024
	ds_read_b128 v[184:187], v148 offset:2048
	ds_read_b128 v[188:191], v148 offset:3072
	v_lshl_add_u64 v[146:147], v[146:147], 0, s[94:95]
	s_mov_b32 m0, s51
	v_lshl_add_u64 v[226:227], v[146:147], 0, v[132:133]
	ds_read_b128 v[192:195], v151 offset:32768
	ds_read_b128 v[196:199], v151 offset:33792
	ds_read_b128 v[200:203], v151 offset:34816
	ds_read_b128 v[204:207], v151 offset:35840
	ds_read_b128 v[208:211], v151 offset:36864
	ds_read_b128 v[212:215], v151 offset:37888
	ds_read_b128 v[216:219], v151 offset:38912
	ds_read_b128 v[240:243], v151 offset:39936
	global_load_lds_dwordx4 v[226:227], off
	v_lshl_add_u64 v[146:147], v[146:147], 0, v[130:131]
	s_mov_b32 m0, s52
	s_nop 0
	global_load_lds_dwordx4 v[146:147], off
	s_waitcnt vmcnt(8)
	s_waitcnt lgkmcnt(0)
	s_setprio 1
	s_barrier
	s_waitcnt lgkmcnt(0)
	v_mfma_f32_16x16x32_bf16 v[124:127], v[152:155], v[192:195], v[124:127]
	v_mfma_f32_16x16x32_bf16 v[120:123], v[160:163], v[192:195], v[120:123]
	v_mfma_f32_16x16x32_bf16 v[108:111], v[152:155], v[200:203], v[108:111]
	v_mfma_f32_16x16x32_bf16 v[104:107], v[160:163], v[200:203], v[104:107]
	v_mfma_f32_16x16x32_bf16 v[92:95], v[152:155], v[208:211], v[92:95]
	v_mfma_f32_16x16x32_bf16 v[88:91], v[160:163], v[208:211], v[88:91]
	v_mfma_f32_16x16x32_bf16 v[76:79], v[152:155], v[216:219], v[76:79]
	v_mfma_f32_16x16x32_bf16 v[72:75], v[160:163], v[216:219], v[72:75]
	v_mfma_f32_16x16x32_bf16 v[124:127], v[156:159], v[196:199], v[124:127]
	v_mfma_f32_16x16x32_bf16 v[120:123], v[164:167], v[196:199], v[120:123]
	v_mfma_f32_16x16x32_bf16 v[108:111], v[156:159], v[204:207], v[108:111]
	v_mfma_f32_16x16x32_bf16 v[104:107], v[164:167], v[204:207], v[104:107]
	v_mfma_f32_16x16x32_bf16 v[92:95], v[156:159], v[212:215], v[92:95]
	v_mfma_f32_16x16x32_bf16 v[88:91], v[164:167], v[212:215], v[88:91]
	v_mfma_f32_16x16x32_bf16 v[76:79], v[156:159], v[240:243], v[76:79]
	v_mfma_f32_16x16x32_bf16 v[72:75], v[164:167], v[240:243], v[72:75]
	s_setprio 0
	s_setprio 1
	v_mfma_f32_16x16x32_bf16 v[116:119], v[176:179], v[192:195], v[116:119]
	v_mfma_f32_16x16x32_bf16 v[112:115], v[184:187], v[192:195], v[112:115]
	v_mfma_f32_16x16x32_bf16 v[100:103], v[176:179], v[200:203], v[100:103]
	v_mfma_f32_16x16x32_bf16 v[96:99], v[184:187], v[200:203], v[96:99]
	v_mfma_f32_16x16x32_bf16 v[84:87], v[176:179], v[208:211], v[84:87]
	v_mfma_f32_16x16x32_bf16 v[80:83], v[184:187], v[208:211], v[80:83]
	v_mfma_f32_16x16x32_bf16 v[68:71], v[176:179], v[216:219], v[68:71]
	v_mfma_f32_16x16x32_bf16 v[64:67], v[184:187], v[216:219], v[64:67]
	v_mfma_f32_16x16x32_bf16 v[116:119], v[180:183], v[196:199], v[116:119]
	v_mfma_f32_16x16x32_bf16 v[112:115], v[188:191], v[196:199], v[112:115]
	v_mfma_f32_16x16x32_bf16 v[100:103], v[180:183], v[204:207], v[100:103]
	v_mfma_f32_16x16x32_bf16 v[96:99], v[188:191], v[204:207], v[96:99]
	v_mfma_f32_16x16x32_bf16 v[84:87], v[180:183], v[212:215], v[84:87]
	v_mfma_f32_16x16x32_bf16 v[80:83], v[188:191], v[212:215], v[80:83]
	v_mfma_f32_16x16x32_bf16 v[68:71], v[180:183], v[240:243], v[68:71]
	v_mfma_f32_16x16x32_bf16 v[64:67], v[188:191], v[240:243], v[64:67]
	s_barrier
; #define PG8_STAGE(bufoff, gbase, voff) do { _Pragma("unroll") for (int _i = 0; _i < 2; ++_i) \
;         __builtin_amdgcn_global_load_lds((const unsigned*)((const char*)(gbase) + (voff)[_i]), (LAS unsigned*)(lds + (bufoff) + ldsw + _i * 8192), 16, 0, 0); } while (0)
; #define PG8_LDA(dst, b, h) do { _Pragma("unroll") for (int m = 0; m < 4; ++m) _Pragma("unroll") for (int k = 0; k < 2; ++k) dst[m][k] = *(const LAS bf16x8*)(lds + PG8_SA(b, h) + aoff + m * 2048 + k * 1024); } while (0)
; #define PG8_LDB(dst, b, h) do { _Pragma("unroll") for (int n = 0; n < 2; ++n) _Pragma("unroll") for (int k = 0; k < 2; ++k) dst[n][k] = *(const LAS bf16x8*)(lds + PG8_SB(b, h) + boff + n * 2048 + k * 1024); } while (0)
; #define PG8_MMA(ai, bj, At, Bt) do { __builtin_amdgcn_s_setprio(1); _Pragma("unroll") for (int k = 0; k < 2; ++k) _Pragma("unroll") for (int m = 0; m < 4; ++m) _Pragma("unroll") for (int n = 0; n < 2; ++n) \
;         acc[ai][bj][m][n] = __builtin_amdgcn_mfma_f32_16x16x32_bf16(Bt[n][k], At[m][k], acc[ai][bj][m][n], 0, 0, 0); __builtin_amdgcn_s_setprio(0); } while (0)
; #define PG8_WAIT_V(n) asm volatile("s_waitcnt vmcnt(" #n ")" ::: "memory")
; #define PG8_BAR __builtin_amdgcn_s_barrier()
; template <class Epi, bool ALIGN_EPI>
; __device__ __forceinline__ void gemm_phase(LAS unsigned char* lds, const Gemm g, const StaticOrder& S, const Epi& E, const int tid) {
;     ...
;             PG8_LDB(B0, 0, 0); PG8_LDB(B1, 0, 1); PG8_SCHED; PG8_LDA(At, 0, 0); PG8_STAGE(PG8_SA(1, 1), a1 + hA, voffA);
;             PG8_WAIT_V(8); PG8_WAIT_L(0); PG8_BAR; PG8_MMA(0, 0, At, B0); PG8_MMA(0, 1, At, B1); PG8_BAR; PG8_SCHED;
;             PG8_LDA(At, 0, 1); PG8_STAGE(PG8_SB(0, 0), b2, voffB); PG8_STAGE(PG8_SB(0, 1), b2 + hB, voffB); PG8_STAGE(PG8_SA(0, 0), a2, voffA);
;             PG8_WAIT_V(8); PG8_WAIT_L(0); PG8_BAR; PG8_MMA(1, 0, At, B0); PG8_MMA(1, 1, At, B1); PG8_BAR; PG8_SCHED;
;             PG8_LDB(B0, 1, 0); PG8_LDB(B1, 1, 1); PG8_SCHED; PG8_LDA(At, 1, 0); PG8_STAGE(PG8_SA(0, 1), a2 + hA, voffA);
;             PG8_WAIT_V(8); PG8_WAIT_L(0); PG8_BAR; PG8_MMA(0, 0, At, B0); PG8_MMA(0, 1, At, B1); PG8_BAR; PG8_SCHED;
;             PG8_LDA(At, 1, 1); PG8_STAGE(PG8_SB(1, 0), b3, voffB); PG8_STAGE(PG8_SB(1, 1), b3 + hB, voffB); PG8_STAGE(PG8_SA(1, 0), a3, voffA);
;             PG8_WAIT_V(8); PG8_WAIT_L(0); PG8_BAR; PG8_MMA(1, 0, At, B0); PG8_MMA(1, 1, At, B1); PG8_BAR; PG8_SCHED;
	s_setprio 0
	s_add_i32 s10, s10, s45
	v_lshl_add_u64 v[146:147], v[244:245], 0, s[92:93]
	s_mov_b32 m0, s10
	ds_read_b128 v[192:195], v151 offset:49152
	ds_read_b128 v[196:199], v151 offset:50176
	ds_read_b128 v[200:203], v151 offset:51200
	ds_read_b128 v[204:207], v151 offset:52224
	ds_read_b128 v[208:211], v151 offset:53248
	ds_read_b128 v[212:215], v151 offset:54272
	ds_read_b128 v[216:219], v151 offset:55296
	ds_read_b128 v[240:243], v151 offset:56320
	global_load_lds_dwordx4 v[146:147], off
	v_lshl_add_u64 v[146:147], v[246:247], 0, s[92:93]
	s_add_i32 m0, s10, 0x2000
	s_add_i32 s10, s62, s45
	global_load_lds_dwordx4 v[146:147], off
	v_lshl_add_u64 v[146:147], v[248:249], 0, s[92:93]
	s_mov_b32 m0, s10
	s_nop 0
	global_load_lds_dwordx4 v[146:147], off
	v_lshl_add_u64 v[146:147], v[220:221], 0, s[92:93]
	s_add_i32 m0, s10, 0x2000
	s_nop 0
	global_load_lds_dwordx4 v[146:147], off
	v_lshl_add_u64 v[146:147], v[250:251], 0, s[92:93]
	s_mov_b32 m0, s53
	s_nop 0
	global_load_lds_dwordx4 v[146:147], off
	v_lshl_add_u64 v[146:147], v[252:253], 0, s[92:93]
	s_mov_b32 m0, s54
	s_nop 0
	global_load_lds_dwordx4 v[146:147], off
	s_waitcnt vmcnt(8)
	s_waitcnt lgkmcnt(0)
	s_setprio 1
	s_barrier
	s_waitcnt lgkmcnt(0)
	v_mfma_f32_16x16x32_bf16 v[60:63], v[152:155], v[192:195], v[60:63]
	v_mfma_f32_16x16x32_bf16 v[56:59], v[160:163], v[192:195], v[56:59]
	v_mfma_f32_16x16x32_bf16 v[44:47], v[152:155], v[200:203], v[44:47]
	v_mfma_f32_16x16x32_bf16 v[40:43], v[160:163], v[200:203], v[40:43]
	v_mfma_f32_16x16x32_bf16 v[28:31], v[152:155], v[208:211], v[28:31]
	v_mfma_f32_16x16x32_bf16 v[24:27], v[160:163], v[208:211], v[24:27]
	v_mfma_f32_16x16x32_bf16 v[12:15], v[152:155], v[216:219], v[12:15]
	v_mfma_f32_16x16x32_bf16 v[8:11], v[160:163], v[216:219], v[8:11]
	v_mfma_f32_16x16x32_bf16 v[60:63], v[156:159], v[196:199], v[60:63]
	v_mfma_f32_16x16x32_bf16 v[56:59], v[164:167], v[196:199], v[56:59]
	v_mfma_f32_16x16x32_bf16 v[44:47], v[156:159], v[204:207], v[44:47]
	v_mfma_f32_16x16x32_bf16 v[40:43], v[164:167], v[204:207], v[40:43]
	v_mfma_f32_16x16x32_bf16 v[28:31], v[156:159], v[212:215], v[28:31]
	v_mfma_f32_16x16x32_bf16 v[24:27], v[164:167], v[212:215], v[24:27]
	v_mfma_f32_16x16x32_bf16 v[12:15], v[156:159], v[240:243], v[12:15]
	v_mfma_f32_16x16x32_bf16 v[8:11], v[164:167], v[240:243], v[8:11]
	s_setprio 0
	s_setprio 1
	v_mfma_f32_16x16x32_bf16 v[52:55], v[176:179], v[192:195], v[52:55]
	v_mfma_f32_16x16x32_bf16 v[48:51], v[184:187], v[192:195], v[48:51]
	v_mfma_f32_16x16x32_bf16 v[36:39], v[176:179], v[200:203], v[36:39]
	v_mfma_f32_16x16x32_bf16 v[32:35], v[184:187], v[200:203], v[32:35]
	v_mfma_f32_16x16x32_bf16 v[20:23], v[176:179], v[208:211], v[20:23]
	v_mfma_f32_16x16x32_bf16 v[16:19], v[184:187], v[208:211], v[16:19]
	v_mfma_f32_16x16x32_bf16 v[4:7], v[176:179], v[216:219], v[4:7]
	v_mfma_f32_16x16x32_bf16 v[0:3], v[184:187], v[216:219], v[0:3]
	v_mfma_f32_16x16x32_bf16 v[52:55], v[180:183], v[196:199], v[52:55]
	v_mfma_f32_16x16x32_bf16 v[48:51], v[188:191], v[196:199], v[48:51]
	v_mfma_f32_16x16x32_bf16 v[36:39], v[180:183], v[204:207], v[36:39]
	v_mfma_f32_16x16x32_bf16 v[32:35], v[188:191], v[204:207], v[32:35]
	v_mfma_f32_16x16x32_bf16 v[20:23], v[180:183], v[212:215], v[20:23]
	v_mfma_f32_16x16x32_bf16 v[16:19], v[188:191], v[212:215], v[16:19]
	v_mfma_f32_16x16x32_bf16 v[4:7], v[180:183], v[240:243], v[4:7]
	v_mfma_f32_16x16x32_bf16 v[0:3], v[188:191], v[240:243], v[0:3]
	s_barrier
	s_setprio 0
	v_lshl_add_u64 v[142:143], v[142:143], 0, s[80:81]
	v_lshl_add_u64 v[144:145], v[144:145], 0, s[80:81]
	s_mov_b32 s10, s11
	s_cmp_eq_u32 s10, s55
	s_cbranch_scc1 .Lq5_last
.LBB0_354:
	s_add_i32 s11, s10, 2
	s_cmp_eq_u32 s55, s10
	s_cselect_b64 vcc, -1, 0
	v_add_u32_e32 v148, s33, v149
	s_add_i32 s10, 0, 0x14000
	ds_read_b128 v[152:155], v148
	ds_read_b128 v[156:159], v148 offset:1024
	ds_read_b128 v[160:163], v148 offset:2048
	ds_read_b128 v[164:167], v148 offset:3072
	v_add_u32_e32 v148, s10, v149
	ds_read_b128 v[176:179], v148
	ds_read_b128 v[180:183], v148 offset:1024
	ds_read_b128 v[184:187], v148 offset:2048
	ds_read_b128 v[188:191], v148 offset:3072
	v_lshl_add_u64 v[146:147], v[142:143], 0, s[92:93]
	v_cndmask_b32_e32 v147, v147, v139, vcc
	v_cndmask_b32_e32 v146, v146, v138, vcc
	v_cndmask_b32_e32 v221, v145, v141, vcc
	v_cndmask_b32_e32 v220, v144, v140, vcc
	v_lshl_add_u64 v[244:245], v[142:143], 0, v[134:135]
	s_add_i32 m0, s25, 0xc000
	ds_read_b128 v[192:195], v151
	ds_read_b128 v[196:199], v151 offset:1024
	ds_read_b128 v[200:203], v151 offset:2048
	ds_read_b128 v[204:207], v151 offset:3072
	ds_read_b128 v[208:211], v151 offset:4096
	ds_read_b128 v[212:215], v151 offset:5120
	ds_read_b128 v[216:219], v151 offset:6144
	ds_read_b128 v[240:243], v151 offset:7168
	global_load_lds_dwordx4 v[244:245], off
	v_lshl_add_u64 v[244:245], v[142:143], 0, v[136:137]
	s_add_i32 m0, s25, 0xe000
	s_nop 0
	global_load_lds_dwordx4 v[244:245], off
	s_waitcnt vmcnt(8)
	s_waitcnt lgkmcnt(0)
	s_setprio 1
	s_barrier
; #define PG8_STAGE(bufoff, gbase, voff) do { _Pragma("unroll") for (int _i = 0; _i < 2; ++_i) \
;         __builtin_amdgcn_global_load_lds((const unsigned*)((const char*)(gbase) + (voff)[_i]), (LAS unsigned*)(lds + (bufoff) + ldsw + _i * 8192), 16, 0, 0); } while (0)
; #define PG8_LDA(dst, b, h) do { _Pragma("unroll") for (int m = 0; m < 4; ++m) _Pragma("unroll") for (int k = 0; k < 2; ++k) dst[m][k] = *(const LAS bf16x8*)(lds + PG8_SA(b, h) + aoff + m * 2048 + k * 1024); } while (0)
; #define PG8_LDB(dst, b, h) do { _Pragma("unroll") for (int n = 0; n < 2; ++n) _Pragma("unroll") for (int k = 0; k < 2; ++k) dst[n][k] = *(const LAS bf16x8*)(lds + PG8_SB(b, h) + boff + n * 2048 + k * 1024); } while (0)
; #define PG8_MMA(ai, bj, At, Bt) do { __builtin_amdgcn_s_setprio(1); _Pragma("unroll") for (int k = 0; k < 2; ++k) _Pragma("unroll") for (int m = 0; m < 4; ++m) _Pragma("unroll") for (int n = 0; n < 2; ++n) \
;         acc[ai][bj][m][n] = __builtin_amdgcn_mfma_f32_16x16x32_bf16(Bt[n][k], At[m][k], acc[ai][bj][m][n], 0, 0, 0); __builtin_amdgcn_s_setprio(0); } while (0)
; #define PG8_WAIT_V(n) asm volatile("s_waitcnt vmcnt(" #n ")" ::: "memory")
; #define PG8_BAR __builtin_amdgcn_s_barrier()
; template <class Epi, bool ALIGN_EPI>
; __device__ __forceinline__ void gemm_phase(LAS unsigned char* lds, const Gemm g, const StaticOrder& S, const Epi& E, const int tid) {
;     ...
;             PG8_LDB(B0, 0, 0); PG8_LDB(B1, 0, 1); PG8_SCHED; PG8_LDA(At, 0, 0); PG8_STAGE(PG8_SA(1, 1), a1 + hA, voffA);
;             PG8_WAIT_V(8); PG8_WAIT_L(0); PG8_BAR; PG8_MMA(0, 0, At, B0); PG8_MMA(0, 1, At, B1); PG8_BAR; PG8_SCHED;
;             PG8_LDA(At, 0, 1); PG8_STAGE(PG8_SB(0, 0), b2, voffB); PG8_STAGE(PG8_SB(0, 1), b2 + hB, voffB); PG8_STAGE(PG8_SA(0, 0), a2, voffA);
;             PG8_WAIT_V(8); PG8_WAIT_L(0); PG8_BAR; PG8_MMA(1, 0, At, B0); PG8_MMA(1, 1, At, B1); PG8_BAR; PG8_SCHED;
;             PG8_LDB(B0, 1, 0); PG8_LDB(B1, 1, 1); PG8_SCHED; PG8_LDA(At, 1, 0); PG8_STAGE(PG8_SA(0, 1), a2 + hA, voffA);
;             PG8_WAIT_V(8); PG8_WAIT_L(0); PG8_BAR; PG8_MMA(0, 0, At, B0); PG8_MMA(0, 1, At, B1); PG8_BAR; PG8_SCHED;
;             PG8_LDA(At, 1, 1); PG8_STAGE(PG8_SB(1, 0), b3, voffB); PG8_STAGE(PG8_SB(1, 1), b3 + hB, voffB); PG8_STAGE(PG8_SA(1, 0), a3, voffA);
;             PG8_WAIT_V(8); PG8_WAIT_L(0); PG8_BAR; PG8_MMA(1, 0, At, B0); PG8_MMA(1, 1, At, B1); PG8_BAR; PG8_SCHED;
	s_waitcnt lgkmcnt(0)
	v_mfma_f32_16x16x32_bf16 v[124:127], v[152:155], v[192:195], v[124:127]
	v_mfma_f32_16x16x32_bf16 v[120:123], v[160:163], v[192:195], v[120:123]
	v_mfma_f32_16x16x32_bf16 v[108:111], v[152:155], v[200:203], v[108:111]
	v_mfma_f32_16x16x32_bf16 v[104:107], v[160:163], v[200:203], v[104:107]
	v_mfma_f32_16x16x32_bf16 v[92:95], v[152:155], v[208:211], v[92:95]
	v_mfma_f32_16x16x32_bf16 v[88:91], v[160:163], v[208:211], v[88:91]
	v_mfma_f32_16x16x32_bf16 v[76:79], v[152:155], v[216:219], v[76:79]
	v_mfma_f32_16x16x32_bf16 v[72:75], v[160:163], v[216:219], v[72:75]
	v_mfma_f32_16x16x32_bf16 v[124:127], v[156:159], v[196:199], v[124:127]
	v_mfma_f32_16x16x32_bf16 v[120:123], v[164:167], v[196:199], v[120:123]
	v_mfma_f32_16x16x32_bf16 v[108:111], v[156:159], v[204:207], v[108:111]
	v_mfma_f32_16x16x32_bf16 v[104:107], v[164:167], v[204:207], v[104:107]
	v_mfma_f32_16x16x32_bf16 v[92:95], v[156:159], v[212:215], v[92:95]
	v_mfma_f32_16x16x32_bf16 v[88:91], v[164:167], v[212:215], v[88:91]
	v_mfma_f32_16x16x32_bf16 v[76:79], v[156:159], v[240:243], v[76:79]
	v_mfma_f32_16x16x32_bf16 v[72:75], v[164:167], v[240:243], v[72:75]
	s_setprio 0
	s_setprio 1
	v_mfma_f32_16x16x32_bf16 v[116:119], v[176:179], v[192:195], v[116:119]
	v_mfma_f32_16x16x32_bf16 v[112:115], v[184:187], v[192:195], v[112:115]
	v_mfma_f32_16x16x32_bf16 v[100:103], v[176:179], v[200:203], v[100:103]
	v_mfma_f32_16x16x32_bf16 v[96:99], v[184:187], v[200:203], v[96:99]
	v_mfma_f32_16x16x32_bf16 v[84:87], v[176:179], v[208:211], v[84:87]
	v_mfma_f32_16x16x32_bf16 v[80:83], v[184:187], v[208:211], v[80:83]
	v_mfma_f32_16x16x32_bf16 v[68:71], v[176:179], v[216:219], v[68:71]
	v_mfma_f32_16x16x32_bf16 v[64:67], v[184:187], v[216:219], v[64:67]
	v_mfma_f32_16x16x32_bf16 v[116:119], v[180:183], v[196:199], v[116:119]
	v_mfma_f32_16x16x32_bf16 v[112:115], v[188:191], v[196:199], v[112:115]
	v_mfma_f32_16x16x32_bf16 v[100:103], v[180:183], v[204:207], v[100:103]
	v_mfma_f32_16x16x32_bf16 v[96:99], v[188:191], v[204:207], v[96:99]
	v_mfma_f32_16x16x32_bf16 v[84:87], v[180:183], v[212:215], v[84:87]
	v_mfma_f32_16x16x32_bf16 v[80:83], v[188:191], v[212:215], v[80:83]
	v_mfma_f32_16x16x32_bf16 v[68:71], v[180:183], v[240:243], v[68:71]
	v_mfma_f32_16x16x32_bf16 v[64:67], v[188:191], v[240:243], v[64:67]
	s_barrier
	s_setprio 0
	s_add_i32 s62, s33, s45
	v_lshl_add_u64 v[244:245], v[220:221], 0, v[168:169]
	s_mov_b32 m0, s62
	ds_read_b128 v[192:195], v151 offset:16384
	ds_read_b128 v[196:199], v151 offset:17408
	ds_read_b128 v[200:203], v151 offset:18432
	ds_read_b128 v[204:207], v151 offset:19456
	ds_read_b128 v[208:211], v151 offset:20480
	ds_read_b128 v[212:215], v151 offset:21504
	ds_read_b128 v[216:219], v151 offset:22528
	ds_read_b128 v[240:243], v151 offset:23552
	global_load_lds_dwordx4 v[244:245], off
	v_lshl_add_u64 v[246:247], v[220:221], 0, v[128:129]
	s_add_i32 m0, s62, 0x2000
	v_lshl_add_u64 v[220:221], v[220:221], 0, s[12:13]
	s_add_i32 s10, s10, s45
	global_load_lds_dwordx4 v[246:247], off
	v_lshl_add_u64 v[248:249], v[220:221], 0, v[168:169]
	s_mov_b32 m0, s10
	v_lshl_add_u64 v[220:221], v[220:221], 0, v[128:129]
	global_load_lds_dwordx4 v[248:249], off
	s_add_i32 m0, s10, 0x2000
	v_lshl_add_u64 v[250:251], v[146:147], 0, v[132:133]
	global_load_lds_dwordx4 v[220:221], off
	s_mov_b32 m0, s25
	v_lshl_add_u64 v[252:253], v[146:147], 0, v[130:131]
	global_load_lds_dwordx4 v[250:251], off
	s_mov_b32 m0, s50
	s_nop 0
	global_load_lds_dwordx4 v[252:253], off
	s_waitcnt vmcnt(8)
	s_waitcnt lgkmcnt(0)
	s_setprio 1
	s_barrier
	s_waitcnt lgkmcnt(0)
	v_mfma_f32_16x16x32_bf16 v[60:63], v[152:155], v[192:195], v[60:63]
	v_mfma_f32_16x16x32_bf16 v[56:59], v[160:163], v[192:195], v[56:59]
	v_mfma_f32_16x16x32_bf16 v[44:47], v[152:155], v[200:203], v[44:47]
	v_mfma_f32_16x16x32_bf16 v[40:43], v[160:163], v[200:203], v[40:43]
	v_mfma_f32_16x16x32_bf16 v[28:31], v[152:155], v[208:211], v[28:31]
	v_mfma_f32_16x16x32_bf16 v[24:27], v[160:163], v[208:211], v[24:27]
	v_mfma_f32_16x16x32_bf16 v[12:15], v[152:155], v[216:219], v[12:15]
	v_mfma_f32_16x16x32_bf16 v[8:11], v[160:163], v[216:219], v[8:11]
	v_mfma_f32_16x16x32_bf16 v[60:63], v[156:159], v[196:199], v[60:63]
	v_mfma_f32_16x16x32_bf16 v[56:59], v[164:167], v[196:199], v[56:59]
	v_mfma_f32_16x16x32_bf16 v[44:47], v[156:159], v[204:207], v[44:47]
	v_mfma_f32_16x16x32_bf16 v[40:43], v[164:167], v[204:207], v[40:43]
	v_mfma_f32_16x16x32_bf16 v[28:31], v[156:159], v[212:215], v[28:31]
	v_mfma_f32_16x16x32_bf16 v[24:27], v[164:167], v[212:215], v[24:27]
	v_mfma_f32_16x16x32_bf16 v[12:15], v[156:159], v[240:243], v[12:15]
	v_mfma_f32_16x16x32_bf16 v[8:11], v[164:167], v[240:243], v[8:11]
	s_setprio 0
	s_setprio 1
	v_mfma_f32_16x16x32_bf16 v[52:55], v[176:179], v[192:195], v[52:55]
	v_mfma_f32_16x16x32_bf16 v[48:51], v[184:187], v[192:195], v[48:51]
	v_mfma_f32_16x16x32_bf16 v[36:39], v[176:179], v[200:203], v[36:39]
	v_mfma_f32_16x16x32_bf16 v[32:35], v[184:187], v[200:203], v[32:35]
	v_mfma_f32_16x16x32_bf16 v[20:23], v[176:179], v[208:211], v[20:23]
	v_mfma_f32_16x16x32_bf16 v[16:19], v[184:187], v[208:211], v[16:19]
	v_mfma_f32_16x16x32_bf16 v[4:7], v[176:179], v[216:219], v[4:7]
	v_mfma_f32_16x16x32_bf16 v[0:3], v[184:187], v[216:219], v[0:3]
	v_mfma_f32_16x16x32_bf16 v[52:55], v[180:183], v[196:199], v[52:55]
	v_mfma_f32_16x16x32_bf16 v[48:51], v[188:191], v[196:199], v[48:51]
	v_mfma_f32_16x16x32_bf16 v[36:39], v[180:183], v[204:207], v[36:39]
	v_mfma_f32_16x16x32_bf16 v[32:35], v[188:191], v[204:207], v[32:35]
	v_mfma_f32_16x16x32_bf16 v[20:23], v[180:183], v[212:215], v[20:23]
	v_mfma_f32_16x16x32_bf16 v[16:19], v[188:191], v[212:215], v[16:19]
	v_mfma_f32_16x16x32_bf16 v[4:7], v[180:183], v[240:243], v[4:7]
	v_mfma_f32_16x16x32_bf16 v[0:3], v[188:191], v[240:243], v[0:3]
	s_barrier
; #define PG8_STAGE(bufoff, gbase, voff) do { _Pragma("unroll") for (int _i = 0; _i < 2; ++_i) \
;         __builtin_amdgcn_global_load_lds((const unsigned*)((const char*)(gbase) + (voff)[_i]), (LAS unsigned*)(lds + (bufoff) + ldsw + _i * 8192), 16, 0, 0); } while (0)
; #define PG8_LDA(dst, b, h) do { _Pragma("unroll") for (int m = 0; m < 4; ++m) _Pragma("unroll") for (int k = 0; k < 2; ++k) dst[m][k] = *(const LAS bf16x8*)(lds + PG8_SA(b, h) + aoff + m * 2048 + k * 1024); } while (0)
; #define PG8_LDB(dst, b, h) do { _Pragma("unroll") for (int n = 0; n < 2; ++n) _Pragma("unroll") for (int k = 0; k < 2; ++k) dst[n][k] = *(const LAS bf16x8*)(lds + PG8_SB(b, h) + boff + n * 2048 + k * 1024); } while (0)
; #define PG8_MMA(ai, bj, At, Bt) do { __builtin_amdgcn_s_setprio(1); _Pragma("unroll") for (int k = 0; k < 2; ++k) _Pragma("unroll") for (int m = 0; m < 4; ++m) _Pragma("unroll") for (int n = 0; n < 2; ++n) \
;         acc[ai][bj][m][n] = __builtin_amdgcn_mfma_f32_16x16x32_bf16(Bt[n][k], At[m][k], acc[ai][bj][m][n], 0, 0, 0); __builtin_amdgcn_s_setprio(0); } while (0)
; #define PG8_WAIT_V(n) asm volatile("s_waitcnt vmcnt(" #n ")" ::: "memory")
; #define PG8_BAR __builtin_amdgcn_s_barrier()
; template <class Epi, bool ALIGN_EPI>
; __device__ __forceinline__ void gemm_phase(LAS unsigned char* lds, const Gemm g, const StaticOrder& S, const Epi& E, const int tid) {
;     ...
;             PG8_LDB(B0, 0, 0); PG8_LDB(B1, 0, 1); PG8_SCHED; PG8_LDA(At, 0, 0); PG8_STAGE(PG8_SA(1, 1), a1 + hA, voffA);
;             PG8_WAIT_V(8); PG8_WAIT_L(0); PG8_BAR; PG8_MMA(0, 0, At, B0); PG8_MMA(0, 1, At, B1); PG8_BAR; PG8_SCHED;
;             PG8_LDA(At, 0, 1); PG8_STAGE(PG8_SB(0, 0), b2, voffB); PG8_STAGE(PG8_SB(0, 1), b2 + hB, voffB); PG8_STAGE(PG8_SA(0, 0), a2, voffA);
;             PG8_WAIT_V(8); PG8_WAIT_L(0); PG8_BAR; PG8_MMA(1, 0, At, B0); PG8_MMA(1, 1, At, B1); PG8_BAR; PG8_SCHED;
;             PG8_LDB(B0, 1, 0); PG8_LDB(B1, 1, 1); PG8_SCHED; PG8_LDA(At, 1, 0); PG8_STAGE(PG8_SA(0, 1), a2 + hA, voffA);
;             PG8_WAIT_V(8); PG8_WAIT_L(0); PG8_BAR; PG8_MMA(0, 0, At, B0); PG8_MMA(0, 1, At, B1); PG8_BAR; PG8_SCHED;
;             PG8_LDA(At, 1, 1); PG8_STAGE(PG8_SB(1, 0), b3, voffB); PG8_STAGE(PG8_SB(1, 1), b3 + hB, voffB); PG8_STAGE(PG8_SA(1, 0), a3, voffA);
;             PG8_WAIT_V(8); PG8_WAIT_L(0); PG8_BAR; PG8_MMA(1, 0, At, B0); PG8_MMA(1, 1, At, B1); PG8_BAR; PG8_SCHED;
	s_setprio 0
	s_add_i32 s10, 0, 0x18000
	v_add_u32_e32 v148, s10, v149
	s_add_i32 s62, 0, 0x1c000
	ds_read_b128 v[152:155], v148
	ds_read_b128 v[156:159], v148 offset:1024
	ds_read_b128 v[160:163], v148 offset:2048
	ds_read_b128 v[164:167], v148 offset:3072
	v_add_u32_e32 v148, s62, v149
	ds_read_b128 v[176:179], v148
	ds_read_b128 v[180:183], v148 offset:1024
	ds_read_b128 v[184:187], v148 offset:2048
	ds_read_b128 v[188:191], v148 offset:3072
	v_lshl_add_u64 v[146:147], v[146:147], 0, s[94:95]
	s_mov_b32 m0, s51
	v_lshl_add_u64 v[226:227], v[146:147], 0, v[132:133]
	ds_read_b128 v[192:195], v151 offset:32768
	ds_read_b128 v[196:199], v151 offset:33792
	ds_read_b128 v[200:203], v151 offset:34816
	ds_read_b128 v[204:207], v151 offset:35840
	ds_read_b128 v[208:211], v151 offset:36864
	ds_read_b128 v[212:215], v151 offset:37888
	ds_read_b128 v[216:219], v151 offset:38912
	ds_read_b128 v[240:243], v151 offset:39936
	global_load_lds_dwordx4 v[226:227], off
	v_lshl_add_u64 v[146:147], v[146:147], 0, v[130:131]
	s_mov_b32 m0, s52
	s_nop 0
	global_load_lds_dwordx4 v[146:147], off
	s_waitcnt vmcnt(8)
	s_waitcnt lgkmcnt(0)
	s_setprio 1
	s_barrier
	s_waitcnt lgkmcnt(0)
	v_mfma_f32_16x16x32_bf16 v[124:127], v[152:155], v[192:195], v[124:127]
	v_mfma_f32_16x16x32_bf16 v[120:123], v[160:163], v[192:195], v[120:123]
	v_mfma_f32_16x16x32_bf16 v[108:111], v[152:155], v[200:203], v[108:111]
	v_mfma_f32_16x16x32_bf16 v[104:107], v[160:163], v[200:203], v[104:107]
	v_mfma_f32_16x16x32_bf16 v[92:95], v[152:155], v[208:211], v[92:95]
	v_mfma_f32_16x16x32_bf16 v[88:91], v[160:163], v[208:211], v[88:91]
	v_mfma_f32_16x16x32_bf16 v[76:79], v[152:155], v[216:219], v[76:79]
	v_mfma_f32_16x16x32_bf16 v[72:75], v[160:163], v[216:219], v[72:75]
	v_mfma_f32_16x16x32_bf16 v[124:127], v[156:159], v[196:199], v[124:127]
	v_mfma_f32_16x16x32_bf16 v[120:123], v[164:167], v[196:199], v[120:123]
	v_mfma_f32_16x16x32_bf16 v[108:111], v[156:159], v[204:207], v[108:111]
	v_mfma_f32_16x16x32_bf16 v[104:107], v[164:167], v[204:207], v[104:107]
	v_mfma_f32_16x16x32_bf16 v[92:95], v[156:159], v[212:215], v[92:95]
	v_mfma_f32_16x16x32_bf16 v[88:91], v[164:167], v[212:215], v[88:91]
	v_mfma_f32_16x16x32_bf16 v[76:79], v[156:159], v[240:243], v[76:79]
	v_mfma_f32_16x16x32_bf16 v[72:75], v[164:167], v[240:243], v[72:75]
	s_setprio 0
	s_setprio 1
	v_mfma_f32_16x16x32_bf16 v[116:119], v[176:179], v[192:195], v[116:119]
	v_mfma_f32_16x16x32_bf16 v[112:115], v[184:187], v[192:195], v[112:115]
	v_mfma_f32_16x16x32_bf16 v[100:103], v[176:179], v[200:203], v[100:103]
	v_mfma_f32_16x16x32_bf16 v[96:99], v[184:187], v[200:203], v[96:99]
	v_mfma_f32_16x16x32_bf16 v[84:87], v[176:179], v[208:211], v[84:87]
	v_mfma_f32_16x16x32_bf16 v[80:83], v[184:187], v[208:211], v[80:83]
	v_mfma_f32_16x16x32_bf16 v[68:71], v[176:179], v[216:219], v[68:71]
	v_mfma_f32_16x16x32_bf16 v[64:67], v[184:187], v[216:219], v[64:67]
	v_mfma_f32_16x16x32_bf16 v[116:119], v[180:183], v[196:199], v[116:119]
	v_mfma_f32_16x16x32_bf16 v[112:115], v[188:191], v[196:199], v[112:115]
	v_mfma_f32_16x16x32_bf16 v[100:103], v[180:183], v[204:207], v[100:103]
	v_mfma_f32_16x16x32_bf16 v[96:99], v[188:191], v[204:207], v[96:99]
	v_mfma_f32_16x16x32_bf16 v[84:87], v[180:183], v[212:215], v[84:87]
	v_mfma_f32_16x16x32_bf16 v[80:83], v[188:191], v[212:215], v[80:83]
	v_mfma_f32_16x16x32_bf16 v[68:71], v[180:183], v[240:243], v[68:71]
	v_mfma_f32_16x16x32_bf16 v[64:67], v[188:191], v[240:243], v[64:67]
	s_barrier
	s_setprio 0
	s_add_i32 s10, s10, s45
	v_lshl_add_u64 v[146:147], v[244:245], 0, s[92:93]
	s_mov_b32 m0, s10
	ds_read_b128 v[192:195], v151 offset:49152
	ds_read_b128 v[196:199], v151 offset:50176
	ds_read_b128 v[200:203], v151 offset:51200
	ds_read_b128 v[204:207], v151 offset:52224
	ds_read_b128 v[208:211], v151 offset:53248
	ds_read_b128 v[212:215], v151 offset:54272
	ds_read_b128 v[216:219], v151 offset:55296
	ds_read_b128 v[240:243], v151 offset:56320
	global_load_lds_dwordx4 v[146:147], off
	v_lshl_add_u64 v[146:147], v[246:247], 0, s[92:93]
	s_add_i32 m0, s10, 0x2000
	s_add_i32 s10, s62, s45
	global_load_lds_dwordx4 v[146:147], off
	v_lshl_add_u64 v[146:147], v[248:249], 0, s[92:93]
	s_mov_b32 m0, s10
	s_nop 0
	global_load_lds_dwordx4 v[146:147], off
	v_lshl_add_u64 v[146:147], v[220:221], 0, s[92:93]
	s_add_i32 m0, s10, 0x2000
	s_nop 0
	global_load_lds_dwordx4 v[146:147], off
	v_lshl_add_u64 v[146:147], v[250:251], 0, s[92:93]
	s_mov_b32 m0, s53
	s_nop 0
	global_load_lds_dwordx4 v[146:147], off
	v_lshl_add_u64 v[146:147], v[252:253], 0, s[92:93]
	s_mov_b32 m0, s54
	s_nop 0
	global_load_lds_dwordx4 v[146:147], off
	s_waitcnt vmcnt(8)
	s_waitcnt lgkmcnt(0)
	s_setprio 1
	s_barrier
; #define PG8_STAGE(bufoff, gbase, voff) do { _Pragma("unroll") for (int _i = 0; _i < 2; ++_i) \
;         __builtin_amdgcn_global_load_lds((const unsigned*)((const char*)(gbase) + (voff)[_i]), (LAS unsigned*)(lds + (bufoff) + ldsw + _i * 8192), 16, 0, 0); } while (0)
; #define PG8_LDA(dst, b, h) do { _Pragma("unroll") for (int m = 0; m < 4; ++m) _Pragma("unroll") for (int k = 0; k < 2; ++k) dst[m][k] = *(const LAS bf16x8*)(lds + PG8_SA(b, h) + aoff + m * 2048 + k * 1024); } while (0)
; #define PG8_LDB(dst, b, h) do { _Pragma("unroll") for (int n = 0; n < 2; ++n) _Pragma("unroll") for (int k = 0; k < 2; ++k) dst[n][k] = *(const LAS bf16x8*)(lds + PG8_SB(b, h) + boff + n * 2048 + k * 1024); } while (0)
; #define PG8_WAIT_V(n) asm volatile("s_waitcnt vmcnt(" #n ")" ::: "memory")
; #define PG8_BAR __builtin_amdgcn_s_barrier()
; template <class Epi, bool ALIGN_EPI>
; __device__ __forceinline__ void gemm_phase(LAS unsigned char* lds, const Gemm g, const StaticOrder& S, const Epi& E, const int tid) {
;     ...
;         for (int t = 0; t < nt; t += 2) {
;             const bool last = (t == nt - 2);
;             const char* a1 = cA + (size_t)(t + 1) * kstep;
;             const char* a2 = last ? nA : cA + (size_t)(t + 2) * kstep; const char* b2 = last ? nB : cB + (size_t)(t + 2) * kstep;
;             const char* a3 = a2 + kstep; const char* b3 = b2 + kstep;
;             PG8_LDB(B0, 0, 0); PG8_LDB(B1, 0, 1); PG8_SCHED; PG8_LDA(At, 0, 0); PG8_STAGE(PG8_SA(1, 1), a1 + hA, voffA);
;             PG8_WAIT_V(8); PG8_WAIT_L(0); PG8_BAR; PG8_MMA(0, 0, At, B0); PG8_MMA(0, 1, At, B1); PG8_BAR; PG8_SCHED;
;             PG8_LDA(At, 0, 1); PG8_STAGE(PG8_SB(0, 0), b2, voffB); PG8_STAGE(PG8_SB(0, 1), b2 + hB, voffB); PG8_STAGE(PG8_SA(0, 0), a2, voffA);
;             PG8_WAIT_V(8); PG8_WAIT_L(0); PG8_BAR; PG8_MMA(1, 0, At, B0); PG8_MMA(1, 1, At, B1); PG8_BAR; PG8_SCHED;
;             PG8_LDB(B0, 1, 0); PG8_LDB(B1, 1, 1); PG8_SCHED; PG8_LDA(At, 1, 0); PG8_STAGE(PG8_SA(0, 1), a2 + hA, voffA);
;             PG8_WAIT_V(8); PG8_WAIT_L(0); PG8_BAR; PG8_MMA(0, 0, At, B0); PG8_MMA(0, 1, At, B1); PG8_BAR; PG8_SCHED;
;             PG8_LDA(At, 1, 1); PG8_STAGE(PG8_SB(1, 0), b3, voffB); PG8_STAGE(PG8_SB(1, 1), b3 + hB, voffB); PG8_STAGE(PG8_SA(1, 0), a3, voffA);
;             PG8_WAIT_V(8); PG8_WAIT_L(0); PG8_BAR; PG8_MMA(1, 0, At, B0); PG8_MMA(1, 1, At, B1); PG8_BAR; PG8_SCHED;
	s_waitcnt lgkmcnt(0)
	v_mfma_f32_16x16x32_bf16 v[60:63], v[152:155], v[192:195], v[60:63]
	v_mfma_f32_16x16x32_bf16 v[56:59], v[160:163], v[192:195], v[56:59]
	v_mfma_f32_16x16x32_bf16 v[44:47], v[152:155], v[200:203], v[44:47]
	v_mfma_f32_16x16x32_bf16 v[40:43], v[160:163], v[200:203], v[40:43]
	v_mfma_f32_16x16x32_bf16 v[28:31], v[152:155], v[208:211], v[28:31]
	v_mfma_f32_16x16x32_bf16 v[24:27], v[160:163], v[208:211], v[24:27]
	v_mfma_f32_16x16x32_bf16 v[12:15], v[152:155], v[216:219], v[12:15]
	v_mfma_f32_16x16x32_bf16 v[8:11], v[160:163], v[216:219], v[8:11]
	v_mfma_f32_16x16x32_bf16 v[60:63], v[156:159], v[196:199], v[60:63]
	v_mfma_f32_16x16x32_bf16 v[56:59], v[164:167], v[196:199], v[56:59]
	v_mfma_f32_16x16x32_bf16 v[44:47], v[156:159], v[204:207], v[44:47]
	v_mfma_f32_16x16x32_bf16 v[40:43], v[164:167], v[204:207], v[40:43]
	v_mfma_f32_16x16x32_bf16 v[28:31], v[156:159], v[212:215], v[28:31]
	v_mfma_f32_16x16x32_bf16 v[24:27], v[164:167], v[212:215], v[24:27]
	v_mfma_f32_16x16x32_bf16 v[12:15], v[156:159], v[240:243], v[12:15]
	v_mfma_f32_16x16x32_bf16 v[8:11], v[164:167], v[240:243], v[8:11]
	s_setprio 0
	s_setprio 1
	v_mfma_f32_16x16x32_bf16 v[52:55], v[176:179], v[192:195], v[52:55]
	v_mfma_f32_16x16x32_bf16 v[48:51], v[184:187], v[192:195], v[48:51]
	v_mfma_f32_16x16x32_bf16 v[36:39], v[176:179], v[200:203], v[36:39]
	v_mfma_f32_16x16x32_bf16 v[32:35], v[184:187], v[200:203], v[32:35]
	v_mfma_f32_16x16x32_bf16 v[20:23], v[176:179], v[208:211], v[20:23]
	v_mfma_f32_16x16x32_bf16 v[16:19], v[184:187], v[208:211], v[16:19]
	v_mfma_f32_16x16x32_bf16 v[4:7], v[176:179], v[216:219], v[4:7]
	v_mfma_f32_16x16x32_bf16 v[0:3], v[184:187], v[216:219], v[0:3]
	v_mfma_f32_16x16x32_bf16 v[52:55], v[180:183], v[196:199], v[52:55]
	v_mfma_f32_16x16x32_bf16 v[48:51], v[188:191], v[196:199], v[48:51]
	v_mfma_f32_16x16x32_bf16 v[36:39], v[180:183], v[204:207], v[36:39]
	v_mfma_f32_16x16x32_bf16 v[32:35], v[188:191], v[204:207], v[32:35]
	v_mfma_f32_16x16x32_bf16 v[20:23], v[180:183], v[212:215], v[20:23]
	v_mfma_f32_16x16x32_bf16 v[16:19], v[188:191], v[212:215], v[16:19]
	v_mfma_f32_16x16x32_bf16 v[4:7], v[180:183], v[240:243], v[4:7]
	v_mfma_f32_16x16x32_bf16 v[0:3], v[188:191], v[240:243], v[0:3]
	s_barrier
	s_setprio 0
	v_lshl_add_u64 v[142:143], v[142:143], 0, s[80:81]
	v_lshl_add_u64 v[144:145], v[144:145], 0, s[80:81]
	s_mov_b32 s10, s11
	s_cmp_lg_u32 s10, s55
	s_cbranch_scc1 .LBB0_354
.Lq5_last:
	s_add_i32 s11, s10, 2
	s_cmp_eq_u32 s55, s10
	s_cselect_b64 vcc, -1, 0
	v_add_u32_e32 v148, s33, v149
	s_add_i32 s10, 0, 0x14000
	ds_read_b128 v[152:155], v148
	ds_read_b128 v[156:159], v148 offset:1024
	ds_read_b128 v[160:163], v148 offset:2048
	ds_read_b128 v[164:167], v148 offset:3072
	v_add_u32_e32 v148, s10, v149
	ds_read_b128 v[176:179], v148
	ds_read_b128 v[180:183], v148 offset:1024
	ds_read_b128 v[184:187], v148 offset:2048
	ds_read_b128 v[188:191], v148 offset:3072
	v_lshl_add_u64 v[146:147], v[142:143], 0, s[92:93]
	v_cndmask_b32_e32 v147, v147, v139, vcc
	v_cndmask_b32_e32 v146, v146, v138, vcc
	v_cndmask_b32_e32 v221, v145, v141, vcc
	v_cndmask_b32_e32 v220, v144, v140, vcc
	v_lshl_add_u64 v[244:245], v[142:143], 0, v[134:135]
	s_add_i32 m0, s25, 0xc000
	ds_read_b128 v[192:195], v151
	ds_read_b128 v[196:199], v151 offset:1024
	ds_read_b128 v[200:203], v151 offset:2048
	ds_read_b128 v[204:207], v151 offset:3072
	ds_read_b128 v[208:211], v151 offset:4096
	ds_read_b128 v[212:215], v151 offset:5120
	ds_read_b128 v[216:219], v151 offset:6144
	ds_read_b128 v[240:243], v151 offset:7168
	global_load_lds_dwordx4 v[244:245], off
	v_lshl_add_u64 v[244:245], v[142:143], 0, v[136:137]
	s_add_i32 m0, s25, 0xe000
	s_nop 0
	global_load_lds_dwordx4 v[244:245], off
	s_waitcnt vmcnt(8)
	s_waitcnt lgkmcnt(0)
	s_setprio 1
	s_barrier
	s_waitcnt lgkmcnt(0)
	v_mfma_f32_16x16x32_bf16 v[124:127], v[152:155], v[192:195], v[124:127]
	v_mfma_f32_16x16x32_bf16 v[120:123], v[160:163], v[192:195], v[120:123]
	v_mfma_f32_16x16x32_bf16 v[108:111], v[152:155], v[200:203], v[108:111]
	v_mfma_f32_16x16x32_bf16 v[104:107], v[160:163], v[200:203], v[104:107]
	v_mfma_f32_16x16x32_bf16 v[92:95], v[152:155], v[208:211], v[92:95]
	v_mfma_f32_16x16x32_bf16 v[88:91], v[160:163], v[208:211], v[88:91]
	v_mfma_f32_16x16x32_bf16 v[76:79], v[152:155], v[216:219], v[76:79]
	v_mfma_f32_16x16x32_bf16 v[72:75], v[160:163], v[216:219], v[72:75]
	v_mfma_f32_16x16x32_bf16 v[124:127], v[156:159], v[196:199], v[124:127]
	v_mfma_f32_16x16x32_bf16 v[120:123], v[164:167], v[196:199], v[120:123]
	v_mfma_f32_16x16x32_bf16 v[108:111], v[156:159], v[204:207], v[108:111]
	v_mfma_f32_16x16x32_bf16 v[104:107], v[164:167], v[204:207], v[104:107]
	v_mfma_f32_16x16x32_bf16 v[92:95], v[156:159], v[212:215], v[92:95]
	v_mfma_f32_16x16x32_bf16 v[88:91], v[164:167], v[212:215], v[88:91]
	v_mfma_f32_16x16x32_bf16 v[76:79], v[156:159], v[240:243], v[76:79]
	v_mfma_f32_16x16x32_bf16 v[72:75], v[164:167], v[240:243], v[72:75]
	s_setprio 0
	s_setprio 1
	v_mfma_f32_16x16x32_bf16 v[116:119], v[176:179], v[192:195], v[116:119]
	v_mfma_f32_16x16x32_bf16 v[112:115], v[184:187], v[192:195], v[112:115]
	v_mfma_f32_16x16x32_bf16 v[100:103], v[176:179], v[200:203], v[100:103]
	v_mfma_f32_16x16x32_bf16 v[96:99], v[184:187], v[200:203], v[96:99]
	v_mfma_f32_16x16x32_bf16 v[84:87], v[176:179], v[208:211], v[84:87]
	v_mfma_f32_16x16x32_bf16 v[80:83], v[184:187], v[208:211], v[80:83]
	v_mfma_f32_16x16x32_bf16 v[68:71], v[176:179], v[216:219], v[68:71]
	v_mfma_f32_16x16x32_bf16 v[64:67], v[184:187], v[216:219], v[64:67]
	v_mfma_f32_16x16x32_bf16 v[116:119], v[180:183], v[196:199], v[116:119]
	v_mfma_f32_16x16x32_bf16 v[112:115], v[188:191], v[196:199], v[112:115]
	v_mfma_f32_16x16x32_bf16 v[100:103], v[180:183], v[204:207], v[100:103]
	v_mfma_f32_16x16x32_bf16 v[96:99], v[188:191], v[204:207], v[96:99]
	v_mfma_f32_16x16x32_bf16 v[84:87], v[180:183], v[212:215], v[84:87]
	v_mfma_f32_16x16x32_bf16 v[80:83], v[188:191], v[212:215], v[80:83]
	v_mfma_f32_16x16x32_bf16 v[68:71], v[180:183], v[240:243], v[68:71]
	v_mfma_f32_16x16x32_bf16 v[64:67], v[188:191], v[240:243], v[64:67]
	s_barrier
; #define PG8_STAGE(bufoff, gbase, voff) do { _Pragma("unroll") for (int _i = 0; _i < 2; ++_i) \
;         __builtin_amdgcn_global_load_lds((const unsigned*)((const char*)(gbase) + (voff)[_i]), (LAS unsigned*)(lds + (bufoff) + ldsw + _i * 8192), 16, 0, 0); } while (0)
; #define PG8_LDA(dst, b, h) do { _Pragma("unroll") for (int m = 0; m < 4; ++m) _Pragma("unroll") for (int k = 0; k < 2; ++k) dst[m][k] = *(const LAS bf16x8*)(lds + PG8_SA(b, h) + aoff + m * 2048 + k * 1024); } while (0)
; #define PG8_LDB(dst, b, h) do { _Pragma("unroll") for (int n = 0; n < 2; ++n) _Pragma("unroll") for (int k = 0; k < 2; ++k) dst[n][k] = *(const LAS bf16x8*)(lds + PG8_SB(b, h) + boff + n * 2048 + k * 1024); } while (0)
; #define PG8_MMA(ai, bj, At, Bt) do { __builtin_amdgcn_s_setprio(1); _Pragma("unroll") for (int k = 0; k < 2; ++k) _Pragma("unroll") for (int m = 0; m < 4; ++m) _Pragma("unroll") for (int n = 0; n < 2; ++n) \
;         acc[ai][bj][m][n] = __builtin_amdgcn_mfma_f32_16x16x32_bf16(Bt[n][k], At[m][k], acc[ai][bj][m][n], 0, 0, 0); __builtin_amdgcn_s_setprio(0); } while (0)
; #define PG8_WAIT_V(n) asm volatile("s_waitcnt vmcnt(" #n ")" ::: "memory")
; #define PG8_BAR __builtin_amdgcn_s_barrier()
; template <class Epi, bool ALIGN_EPI>
; __device__ __forceinline__ void gemm_phase(LAS unsigned char* lds, const Gemm g, const StaticOrder& S, const Epi& E, const int tid) {
;     ...
;             PG8_LDB(B0, 0, 0); PG8_LDB(B1, 0, 1); PG8_SCHED; PG8_LDA(At, 0, 0); PG8_STAGE(PG8_SA(1, 1), a1 + hA, voffA);
;             PG8_WAIT_V(8); PG8_WAIT_L(0); PG8_BAR; PG8_MMA(0, 0, At, B0); PG8_MMA(0, 1, At, B1); PG8_BAR; PG8_SCHED;
;             PG8_LDA(At, 0, 1); PG8_STAGE(PG8_SB(0, 0), b2, voffB); PG8_STAGE(PG8_SB(0, 1), b2 + hB, voffB); PG8_STAGE(PG8_SA(0, 0), a2, voffA);
;             PG8_WAIT_V(8); PG8_WAIT_L(0); PG8_BAR; PG8_MMA(1, 0, At, B0); PG8_MMA(1, 1, At, B1); PG8_BAR; PG8_SCHED;
;             PG8_LDB(B0, 1, 0); PG8_LDB(B1, 1, 1); PG8_SCHED; PG8_LDA(At, 1, 0); PG8_STAGE(PG8_SA(0, 1), a2 + hA, voffA);
;             PG8_WAIT_V(8); PG8_WAIT_L(0); PG8_BAR; PG8_MMA(0, 0, At, B0); PG8_MMA(0, 1, At, B1); PG8_BAR; PG8_SCHED;
;             PG8_LDA(At, 1, 1); PG8_STAGE(PG8_SB(1, 0), b3, voffB); PG8_STAGE(PG8_SB(1, 1), b3 + hB, voffB); PG8_STAGE(PG8_SA(1, 0), a3, voffA);
;             PG8_WAIT_V(8); PG8_WAIT_L(0); PG8_BAR; PG8_MMA(1, 0, At, B0); PG8_MMA(1, 1, At, B1); PG8_BAR; PG8_SCHED;
	s_setprio 0
	s_add_i32 s62, s33, s45
	v_lshl_add_u64 v[244:245], v[220:221], 0, v[168:169]
	s_mov_b32 m0, s62
	ds_read_b128 v[192:195], v151 offset:16384
	ds_read_b128 v[196:199], v151 offset:17408
	ds_read_b128 v[200:203], v151 offset:18432
	ds_read_b128 v[204:207], v151 offset:19456
	ds_read_b128 v[208:211], v151 offset:20480
	ds_read_b128 v[212:215], v151 offset:21504
	ds_read_b128 v[216:219], v151 offset:22528
	ds_read_b128 v[240:243], v151 offset:23552
	global_load_lds_dwordx4 v[244:245], off
	v_lshl_add_u64 v[246:247], v[220:221], 0, v[128:129]
	s_add_i32 m0, s62, 0x2000
	v_lshl_add_u64 v[220:221], v[220:221], 0, s[12:13]
	s_add_i32 s10, s10, s45
	global_load_lds_dwordx4 v[246:247], off
	v_lshl_add_u64 v[248:249], v[220:221], 0, v[168:169]
	s_mov_b32 m0, s10
	v_lshl_add_u64 v[220:221], v[220:221], 0, v[128:129]
	global_load_lds_dwordx4 v[248:249], off
	s_add_i32 m0, s10, 0x2000
	v_lshl_add_u64 v[250:251], v[146:147], 0, v[132:133]
	global_load_lds_dwordx4 v[220:221], off
	s_mov_b32 m0, s25
	v_lshl_add_u64 v[252:253], v[146:147], 0, v[130:131]
	global_load_lds_dwordx4 v[250:251], off
	s_mov_b32 m0, s50
	s_nop 0
	global_load_lds_dwordx4 v[252:253], off
	s_waitcnt vmcnt(8)
	s_waitcnt lgkmcnt(0)
	s_setprio 1
	s_barrier
	s_waitcnt lgkmcnt(0)
	v_mfma_f32_16x16x32_bf16 v[60:63], v[152:155], v[192:195], v[60:63]
	v_mfma_f32_16x16x32_bf16 v[56:59], v[160:163], v[192:195], v[56:59]
	v_mfma_f32_16x16x32_bf16 v[44:47], v[152:155], v[200:203], v[44:47]
	v_mfma_f32_16x16x32_bf16 v[40:43], v[160:163], v[200:203], v[40:43]
	v_mfma_f32_16x16x32_bf16 v[28:31], v[152:155], v[208:211], v[28:31]
	v_mfma_f32_16x16x32_bf16 v[24:27], v[160:163], v[208:211], v[24:27]
	v_mfma_f32_16x16x32_bf16 v[12:15], v[152:155], v[216:219], v[12:15]
	v_mfma_f32_16x16x32_bf16 v[8:11], v[160:163], v[216:219], v[8:11]
	v_mfma_f32_16x16x32_bf16 v[60:63], v[156:159], v[196:199], v[60:63]
	v_mfma_f32_16x16x32_bf16 v[56:59], v[164:167], v[196:199], v[56:59]
	v_mfma_f32_16x16x32_bf16 v[44:47], v[156:159], v[204:207], v[44:47]
	v_mfma_f32_16x16x32_bf16 v[40:43], v[164:167], v[204:207], v[40:43]
	v_mfma_f32_16x16x32_bf16 v[28:31], v[156:159], v[212:215], v[28:31]
	v_mfma_f32_16x16x32_bf16 v[24:27], v[164:167], v[212:215], v[24:27]
	v_mfma_f32_16x16x32_bf16 v[12:15], v[156:159], v[240:243], v[12:15]
	v_mfma_f32_16x16x32_bf16 v[8:11], v[164:167], v[240:243], v[8:11]
	s_setprio 0
	s_setprio 1
	v_mfma_f32_16x16x32_bf16 v[52:55], v[176:179], v[192:195], v[52:55]
	v_mfma_f32_16x16x32_bf16 v[48:51], v[184:187], v[192:195], v[48:51]
	v_mfma_f32_16x16x32_bf16 v[36:39], v[176:179], v[200:203], v[36:39]
	v_mfma_f32_16x16x32_bf16 v[32:35], v[184:187], v[200:203], v[32:35]
	v_mfma_f32_16x16x32_bf16 v[20:23], v[176:179], v[208:211], v[20:23]
	v_mfma_f32_16x16x32_bf16 v[16:19], v[184:187], v[208:211], v[16:19]
	v_mfma_f32_16x16x32_bf16 v[4:7], v[176:179], v[216:219], v[4:7]
	v_mfma_f32_16x16x32_bf16 v[0:3], v[184:187], v[216:219], v[0:3]
	v_mfma_f32_16x16x32_bf16 v[52:55], v[180:183], v[196:199], v[52:55]
	v_mfma_f32_16x16x32_bf16 v[48:51], v[188:191], v[196:199], v[48:51]
	v_mfma_f32_16x16x32_bf16 v[36:39], v[180:183], v[204:207], v[36:39]
	v_mfma_f32_16x16x32_bf16 v[32:35], v[188:191], v[204:207], v[32:35]
	v_mfma_f32_16x16x32_bf16 v[20:23], v[180:183], v[212:215], v[20:23]
	v_mfma_f32_16x16x32_bf16 v[16:19], v[188:191], v[212:215], v[16:19]
	v_mfma_f32_16x16x32_bf16 v[4:7], v[180:183], v[240:243], v[4:7]
	v_mfma_f32_16x16x32_bf16 v[0:3], v[188:191], v[240:243], v[0:3]
	s_barrier
	s_setprio 0
	s_add_i32 s10, 0, 0x18000
	v_add_u32_e32 v148, s10, v149
	s_add_i32 s62, 0, 0x1c000
	ds_read_b128 v[152:155], v148
	ds_read_b128 v[156:159], v148 offset:1024
	ds_read_b128 v[160:163], v148 offset:2048
	ds_read_b128 v[164:167], v148 offset:3072
	v_add_u32_e32 v148, s62, v149
	ds_read_b128 v[176:179], v148
	ds_read_b128 v[180:183], v148 offset:1024
	ds_read_b128 v[184:187], v148 offset:2048
	ds_read_b128 v[188:191], v148 offset:3072
	v_lshl_add_u64 v[146:147], v[146:147], 0, s[94:95]
	s_mov_b32 m0, s51
	v_lshl_add_u64 v[226:227], v[146:147], 0, v[132:133]
	ds_read_b128 v[192:195], v151 offset:32768
	ds_read_b128 v[196:199], v151 offset:33792
	ds_read_b128 v[200:203], v151 offset:34816
	ds_read_b128 v[204:207], v151 offset:35840
	ds_read_b128 v[208:211], v151 offset:36864
	ds_read_b128 v[212:215], v151 offset:37888
	ds_read_b128 v[216:219], v151 offset:38912
	ds_read_b128 v[240:243], v151 offset:39936
	global_load_lds_dwordx4 v[226:227], off
	v_lshl_add_u64 v[146:147], v[146:147], 0, v[130:131]
	s_mov_b32 m0, s52
	s_nop 0
	global_load_lds_dwordx4 v[146:147], off
	s_waitcnt vmcnt(8)
	s_waitcnt lgkmcnt(0)
	s_setprio 1
	s_barrier
; __device__ __forceinline__ unsigned cvt_pk_bf16(float lo, float hi) { unsigned r; asm volatile("v_cvt_pk_bf16_f32 %0, %1, %2" : "=v"(r) : "v"(lo), "v"(hi)); return r; }
;     __device__ __forceinline__ void operator()(const f32x4 (&acc)[2][2][4][2], const Unit& u, int wr, int wc, int fr, int fq) const {
;         const int row0 = u.pm * BM + wr * 64 + fr, col0 = u.pn * BM + wc * 32 + 8 * fq;
;         float rsv[2][4]; load_rstd(rsv, ssq, row0);
; #pragma unroll
;         for (int ai = 0; ai < 2; ++ai)
; #pragma unroll
;             for (int m = 0; m < 4; ++m) { const int row = row0 + ai * HALF + m * 16; bf16_t* rowp = O + (size_t)row * ldc + col0; const float rs = rsv[ai][m];
; #pragma unroll
;                 for (int bj = 0; bj < 2; ++bj) { f32x4 v0 = acc[ai][bj][m][0] * rs, v1 = acc[ai][bj][m][1] * rs;
;                     if (ACT == 1) {
; #pragma unroll
;                         for (int j = 0; j < 4; ++j) { v0[j] = gelu_tanh(v0[j]); v1[j] = gelu_tanh(v1[j]); } }
;                     u32x4 w; w.x = cvt_pk_bf16(v0[0], v0[1]); w.y = cvt_pk_bf16(v0[2], v0[3]); w.z = cvt_pk_bf16(v1[0], v1[1]); w.w = cvt_pk_bf16(v1[2], v1[3]);
;                     *(u32x4*)(rowp + bj * HALF) = w; } }
; template <class Epi, bool ALIGN_EPI>
; __device__ __forceinline__ void gemm_phase(LAS unsigned char* lds, const Gemm g, const StaticOrder& S, const Epi& E, const int tid) {
;     ...
;             PG8_LDB(B0, 0, 0); PG8_LDB(B1, 0, 1); PG8_SCHED; PG8_LDA(At, 0, 0); PG8_STAGE(PG8_SA(1, 1), a1 + hA, voffA);
;             PG8_WAIT_V(8); PG8_WAIT_L(0); PG8_BAR; PG8_MMA(0, 0, At, B0); PG8_MMA(0, 1, At, B1); PG8_BAR; PG8_SCHED;
;             PG8_LDA(At, 0, 1); PG8_STAGE(PG8_SB(0, 0), b2, voffB); PG8_STAGE(PG8_SB(0, 1), b2 + hB, voffB); PG8_STAGE(PG8_SA(0, 0), a2, voffA);
;             PG8_WAIT_V(8); PG8_WAIT_L(0); PG8_BAR; PG8_MMA(1, 0, At, B0); PG8_MMA(1, 1, At, B1); PG8_BAR; PG8_SCHED;
;             PG8_LDB(B0, 1, 0); PG8_LDB(B1, 1, 1); PG8_SCHED; PG8_LDA(At, 1, 0); PG8_STAGE(PG8_SA(0, 1), a2 + hA, voffA);
;             PG8_WAIT_V(8); PG8_WAIT_L(0); PG8_BAR; PG8_MMA(0, 0, At, B0); PG8_MMA(0, 1, At, B1); PG8_BAR; PG8_SCHED;
;             PG8_LDA(At, 1, 1); PG8_STAGE(PG8_SB(1, 0), b3, voffB); PG8_STAGE(PG8_SB(1, 1), b3 + hB, voffB); PG8_STAGE(PG8_SA(1, 0), a3, voffA);
;             PG8_WAIT_V(8); PG8_WAIT_L(0); PG8_BAR; PG8_MMA(1, 0, At, B0); PG8_MMA(1, 1, At, B1); PG8_BAR; PG8_SCHED;
	s_waitcnt lgkmcnt(0)
	v_mfma_f32_16x16x32_bf16 v[124:127], v[152:155], v[192:195], v[124:127]
	v_mfma_f32_16x16x32_bf16 v[120:123], v[160:163], v[192:195], v[120:123]
	v_mfma_f32_16x16x32_bf16 v[108:111], v[152:155], v[200:203], v[108:111]
	v_mfma_f32_16x16x32_bf16 v[104:107], v[160:163], v[200:203], v[104:107]
	v_mfma_f32_16x16x32_bf16 v[92:95], v[152:155], v[208:211], v[92:95]
	v_mfma_f32_16x16x32_bf16 v[88:91], v[160:163], v[208:211], v[88:91]
	v_mfma_f32_16x16x32_bf16 v[76:79], v[152:155], v[216:219], v[76:79]
	v_mfma_f32_16x16x32_bf16 v[72:75], v[160:163], v[216:219], v[72:75]
	v_mfma_f32_16x16x32_bf16 v[124:127], v[156:159], v[196:199], v[124:127]
	v_mfma_f32_16x16x32_bf16 v[120:123], v[164:167], v[196:199], v[120:123]
	v_mfma_f32_16x16x32_bf16 v[108:111], v[156:159], v[204:207], v[108:111]
	v_mfma_f32_16x16x32_bf16 v[104:107], v[164:167], v[204:207], v[104:107]
	v_mfma_f32_16x16x32_bf16 v[92:95], v[156:159], v[212:215], v[92:95]
	v_mfma_f32_16x16x32_bf16 v[88:91], v[164:167], v[212:215], v[88:91]
	v_mfma_f32_16x16x32_bf16 v[76:79], v[156:159], v[240:243], v[76:79]
	v_mfma_f32_16x16x32_bf16 v[72:75], v[164:167], v[240:243], v[72:75]
	s_setprio 0
	s_setprio 1
	v_mfma_f32_16x16x32_bf16 v[116:119], v[176:179], v[192:195], v[116:119]
	v_mfma_f32_16x16x32_bf16 v[112:115], v[184:187], v[192:195], v[112:115]
	v_mfma_f32_16x16x32_bf16 v[100:103], v[176:179], v[200:203], v[100:103]
	v_mfma_f32_16x16x32_bf16 v[96:99], v[184:187], v[200:203], v[96:99]
	v_mfma_f32_16x16x32_bf16 v[84:87], v[176:179], v[208:211], v[84:87]
	v_mfma_f32_16x16x32_bf16 v[80:83], v[184:187], v[208:211], v[80:83]
	v_mfma_f32_16x16x32_bf16 v[68:71], v[176:179], v[216:219], v[68:71]
	v_mfma_f32_16x16x32_bf16 v[64:67], v[184:187], v[216:219], v[64:67]
	v_mfma_f32_16x16x32_bf16 v[116:119], v[180:183], v[196:199], v[116:119]
	v_mfma_f32_16x16x32_bf16 v[112:115], v[188:191], v[196:199], v[112:115]
	v_mfma_f32_16x16x32_bf16 v[100:103], v[180:183], v[204:207], v[100:103]
	v_mfma_f32_16x16x32_bf16 v[96:99], v[188:191], v[204:207], v[96:99]
	v_mfma_f32_16x16x32_bf16 v[84:87], v[180:183], v[212:215], v[84:87]
	v_mfma_f32_16x16x32_bf16 v[80:83], v[188:191], v[212:215], v[80:83]
	v_mfma_f32_16x16x32_bf16 v[68:71], v[180:183], v[240:243], v[68:71]
	v_mfma_f32_16x16x32_bf16 v[64:67], v[188:191], v[240:243], v[64:67]
	s_barrier
	s_setprio 0
	s_add_i32 s10, s10, s45
	v_lshl_add_u64 v[146:147], v[244:245], 0, s[92:93]
	s_mov_b32 m0, s10
	ds_read_b128 v[192:195], v151 offset:49152
	ds_read_b128 v[196:199], v151 offset:50176
	ds_read_b128 v[200:203], v151 offset:51200
	ds_read_b128 v[204:207], v151 offset:52224
	ds_read_b128 v[208:211], v151 offset:53248
	ds_read_b128 v[212:215], v151 offset:54272
	ds_read_b128 v[216:219], v151 offset:55296
	ds_read_b128 v[240:243], v151 offset:56320
	global_load_lds_dwordx4 v[146:147], off
	v_lshl_add_u64 v[146:147], v[246:247], 0, s[92:93]
	s_add_i32 m0, s10, 0x2000
	s_add_i32 s10, s62, s45
	global_load_lds_dwordx4 v[146:147], off
	v_lshl_add_u64 v[146:147], v[248:249], 0, s[92:93]
	s_mov_b32 m0, s10
	s_nop 0
	global_load_lds_dwordx4 v[146:147], off
	v_lshl_add_u64 v[146:147], v[220:221], 0, s[92:93]
	s_add_i32 m0, s10, 0x2000
	s_nop 0
	global_load_lds_dwordx4 v[146:147], off
	v_lshl_add_u64 v[146:147], v[250:251], 0, s[92:93]
	s_mov_b32 m0, s53
	s_nop 0
	global_load_lds_dwordx4 v[146:147], off
	v_lshl_add_u64 v[146:147], v[252:253], 0, s[92:93]
	s_mov_b32 m0, s54
	s_nop 0
	global_load_lds_dwordx4 v[146:147], off
	s_waitcnt vmcnt(8)
	s_waitcnt lgkmcnt(0)
	s_setprio 1
	s_barrier
	s_waitcnt lgkmcnt(0)
	v_mfma_f32_16x16x32_bf16 v[60:63], v[152:155], v[192:195], v[60:63]
	v_lshrrev_b32_e32 v171, 8, v170
	v_and_b32_e32 v234, 15, v170
	v_lshl_add_u32 v171, v171, 6, v234
	s_lshl_b32 s98, s61, 8
	v_add_u32_e32 v171, s98, v171
	v_mfma_f32_16x16x32_bf16 v[56:59], v[160:163], v[192:195], v[56:59]
	v_mul_lo_u32 v171, v171, s28
	v_bfe_u32 v234, v170, 6, 2
	v_bfe_u32 v224, v170, 4, 2
	v_lshlrev_b32_e32 v234, 5, v234
	v_lshl_or_b32 v234, v224, 3, v234
	v_mfma_f32_16x16x32_bf16 v[44:47], v[152:155], v[200:203], v[44:47]
	s_lshl_b32 s98, s60, 8
	v_add_u32_e32 v234, s98, v234
	v_add_lshl_u32 v232, v171, v234, 1
	v_mov_b32_e32 v233, 0
	v_lshl_add_u64 v[232:233], v[232:233], 0, s[30:31]
	v_mfma_f32_16x16x32_bf16 v[40:43], v[160:163], v[200:203], v[40:43]
	s_lshl_b32 s98, s28, 5
	s_mov_b32 s99, 0
	v_mul_f32_e32 v124, v172, v124
	v_mul_f32_e32 v125, v172, v125
	v_mul_f32_e32 v126, v172, v126
	v_mfma_f32_16x16x32_bf16 v[28:31], v[152:155], v[208:211], v[28:31]
	v_mul_f32_e32 v127, v172, v127
	v_mul_f32_e32 v120, v172, v120
	v_mul_f32_e32 v121, v172, v121
	v_mul_f32_e32 v122, v172, v122
	v_mul_f32_e32 v123, v172, v123
	v_mfma_f32_16x16x32_bf16 v[24:27], v[160:163], v[208:211], v[24:27]
	v_cvt_pk_bf16_f32 v124, v124, v125
	v_cvt_pk_bf16_f32 v125, v126, v127
	v_cvt_pk_bf16_f32 v126, v120, v121
	v_cvt_pk_bf16_f32 v127, v122, v123
	global_store_dwordx4 v[232:233], v[124:127], off
	v_mfma_f32_16x16x32_bf16 v[12:15], v[152:155], v[216:219], v[12:15]
	v_mul_f32_e32 v116, v172, v116
	v_mul_f32_e32 v117, v172, v117
	v_mul_f32_e32 v118, v172, v118
	v_mul_f32_e32 v119, v172, v119
	v_mul_f32_e32 v112, v172, v112
	v_mfma_f32_16x16x32_bf16 v[8:11], v[160:163], v[216:219], v[8:11]
	v_mul_f32_e32 v113, v172, v113
	v_mul_f32_e32 v114, v172, v114
; __device__ __forceinline__ unsigned cvt_pk_bf16(float lo, float hi) { unsigned r; asm volatile("v_cvt_pk_bf16_f32 %0, %1, %2" : "=v"(r) : "v"(lo), "v"(hi)); return r; }
;     __device__ __forceinline__ void operator()(const f32x4 (&acc)[2][2][4][2], const Unit& u, int wr, int wc, int fr, int fq) const {
;         const int row0 = u.pm * BM + wr * 64 + fr, col0 = u.pn * BM + wc * 32 + 8 * fq;
;         float rsv[2][4]; load_rstd(rsv, ssq, row0);
; #pragma unroll
;         for (int ai = 0; ai < 2; ++ai)
; #pragma unroll
;             for (int m = 0; m < 4; ++m) { const int row = row0 + ai * HALF + m * 16; bf16_t* rowp = O + (size_t)row * ldc + col0; const float rs = rsv[ai][m];
; #pragma unroll
;                 for (int bj = 0; bj < 2; ++bj) { f32x4 v0 = acc[ai][bj][m][0] * rs, v1 = acc[ai][bj][m][1] * rs;
;                     if (ACT == 1) {
; #pragma unroll
;                         for (int j = 0; j < 4; ++j) { v0[j] = gelu_tanh(v0[j]); v1[j] = gelu_tanh(v1[j]); } }
;                     u32x4 w; w.x = cvt_pk_bf16(v0[0], v0[1]); w.y = cvt_pk_bf16(v0[2], v0[3]); w.z = cvt_pk_bf16(v1[0], v1[1]); w.w = cvt_pk_bf16(v1[2], v1[3]);
;                     *(u32x4*)(rowp + bj * HALF) = w; } }
; template <class Epi, bool ALIGN_EPI>
; __device__ __forceinline__ void gemm_phase(LAS unsigned char* lds, const Gemm g, const StaticOrder& S, const Epi& E, const int tid) {
;     ...
;             PG8_LDB(B0, 0, 0); PG8_LDB(B1, 0, 1); PG8_SCHED; PG8_LDA(At, 0, 0); PG8_STAGE(PG8_SA(1, 1), a1 + hA, voffA);
;             PG8_WAIT_V(8); PG8_WAIT_L(0); PG8_BAR; PG8_MMA(0, 0, At, B0); PG8_MMA(0, 1, At, B1); PG8_BAR; PG8_SCHED;
;             PG8_LDA(At, 0, 1); PG8_STAGE(PG8_SB(0, 0), b2, voffB); PG8_STAGE(PG8_SB(0, 1), b2 + hB, voffB); PG8_STAGE(PG8_SA(0, 0), a2, voffA);
;             PG8_WAIT_V(8); PG8_WAIT_L(0); PG8_BAR; PG8_MMA(1, 0, At, B0); PG8_MMA(1, 1, At, B1); PG8_BAR; PG8_SCHED;
;             PG8_LDB(B0, 1, 0); PG8_LDB(B1, 1, 1); PG8_SCHED; PG8_LDA(At, 1, 0); PG8_STAGE(PG8_SA(0, 1), a2 + hA, voffA);
;             PG8_WAIT_V(8); PG8_WAIT_L(0); PG8_BAR; PG8_MMA(0, 0, At, B0); PG8_MMA(0, 1, At, B1); PG8_BAR; PG8_SCHED;
;             PG8_LDA(At, 1, 1); PG8_STAGE(PG8_SB(1, 0), b3, voffB); PG8_STAGE(PG8_SB(1, 1), b3 + hB, voffB); PG8_STAGE(PG8_SA(1, 0), a3, voffA);
;             PG8_WAIT_V(8); PG8_WAIT_L(0); PG8_BAR; PG8_MMA(1, 0, At, B0); PG8_MMA(1, 1, At, B1); PG8_BAR; PG8_SCHED;
	v_mul_f32_e32 v115, v172, v115
	v_cvt_pk_bf16_f32 v116, v116, v117
	v_cvt_pk_bf16_f32 v117, v118, v119
	v_mfma_f32_16x16x32_bf16 v[60:63], v[156:159], v[196:199], v[60:63]
	v_cvt_pk_bf16_f32 v118, v112, v113
	v_cvt_pk_bf16_f32 v119, v114, v115
	global_store_dwordx4 v[232:233], v[116:119], off offset:256
	v_lshl_add_u64 v[232:233], v[232:233], 0, s[98:99]
	v_mul_f32_e32 v108, v173, v108
	v_mfma_f32_16x16x32_bf16 v[56:59], v[164:167], v[196:199], v[56:59]
	v_mul_f32_e32 v109, v173, v109
	v_mul_f32_e32 v110, v173, v110
	v_mul_f32_e32 v111, v173, v111
	v_mul_f32_e32 v104, v173, v104
	v_mul_f32_e32 v105, v173, v105
	v_mfma_f32_16x16x32_bf16 v[44:47], v[156:159], v[204:207], v[44:47]
	v_mul_f32_e32 v106, v173, v106
	v_mul_f32_e32 v107, v173, v107
	v_cvt_pk_bf16_f32 v108, v108, v109
	v_cvt_pk_bf16_f32 v109, v110, v111
	v_cvt_pk_bf16_f32 v110, v104, v105
	v_mfma_f32_16x16x32_bf16 v[40:43], v[164:167], v[204:207], v[40:43]
	v_cvt_pk_bf16_f32 v111, v106, v107
	global_store_dwordx4 v[232:233], v[108:111], off
	v_mul_f32_e32 v100, v173, v100
	v_mul_f32_e32 v101, v173, v101
	v_mul_f32_e32 v102, v173, v102
	v_mfma_f32_16x16x32_bf16 v[28:31], v[156:159], v[212:215], v[28:31]
	v_mul_f32_e32 v103, v173, v103
	v_mul_f32_e32 v96, v173, v96
	v_mul_f32_e32 v97, v173, v97
	v_mul_f32_e32 v98, v173, v98
	v_mul_f32_e32 v99, v173, v99
	v_mfma_f32_16x16x32_bf16 v[24:27], v[164:167], v[212:215], v[24:27]
	v_cvt_pk_bf16_f32 v100, v100, v101
	v_cvt_pk_bf16_f32 v101, v102, v103
	v_cvt_pk_bf16_f32 v102, v96, v97
	v_cvt_pk_bf16_f32 v103, v98, v99
	global_store_dwordx4 v[232:233], v[100:103], off offset:256
	v_mfma_f32_16x16x32_bf16 v[12:15], v[156:159], v[240:243], v[12:15]
	v_lshl_add_u64 v[232:233], v[232:233], 0, s[98:99]
	v_mul_f32_e32 v92, v236, v92
	v_mul_f32_e32 v93, v236, v93
	v_mul_f32_e32 v94, v236, v94
	v_mul_f32_e32 v95, v236, v95
	v_mfma_f32_16x16x32_bf16 v[8:11], v[164:167], v[240:243], v[8:11]
	v_mul_f32_e32 v88, v236, v88
	v_mul_f32_e32 v89, v236, v89
	v_mul_f32_e32 v90, v236, v90
	v_mul_f32_e32 v91, v236, v91
	v_cvt_pk_bf16_f32 v92, v92, v93
	s_setprio 0
	s_setprio 1
	v_mfma_f32_16x16x32_bf16 v[52:55], v[176:179], v[192:195], v[52:55]
	v_cvt_pk_bf16_f32 v93, v94, v95
	v_cvt_pk_bf16_f32 v94, v88, v89
	v_cvt_pk_bf16_f32 v95, v90, v91
	global_store_dwordx4 v[232:233], v[92:95], off
	v_mul_f32_e32 v84, v236, v84
	v_mfma_f32_16x16x32_bf16 v[48:51], v[184:187], v[192:195], v[48:51]
	v_mul_f32_e32 v85, v236, v85
	v_mul_f32_e32 v86, v236, v86
	v_mul_f32_e32 v87, v236, v87
	v_mul_f32_e32 v80, v236, v80
	v_mul_f32_e32 v81, v236, v81
	v_mfma_f32_16x16x32_bf16 v[36:39], v[176:179], v[200:203], v[36:39]
	v_mul_f32_e32 v82, v236, v82
	v_mul_f32_e32 v83, v236, v83
	v_cvt_pk_bf16_f32 v84, v84, v85
	v_cvt_pk_bf16_f32 v85, v86, v87
	v_cvt_pk_bf16_f32 v86, v80, v81
	v_mfma_f32_16x16x32_bf16 v[32:35], v[184:187], v[200:203], v[32:35]
	v_cvt_pk_bf16_f32 v87, v82, v83
	global_store_dwordx4 v[232:233], v[84:87], off offset:256
	v_lshl_add_u64 v[232:233], v[232:233], 0, s[98:99]
	v_mul_f32_e32 v76, v237, v76
	v_mul_f32_e32 v77, v237, v77
	v_mfma_f32_16x16x32_bf16 v[20:23], v[176:179], v[208:211], v[20:23]
	v_mul_f32_e32 v78, v237, v78
	v_mul_f32_e32 v79, v237, v79
	v_mul_f32_e32 v72, v237, v72
	v_mul_f32_e32 v73, v237, v73
	v_mul_f32_e32 v74, v237, v74
	v_mfma_f32_16x16x32_bf16 v[16:19], v[184:187], v[208:211], v[16:19]
	v_mul_f32_e32 v75, v237, v75
	v_cvt_pk_bf16_f32 v76, v76, v77
	v_cvt_pk_bf16_f32 v77, v78, v79
	v_cvt_pk_bf16_f32 v78, v72, v73
	v_cvt_pk_bf16_f32 v79, v74, v75
	v_mfma_f32_16x16x32_bf16 v[4:7], v[176:179], v[216:219], v[4:7]
	global_store_dwordx4 v[232:233], v[76:79], off
	v_mul_f32_e32 v68, v237, v68
	v_mul_f32_e32 v69, v237, v69
	v_mul_f32_e32 v70, v237, v70
	v_mul_f32_e32 v71, v237, v71
	v_mfma_f32_16x16x32_bf16 v[0:3], v[184:187], v[216:219], v[0:3]
	v_mul_f32_e32 v64, v237, v64
	v_mul_f32_e32 v65, v237, v65
	v_mul_f32_e32 v66, v237, v66
	v_mul_f32_e32 v67, v237, v67
	v_cvt_pk_bf16_f32 v68, v68, v69
	v_mfma_f32_16x16x32_bf16 v[52:55], v[180:183], v[196:199], v[52:55]
	v_cvt_pk_bf16_f32 v69, v70, v71
	v_cvt_pk_bf16_f32 v70, v64, v65
	v_cvt_pk_bf16_f32 v71, v66, v67
	global_store_dwordx4 v[232:233], v[68:71], off offset:256
	v_lshl_add_u64 v[232:233], v[232:233], 0, s[98:99]
	v_mfma_f32_16x16x32_bf16 v[48:51], v[188:191], v[196:199], v[48:51]
	v_lshl_add_u64 v[232:233], v[232:233], 0, s[98:99]
	v_lshl_add_u64 v[232:233], v[232:233], 0, s[98:99]
	v_lshl_add_u64 v[232:233], v[232:233], 0, s[98:99]
	v_lshl_add_u64 v[232:233], v[232:233], 0, s[98:99]
	v_mfma_f32_16x16x32_bf16 v[36:39], v[180:183], v[204:207], v[36:39]
	v_mfma_f32_16x16x32_bf16 v[32:35], v[188:191], v[204:207], v[32:35]
	v_mfma_f32_16x16x32_bf16 v[20:23], v[180:183], v[212:215], v[20:23]
	v_mfma_f32_16x16x32_bf16 v[16:19], v[188:191], v[212:215], v[16:19]
	v_mfma_f32_16x16x32_bf16 v[4:7], v[180:183], v[240:243], v[4:7]
	v_mfma_f32_16x16x32_bf16 v[0:3], v[188:191], v[240:243], v[0:3]
	s_barrier
	s_setprio 0
	v_lshl_add_u64 v[142:143], v[142:143], 0, s[80:81]
	v_lshl_add_u64 v[144:145], v[144:145], 0, s[80:81]
	s_and_b64 vcc, exec, s[8:9]
	s_cbranch_vccnz .Lq5_notdefer
	s_cmp_lg_u32 s59, s61
	s_cbranch_scc1 .Lq5_notdefer
	s_mov_b32 s101, 1
	s_mov_b32 s60, s58
	s_mov_b32 s61, s59
	v_mov_b64_e32 v[144:145], v[140:141]
	v_mov_b64_e32 v[142:143], v[138:139]
	s_branch .LBB0_346

; #define PG8_STAGE(bufoff, gbase, voff) do { _Pragma("unroll") for (int _i = 0; _i < 2; ++_i) \
;         __builtin_amdgcn_global_load_lds((const unsigned*)((const char*)(gbase) + (voff)[_i]), (LAS unsigned*)(lds + (bufoff) + ldsw + _i * 8192), 16, 0, 0); } while (0)
; #define PG8_LDA(dst, b, h) do { _Pragma("unroll") for (int m = 0; m < 4; ++m) _Pragma("unroll") for (int k = 0; k < 2; ++k) dst[m][k] = *(const LAS bf16x8*)(lds + PG8_SA(b, h) + aoff + m * 2048 + k * 1024); } while (0)
; #define PG8_WAIT_V(n) asm volatile("s_waitcnt vmcnt(" #n ")" ::: "memory")
; #define PG8_WAIT_L(n) asm volatile("s_waitcnt lgkmcnt(" #n ")" ::: "memory")
; template <class Epi, bool ALIGN_EPI>
; __device__ __forceinline__ void gemm_phase(LAS unsigned char* lds, const Gemm g, const StaticOrder& S, const Epi& E, const int tid) {
;     ...
;         const char* nA = has_next ? (const char*)g.A + (size_t)nxt.pm * tA + (size_t)nxt.pn * g.apn * 2 : cA; const char* nB = has_next ? (const char*)g.Bt + (size_t)nxt.pn * tB : cB;
;         for (int t = 0; t < nt; t += 2) {
;             const bool last = (t == nt - 2);
;             const char* a1 = cA + (size_t)(t + 1) * kstep;
;             const char* a2 = last ? nA : cA + (size_t)(t + 2) * kstep; const char* b2 = last ? nB : cB + (size_t)(t + 2) * kstep;
;             const char* a3 = a2 + kstep; const char* b3 = b2 + kstep;
;             PG8_LDB(B0, 0, 0); PG8_LDB(B1, 0, 1); PG8_SCHED; PG8_LDA(At, 0, 0); PG8_STAGE(PG8_SA(1, 1), a1 + hA, voffA);
;             PG8_WAIT_V(8); PG8_WAIT_L(0); PG8_BAR; PG8_MMA(0, 0, At, B0); PG8_MMA(0, 1, At, B1); PG8_BAR; PG8_SCHED;
;             PG8_LDA(At, 0, 1); PG8_STAGE(PG8_SB(0, 0), b2, voffB); PG8_STAGE(PG8_SB(0, 1), b2 + hB, voffB); PG8_STAGE(PG8_SA(0, 0), a2, voffA);
;             PG8_WAIT_V(8); PG8_WAIT_L(0); PG8_BAR; PG8_MMA(1, 0, At, B0); PG8_MMA(1, 1, At, B1); PG8_BAR; PG8_SCHED;
;             PG8_LDB(B0, 1, 0); PG8_LDB(B1, 1, 1); PG8_SCHED; PG8_LDA(At, 1, 0); PG8_STAGE(PG8_SA(0, 1), a2 + hA, voffA);
;             PG8_WAIT_V(8); PG8_WAIT_L(0); PG8_BAR; PG8_MMA(0, 0, At, B0); PG8_MMA(0, 1, At, B1); PG8_BAR; PG8_SCHED;
;             PG8_LDA(At, 1, 1); PG8_STAGE(PG8_SB(1, 0), b3, voffB); PG8_STAGE(PG8_SB(1, 1), b3 + hB, voffB); PG8_STAGE(PG8_SA(1, 0), a3, voffA);
;             PG8_WAIT_V(8); PG8_WAIT_L(0); PG8_BAR; PG8_MMA(1, 0, At, B0); PG8_MMA(1, 1, At, B1); PG8_BAR; PG8_SCHED;
.LBB0_378:
	s_ashr_i32 s17, s16, 31
	s_lshl_b64 s[22:23], s[16:17], 17
	s_add_u32 s22, s4, s22
	s_addc_u32 s23, s5, s23
	s_and_b64 s[26:27], s[8:9], exec
	s_cselect_b32 s17, s23, s35
	s_cselect_b32 s59, s22, s34
	s_ashr_i32 s15, s14, 31
	s_lshl_b64 s[26:27], s[14:15], 17
	s_add_u32 s26, s7, s26
	s_addc_u32 s27, s25, s27
	s_and_b64 s[36:37], s[8:9], exec
	s_cselect_b32 s15, s27, s31
	s_cselect_b32 s60, s26, s30
	s_mov_b32 s40, 0
	s_mov_b64 s[36:37], -1
	s_mov_b64 s[38:39], 0
	s_add_u32 s41, s34, s40
	s_addc_u32 s46, s35, 0
	s_add_u32 s44, s41, 0x100
	s_addc_u32 s45, s46, 0
	s_and_b64 s[42:43], s[38:39], exec
	s_cselect_b32 s43, s17, s45
	s_cselect_b32 s42, s59, s44
	s_add_u32 s40, s30, s40
	s_addc_u32 s44, s31, 0
	s_add_u32 s40, s40, 0x100
	s_addc_u32 s44, s44, 0
	s_and_b64 s[38:39], s[38:39], exec
	s_cselect_b32 s45, s15, s44
	s_cselect_b32 s44, s60, s40
	s_add_i32 s39, 0, 0x14000
	s_add_u32 s48, s41, 0x10080
	s_addc_u32 s49, s46, 0
	s_add_i32 s68, s33, s50
	s_add_i32 m0, s51, 0xc000
	s_add_i32 s71, s51, 0xe000
	s_add_i32 s65, s68, 0x2000
	v_add_u32_e32 v138, s33, v141
	s_add_u32 s46, s44, 0x10000
	ds_read_b128 v[134:137], v138
	ds_read_b128 v[146:149], v138 offset:1024
	ds_read_b128 v[150:153], v138 offset:2048
	ds_read_b128 v[154:157], v138 offset:3072
	v_add_u32_e32 v138, s39, v141
	s_addc_u32 s47, s45, 0
	s_add_i32 s67, s39, s50
	ds_read_b128 v[158:161], v138
	ds_read_b128 v[162:165], v138 offset:1024
	ds_read_b128 v[174:177], v138 offset:2048
	ds_read_b128 v[178:181], v138 offset:3072
	s_add_i32 s66, s67, 0x2000
	s_add_i32 s64, 0, 0x18000
	s_add_i32 s63, 0, 0x1c000
	s_add_u32 s40, s42, 0x10000
	s_addc_u32 s41, s43, 0
	s_add_i32 s62, s64, s50
	s_add_i32 s61, s62, 0x2000
	s_add_u32 s38, s44, 0x10080
	s_addc_u32 s39, s45, 0
	s_add_i32 s70, s63, s50
	s_add_i32 s69, s70, 0x2000
	v_lshl_add_u64 v[138:139], s[48:49], 0, v[128:129]
	ds_read_b128 v[182:185], v145
	ds_read_b128 v[186:189], v145 offset:1024
	ds_read_b128 v[190:193], v145 offset:2048
	ds_read_b128 v[194:197], v145 offset:3072
	ds_read_b128 v[198:201], v145 offset:4096
	ds_read_b128 v[202:205], v145 offset:5120
	ds_read_b128 v[206:209], v145 offset:6144
	ds_read_b128 v[210:213], v145 offset:7168
	global_load_lds_dwordx4 v[138:139], off
	v_lshl_add_u64 v[138:139], s[48:49], 0, v[130:131]
	s_mov_b32 m0, s71
	s_nop 0
	global_load_lds_dwordx4 v[138:139], off
	s_waitcnt vmcnt(8)
	s_waitcnt lgkmcnt(0)
	s_setprio 1
	s_barrier
	s_waitcnt lgkmcnt(0)
	v_mfma_f32_16x16x32_bf16 v[124:127], v[134:137], v[182:185], 0
	v_mfma_f32_16x16x32_bf16 v[120:123], v[150:153], v[182:185], 0
	v_mfma_f32_16x16x32_bf16 v[108:111], v[134:137], v[190:193], 0
	v_mfma_f32_16x16x32_bf16 v[104:107], v[150:153], v[190:193], 0
	v_mfma_f32_16x16x32_bf16 v[92:95], v[134:137], v[198:201], 0
	v_mfma_f32_16x16x32_bf16 v[88:91], v[150:153], v[198:201], 0
	v_mfma_f32_16x16x32_bf16 v[76:79], v[134:137], v[206:209], 0
	v_mfma_f32_16x16x32_bf16 v[72:75], v[150:153], v[206:209], 0
	v_mfma_f32_16x16x32_bf16 v[124:127], v[146:149], v[186:189], v[124:127]
	v_mfma_f32_16x16x32_bf16 v[120:123], v[154:157], v[186:189], v[120:123]
	v_mfma_f32_16x16x32_bf16 v[108:111], v[146:149], v[194:197], v[108:111]
	v_mfma_f32_16x16x32_bf16 v[104:107], v[154:157], v[194:197], v[104:107]
	v_mfma_f32_16x16x32_bf16 v[92:95], v[146:149], v[202:205], v[92:95]
	v_mfma_f32_16x16x32_bf16 v[88:91], v[154:157], v[202:205], v[88:91]
	v_mfma_f32_16x16x32_bf16 v[76:79], v[146:149], v[210:213], v[76:79]
	v_mfma_f32_16x16x32_bf16 v[72:75], v[154:157], v[210:213], v[72:75]
	s_setprio 0
	s_setprio 1
	v_mfma_f32_16x16x32_bf16 v[116:119], v[158:161], v[182:185], 0
	v_mfma_f32_16x16x32_bf16 v[112:115], v[174:177], v[182:185], 0
	v_mfma_f32_16x16x32_bf16 v[100:103], v[158:161], v[190:193], 0
	v_mfma_f32_16x16x32_bf16 v[96:99], v[174:177], v[190:193], 0
	v_mfma_f32_16x16x32_bf16 v[84:87], v[158:161], v[198:201], 0
	v_mfma_f32_16x16x32_bf16 v[80:83], v[174:177], v[198:201], 0
	v_mfma_f32_16x16x32_bf16 v[68:71], v[158:161], v[206:209], 0
	v_mfma_f32_16x16x32_bf16 v[64:67], v[174:177], v[206:209], 0
	v_mfma_f32_16x16x32_bf16 v[116:119], v[162:165], v[186:189], v[116:119]
	v_mfma_f32_16x16x32_bf16 v[112:115], v[178:181], v[186:189], v[112:115]
	v_mfma_f32_16x16x32_bf16 v[100:103], v[162:165], v[194:197], v[100:103]
	v_mfma_f32_16x16x32_bf16 v[96:99], v[178:181], v[194:197], v[96:99]
	v_mfma_f32_16x16x32_bf16 v[84:87], v[162:165], v[202:205], v[84:87]
	v_mfma_f32_16x16x32_bf16 v[80:83], v[178:181], v[202:205], v[80:83]
	v_mfma_f32_16x16x32_bf16 v[68:71], v[162:165], v[210:213], v[68:71]
	v_mfma_f32_16x16x32_bf16 v[64:67], v[178:181], v[210:213], v[64:67]
	s_barrier
	s_setprio 0
	s_mov_b32 m0, s68
	v_lshl_add_u64 v[138:139], s[44:45], 0, v[168:169]
	ds_read_b128 v[182:185], v145 offset:16384
	ds_read_b128 v[186:189], v145 offset:17408
	ds_read_b128 v[190:193], v145 offset:18432
	ds_read_b128 v[194:197], v145 offset:19456
	ds_read_b128 v[198:201], v145 offset:20480
	ds_read_b128 v[202:205], v145 offset:21504
	ds_read_b128 v[206:209], v145 offset:22528
	ds_read_b128 v[210:213], v145 offset:23552
	global_load_lds_dwordx4 v[138:139], off
	v_lshl_add_u64 v[142:143], s[44:45], 0, v[132:133]
	s_mov_b32 m0, s65
	v_lshl_add_u64 v[166:167], s[46:47], 0, v[168:169]
	global_load_lds_dwordx4 v[142:143], off
	s_mov_b32 m0, s67
	v_lshl_add_u64 v[214:215], s[42:43], 0, v[130:131]
	global_load_lds_dwordx4 v[166:167], off
	v_lshl_add_u64 v[166:167], s[46:47], 0, v[132:133]
	s_mov_b32 m0, s66
	s_nop 0
	global_load_lds_dwordx4 v[166:167], off
	v_lshl_add_u64 v[166:167], s[42:43], 0, v[128:129]
	s_mov_b32 m0, s51
	s_nop 0
	global_load_lds_dwordx4 v[166:167], off
	s_mov_b32 m0, s52
	s_nop 0
	global_load_lds_dwordx4 v[214:215], off
	s_waitcnt vmcnt(8)
	s_waitcnt lgkmcnt(0)
	s_setprio 1
	s_barrier
; #define PG8_STAGE(bufoff, gbase, voff) do { _Pragma("unroll") for (int _i = 0; _i < 2; ++_i) \
;         __builtin_amdgcn_global_load_lds((const unsigned*)((const char*)(gbase) + (voff)[_i]), (LAS unsigned*)(lds + (bufoff) + ldsw + _i * 8192), 16, 0, 0); } while (0)
; #define PG8_LDA(dst, b, h) do { _Pragma("unroll") for (int m = 0; m < 4; ++m) _Pragma("unroll") for (int k = 0; k < 2; ++k) dst[m][k] = *(const LAS bf16x8*)(lds + PG8_SA(b, h) + aoff + m * 2048 + k * 1024); } while (0)
; #define PG8_LDB(dst, b, h) do { _Pragma("unroll") for (int n = 0; n < 2; ++n) _Pragma("unroll") for (int k = 0; k < 2; ++k) dst[n][k] = *(const LAS bf16x8*)(lds + PG8_SB(b, h) + boff + n * 2048 + k * 1024); } while (0)
; #define PG8_MMA(ai, bj, At, Bt) do { __builtin_amdgcn_s_setprio(1); _Pragma("unroll") for (int k = 0; k < 2; ++k) _Pragma("unroll") for (int m = 0; m < 4; ++m) _Pragma("unroll") for (int n = 0; n < 2; ++n) \
;         acc[ai][bj][m][n] = __builtin_amdgcn_mfma_f32_16x16x32_bf16(Bt[n][k], At[m][k], acc[ai][bj][m][n], 0, 0, 0); __builtin_amdgcn_s_setprio(0); } while (0)
; #define PG8_WAIT_V(n) asm volatile("s_waitcnt vmcnt(" #n ")" ::: "memory")
; #define PG8_BAR __builtin_amdgcn_s_barrier()
; template <class Epi, bool ALIGN_EPI>
; __device__ __forceinline__ void gemm_phase(LAS unsigned char* lds, const Gemm g, const StaticOrder& S, const Epi& E, const int tid) {
;     ...
;             PG8_LDB(B0, 0, 0); PG8_LDB(B1, 0, 1); PG8_SCHED; PG8_LDA(At, 0, 0); PG8_STAGE(PG8_SA(1, 1), a1 + hA, voffA);
;             PG8_WAIT_V(8); PG8_WAIT_L(0); PG8_BAR; PG8_MMA(0, 0, At, B0); PG8_MMA(0, 1, At, B1); PG8_BAR; PG8_SCHED;
;             PG8_LDA(At, 0, 1); PG8_STAGE(PG8_SB(0, 0), b2, voffB); PG8_STAGE(PG8_SB(0, 1), b2 + hB, voffB); PG8_STAGE(PG8_SA(0, 0), a2, voffA);
;             PG8_WAIT_V(8); PG8_WAIT_L(0); PG8_BAR; PG8_MMA(1, 0, At, B0); PG8_MMA(1, 1, At, B1); PG8_BAR; PG8_SCHED;
;             PG8_LDB(B0, 1, 0); PG8_LDB(B1, 1, 1); PG8_SCHED; PG8_LDA(At, 1, 0); PG8_STAGE(PG8_SA(0, 1), a2 + hA, voffA);
;             PG8_WAIT_V(8); PG8_WAIT_L(0); PG8_BAR; PG8_MMA(0, 0, At, B0); PG8_MMA(0, 1, At, B1); PG8_BAR; PG8_SCHED;
;             PG8_LDA(At, 1, 1); PG8_STAGE(PG8_SB(1, 0), b3, voffB); PG8_STAGE(PG8_SB(1, 1), b3 + hB, voffB); PG8_STAGE(PG8_SA(1, 0), a3, voffA);
;             PG8_WAIT_V(8); PG8_WAIT_L(0); PG8_BAR; PG8_MMA(1, 0, At, B0); PG8_MMA(1, 1, At, B1); PG8_BAR; PG8_SCHED;
	s_waitcnt lgkmcnt(0)
	v_mfma_f32_16x16x32_bf16 v[60:63], v[134:137], v[182:185], 0
	v_mfma_f32_16x16x32_bf16 v[56:59], v[150:153], v[182:185], 0
	v_mfma_f32_16x16x32_bf16 v[48:51], v[134:137], v[190:193], 0
	v_mfma_f32_16x16x32_bf16 v[40:43], v[150:153], v[190:193], 0
	v_mfma_f32_16x16x32_bf16 v[32:35], v[134:137], v[198:201], 0
	v_mfma_f32_16x16x32_bf16 v[24:27], v[150:153], v[198:201], 0
	v_mfma_f32_16x16x32_bf16 v[16:19], v[134:137], v[206:209], 0
	v_mfma_f32_16x16x32_bf16 v[8:11], v[150:153], v[206:209], 0
	v_mfma_f32_16x16x32_bf16 v[60:63], v[146:149], v[186:189], v[60:63]
	v_mfma_f32_16x16x32_bf16 v[56:59], v[154:157], v[186:189], v[56:59]
	v_mfma_f32_16x16x32_bf16 v[48:51], v[146:149], v[194:197], v[48:51]
	v_mfma_f32_16x16x32_bf16 v[40:43], v[154:157], v[194:197], v[40:43]
	v_mfma_f32_16x16x32_bf16 v[32:35], v[146:149], v[202:205], v[32:35]
	v_mfma_f32_16x16x32_bf16 v[24:27], v[154:157], v[202:205], v[24:27]
	v_mfma_f32_16x16x32_bf16 v[16:19], v[146:149], v[210:213], v[16:19]
	v_mfma_f32_16x16x32_bf16 v[8:11], v[154:157], v[210:213], v[8:11]
	s_setprio 0
	s_setprio 1
	v_mfma_f32_16x16x32_bf16 v[52:55], v[158:161], v[182:185], 0
	v_mfma_f32_16x16x32_bf16 v[44:47], v[174:177], v[182:185], 0
	v_mfma_f32_16x16x32_bf16 v[36:39], v[158:161], v[190:193], 0
	v_mfma_f32_16x16x32_bf16 v[28:31], v[174:177], v[190:193], 0
	v_mfma_f32_16x16x32_bf16 v[20:23], v[158:161], v[198:201], 0
	v_mfma_f32_16x16x32_bf16 v[12:15], v[174:177], v[198:201], 0
	v_mfma_f32_16x16x32_bf16 v[4:7], v[158:161], v[206:209], 0
	v_mfma_f32_16x16x32_bf16 v[0:3], v[174:177], v[206:209], 0
	v_mfma_f32_16x16x32_bf16 v[52:55], v[162:165], v[186:189], v[52:55]
	v_mfma_f32_16x16x32_bf16 v[44:47], v[178:181], v[186:189], v[44:47]
	v_mfma_f32_16x16x32_bf16 v[36:39], v[162:165], v[194:197], v[36:39]
	v_mfma_f32_16x16x32_bf16 v[28:31], v[178:181], v[194:197], v[28:31]
	v_mfma_f32_16x16x32_bf16 v[20:23], v[162:165], v[202:205], v[20:23]
	v_mfma_f32_16x16x32_bf16 v[12:15], v[178:181], v[202:205], v[12:15]
	v_mfma_f32_16x16x32_bf16 v[4:7], v[162:165], v[210:213], v[4:7]
	v_mfma_f32_16x16x32_bf16 v[0:3], v[178:181], v[210:213], v[0:3]
	s_barrier
	s_setprio 0
	v_add_u32_e32 v140, s64, v141
	ds_read_b128 v[134:137], v140
	ds_read_b128 v[146:149], v140 offset:1024
	ds_read_b128 v[150:153], v140 offset:2048
	ds_read_b128 v[154:157], v140 offset:3072
	v_add_u32_e32 v140, s63, v141
	ds_read_b128 v[158:161], v140
	ds_read_b128 v[162:165], v140 offset:1024
	ds_read_b128 v[174:177], v140 offset:2048
	ds_read_b128 v[178:181], v140 offset:3072
	s_mov_b32 m0, s53
	v_lshl_add_u64 v[216:217], s[40:41], 0, v[128:129]
	ds_read_b128 v[182:185], v145 offset:32768
	ds_read_b128 v[186:189], v145 offset:33792
	ds_read_b128 v[190:193], v145 offset:34816
	ds_read_b128 v[194:197], v145 offset:35840
	ds_read_b128 v[198:201], v145 offset:36864
	ds_read_b128 v[202:205], v145 offset:37888
	ds_read_b128 v[206:209], v145 offset:38912
	ds_read_b128 v[210:213], v145 offset:39936
	global_load_lds_dwordx4 v[216:217], off
	v_lshl_add_u64 v[216:217], s[40:41], 0, v[130:131]
	s_mov_b32 m0, s54
	s_nop 0
	global_load_lds_dwordx4 v[216:217], off
	s_waitcnt vmcnt(8)
	s_waitcnt lgkmcnt(0)
	s_setprio 1
	s_barrier
	s_waitcnt lgkmcnt(0)
	v_mfma_f32_16x16x32_bf16 v[124:127], v[134:137], v[182:185], v[124:127]
	v_mfma_f32_16x16x32_bf16 v[120:123], v[150:153], v[182:185], v[120:123]
	v_mfma_f32_16x16x32_bf16 v[108:111], v[134:137], v[190:193], v[108:111]
	v_mfma_f32_16x16x32_bf16 v[104:107], v[150:153], v[190:193], v[104:107]
	v_mfma_f32_16x16x32_bf16 v[92:95], v[134:137], v[198:201], v[92:95]
	v_mfma_f32_16x16x32_bf16 v[88:91], v[150:153], v[198:201], v[88:91]
	v_mfma_f32_16x16x32_bf16 v[76:79], v[134:137], v[206:209], v[76:79]
	v_mfma_f32_16x16x32_bf16 v[72:75], v[150:153], v[206:209], v[72:75]
	v_mfma_f32_16x16x32_bf16 v[124:127], v[146:149], v[186:189], v[124:127]
	v_mfma_f32_16x16x32_bf16 v[120:123], v[154:157], v[186:189], v[120:123]
	v_mfma_f32_16x16x32_bf16 v[108:111], v[146:149], v[194:197], v[108:111]
	v_mfma_f32_16x16x32_bf16 v[104:107], v[154:157], v[194:197], v[104:107]
	v_mfma_f32_16x16x32_bf16 v[92:95], v[146:149], v[202:205], v[92:95]
	v_mfma_f32_16x16x32_bf16 v[88:91], v[154:157], v[202:205], v[88:91]
	v_mfma_f32_16x16x32_bf16 v[76:79], v[146:149], v[210:213], v[76:79]
	v_mfma_f32_16x16x32_bf16 v[72:75], v[154:157], v[210:213], v[72:75]
	s_setprio 0
	s_setprio 1
	v_mfma_f32_16x16x32_bf16 v[116:119], v[158:161], v[182:185], v[116:119]
	v_mfma_f32_16x16x32_bf16 v[112:115], v[174:177], v[182:185], v[112:115]
	v_mfma_f32_16x16x32_bf16 v[100:103], v[158:161], v[190:193], v[100:103]
	v_mfma_f32_16x16x32_bf16 v[96:99], v[174:177], v[190:193], v[96:99]
	v_mfma_f32_16x16x32_bf16 v[84:87], v[158:161], v[198:201], v[84:87]
	v_mfma_f32_16x16x32_bf16 v[80:83], v[174:177], v[198:201], v[80:83]
	v_mfma_f32_16x16x32_bf16 v[68:71], v[158:161], v[206:209], v[68:71]
	v_mfma_f32_16x16x32_bf16 v[64:67], v[174:177], v[206:209], v[64:67]
	v_mfma_f32_16x16x32_bf16 v[116:119], v[162:165], v[186:189], v[116:119]
	v_mfma_f32_16x16x32_bf16 v[112:115], v[178:181], v[186:189], v[112:115]
	v_mfma_f32_16x16x32_bf16 v[100:103], v[162:165], v[194:197], v[100:103]
	v_mfma_f32_16x16x32_bf16 v[96:99], v[178:181], v[194:197], v[96:99]
	v_mfma_f32_16x16x32_bf16 v[84:87], v[162:165], v[202:205], v[84:87]
	v_mfma_f32_16x16x32_bf16 v[80:83], v[178:181], v[202:205], v[80:83]
	v_mfma_f32_16x16x32_bf16 v[68:71], v[162:165], v[210:213], v[68:71]
	v_mfma_f32_16x16x32_bf16 v[64:67], v[178:181], v[210:213], v[64:67]
	s_barrier
; #define PG8_STAGE(bufoff, gbase, voff) do { _Pragma("unroll") for (int _i = 0; _i < 2; ++_i) \
;         __builtin_amdgcn_global_load_lds((const unsigned*)((const char*)(gbase) + (voff)[_i]), (LAS unsigned*)(lds + (bufoff) + ldsw + _i * 8192), 16, 0, 0); } while (0)
; #define PG8_LDA(dst, b, h) do { _Pragma("unroll") for (int m = 0; m < 4; ++m) _Pragma("unroll") for (int k = 0; k < 2; ++k) dst[m][k] = *(const LAS bf16x8*)(lds + PG8_SA(b, h) + aoff + m * 2048 + k * 1024); } while (0)
; #define PG8_LDB(dst, b, h) do { _Pragma("unroll") for (int n = 0; n < 2; ++n) _Pragma("unroll") for (int k = 0; k < 2; ++k) dst[n][k] = *(const LAS bf16x8*)(lds + PG8_SB(b, h) + boff + n * 2048 + k * 1024); } while (0)
; #define PG8_WAIT_V(n) asm volatile("s_waitcnt vmcnt(" #n ")" ::: "memory")
; #define PG8_BAR __builtin_amdgcn_s_barrier()
; template <class Epi, bool ALIGN_EPI>
; __device__ __forceinline__ void gemm_phase(LAS unsigned char* lds, const Gemm g, const StaticOrder& S, const Epi& E, const int tid) {
;     ...
;         for (int t = 0; t < nt; t += 2) {
;             const bool last = (t == nt - 2);
;             const char* a1 = cA + (size_t)(t + 1) * kstep;
;             const char* a2 = last ? nA : cA + (size_t)(t + 2) * kstep; const char* b2 = last ? nB : cB + (size_t)(t + 2) * kstep;
;             const char* a3 = a2 + kstep; const char* b3 = b2 + kstep;
;             PG8_LDB(B0, 0, 0); PG8_LDB(B1, 0, 1); PG8_SCHED; PG8_LDA(At, 0, 0); PG8_STAGE(PG8_SA(1, 1), a1 + hA, voffA);
;             PG8_WAIT_V(8); PG8_WAIT_L(0); PG8_BAR; PG8_MMA(0, 0, At, B0); PG8_MMA(0, 1, At, B1); PG8_BAR; PG8_SCHED;
;             PG8_LDA(At, 0, 1); PG8_STAGE(PG8_SB(0, 0), b2, voffB); PG8_STAGE(PG8_SB(0, 1), b2 + hB, voffB); PG8_STAGE(PG8_SA(0, 0), a2, voffA);
;             PG8_WAIT_V(8); PG8_WAIT_L(0); PG8_BAR; PG8_MMA(1, 0, At, B0); PG8_MMA(1, 1, At, B1); PG8_BAR; PG8_SCHED;
;             PG8_LDB(B0, 1, 0); PG8_LDB(B1, 1, 1); PG8_SCHED; PG8_LDA(At, 1, 0); PG8_STAGE(PG8_SA(0, 1), a2 + hA, voffA);
;             PG8_WAIT_V(8); PG8_WAIT_L(0); PG8_BAR; PG8_MMA(0, 0, At, B0); PG8_MMA(0, 1, At, B1); PG8_BAR; PG8_SCHED;
;             PG8_LDA(At, 1, 1); PG8_STAGE(PG8_SB(1, 0), b3, voffB); PG8_STAGE(PG8_SB(1, 1), b3 + hB, voffB); PG8_STAGE(PG8_SA(1, 0), a3, voffA);
;             PG8_WAIT_V(8); PG8_WAIT_L(0); PG8_BAR; PG8_MMA(1, 0, At, B0); PG8_MMA(1, 1, At, B1); PG8_BAR; PG8_SCHED;
	s_setprio 0
	s_mov_b32 m0, s62
	v_lshl_add_u64 v[138:139], v[138:139], 0, s[92:93]
	ds_read_b128 v[182:185], v145 offset:49152
	ds_read_b128 v[186:189], v145 offset:50176
	ds_read_b128 v[190:193], v145 offset:51200
	ds_read_b128 v[194:197], v145 offset:52224
	ds_read_b128 v[198:201], v145 offset:53248
	ds_read_b128 v[202:205], v145 offset:54272
	ds_read_b128 v[206:209], v145 offset:55296
	ds_read_b128 v[210:213], v145 offset:56320
	global_load_lds_dwordx4 v[138:139], off
	v_lshl_add_u64 v[138:139], v[142:143], 0, s[92:93]
	s_mov_b32 m0, s61
	s_nop 0
	global_load_lds_dwordx4 v[138:139], off
	v_lshl_add_u64 v[138:139], s[38:39], 0, v[168:169]
	s_mov_b32 m0, s70
	s_nop 0
	global_load_lds_dwordx4 v[138:139], off
	v_lshl_add_u64 v[138:139], s[38:39], 0, v[132:133]
	s_mov_b32 m0, s69
	s_nop 0
	global_load_lds_dwordx4 v[138:139], off
	v_lshl_add_u64 v[138:139], v[166:167], 0, s[92:93]
	s_mov_b32 m0, s55
	s_nop 0
	global_load_lds_dwordx4 v[138:139], off
	v_lshl_add_u64 v[138:139], v[214:215], 0, s[92:93]
	s_mov_b32 m0, s56
	s_nop 0
	global_load_lds_dwordx4 v[138:139], off
	s_waitcnt vmcnt(8)
	s_waitcnt lgkmcnt(0)
	s_setprio 1
	s_barrier
	s_waitcnt lgkmcnt(0)
	v_mfma_f32_16x16x32_bf16 v[60:63], v[134:137], v[182:185], v[60:63]
	v_mfma_f32_16x16x32_bf16 v[56:59], v[150:153], v[182:185], v[56:59]
	v_mfma_f32_16x16x32_bf16 v[48:51], v[134:137], v[190:193], v[48:51]
	v_mfma_f32_16x16x32_bf16 v[40:43], v[150:153], v[190:193], v[40:43]
	v_mfma_f32_16x16x32_bf16 v[32:35], v[134:137], v[198:201], v[32:35]
	v_mfma_f32_16x16x32_bf16 v[24:27], v[150:153], v[198:201], v[24:27]
	v_mfma_f32_16x16x32_bf16 v[16:19], v[134:137], v[206:209], v[16:19]
	v_mfma_f32_16x16x32_bf16 v[8:11], v[150:153], v[206:209], v[8:11]
	v_mfma_f32_16x16x32_bf16 v[60:63], v[146:149], v[186:189], v[60:63]
	v_mfma_f32_16x16x32_bf16 v[56:59], v[154:157], v[186:189], v[56:59]
	v_mfma_f32_16x16x32_bf16 v[48:51], v[146:149], v[194:197], v[48:51]
	v_mfma_f32_16x16x32_bf16 v[40:43], v[154:157], v[194:197], v[40:43]
	v_mfma_f32_16x16x32_bf16 v[32:35], v[146:149], v[202:205], v[32:35]
	v_mfma_f32_16x16x32_bf16 v[24:27], v[154:157], v[202:205], v[24:27]
	v_mfma_f32_16x16x32_bf16 v[16:19], v[146:149], v[210:213], v[16:19]
	v_mfma_f32_16x16x32_bf16 v[8:11], v[154:157], v[210:213], v[8:11]
	s_setprio 0
	s_setprio 1
	v_mfma_f32_16x16x32_bf16 v[52:55], v[158:161], v[182:185], v[52:55]
	v_mfma_f32_16x16x32_bf16 v[44:47], v[174:177], v[182:185], v[44:47]
	v_mfma_f32_16x16x32_bf16 v[36:39], v[158:161], v[190:193], v[36:39]
	v_mfma_f32_16x16x32_bf16 v[28:31], v[174:177], v[190:193], v[28:31]
	v_mfma_f32_16x16x32_bf16 v[20:23], v[158:161], v[198:201], v[20:23]
	v_mfma_f32_16x16x32_bf16 v[12:15], v[174:177], v[198:201], v[12:15]
	v_mfma_f32_16x16x32_bf16 v[4:7], v[158:161], v[206:209], v[4:7]
	v_mfma_f32_16x16x32_bf16 v[0:3], v[174:177], v[206:209], v[0:3]
	v_mfma_f32_16x16x32_bf16 v[52:55], v[162:165], v[186:189], v[52:55]
	v_mfma_f32_16x16x32_bf16 v[44:47], v[178:181], v[186:189], v[44:47]
	v_mfma_f32_16x16x32_bf16 v[36:39], v[162:165], v[194:197], v[36:39]
	v_mfma_f32_16x16x32_bf16 v[28:31], v[178:181], v[194:197], v[28:31]
	v_mfma_f32_16x16x32_bf16 v[20:23], v[162:165], v[202:205], v[20:23]
	v_mfma_f32_16x16x32_bf16 v[12:15], v[178:181], v[202:205], v[12:15]
	v_mfma_f32_16x16x32_bf16 v[4:7], v[162:165], v[210:213], v[4:7]
	v_mfma_f32_16x16x32_bf16 v[0:3], v[178:181], v[210:213], v[0:3]
	s_barrier
	s_setprio 0
	s_movk_i32 s40, 0x100
	s_andn2_b64 vcc, exec, s[36:37]
	s_mov_b64 s[38:39], -1
	s_mov_b64 s[36:37], 0
.LBB0_379:
	s_add_u32 s41, s34, s40
	s_addc_u32 s46, s35, 0
	s_add_u32 s44, s41, 0x100
	s_addc_u32 s45, s46, 0
	s_and_b64 s[42:43], s[38:39], exec
	s_cselect_b32 s43, s17, s45
	s_cselect_b32 s42, s59, s44
	s_add_u32 s40, s30, s40
	s_addc_u32 s44, s31, 0
	s_add_u32 s40, s40, 0x100
	s_addc_u32 s44, s44, 0
	s_and_b64 s[38:39], s[38:39], exec
	s_cselect_b32 s45, s15, s44
	s_cselect_b32 s44, s60, s40
	s_add_i32 s39, 0, 0x14000
	s_add_u32 s48, s41, 0x10080
	s_addc_u32 s49, s46, 0
	s_add_i32 s68, s33, s50
	s_add_i32 m0, s51, 0xc000
	s_add_i32 s71, s51, 0xe000
	s_add_i32 s65, s68, 0x2000
	v_add_u32_e32 v138, s33, v141
	s_add_u32 s46, s44, 0x10000
	ds_read_b128 v[134:137], v138
	ds_read_b128 v[146:149], v138 offset:1024
	ds_read_b128 v[150:153], v138 offset:2048
	ds_read_b128 v[154:157], v138 offset:3072
	v_add_u32_e32 v138, s39, v141
	s_addc_u32 s47, s45, 0
	s_add_i32 s67, s39, s50
	ds_read_b128 v[158:161], v138
	ds_read_b128 v[162:165], v138 offset:1024
	ds_read_b128 v[174:177], v138 offset:2048
	ds_read_b128 v[178:181], v138 offset:3072
	s_add_i32 s66, s67, 0x2000
	s_add_i32 s64, 0, 0x18000
	s_add_i32 s63, 0, 0x1c000
	s_add_u32 s40, s42, 0x10000
	s_addc_u32 s41, s43, 0
	s_add_i32 s62, s64, s50
	s_add_i32 s61, s62, 0x2000
	s_add_u32 s38, s44, 0x10080
	s_addc_u32 s39, s45, 0
	s_add_i32 s70, s63, s50
	s_add_i32 s69, s70, 0x2000
	v_lshl_add_u64 v[138:139], s[48:49], 0, v[128:129]
	ds_read_b128 v[182:185], v145
	ds_read_b128 v[186:189], v145 offset:1024
	ds_read_b128 v[190:193], v145 offset:2048
	ds_read_b128 v[194:197], v145 offset:3072
	ds_read_b128 v[198:201], v145 offset:4096
	ds_read_b128 v[202:205], v145 offset:5120
	ds_read_b128 v[206:209], v145 offset:6144
	ds_read_b128 v[210:213], v145 offset:7168
	global_load_lds_dwordx4 v[138:139], off
	v_lshl_add_u64 v[138:139], s[48:49], 0, v[130:131]
	s_mov_b32 m0, s71
	s_nop 0
	global_load_lds_dwordx4 v[138:139], off
	s_waitcnt vmcnt(8)
	s_waitcnt lgkmcnt(0)
	s_setprio 1
	s_barrier
; #define PG8_STAGE(bufoff, gbase, voff) do { _Pragma("unroll") for (int _i = 0; _i < 2; ++_i) \
;         __builtin_amdgcn_global_load_lds((const unsigned*)((const char*)(gbase) + (voff)[_i]), (LAS unsigned*)(lds + (bufoff) + ldsw + _i * 8192), 16, 0, 0); } while (0)
; #define PG8_LDA(dst, b, h) do { _Pragma("unroll") for (int m = 0; m < 4; ++m) _Pragma("unroll") for (int k = 0; k < 2; ++k) dst[m][k] = *(const LAS bf16x8*)(lds + PG8_SA(b, h) + aoff + m * 2048 + k * 1024); } while (0)
; #define PG8_LDB(dst, b, h) do { _Pragma("unroll") for (int n = 0; n < 2; ++n) _Pragma("unroll") for (int k = 0; k < 2; ++k) dst[n][k] = *(const LAS bf16x8*)(lds + PG8_SB(b, h) + boff + n * 2048 + k * 1024); } while (0)
; #define PG8_MMA(ai, bj, At, Bt) do { __builtin_amdgcn_s_setprio(1); _Pragma("unroll") for (int k = 0; k < 2; ++k) _Pragma("unroll") for (int m = 0; m < 4; ++m) _Pragma("unroll") for (int n = 0; n < 2; ++n) \
;         acc[ai][bj][m][n] = __builtin_amdgcn_mfma_f32_16x16x32_bf16(Bt[n][k], At[m][k], acc[ai][bj][m][n], 0, 0, 0); __builtin_amdgcn_s_setprio(0); } while (0)
; #define PG8_WAIT_V(n) asm volatile("s_waitcnt vmcnt(" #n ")" ::: "memory")
; #define PG8_BAR __builtin_amdgcn_s_barrier()
; template <class Epi, bool ALIGN_EPI>
; __device__ __forceinline__ void gemm_phase(LAS unsigned char* lds, const Gemm g, const StaticOrder& S, const Epi& E, const int tid) {
;     ...
;             PG8_LDB(B0, 0, 0); PG8_LDB(B1, 0, 1); PG8_SCHED; PG8_LDA(At, 0, 0); PG8_STAGE(PG8_SA(1, 1), a1 + hA, voffA);
;             PG8_WAIT_V(8); PG8_WAIT_L(0); PG8_BAR; PG8_MMA(0, 0, At, B0); PG8_MMA(0, 1, At, B1); PG8_BAR; PG8_SCHED;
;             PG8_LDA(At, 0, 1); PG8_STAGE(PG8_SB(0, 0), b2, voffB); PG8_STAGE(PG8_SB(0, 1), b2 + hB, voffB); PG8_STAGE(PG8_SA(0, 0), a2, voffA);
;             PG8_WAIT_V(8); PG8_WAIT_L(0); PG8_BAR; PG8_MMA(1, 0, At, B0); PG8_MMA(1, 1, At, B1); PG8_BAR; PG8_SCHED;
;             PG8_LDB(B0, 1, 0); PG8_LDB(B1, 1, 1); PG8_SCHED; PG8_LDA(At, 1, 0); PG8_STAGE(PG8_SA(0, 1), a2 + hA, voffA);
;             PG8_WAIT_V(8); PG8_WAIT_L(0); PG8_BAR; PG8_MMA(0, 0, At, B0); PG8_MMA(0, 1, At, B1); PG8_BAR; PG8_SCHED;
;             PG8_LDA(At, 1, 1); PG8_STAGE(PG8_SB(1, 0), b3, voffB); PG8_STAGE(PG8_SB(1, 1), b3 + hB, voffB); PG8_STAGE(PG8_SA(1, 0), a3, voffA);
;             PG8_WAIT_V(8); PG8_WAIT_L(0); PG8_BAR; PG8_MMA(1, 0, At, B0); PG8_MMA(1, 1, At, B1); PG8_BAR; PG8_SCHED;
	s_waitcnt lgkmcnt(0)
	v_mfma_f32_16x16x32_bf16 v[124:127], v[134:137], v[182:185], v[124:127]
	v_mfma_f32_16x16x32_bf16 v[120:123], v[150:153], v[182:185], v[120:123]
	v_mfma_f32_16x16x32_bf16 v[108:111], v[134:137], v[190:193], v[108:111]
	v_mfma_f32_16x16x32_bf16 v[104:107], v[150:153], v[190:193], v[104:107]
	v_mfma_f32_16x16x32_bf16 v[92:95], v[134:137], v[198:201], v[92:95]
	v_mfma_f32_16x16x32_bf16 v[88:91], v[150:153], v[198:201], v[88:91]
	v_mfma_f32_16x16x32_bf16 v[76:79], v[134:137], v[206:209], v[76:79]
	v_mfma_f32_16x16x32_bf16 v[72:75], v[150:153], v[206:209], v[72:75]
	v_mfma_f32_16x16x32_bf16 v[124:127], v[146:149], v[186:189], v[124:127]
	v_mfma_f32_16x16x32_bf16 v[120:123], v[154:157], v[186:189], v[120:123]
	v_mfma_f32_16x16x32_bf16 v[108:111], v[146:149], v[194:197], v[108:111]
	v_mfma_f32_16x16x32_bf16 v[104:107], v[154:157], v[194:197], v[104:107]
	v_mfma_f32_16x16x32_bf16 v[92:95], v[146:149], v[202:205], v[92:95]
	v_mfma_f32_16x16x32_bf16 v[88:91], v[154:157], v[202:205], v[88:91]
	v_mfma_f32_16x16x32_bf16 v[76:79], v[146:149], v[210:213], v[76:79]
	v_mfma_f32_16x16x32_bf16 v[72:75], v[154:157], v[210:213], v[72:75]
	s_setprio 0
	s_setprio 1
	v_mfma_f32_16x16x32_bf16 v[116:119], v[158:161], v[182:185], v[116:119]
	v_mfma_f32_16x16x32_bf16 v[112:115], v[174:177], v[182:185], v[112:115]
	v_mfma_f32_16x16x32_bf16 v[100:103], v[158:161], v[190:193], v[100:103]
	v_mfma_f32_16x16x32_bf16 v[96:99], v[174:177], v[190:193], v[96:99]
	v_mfma_f32_16x16x32_bf16 v[84:87], v[158:161], v[198:201], v[84:87]
	v_mfma_f32_16x16x32_bf16 v[80:83], v[174:177], v[198:201], v[80:83]
	v_mfma_f32_16x16x32_bf16 v[68:71], v[158:161], v[206:209], v[68:71]
	v_mfma_f32_16x16x32_bf16 v[64:67], v[174:177], v[206:209], v[64:67]
	v_mfma_f32_16x16x32_bf16 v[116:119], v[162:165], v[186:189], v[116:119]
	v_mfma_f32_16x16x32_bf16 v[112:115], v[178:181], v[186:189], v[112:115]
	v_mfma_f32_16x16x32_bf16 v[100:103], v[162:165], v[194:197], v[100:103]
	v_mfma_f32_16x16x32_bf16 v[96:99], v[178:181], v[194:197], v[96:99]
	v_mfma_f32_16x16x32_bf16 v[84:87], v[162:165], v[202:205], v[84:87]
	v_mfma_f32_16x16x32_bf16 v[80:83], v[178:181], v[202:205], v[80:83]
	v_mfma_f32_16x16x32_bf16 v[68:71], v[162:165], v[210:213], v[68:71]
	v_mfma_f32_16x16x32_bf16 v[64:67], v[178:181], v[210:213], v[64:67]
	s_barrier
	s_setprio 0
	s_mov_b32 m0, s68
	v_lshl_add_u64 v[138:139], s[44:45], 0, v[168:169]
	ds_read_b128 v[182:185], v145 offset:16384
	ds_read_b128 v[186:189], v145 offset:17408
	ds_read_b128 v[190:193], v145 offset:18432
	ds_read_b128 v[194:197], v145 offset:19456
	ds_read_b128 v[198:201], v145 offset:20480
	ds_read_b128 v[202:205], v145 offset:21504
	ds_read_b128 v[206:209], v145 offset:22528
	ds_read_b128 v[210:213], v145 offset:23552
	global_load_lds_dwordx4 v[138:139], off
	v_lshl_add_u64 v[142:143], s[44:45], 0, v[132:133]
	s_mov_b32 m0, s65
	v_lshl_add_u64 v[166:167], s[46:47], 0, v[168:169]
	global_load_lds_dwordx4 v[142:143], off
	s_mov_b32 m0, s67
	v_lshl_add_u64 v[214:215], s[42:43], 0, v[130:131]
	global_load_lds_dwordx4 v[166:167], off
	v_lshl_add_u64 v[166:167], s[46:47], 0, v[132:133]
	s_mov_b32 m0, s66
	s_nop 0
	global_load_lds_dwordx4 v[166:167], off
	v_lshl_add_u64 v[166:167], s[42:43], 0, v[128:129]
	s_mov_b32 m0, s51
	s_nop 0
	global_load_lds_dwordx4 v[166:167], off
	s_mov_b32 m0, s52
	s_nop 0
	global_load_lds_dwordx4 v[214:215], off
	s_waitcnt vmcnt(8)
	s_waitcnt lgkmcnt(0)
	s_setprio 1
	s_barrier
	s_waitcnt lgkmcnt(0)
	v_mfma_f32_16x16x32_bf16 v[60:63], v[134:137], v[182:185], v[60:63]
	v_mfma_f32_16x16x32_bf16 v[56:59], v[150:153], v[182:185], v[56:59]
	v_mfma_f32_16x16x32_bf16 v[48:51], v[134:137], v[190:193], v[48:51]
	v_mfma_f32_16x16x32_bf16 v[40:43], v[150:153], v[190:193], v[40:43]
	v_mfma_f32_16x16x32_bf16 v[32:35], v[134:137], v[198:201], v[32:35]
	v_mfma_f32_16x16x32_bf16 v[24:27], v[150:153], v[198:201], v[24:27]
	v_mfma_f32_16x16x32_bf16 v[16:19], v[134:137], v[206:209], v[16:19]
	v_mfma_f32_16x16x32_bf16 v[8:11], v[150:153], v[206:209], v[8:11]
	v_mfma_f32_16x16x32_bf16 v[60:63], v[146:149], v[186:189], v[60:63]
	v_mfma_f32_16x16x32_bf16 v[56:59], v[154:157], v[186:189], v[56:59]
	v_mfma_f32_16x16x32_bf16 v[48:51], v[146:149], v[194:197], v[48:51]
	v_mfma_f32_16x16x32_bf16 v[40:43], v[154:157], v[194:197], v[40:43]
	v_mfma_f32_16x16x32_bf16 v[32:35], v[146:149], v[202:205], v[32:35]
	v_mfma_f32_16x16x32_bf16 v[24:27], v[154:157], v[202:205], v[24:27]
	v_mfma_f32_16x16x32_bf16 v[16:19], v[146:149], v[210:213], v[16:19]
	v_mfma_f32_16x16x32_bf16 v[8:11], v[154:157], v[210:213], v[8:11]
	s_setprio 0
	s_setprio 1
	v_mfma_f32_16x16x32_bf16 v[52:55], v[158:161], v[182:185], v[52:55]
	v_mfma_f32_16x16x32_bf16 v[44:47], v[174:177], v[182:185], v[44:47]
	v_mfma_f32_16x16x32_bf16 v[36:39], v[158:161], v[190:193], v[36:39]
	v_mfma_f32_16x16x32_bf16 v[28:31], v[174:177], v[190:193], v[28:31]
	v_mfma_f32_16x16x32_bf16 v[20:23], v[158:161], v[198:201], v[20:23]
	v_mfma_f32_16x16x32_bf16 v[12:15], v[174:177], v[198:201], v[12:15]
	v_mfma_f32_16x16x32_bf16 v[4:7], v[158:161], v[206:209], v[4:7]
	v_mfma_f32_16x16x32_bf16 v[0:3], v[174:177], v[206:209], v[0:3]
	v_mfma_f32_16x16x32_bf16 v[52:55], v[162:165], v[186:189], v[52:55]
	v_mfma_f32_16x16x32_bf16 v[44:47], v[178:181], v[186:189], v[44:47]
	v_mfma_f32_16x16x32_bf16 v[36:39], v[162:165], v[194:197], v[36:39]
	v_mfma_f32_16x16x32_bf16 v[28:31], v[178:181], v[194:197], v[28:31]
	v_mfma_f32_16x16x32_bf16 v[20:23], v[162:165], v[202:205], v[20:23]
	v_mfma_f32_16x16x32_bf16 v[12:15], v[178:181], v[202:205], v[12:15]
	v_mfma_f32_16x16x32_bf16 v[4:7], v[162:165], v[210:213], v[4:7]
	v_mfma_f32_16x16x32_bf16 v[0:3], v[178:181], v[210:213], v[0:3]
	s_barrier
; #define PG8_STAGE(bufoff, gbase, voff) do { _Pragma("unroll") for (int _i = 0; _i < 2; ++_i) \
;         __builtin_amdgcn_global_load_lds((const unsigned*)((const char*)(gbase) + (voff)[_i]), (LAS unsigned*)(lds + (bufoff) + ldsw + _i * 8192), 16, 0, 0); } while (0)
; #define PG8_LDA(dst, b, h) do { _Pragma("unroll") for (int m = 0; m < 4; ++m) _Pragma("unroll") for (int k = 0; k < 2; ++k) dst[m][k] = *(const LAS bf16x8*)(lds + PG8_SA(b, h) + aoff + m * 2048 + k * 1024); } while (0)
; #define PG8_LDB(dst, b, h) do { _Pragma("unroll") for (int n = 0; n < 2; ++n) _Pragma("unroll") for (int k = 0; k < 2; ++k) dst[n][k] = *(const LAS bf16x8*)(lds + PG8_SB(b, h) + boff + n * 2048 + k * 1024); } while (0)
; #define PG8_MMA(ai, bj, At, Bt) do { __builtin_amdgcn_s_setprio(1); _Pragma("unroll") for (int k = 0; k < 2; ++k) _Pragma("unroll") for (int m = 0; m < 4; ++m) _Pragma("unroll") for (int n = 0; n < 2; ++n) \
;         acc[ai][bj][m][n] = __builtin_amdgcn_mfma_f32_16x16x32_bf16(Bt[n][k], At[m][k], acc[ai][bj][m][n], 0, 0, 0); __builtin_amdgcn_s_setprio(0); } while (0)
; #define PG8_BAR __builtin_amdgcn_s_barrier()
; template <class Epi, bool ALIGN_EPI>
; __device__ __forceinline__ void gemm_phase(LAS unsigned char* lds, const Gemm g, const StaticOrder& S, const Epi& E, const int tid) {
;     ...
;             PG8_LDB(B0, 0, 0); PG8_LDB(B1, 0, 1); PG8_SCHED; PG8_LDA(At, 0, 0); PG8_STAGE(PG8_SA(1, 1), a1 + hA, voffA);
;             PG8_WAIT_V(8); PG8_WAIT_L(0); PG8_BAR; PG8_MMA(0, 0, At, B0); PG8_MMA(0, 1, At, B1); PG8_BAR; PG8_SCHED;
;             PG8_LDA(At, 0, 1); PG8_STAGE(PG8_SB(0, 0), b2, voffB); PG8_STAGE(PG8_SB(0, 1), b2 + hB, voffB); PG8_STAGE(PG8_SA(0, 0), a2, voffA);
;             PG8_WAIT_V(8); PG8_WAIT_L(0); PG8_BAR; PG8_MMA(1, 0, At, B0); PG8_MMA(1, 1, At, B1); PG8_BAR; PG8_SCHED;
;             PG8_LDB(B0, 1, 0); PG8_LDB(B1, 1, 1); PG8_SCHED; PG8_LDA(At, 1, 0); PG8_STAGE(PG8_SA(0, 1), a2 + hA, voffA);
;             PG8_WAIT_V(8); PG8_WAIT_L(0); PG8_BAR; PG8_MMA(0, 0, At, B0); PG8_MMA(0, 1, At, B1); PG8_BAR; PG8_SCHED;
;             PG8_LDA(At, 1, 1); PG8_STAGE(PG8_SB(1, 0), b3, voffB); PG8_STAGE(PG8_SB(1, 1), b3 + hB, voffB); PG8_STAGE(PG8_SA(1, 0), a3, voffA);
;             PG8_WAIT_V(8); PG8_WAIT_L(0); PG8_BAR; PG8_MMA(1, 0, At, B0); PG8_MMA(1, 1, At, B1); PG8_BAR; PG8_SCHED;
;         }
;         if constexpr (ALIGN_EPI) { if (wr == 0) PG8_BAR; }
	s_setprio 0
	v_add_u32_e32 v140, s64, v141
	ds_read_b128 v[134:137], v140
	ds_read_b128 v[146:149], v140 offset:1024
	ds_read_b128 v[150:153], v140 offset:2048
	ds_read_b128 v[154:157], v140 offset:3072
	v_add_u32_e32 v140, s63, v141
	ds_read_b128 v[158:161], v140
	ds_read_b128 v[162:165], v140 offset:1024
	ds_read_b128 v[174:177], v140 offset:2048
	ds_read_b128 v[178:181], v140 offset:3072
	s_mov_b32 m0, s53
	v_lshl_add_u64 v[216:217], s[40:41], 0, v[128:129]
	ds_read_b128 v[182:185], v145 offset:32768
	ds_read_b128 v[186:189], v145 offset:33792
	ds_read_b128 v[190:193], v145 offset:34816
	ds_read_b128 v[194:197], v145 offset:35840
	ds_read_b128 v[198:201], v145 offset:36864
	ds_read_b128 v[202:205], v145 offset:37888
	ds_read_b128 v[206:209], v145 offset:38912
	ds_read_b128 v[210:213], v145 offset:39936
	global_load_lds_dwordx4 v[216:217], off
	v_lshl_add_u64 v[216:217], s[40:41], 0, v[130:131]
	s_mov_b32 m0, s54
	s_nop 0
	global_load_lds_dwordx4 v[216:217], off
	s_waitcnt vmcnt(8)
	s_waitcnt lgkmcnt(0)
	s_setprio 1
	s_barrier
	s_waitcnt lgkmcnt(0)
	v_mfma_f32_16x16x32_bf16 v[124:127], v[134:137], v[182:185], v[124:127]
	v_mfma_f32_16x16x32_bf16 v[120:123], v[150:153], v[182:185], v[120:123]
	v_mfma_f32_16x16x32_bf16 v[108:111], v[134:137], v[190:193], v[108:111]
	v_mfma_f32_16x16x32_bf16 v[104:107], v[150:153], v[190:193], v[104:107]
	v_mfma_f32_16x16x32_bf16 v[92:95], v[134:137], v[198:201], v[92:95]
	v_mfma_f32_16x16x32_bf16 v[88:91], v[150:153], v[198:201], v[88:91]
	v_mfma_f32_16x16x32_bf16 v[76:79], v[134:137], v[206:209], v[76:79]
	v_mfma_f32_16x16x32_bf16 v[72:75], v[150:153], v[206:209], v[72:75]
	v_mfma_f32_16x16x32_bf16 v[124:127], v[146:149], v[186:189], v[124:127]
	v_mfma_f32_16x16x32_bf16 v[120:123], v[154:157], v[186:189], v[120:123]
	v_mfma_f32_16x16x32_bf16 v[108:111], v[146:149], v[194:197], v[108:111]
	v_mfma_f32_16x16x32_bf16 v[104:107], v[154:157], v[194:197], v[104:107]
	v_mfma_f32_16x16x32_bf16 v[92:95], v[146:149], v[202:205], v[92:95]
	v_mfma_f32_16x16x32_bf16 v[88:91], v[154:157], v[202:205], v[88:91]
	v_mfma_f32_16x16x32_bf16 v[76:79], v[146:149], v[210:213], v[76:79]
	v_mfma_f32_16x16x32_bf16 v[72:75], v[154:157], v[210:213], v[72:75]
	s_setprio 0
	s_setprio 1
	v_mfma_f32_16x16x32_bf16 v[116:119], v[158:161], v[182:185], v[116:119]
	v_mfma_f32_16x16x32_bf16 v[112:115], v[174:177], v[182:185], v[112:115]
	v_mfma_f32_16x16x32_bf16 v[100:103], v[158:161], v[190:193], v[100:103]
	v_mfma_f32_16x16x32_bf16 v[96:99], v[174:177], v[190:193], v[96:99]
	v_mfma_f32_16x16x32_bf16 v[84:87], v[158:161], v[198:201], v[84:87]
	v_mfma_f32_16x16x32_bf16 v[80:83], v[174:177], v[198:201], v[80:83]
	v_mfma_f32_16x16x32_bf16 v[68:71], v[158:161], v[206:209], v[68:71]
	v_mfma_f32_16x16x32_bf16 v[64:67], v[174:177], v[206:209], v[64:67]
	v_mfma_f32_16x16x32_bf16 v[116:119], v[162:165], v[186:189], v[116:119]
	v_mfma_f32_16x16x32_bf16 v[112:115], v[178:181], v[186:189], v[112:115]
	v_mfma_f32_16x16x32_bf16 v[100:103], v[162:165], v[194:197], v[100:103]
	v_mfma_f32_16x16x32_bf16 v[96:99], v[178:181], v[194:197], v[96:99]
	v_mfma_f32_16x16x32_bf16 v[84:87], v[162:165], v[202:205], v[84:87]
	v_mfma_f32_16x16x32_bf16 v[80:83], v[178:181], v[202:205], v[80:83]
	v_mfma_f32_16x16x32_bf16 v[68:71], v[162:165], v[210:213], v[68:71]
	v_mfma_f32_16x16x32_bf16 v[64:67], v[178:181], v[210:213], v[64:67]
	s_barrier
	s_setprio 0
	s_mov_b32 m0, s62
	v_lshl_add_u64 v[138:139], v[138:139], 0, s[92:93]
	ds_read_b128 v[182:185], v145 offset:49152
	ds_read_b128 v[186:189], v145 offset:50176
	ds_read_b128 v[190:193], v145 offset:51200
	ds_read_b128 v[194:197], v145 offset:52224
	ds_read_b128 v[198:201], v145 offset:53248
	ds_read_b128 v[202:205], v145 offset:54272
	ds_read_b128 v[206:209], v145 offset:55296
	ds_read_b128 v[210:213], v145 offset:56320
	global_load_lds_dwordx4 v[138:139], off
	v_lshl_add_u64 v[138:139], v[142:143], 0, s[92:93]
	s_mov_b32 m0, s61
	s_nop 0
	global_load_lds_dwordx4 v[138:139], off
	v_lshl_add_u64 v[138:139], s[38:39], 0, v[168:169]
	s_mov_b32 m0, s70
	s_nop 0
	global_load_lds_dwordx4 v[138:139], off
	v_lshl_add_u64 v[138:139], s[38:39], 0, v[132:133]
	s_mov_b32 m0, s69
	s_nop 0
	global_load_lds_dwordx4 v[138:139], off
	v_lshl_add_u64 v[138:139], v[166:167], 0, s[92:93]
	s_mov_b32 m0, s55
	s_nop 0
	global_load_lds_dwordx4 v[138:139], off
	v_lshl_add_u64 v[138:139], v[214:215], 0, s[92:93]
	s_mov_b32 m0, s56
	s_nop 0
	global_load_lds_dwordx4 v[138:139], off
	s_waitcnt vmcnt(8)
	s_waitcnt lgkmcnt(0)
	s_setprio 1
	s_barrier
	s_waitcnt lgkmcnt(0)
	v_mfma_f32_16x16x32_bf16 v[60:63], v[134:137], v[182:185], v[60:63]
	v_mfma_f32_16x16x32_bf16 v[56:59], v[150:153], v[182:185], v[56:59]
	v_mfma_f32_16x16x32_bf16 v[48:51], v[134:137], v[190:193], v[48:51]
	v_mfma_f32_16x16x32_bf16 v[40:43], v[150:153], v[190:193], v[40:43]
	v_mfma_f32_16x16x32_bf16 v[32:35], v[134:137], v[198:201], v[32:35]
	v_mfma_f32_16x16x32_bf16 v[24:27], v[150:153], v[198:201], v[24:27]
	v_mfma_f32_16x16x32_bf16 v[16:19], v[134:137], v[206:209], v[16:19]
	v_mfma_f32_16x16x32_bf16 v[8:11], v[150:153], v[206:209], v[8:11]
	v_mfma_f32_16x16x32_bf16 v[60:63], v[146:149], v[186:189], v[60:63]
	v_mfma_f32_16x16x32_bf16 v[56:59], v[154:157], v[186:189], v[56:59]
	v_mfma_f32_16x16x32_bf16 v[48:51], v[146:149], v[194:197], v[48:51]
	v_mfma_f32_16x16x32_bf16 v[40:43], v[154:157], v[194:197], v[40:43]
	v_mfma_f32_16x16x32_bf16 v[32:35], v[146:149], v[202:205], v[32:35]
	v_mfma_f32_16x16x32_bf16 v[24:27], v[154:157], v[202:205], v[24:27]
	v_mfma_f32_16x16x32_bf16 v[16:19], v[146:149], v[210:213], v[16:19]
	v_mfma_f32_16x16x32_bf16 v[8:11], v[154:157], v[210:213], v[8:11]
	s_setprio 0
	s_setprio 1
	v_mfma_f32_16x16x32_bf16 v[52:55], v[158:161], v[182:185], v[52:55]
	v_mfma_f32_16x16x32_bf16 v[44:47], v[174:177], v[182:185], v[44:47]
	v_mfma_f32_16x16x32_bf16 v[36:39], v[158:161], v[190:193], v[36:39]
	v_mfma_f32_16x16x32_bf16 v[28:31], v[174:177], v[190:193], v[28:31]
	v_mfma_f32_16x16x32_bf16 v[20:23], v[158:161], v[198:201], v[20:23]
	v_mfma_f32_16x16x32_bf16 v[12:15], v[174:177], v[198:201], v[12:15]
	v_mfma_f32_16x16x32_bf16 v[4:7], v[158:161], v[206:209], v[4:7]
	v_mfma_f32_16x16x32_bf16 v[0:3], v[174:177], v[206:209], v[0:3]
	v_mfma_f32_16x16x32_bf16 v[52:55], v[162:165], v[186:189], v[52:55]
	v_mfma_f32_16x16x32_bf16 v[44:47], v[178:181], v[186:189], v[44:47]
	v_mfma_f32_16x16x32_bf16 v[36:39], v[162:165], v[194:197], v[36:39]
	v_mfma_f32_16x16x32_bf16 v[28:31], v[178:181], v[194:197], v[28:31]
	v_mfma_f32_16x16x32_bf16 v[20:23], v[162:165], v[202:205], v[20:23]
	v_mfma_f32_16x16x32_bf16 v[12:15], v[178:181], v[202:205], v[12:15]
	v_mfma_f32_16x16x32_bf16 v[4:7], v[162:165], v[210:213], v[4:7]
	v_mfma_f32_16x16x32_bf16 v[0:3], v[178:181], v[210:213], v[0:3]
	s_barrier
	s_setprio 0
	s_movk_i32 s40, 0x100
	s_andn2_b64 vcc, exec, s[36:37]
	s_mov_b64 s[38:39], -1
	s_mov_b64 s[36:37], 0
	s_cbranch_vccz .LBB0_379
	v_readlane_b32 s60, v255, 51
	s_and_b64 vcc, exec, s[12:13]
	v_readlane_b32 s61, v255, 52
	s_cbranch_vccz .LBB0_382
	s_barrier
